# v5 + K-loop MFMA order: the two K-halves of each accumulator issued back to back (accumulate chain forwarded) instead of 8 MFMAs apart
# speedup vs baseline: 1.0036x; 1.0036x over previous
; #define PG8_STAGE(bufoff, gbase, voff) do { _Pragma("unroll") for (int _i = 0; _i < 2; ++_i) \
;         __builtin_amdgcn_global_load_lds((const unsigned*)((const char*)(gbase) + (voff)[_i]), (PG8_LAS unsigned*)(lds + (bufoff) + ldsw + _i * 8192), 16, 0, 0); } while (0)
; #define PG8_LDA(dst, b, h) do { _Pragma("unroll") for (int m = 0; m < 4; ++m) _Pragma("unroll") for (int k = 0; k < 2; ++k) dst[m][k] = *(const PG8_LAS bf16x8*)(lds + PG8_SA(b, h) + aoff + m * 2048 + k * 1024); } while (0)
; #define PG8_LDB(dst, b, h) do { _Pragma("unroll") for (int n = 0; n < 2; ++n) _Pragma("unroll") for (int k = 0; k < 2; ++k) dst[n][k] = *(const PG8_LAS bf16x8*)(lds + PG8_SB(b, h) + boff + n * 2048 + k * 1024); } while (0)
; #define PG8_MMA(ai, bj, At, Bt) do { __builtin_amdgcn_s_setprio(1); _Pragma("unroll") for (int m = 0; m < 4; ++m) _Pragma("unroll") for (int n = 0; n < 2; ++n) _Pragma("unroll") for (int k = 0; k < 2; ++k) \
;         acc[ai][bj][m][n] = __builtin_amdgcn_mfma_f32_16x16x32_bf16(Bt[n][k], At[m][k], acc[ai][bj][m][n], 0, 0, 0); __builtin_amdgcn_s_setprio(0); } while (0)
; #define PG8_WAIT_V(n) asm volatile("s_waitcnt vmcnt(" #n ")" ::: "memory")
; #define PG8_WAIT_L(n) asm volatile("s_waitcnt lgkmcnt(" #n ")" ::: "memory")
; template <class Epi, class Sched, bool ALIGN_EPI = false, bool SP2 = false, bool APERM = false  >
; __device__ __forceinline__ void gemm_phase(PG8_LAS unsigned char* lds, const Gemm g, const Sched& S, const Epi& E, const int wid  ) {
;     ...
;             const bool last = (t == nt - 2);
;             const char* a1 = cA + (size_t)(t + 1) * kstep;
;             const char* a2 = last ? nA : cA + (size_t)(t + 2) * kstep; const char* b2 = last ? nB : cB + (size_t)(t + 2) * kstep;
;             const char* a3 = a2 + kstep; const char* b3 = b2 + kstep;
;             if (last && has_next) S.a_ready(nxt);
;             if constexpr (SP2) {
;             PG8_LDB(B0, 0, 0); PG8_LDB(B1, 0, 1); PG8_SCHED; PG8_LDA(At, 0, 0); PG8_STAGE(PG8_SA(1, 1), a1 + hstep, voffA);
;             PG8_WAIT_V(8); PG8_WAIT_L(0); PG8_BAR; PG8_MMA(0, 0, At, B0); PG8_MMA(0, 1, At, B1); PG8_BAR; PG8_SCHED;
;             PG8_LDA(At, 0, 1); PG8_STAGE(PG8_SB(0, 0), b2, voffB); PG8_STAGE(PG8_SB(0, 1), b2 + hstep, voffB); PG8_STAGE(PG8_SA(0, 0), a2, voffA);
;             PG8_WAIT_V(8); PG8_WAIT_L(0); PG8_BAR; PG8_MMA(1, 0, At, B0); PG8_MMA(1, 1, At, B1); PG8_BAR; PG8_SCHED;
.LBB0_84:
	v_add_u32_e32 v140, s59, v145
	ds_read_b128 v[154:157], v140
	ds_read_b128 v[158:161], v140 offset:1024
	ds_read_b128 v[162:165], v140 offset:2048
	ds_read_b128 v[166:169], v140 offset:3072
	v_add_u32_e32 v140, s60, v145
	s_add_u32 s69, s26, s86
	ds_read_b128 v[170:173], v140
	ds_read_b128 v[174:177], v140 offset:1024
	ds_read_b128 v[178:181], v140 offset:2048
	ds_read_b128 v[182:185], v140 offset:3072
	s_addc_u32 s70, s27, s87
	s_add_u32 s69, s69, 0x100
	s_addc_u32 s70, s70, 0
	s_add_u32 s71, s64, s86
	s_addc_u32 s72, s65, s87
	s_cmpk_eq_i32 s86, 0xf00
	s_cselect_b32 s91, s19, s70
	s_cselect_b32 s90, s66, s69
	s_cselect_b32 s89, s25, s72
	s_cselect_b32 s88, s67, s71
	v_lshl_add_u64 v[150:151], v[136:137], 0, s[86:87]
	s_add_i32 m0, s3, 0xc000
	ds_read_b128 v[186:189], v149
	ds_read_b128 v[190:193], v149 offset:1024
	ds_read_b128 v[194:197], v149 offset:2048
	ds_read_b128 v[198:201], v149 offset:3072
	ds_read_b128 v[202:205], v149 offset:4096
	ds_read_b128 v[206:209], v149 offset:5120
	ds_read_b128 v[210:213], v149 offset:6144
	ds_read_b128 v[214:217], v149 offset:7168
	global_load_lds_dwordx4 v[150:151], off
	v_lshl_add_u64 v[150:151], v[138:139], 0, s[86:87]
	s_add_i32 m0, s3, 0xe000
	s_nop 0
	global_load_lds_dwordx4 v[150:151], off
	s_waitcnt vmcnt(8)
	s_waitcnt lgkmcnt(0)
	s_barrier
	s_setprio 1
	s_waitcnt lgkmcnt(0)
	v_mfma_f32_16x16x32_bf16 v[124:127], v[154:157], v[186:189], v[124:127]
	v_mfma_f32_16x16x32_bf16 v[124:127], v[158:161], v[190:193], v[124:127]
	v_mfma_f32_16x16x32_bf16 v[120:123], v[162:165], v[186:189], v[120:123]
	v_mfma_f32_16x16x32_bf16 v[120:123], v[166:169], v[190:193], v[120:123]
	v_mfma_f32_16x16x32_bf16 v[116:119], v[154:157], v[194:197], v[116:119]
	v_mfma_f32_16x16x32_bf16 v[116:119], v[158:161], v[198:201], v[116:119]
	v_mfma_f32_16x16x32_bf16 v[112:115], v[162:165], v[194:197], v[112:115]
	v_mfma_f32_16x16x32_bf16 v[112:115], v[166:169], v[198:201], v[112:115]
	v_mfma_f32_16x16x32_bf16 v[108:111], v[154:157], v[202:205], v[108:111]
	v_mfma_f32_16x16x32_bf16 v[108:111], v[158:161], v[206:209], v[108:111]
	v_mfma_f32_16x16x32_bf16 v[104:107], v[162:165], v[202:205], v[104:107]
	v_mfma_f32_16x16x32_bf16 v[104:107], v[166:169], v[206:209], v[104:107]
	v_mfma_f32_16x16x32_bf16 v[100:103], v[154:157], v[210:213], v[100:103]
	v_mfma_f32_16x16x32_bf16 v[100:103], v[158:161], v[214:217], v[100:103]
	v_mfma_f32_16x16x32_bf16 v[96:99], v[162:165], v[210:213], v[96:99]
	v_mfma_f32_16x16x32_bf16 v[96:99], v[166:169], v[214:217], v[96:99]
	s_setprio 0
	s_setprio 1
	v_mfma_f32_16x16x32_bf16 v[92:95], v[170:173], v[186:189], v[92:95]
	v_mfma_f32_16x16x32_bf16 v[92:95], v[174:177], v[190:193], v[92:95]
	v_mfma_f32_16x16x32_bf16 v[88:91], v[178:181], v[186:189], v[88:91]
	v_mfma_f32_16x16x32_bf16 v[88:91], v[182:185], v[190:193], v[88:91]
	v_mfma_f32_16x16x32_bf16 v[84:87], v[170:173], v[194:197], v[84:87]
	v_mfma_f32_16x16x32_bf16 v[84:87], v[174:177], v[198:201], v[84:87]
	v_mfma_f32_16x16x32_bf16 v[80:83], v[178:181], v[194:197], v[80:83]
	v_mfma_f32_16x16x32_bf16 v[80:83], v[182:185], v[198:201], v[80:83]
	v_mfma_f32_16x16x32_bf16 v[76:79], v[170:173], v[202:205], v[76:79]
	v_mfma_f32_16x16x32_bf16 v[76:79], v[174:177], v[206:209], v[76:79]
	v_mfma_f32_16x16x32_bf16 v[72:75], v[178:181], v[202:205], v[72:75]
	v_mfma_f32_16x16x32_bf16 v[72:75], v[182:185], v[206:209], v[72:75]
	v_mfma_f32_16x16x32_bf16 v[68:71], v[170:173], v[210:213], v[68:71]
	v_mfma_f32_16x16x32_bf16 v[68:71], v[174:177], v[214:217], v[68:71]
	v_mfma_f32_16x16x32_bf16 v[64:67], v[178:181], v[210:213], v[64:67]
	v_mfma_f32_16x16x32_bf16 v[64:67], v[182:185], v[214:217], v[64:67]
	s_setprio 0
	s_barrier
	s_add_i32 s69, s59, s53
	v_lshl_add_u64 v[150:151], s[88:89], 0, v[130:131]
	s_mov_b32 m0, s69
	ds_read_b128 v[186:189], v149 offset:16384
	ds_read_b128 v[190:193], v149 offset:17408
	ds_read_b128 v[194:197], v149 offset:18432
	ds_read_b128 v[198:201], v149 offset:19456
	ds_read_b128 v[202:205], v149 offset:20480
	ds_read_b128 v[206:209], v149 offset:21504
	ds_read_b128 v[210:213], v149 offset:22528
	ds_read_b128 v[214:217], v149 offset:23552
	global_load_lds_dwordx4 v[150:151], off
	s_add_i32 m0, s69, 0x2000
	s_add_u32 s70, s88, 0x80000
	v_lshl_add_u64 v[218:219], s[88:89], 0, v[128:129]
	s_addc_u32 s71, s89, 0
	s_add_i32 s69, s60, s53
	global_load_lds_dwordx4 v[218:219], off
	v_lshl_add_u64 v[220:221], s[70:71], 0, v[130:131]
	s_mov_b32 m0, s69
	v_lshl_add_u64 v[222:223], s[90:91], 0, v[128:129]
	global_load_lds_dwordx4 v[220:221], off
	v_lshl_add_u64 v[220:221], s[70:71], 0, v[128:129]
	s_add_i32 m0, s69, 0x2000
	s_nop 0
	global_load_lds_dwordx4 v[220:221], off
	v_lshl_add_u64 v[220:221], s[90:91], 0, v[130:131]
	s_mov_b32 m0, s3
	s_nop 0
	global_load_lds_dwordx4 v[220:221], off
	s_mov_b32 m0, s7
	s_nop 0
	global_load_lds_dwordx4 v[222:223], off
	s_waitcnt vmcnt(8)
	s_waitcnt lgkmcnt(0)
	s_barrier
; #define PG8_STAGE(bufoff, gbase, voff) do { _Pragma("unroll") for (int _i = 0; _i < 2; ++_i) \
;         __builtin_amdgcn_global_load_lds((const unsigned*)((const char*)(gbase) + (voff)[_i]), (PG8_LAS unsigned*)(lds + (bufoff) + ldsw + _i * 8192), 16, 0, 0); } while (0)
; #define PG8_LDA(dst, b, h) do { _Pragma("unroll") for (int m = 0; m < 4; ++m) _Pragma("unroll") for (int k = 0; k < 2; ++k) dst[m][k] = *(const PG8_LAS bf16x8*)(lds + PG8_SA(b, h) + aoff + m * 2048 + k * 1024); } while (0)
; #define PG8_LDB(dst, b, h) do { _Pragma("unroll") for (int n = 0; n < 2; ++n) _Pragma("unroll") for (int k = 0; k < 2; ++k) dst[n][k] = *(const PG8_LAS bf16x8*)(lds + PG8_SB(b, h) + boff + n * 2048 + k * 1024); } while (0)
; #define PG8_MMA(ai, bj, At, Bt) do { __builtin_amdgcn_s_setprio(1); _Pragma("unroll") for (int m = 0; m < 4; ++m) _Pragma("unroll") for (int n = 0; n < 2; ++n) _Pragma("unroll") for (int k = 0; k < 2; ++k) \
;         acc[ai][bj][m][n] = __builtin_amdgcn_mfma_f32_16x16x32_bf16(Bt[n][k], At[m][k], acc[ai][bj][m][n], 0, 0, 0); __builtin_amdgcn_s_setprio(0); } while (0)
; #define PG8_WAIT_V(n) asm volatile("s_waitcnt vmcnt(" #n ")" ::: "memory")
; #define PG8_WAIT_L(n) asm volatile("s_waitcnt lgkmcnt(" #n ")" ::: "memory")
; #define PG8_BAR __builtin_amdgcn_s_barrier()
; #define PG8_SCHED __builtin_amdgcn_sched_barrier(0)
; template <class Epi, class Sched, bool ALIGN_EPI = false, bool SP2 = false, bool APERM = false  >
; __device__ __forceinline__ void gemm_phase(PG8_LAS unsigned char* lds, const Gemm g, const Sched& S, const Epi& E, const int wid  ) {
;     ...
;             PG8_WAIT_V(8); PG8_WAIT_L(0); PG8_BAR; PG8_MMA(1, 0, At, B0); PG8_MMA(1, 1, At, B1); PG8_BAR; PG8_SCHED;
;             PG8_LDB(B0, 1, 0); PG8_LDB(B1, 1, 1); PG8_SCHED; PG8_LDA(At, 1, 0); PG8_STAGE(PG8_SA(0, 1), a2 + hstep, voffA);
;             PG8_WAIT_V(8); PG8_WAIT_L(0); PG8_BAR; PG8_MMA(0, 0, At, B0); PG8_MMA(0, 1, At, B1); PG8_BAR; PG8_SCHED;
	s_setprio 1
	s_waitcnt lgkmcnt(0)
	v_mfma_f32_16x16x32_bf16 v[60:63], v[154:157], v[186:189], v[60:63]
	v_mfma_f32_16x16x32_bf16 v[60:63], v[158:161], v[190:193], v[60:63]
	v_mfma_f32_16x16x32_bf16 v[56:59], v[162:165], v[186:189], v[56:59]
	v_mfma_f32_16x16x32_bf16 v[56:59], v[166:169], v[190:193], v[56:59]
	v_mfma_f32_16x16x32_bf16 v[52:55], v[154:157], v[194:197], v[52:55]
	v_mfma_f32_16x16x32_bf16 v[52:55], v[158:161], v[198:201], v[52:55]
	v_mfma_f32_16x16x32_bf16 v[48:51], v[162:165], v[194:197], v[48:51]
	v_mfma_f32_16x16x32_bf16 v[48:51], v[166:169], v[198:201], v[48:51]
	v_mfma_f32_16x16x32_bf16 v[44:47], v[154:157], v[202:205], v[44:47]
	v_mfma_f32_16x16x32_bf16 v[44:47], v[158:161], v[206:209], v[44:47]
	v_mfma_f32_16x16x32_bf16 v[40:43], v[162:165], v[202:205], v[40:43]
	v_mfma_f32_16x16x32_bf16 v[40:43], v[166:169], v[206:209], v[40:43]
	v_mfma_f32_16x16x32_bf16 v[36:39], v[154:157], v[210:213], v[36:39]
	v_mfma_f32_16x16x32_bf16 v[36:39], v[158:161], v[214:217], v[36:39]
	v_mfma_f32_16x16x32_bf16 v[32:35], v[162:165], v[210:213], v[32:35]
	v_mfma_f32_16x16x32_bf16 v[32:35], v[166:169], v[214:217], v[32:35]
	s_setprio 0
	s_setprio 1
	v_mfma_f32_16x16x32_bf16 v[28:31], v[170:173], v[186:189], v[28:31]
	v_mfma_f32_16x16x32_bf16 v[28:31], v[174:177], v[190:193], v[28:31]
	v_mfma_f32_16x16x32_bf16 v[24:27], v[178:181], v[186:189], v[24:27]
	v_mfma_f32_16x16x32_bf16 v[24:27], v[182:185], v[190:193], v[24:27]
	v_mfma_f32_16x16x32_bf16 v[20:23], v[170:173], v[194:197], v[20:23]
	v_mfma_f32_16x16x32_bf16 v[20:23], v[174:177], v[198:201], v[20:23]
	v_mfma_f32_16x16x32_bf16 v[16:19], v[178:181], v[194:197], v[16:19]
	v_mfma_f32_16x16x32_bf16 v[16:19], v[182:185], v[198:201], v[16:19]
	v_mfma_f32_16x16x32_bf16 v[12:15], v[170:173], v[202:205], v[12:15]
	v_mfma_f32_16x16x32_bf16 v[12:15], v[174:177], v[206:209], v[12:15]
	v_mfma_f32_16x16x32_bf16 v[8:11], v[178:181], v[202:205], v[8:11]
	v_mfma_f32_16x16x32_bf16 v[8:11], v[182:185], v[206:209], v[8:11]
	v_mfma_f32_16x16x32_bf16 v[4:7], v[170:173], v[210:213], v[4:7]
	v_mfma_f32_16x16x32_bf16 v[4:7], v[174:177], v[214:217], v[4:7]
	v_mfma_f32_16x16x32_bf16 v[0:3], v[178:181], v[210:213], v[0:3]
	v_mfma_f32_16x16x32_bf16 v[0:3], v[182:185], v[214:217], v[0:3]
	s_setprio 0
	s_barrier
	s_add_i32 s69, 0, 0x18000
	v_add_u32_e32 v140, s69, v145
	s_add_i32 s72, 0, 0x1c000
	ds_read_b128 v[154:157], v140
	ds_read_b128 v[158:161], v140 offset:1024
	ds_read_b128 v[162:165], v140 offset:2048
	ds_read_b128 v[166:169], v140 offset:3072
	v_add_u32_e32 v140, s72, v145
	ds_read_b128 v[170:173], v140
	ds_read_b128 v[174:177], v140 offset:1024
	ds_read_b128 v[178:181], v140 offset:2048
	ds_read_b128 v[182:185], v140 offset:3072
	s_add_u32 s70, s90, 0x80000
	s_addc_u32 s71, s91, 0
	s_mov_b32 m0, s54
	v_lshl_add_u64 v[224:225], s[70:71], 0, v[130:131]
	ds_read_b128 v[186:189], v149 offset:32768
	ds_read_b128 v[190:193], v149 offset:33792
	ds_read_b128 v[194:197], v149 offset:34816
	ds_read_b128 v[198:201], v149 offset:35840
	ds_read_b128 v[202:205], v149 offset:36864
	ds_read_b128 v[206:209], v149 offset:37888
	ds_read_b128 v[210:213], v149 offset:38912
	ds_read_b128 v[214:217], v149 offset:39936
	global_load_lds_dwordx4 v[224:225], off
	v_lshl_add_u64 v[224:225], s[70:71], 0, v[128:129]
	s_mov_b32 m0, s55
	s_nop 0
	global_load_lds_dwordx4 v[224:225], off
	s_waitcnt vmcnt(8)
	s_waitcnt lgkmcnt(0)
	s_barrier
	s_setprio 1
	s_waitcnt lgkmcnt(0)
	v_mfma_f32_16x16x32_bf16 v[124:127], v[154:157], v[186:189], v[124:127]
	v_mfma_f32_16x16x32_bf16 v[124:127], v[158:161], v[190:193], v[124:127]
	v_mfma_f32_16x16x32_bf16 v[120:123], v[162:165], v[186:189], v[120:123]
	v_mfma_f32_16x16x32_bf16 v[120:123], v[166:169], v[190:193], v[120:123]
	v_mfma_f32_16x16x32_bf16 v[116:119], v[154:157], v[194:197], v[116:119]
	v_mfma_f32_16x16x32_bf16 v[116:119], v[158:161], v[198:201], v[116:119]
	v_mfma_f32_16x16x32_bf16 v[112:115], v[162:165], v[194:197], v[112:115]
	v_mfma_f32_16x16x32_bf16 v[112:115], v[166:169], v[198:201], v[112:115]
	v_mfma_f32_16x16x32_bf16 v[108:111], v[154:157], v[202:205], v[108:111]
	v_mfma_f32_16x16x32_bf16 v[108:111], v[158:161], v[206:209], v[108:111]
	v_mfma_f32_16x16x32_bf16 v[104:107], v[162:165], v[202:205], v[104:107]
	v_mfma_f32_16x16x32_bf16 v[104:107], v[166:169], v[206:209], v[104:107]
	v_mfma_f32_16x16x32_bf16 v[100:103], v[154:157], v[210:213], v[100:103]
	v_mfma_f32_16x16x32_bf16 v[100:103], v[158:161], v[214:217], v[100:103]
	v_mfma_f32_16x16x32_bf16 v[96:99], v[162:165], v[210:213], v[96:99]
	v_mfma_f32_16x16x32_bf16 v[96:99], v[166:169], v[214:217], v[96:99]
	s_setprio 0
	s_setprio 1
	v_mfma_f32_16x16x32_bf16 v[92:95], v[170:173], v[186:189], v[92:95]
	v_mfma_f32_16x16x32_bf16 v[92:95], v[174:177], v[190:193], v[92:95]
	v_mfma_f32_16x16x32_bf16 v[88:91], v[178:181], v[186:189], v[88:91]
	v_mfma_f32_16x16x32_bf16 v[88:91], v[182:185], v[190:193], v[88:91]
	v_mfma_f32_16x16x32_bf16 v[84:87], v[170:173], v[194:197], v[84:87]
	v_mfma_f32_16x16x32_bf16 v[84:87], v[174:177], v[198:201], v[84:87]
	v_mfma_f32_16x16x32_bf16 v[80:83], v[178:181], v[194:197], v[80:83]
	v_mfma_f32_16x16x32_bf16 v[80:83], v[182:185], v[198:201], v[80:83]
	v_mfma_f32_16x16x32_bf16 v[76:79], v[170:173], v[202:205], v[76:79]
	v_mfma_f32_16x16x32_bf16 v[76:79], v[174:177], v[206:209], v[76:79]
	v_mfma_f32_16x16x32_bf16 v[72:75], v[178:181], v[202:205], v[72:75]
	v_mfma_f32_16x16x32_bf16 v[72:75], v[182:185], v[206:209], v[72:75]
	v_mfma_f32_16x16x32_bf16 v[68:71], v[170:173], v[210:213], v[68:71]
	v_mfma_f32_16x16x32_bf16 v[68:71], v[174:177], v[214:217], v[68:71]
	v_mfma_f32_16x16x32_bf16 v[64:67], v[178:181], v[210:213], v[64:67]
	v_mfma_f32_16x16x32_bf16 v[64:67], v[182:185], v[214:217], v[64:67]
	s_setprio 0
	s_barrier
; #define PG8_STAGE(bufoff, gbase, voff) do { _Pragma("unroll") for (int _i = 0; _i < 2; ++_i) \
;         __builtin_amdgcn_global_load_lds((const unsigned*)((const char*)(gbase) + (voff)[_i]), (PG8_LAS unsigned*)(lds + (bufoff) + ldsw + _i * 8192), 16, 0, 0); } while (0)
; #define PG8_LDA(dst, b, h) do { _Pragma("unroll") for (int m = 0; m < 4; ++m) _Pragma("unroll") for (int k = 0; k < 2; ++k) dst[m][k] = *(const PG8_LAS bf16x8*)(lds + PG8_SA(b, h) + aoff + m * 2048 + k * 1024); } while (0)
; #define PG8_MMA(ai, bj, At, Bt) do { __builtin_amdgcn_s_setprio(1); _Pragma("unroll") for (int m = 0; m < 4; ++m) _Pragma("unroll") for (int n = 0; n < 2; ++n) _Pragma("unroll") for (int k = 0; k < 2; ++k) \
;         acc[ai][bj][m][n] = __builtin_amdgcn_mfma_f32_16x16x32_bf16(Bt[n][k], At[m][k], acc[ai][bj][m][n], 0, 0, 0); __builtin_amdgcn_s_setprio(0); } while (0)
; #define PG8_WAIT_V(n) asm volatile("s_waitcnt vmcnt(" #n ")" ::: "memory")
; #define PG8_WAIT_L(n) asm volatile("s_waitcnt lgkmcnt(" #n ")" ::: "memory")
; #define PG8_BAR __builtin_amdgcn_s_barrier()
; #define PG8_SCHED __builtin_amdgcn_sched_barrier(0)
; template <class Epi, class Sched, bool ALIGN_EPI = false, bool SP2 = false, bool APERM = false  >
; __device__ __forceinline__ void gemm_phase(PG8_LAS unsigned char* lds, const Gemm g, const Sched& S, const Epi& E, const int wid  ) {
;     ...
;             PG8_LDA(At, 1, 1); PG8_STAGE(PG8_SB(1, 0), b3, voffB); PG8_STAGE(PG8_SB(1, 1), b3 + hstep, voffB); PG8_STAGE(PG8_SA(1, 0), a3, voffA);
;             PG8_WAIT_V(8); PG8_WAIT_L(0); PG8_BAR; PG8_MMA(1, 0, At, B0); PG8_MMA(1, 1, At, B1); PG8_BAR; PG8_SCHED;
	s_add_i32 s69, s69, s53
	v_lshl_add_u64 v[150:151], v[150:151], 0, s[14:15]
	s_mov_b32 m0, s69
	ds_read_b128 v[186:189], v149 offset:49152
	ds_read_b128 v[190:193], v149 offset:50176
	ds_read_b128 v[194:197], v149 offset:51200
	ds_read_b128 v[198:201], v149 offset:52224
	ds_read_b128 v[202:205], v149 offset:53248
	ds_read_b128 v[206:209], v149 offset:54272
	ds_read_b128 v[210:213], v149 offset:55296
	ds_read_b128 v[214:217], v149 offset:56320
	global_load_lds_dwordx4 v[150:151], off
	s_add_i32 m0, s69, 0x2000
	s_add_u32 s70, s88, 0x80080
	v_lshl_add_u64 v[150:151], v[218:219], 0, s[14:15]
	s_addc_u32 s71, s89, 0
	s_add_i32 s69, s72, s53
	global_load_lds_dwordx4 v[150:151], off
	v_lshl_add_u64 v[150:151], s[70:71], 0, v[130:131]
	s_mov_b32 m0, s69
	s_nop 0
	global_load_lds_dwordx4 v[150:151], off
	v_lshl_add_u64 v[150:151], s[70:71], 0, v[128:129]
	s_add_i32 m0, s69, 0x2000
	s_nop 0
	global_load_lds_dwordx4 v[150:151], off
	v_lshl_add_u64 v[150:151], v[220:221], 0, s[14:15]
	s_mov_b32 m0, s57
	s_nop 0
	global_load_lds_dwordx4 v[150:151], off
	v_lshl_add_u64 v[150:151], v[222:223], 0, s[14:15]
	s_mov_b32 m0, s58
	s_nop 0
	global_load_lds_dwordx4 v[150:151], off
	s_waitcnt vmcnt(8)
	s_waitcnt lgkmcnt(0)
	s_barrier
	s_setprio 1
	s_waitcnt lgkmcnt(0)
	v_mfma_f32_16x16x32_bf16 v[60:63], v[154:157], v[186:189], v[60:63]
	v_mfma_f32_16x16x32_bf16 v[60:63], v[158:161], v[190:193], v[60:63]
	v_mfma_f32_16x16x32_bf16 v[56:59], v[162:165], v[186:189], v[56:59]
	v_mfma_f32_16x16x32_bf16 v[56:59], v[166:169], v[190:193], v[56:59]
	v_mfma_f32_16x16x32_bf16 v[52:55], v[154:157], v[194:197], v[52:55]
	v_mfma_f32_16x16x32_bf16 v[52:55], v[158:161], v[198:201], v[52:55]
	v_mfma_f32_16x16x32_bf16 v[48:51], v[162:165], v[194:197], v[48:51]
	v_mfma_f32_16x16x32_bf16 v[48:51], v[166:169], v[198:201], v[48:51]
	v_mfma_f32_16x16x32_bf16 v[44:47], v[154:157], v[202:205], v[44:47]
	v_mfma_f32_16x16x32_bf16 v[44:47], v[158:161], v[206:209], v[44:47]
	v_mfma_f32_16x16x32_bf16 v[40:43], v[162:165], v[202:205], v[40:43]
	v_mfma_f32_16x16x32_bf16 v[40:43], v[166:169], v[206:209], v[40:43]
	v_mfma_f32_16x16x32_bf16 v[36:39], v[154:157], v[210:213], v[36:39]
	v_mfma_f32_16x16x32_bf16 v[36:39], v[158:161], v[214:217], v[36:39]
	v_mfma_f32_16x16x32_bf16 v[32:35], v[162:165], v[210:213], v[32:35]
	v_mfma_f32_16x16x32_bf16 v[32:35], v[166:169], v[214:217], v[32:35]
	s_setprio 0
	s_setprio 1
	v_mfma_f32_16x16x32_bf16 v[28:31], v[170:173], v[186:189], v[28:31]
	v_mfma_f32_16x16x32_bf16 v[28:31], v[174:177], v[190:193], v[28:31]
	v_mfma_f32_16x16x32_bf16 v[24:27], v[178:181], v[186:189], v[24:27]
	v_mfma_f32_16x16x32_bf16 v[24:27], v[182:185], v[190:193], v[24:27]
	v_mfma_f32_16x16x32_bf16 v[20:23], v[170:173], v[194:197], v[20:23]
	v_mfma_f32_16x16x32_bf16 v[20:23], v[174:177], v[198:201], v[20:23]
	v_mfma_f32_16x16x32_bf16 v[16:19], v[178:181], v[194:197], v[16:19]
	v_mfma_f32_16x16x32_bf16 v[16:19], v[182:185], v[198:201], v[16:19]
	v_mfma_f32_16x16x32_bf16 v[12:15], v[170:173], v[202:205], v[12:15]
	v_mfma_f32_16x16x32_bf16 v[12:15], v[174:177], v[206:209], v[12:15]
	v_mfma_f32_16x16x32_bf16 v[8:11], v[178:181], v[202:205], v[8:11]
	v_mfma_f32_16x16x32_bf16 v[8:11], v[182:185], v[206:209], v[8:11]
	v_mfma_f32_16x16x32_bf16 v[4:7], v[170:173], v[210:213], v[4:7]
	v_mfma_f32_16x16x32_bf16 v[4:7], v[174:177], v[214:217], v[4:7]
	v_mfma_f32_16x16x32_bf16 v[0:3], v[178:181], v[210:213], v[0:3]
	v_mfma_f32_16x16x32_bf16 v[0:3], v[182:185], v[214:217], v[0:3]
	s_setprio 0
	s_barrier
	s_add_i32 s68, s68, 2
	s_add_u32 s86, s86, 0x100
	s_addc_u32 s87, s87, 0
	s_cmp_gt_u32 s68, 29
	s_cbranch_scc0 .LBB0_84
	s_and_b64 vcc, exec, s[16:17]
	s_cbranch_vccz .LBB0_87
	s_barrier

; #define PG8_STAGE(bufoff, gbase, voff) do { _Pragma("unroll") for (int _i = 0; _i < 2; ++_i) \
;         __builtin_amdgcn_global_load_lds((const unsigned*)((const char*)(gbase) + (voff)[_i]), (PG8_LAS unsigned*)(lds + (bufoff) + ldsw + _i * 8192), 16, 0, 0); } while (0)
; #define PG8_LDA(dst, b, h) do { _Pragma("unroll") for (int m = 0; m < 4; ++m) _Pragma("unroll") for (int k = 0; k < 2; ++k) dst[m][k] = *(const PG8_LAS bf16x8*)(lds + PG8_SA(b, h) + aoff + m * 2048 + k * 1024); } while (0)
; #define PG8_LDB(dst, b, h) do { _Pragma("unroll") for (int n = 0; n < 2; ++n) _Pragma("unroll") for (int k = 0; k < 2; ++k) dst[n][k] = *(const PG8_LAS bf16x8*)(lds + PG8_SB(b, h) + boff + n * 2048 + k * 1024); } while (0)
; #define PG8_MMA(ai, bj, At, Bt) do { __builtin_amdgcn_s_setprio(1); _Pragma("unroll") for (int m = 0; m < 4; ++m) _Pragma("unroll") for (int n = 0; n < 2; ++n) _Pragma("unroll") for (int k = 0; k < 2; ++k) \
;         acc[ai][bj][m][n] = __builtin_amdgcn_mfma_f32_16x16x32_bf16(Bt[n][k], At[m][k], acc[ai][bj][m][n], 0, 0, 0); __builtin_amdgcn_s_setprio(0); } while (0)
; #define PG8_WAIT_V(n) asm volatile("s_waitcnt vmcnt(" #n ")" ::: "memory")
; #define PG8_WAIT_L(n) asm volatile("s_waitcnt lgkmcnt(" #n ")" ::: "memory")
; template <class Epi, class Sched, bool ALIGN_EPI = false, bool SP2 = false, bool APERM = false  >
; __device__ __forceinline__ void gemm_phase(PG8_LAS unsigned char* lds, const Gemm g, const Sched& S, const Epi& E, const int wid  ) {
;     ...
;             const bool last = (t == nt - 2);
;             const char* a1 = cA + (size_t)(t + 1) * kstep;
;             const char* a2 = last ? nA : cA + (size_t)(t + 2) * kstep; const char* b2 = last ? nB : cB + (size_t)(t + 2) * kstep;
;             const char* a3 = a2 + kstep; const char* b3 = b2 + kstep;
;             if (last && has_next) S.a_ready(nxt);
;             if constexpr (SP2) {
;             PG8_LDB(B0, 0, 0); PG8_LDB(B1, 0, 1); PG8_SCHED; PG8_LDA(At, 0, 0); PG8_STAGE(PG8_SA(1, 1), a1 + hstep, voffA);
;             PG8_WAIT_V(8); PG8_WAIT_L(0); PG8_BAR; PG8_MMA(0, 0, At, B0); PG8_MMA(0, 1, At, B1); PG8_BAR; PG8_SCHED;
;             PG8_LDA(At, 0, 1); PG8_STAGE(PG8_SB(0, 0), b2, voffB); PG8_STAGE(PG8_SB(0, 1), b2 + hstep, voffB); PG8_STAGE(PG8_SA(0, 0), a2, voffA);
;             PG8_WAIT_V(8); PG8_WAIT_L(0); PG8_BAR; PG8_MMA(1, 0, At, B0); PG8_MMA(1, 1, At, B1); PG8_BAR; PG8_SCHED;
.LBB0_310:
	s_or_b32 s58, s55, 1
	v_add_u32_e32 v159, s96, v153
	s_lshl_b64 s[64:65], s[58:59], 7
	s_add_i32 s58, s55, 2
	s_waitcnt lgkmcnt(0)
	ds_read_b128 v[144:147], v159
	ds_read_b128 v[148:151], v159 offset:1024
	ds_read_b128 v[160:163], v159 offset:2048
	ds_read_b128 v[164:167], v159 offset:3072
	v_add_u32_e32 v159, s97, v153
	s_lshl_b64 s[68:69], s[58:59], 7
	ds_read_b128 v[168:171], v159
	ds_read_b128 v[172:175], v159 offset:1024
	ds_read_b128 v[176:179], v159 offset:2048
	ds_read_b128 v[180:183], v159 offset:3072
	s_add_u32 s78, s0, s68
	s_addc_u32 s79, s1, s69
	s_and_b64 s[76:77], s[72:73], exec
	s_cselect_b32 vcc_hi, s13, s79
	s_cselect_b32 vcc_lo, s33, s78
	s_add_u32 s76, s14, s68
	s_addc_u32 s77, s15, s69
	s_and_b64 s[68:69], s[72:73], exec
	s_cselect_b32 s73, s9, s77
	s_cselect_b32 s72, s52, s76
	s_add_u32 s64, s53, s64
	s_addc_u32 s65, s54, s65
	v_lshl_add_u64 v[216:217], s[64:65], 0, v[132:133]
	s_add_i32 m0, s29, 0xc000
	ds_read_b128 v[184:187], v158
	ds_read_b128 v[188:191], v158 offset:1024
	ds_read_b128 v[192:195], v158 offset:2048
	ds_read_b128 v[196:199], v158 offset:3072
	ds_read_b128 v[200:203], v158 offset:4096
	ds_read_b128 v[204:207], v158 offset:5120
	ds_read_b128 v[208:211], v158 offset:6144
	ds_read_b128 v[212:215], v158 offset:7168
	global_load_lds_dwordx4 v[216:217], off
	v_lshl_add_u64 v[216:217], s[64:65], 0, v[136:137]
	s_add_i32 m0, s29, 0xe000
	s_nop 0
	global_load_lds_dwordx4 v[216:217], off
	s_waitcnt vmcnt(8)
	s_waitcnt lgkmcnt(0)
	s_barrier
	s_setprio 1
	s_waitcnt lgkmcnt(0)
	v_mfma_f32_16x16x32_bf16 v[124:127], v[144:147], v[184:187], v[124:127]
	v_mfma_f32_16x16x32_bf16 v[124:127], v[148:151], v[188:191], v[124:127]
	v_mfma_f32_16x16x32_bf16 v[120:123], v[160:163], v[184:187], v[120:123]
	v_mfma_f32_16x16x32_bf16 v[120:123], v[164:167], v[188:191], v[120:123]
	v_mfma_f32_16x16x32_bf16 v[116:119], v[144:147], v[192:195], v[116:119]
	v_mfma_f32_16x16x32_bf16 v[116:119], v[148:151], v[196:199], v[116:119]
	v_mfma_f32_16x16x32_bf16 v[112:115], v[160:163], v[192:195], v[112:115]
	v_mfma_f32_16x16x32_bf16 v[112:115], v[164:167], v[196:199], v[112:115]
	v_mfma_f32_16x16x32_bf16 v[108:111], v[144:147], v[200:203], v[108:111]
	v_mfma_f32_16x16x32_bf16 v[108:111], v[148:151], v[204:207], v[108:111]
	v_mfma_f32_16x16x32_bf16 v[104:107], v[160:163], v[200:203], v[104:107]
	v_mfma_f32_16x16x32_bf16 v[104:107], v[164:167], v[204:207], v[104:107]
	v_mfma_f32_16x16x32_bf16 v[100:103], v[144:147], v[208:211], v[100:103]
	v_mfma_f32_16x16x32_bf16 v[100:103], v[148:151], v[212:215], v[100:103]
	v_mfma_f32_16x16x32_bf16 v[96:99], v[160:163], v[208:211], v[96:99]
	v_mfma_f32_16x16x32_bf16 v[96:99], v[164:167], v[212:215], v[96:99]
	s_setprio 0
	s_setprio 1
	v_mfma_f32_16x16x32_bf16 v[92:95], v[168:171], v[184:187], v[92:95]
	v_mfma_f32_16x16x32_bf16 v[92:95], v[172:175], v[188:191], v[92:95]
	v_mfma_f32_16x16x32_bf16 v[88:91], v[176:179], v[184:187], v[88:91]
	v_mfma_f32_16x16x32_bf16 v[88:91], v[180:183], v[188:191], v[88:91]
	v_mfma_f32_16x16x32_bf16 v[84:87], v[168:171], v[192:195], v[84:87]
	v_mfma_f32_16x16x32_bf16 v[84:87], v[172:175], v[196:199], v[84:87]
	v_mfma_f32_16x16x32_bf16 v[80:83], v[176:179], v[192:195], v[80:83]
	v_mfma_f32_16x16x32_bf16 v[80:83], v[180:183], v[196:199], v[80:83]
	v_mfma_f32_16x16x32_bf16 v[76:79], v[168:171], v[200:203], v[76:79]
	v_mfma_f32_16x16x32_bf16 v[76:79], v[172:175], v[204:207], v[76:79]
	v_mfma_f32_16x16x32_bf16 v[72:75], v[176:179], v[200:203], v[72:75]
	v_mfma_f32_16x16x32_bf16 v[72:75], v[180:183], v[204:207], v[72:75]
	v_mfma_f32_16x16x32_bf16 v[68:71], v[168:171], v[208:211], v[68:71]
	v_mfma_f32_16x16x32_bf16 v[68:71], v[172:175], v[212:215], v[68:71]
	v_mfma_f32_16x16x32_bf16 v[64:67], v[176:179], v[208:211], v[64:67]
	v_mfma_f32_16x16x32_bf16 v[64:67], v[180:183], v[212:215], v[64:67]
	s_setprio 0
	s_barrier
	s_add_i32 s64, s96, s91
	v_lshl_add_u64 v[216:217], s[72:73], 0, v[128:129]
	s_mov_b32 m0, s64
	ds_read_b128 v[184:187], v158 offset:16384
	ds_read_b128 v[188:191], v158 offset:17408
	ds_read_b128 v[192:195], v158 offset:18432
	ds_read_b128 v[196:199], v158 offset:19456
	ds_read_b128 v[200:203], v158 offset:20480
	ds_read_b128 v[204:207], v158 offset:21504
	ds_read_b128 v[208:211], v158 offset:22528
	ds_read_b128 v[212:215], v158 offset:23552
	global_load_lds_dwordx4 v[216:217], off
	s_add_i32 m0, s64, 0x2000
	s_add_u32 s64, s72, 0x80000
	v_lshl_add_u64 v[218:219], s[72:73], 0, v[130:131]
	s_addc_u32 s65, s73, 0
	s_add_i32 s68, s97, s91
	global_load_lds_dwordx4 v[218:219], off
	v_lshl_add_u64 v[220:221], s[64:65], 0, v[128:129]
	s_mov_b32 m0, s68
	v_lshl_add_u64 v[222:223], vcc, 0, v[136:137]
	global_load_lds_dwordx4 v[220:221], off
	v_lshl_add_u64 v[220:221], s[64:65], 0, v[130:131]
	s_add_i32 m0, s68, 0x2000
	s_nop 0
	global_load_lds_dwordx4 v[220:221], off
	v_lshl_add_u64 v[220:221], vcc, 0, v[132:133]
	s_mov_b32 m0, s29
	s_nop 0
	global_load_lds_dwordx4 v[220:221], off
	s_mov_b32 m0, s57
	s_nop 0
	global_load_lds_dwordx4 v[222:223], off
	s_waitcnt vmcnt(8)
	s_waitcnt lgkmcnt(0)
	s_barrier
; #define PG8_STAGE(bufoff, gbase, voff) do { _Pragma("unroll") for (int _i = 0; _i < 2; ++_i) \
;         __builtin_amdgcn_global_load_lds((const unsigned*)((const char*)(gbase) + (voff)[_i]), (PG8_LAS unsigned*)(lds + (bufoff) + ldsw + _i * 8192), 16, 0, 0); } while (0)
; #define PG8_LDA(dst, b, h) do { _Pragma("unroll") for (int m = 0; m < 4; ++m) _Pragma("unroll") for (int k = 0; k < 2; ++k) dst[m][k] = *(const PG8_LAS bf16x8*)(lds + PG8_SA(b, h) + aoff + m * 2048 + k * 1024); } while (0)
; #define PG8_LDB(dst, b, h) do { _Pragma("unroll") for (int n = 0; n < 2; ++n) _Pragma("unroll") for (int k = 0; k < 2; ++k) dst[n][k] = *(const PG8_LAS bf16x8*)(lds + PG8_SB(b, h) + boff + n * 2048 + k * 1024); } while (0)
; #define PG8_MMA(ai, bj, At, Bt) do { __builtin_amdgcn_s_setprio(1); _Pragma("unroll") for (int m = 0; m < 4; ++m) _Pragma("unroll") for (int n = 0; n < 2; ++n) _Pragma("unroll") for (int k = 0; k < 2; ++k) \
;         acc[ai][bj][m][n] = __builtin_amdgcn_mfma_f32_16x16x32_bf16(Bt[n][k], At[m][k], acc[ai][bj][m][n], 0, 0, 0); __builtin_amdgcn_s_setprio(0); } while (0)
; #define PG8_WAIT_V(n) asm volatile("s_waitcnt vmcnt(" #n ")" ::: "memory")
; #define PG8_WAIT_L(n) asm volatile("s_waitcnt lgkmcnt(" #n ")" ::: "memory")
; #define PG8_BAR __builtin_amdgcn_s_barrier()
; #define PG8_SCHED __builtin_amdgcn_sched_barrier(0)
; template <class Epi, class Sched, bool ALIGN_EPI = false, bool SP2 = false, bool APERM = false  >
; __device__ __forceinline__ void gemm_phase(PG8_LAS unsigned char* lds, const Gemm g, const Sched& S, const Epi& E, const int wid  ) {
;     ...
;             PG8_WAIT_V(8); PG8_WAIT_L(0); PG8_BAR; PG8_MMA(1, 0, At, B0); PG8_MMA(1, 1, At, B1); PG8_BAR; PG8_SCHED;
;             PG8_LDB(B0, 1, 0); PG8_LDB(B1, 1, 1); PG8_SCHED; PG8_LDA(At, 1, 0); PG8_STAGE(PG8_SA(0, 1), a2 + hstep, voffA);
;             PG8_WAIT_V(8); PG8_WAIT_L(0); PG8_BAR; PG8_MMA(0, 0, At, B0); PG8_MMA(0, 1, At, B1); PG8_BAR; PG8_SCHED;
	s_setprio 1
	s_waitcnt lgkmcnt(0)
	v_mfma_f32_16x16x32_bf16 v[60:63], v[144:147], v[184:187], v[60:63]
	v_mfma_f32_16x16x32_bf16 v[60:63], v[148:151], v[188:191], v[60:63]
	v_mfma_f32_16x16x32_bf16 v[56:59], v[160:163], v[184:187], v[56:59]
	v_mfma_f32_16x16x32_bf16 v[56:59], v[164:167], v[188:191], v[56:59]
	v_mfma_f32_16x16x32_bf16 v[52:55], v[144:147], v[192:195], v[52:55]
	v_mfma_f32_16x16x32_bf16 v[52:55], v[148:151], v[196:199], v[52:55]
	v_mfma_f32_16x16x32_bf16 v[48:51], v[160:163], v[192:195], v[48:51]
	v_mfma_f32_16x16x32_bf16 v[48:51], v[164:167], v[196:199], v[48:51]
	v_mfma_f32_16x16x32_bf16 v[44:47], v[144:147], v[200:203], v[44:47]
	v_mfma_f32_16x16x32_bf16 v[44:47], v[148:151], v[204:207], v[44:47]
	v_mfma_f32_16x16x32_bf16 v[40:43], v[160:163], v[200:203], v[40:43]
	v_mfma_f32_16x16x32_bf16 v[40:43], v[164:167], v[204:207], v[40:43]
	v_mfma_f32_16x16x32_bf16 v[36:39], v[144:147], v[208:211], v[36:39]
	v_mfma_f32_16x16x32_bf16 v[36:39], v[148:151], v[212:215], v[36:39]
	v_mfma_f32_16x16x32_bf16 v[32:35], v[160:163], v[208:211], v[32:35]
	v_mfma_f32_16x16x32_bf16 v[32:35], v[164:167], v[212:215], v[32:35]
	s_setprio 0
	s_setprio 1
	v_mfma_f32_16x16x32_bf16 v[28:31], v[168:171], v[184:187], v[28:31]
	v_mfma_f32_16x16x32_bf16 v[28:31], v[172:175], v[188:191], v[28:31]
	v_mfma_f32_16x16x32_bf16 v[24:27], v[176:179], v[184:187], v[24:27]
	v_mfma_f32_16x16x32_bf16 v[24:27], v[180:183], v[188:191], v[24:27]
	v_mfma_f32_16x16x32_bf16 v[20:23], v[168:171], v[192:195], v[20:23]
	v_mfma_f32_16x16x32_bf16 v[20:23], v[172:175], v[196:199], v[20:23]
	v_mfma_f32_16x16x32_bf16 v[16:19], v[176:179], v[192:195], v[16:19]
	v_mfma_f32_16x16x32_bf16 v[16:19], v[180:183], v[196:199], v[16:19]
	v_mfma_f32_16x16x32_bf16 v[12:15], v[168:171], v[200:203], v[12:15]
	v_mfma_f32_16x16x32_bf16 v[12:15], v[172:175], v[204:207], v[12:15]
	v_mfma_f32_16x16x32_bf16 v[8:11], v[176:179], v[200:203], v[8:11]
	v_mfma_f32_16x16x32_bf16 v[8:11], v[180:183], v[204:207], v[8:11]
	v_mfma_f32_16x16x32_bf16 v[4:7], v[168:171], v[208:211], v[4:7]
	v_mfma_f32_16x16x32_bf16 v[4:7], v[172:175], v[212:215], v[4:7]
	v_mfma_f32_16x16x32_bf16 v[0:3], v[176:179], v[208:211], v[0:3]
	v_mfma_f32_16x16x32_bf16 v[0:3], v[180:183], v[212:215], v[0:3]
	s_setprio 0
	s_barrier
	s_add_i32 s68, 0, 0x18000
	v_add_u32_e32 v159, s68, v153
	s_add_i32 s69, 0, 0x1c000
	ds_read_b128 v[144:147], v159
	ds_read_b128 v[148:151], v159 offset:1024
	ds_read_b128 v[160:163], v159 offset:2048
	ds_read_b128 v[164:167], v159 offset:3072
	v_add_u32_e32 v159, s69, v153
	ds_read_b128 v[168:171], v159
	ds_read_b128 v[172:175], v159 offset:1024
	ds_read_b128 v[176:179], v159 offset:2048
	ds_read_b128 v[180:183], v159 offset:3072
	s_add_u32 s64, vcc_lo, 0x80000
	s_addc_u32 s65, vcc_hi, 0
	s_mov_b32 m0, s92
	v_lshl_add_u64 v[224:225], s[64:65], 0, v[132:133]
	ds_read_b128 v[184:187], v158 offset:32768
	ds_read_b128 v[188:191], v158 offset:33792
	ds_read_b128 v[192:195], v158 offset:34816
	ds_read_b128 v[196:199], v158 offset:35840
	ds_read_b128 v[200:203], v158 offset:36864
	ds_read_b128 v[204:207], v158 offset:37888
	ds_read_b128 v[208:211], v158 offset:38912
	ds_read_b128 v[212:215], v158 offset:39936
	global_load_lds_dwordx4 v[224:225], off
	v_lshl_add_u64 v[224:225], s[64:65], 0, v[136:137]
	s_mov_b32 m0, s93
	s_nop 0
	global_load_lds_dwordx4 v[224:225], off
	s_waitcnt vmcnt(8)
	s_waitcnt lgkmcnt(0)
	s_barrier
	s_setprio 1
	s_waitcnt lgkmcnt(0)
	v_mfma_f32_16x16x32_bf16 v[124:127], v[144:147], v[184:187], v[124:127]
	v_mfma_f32_16x16x32_bf16 v[124:127], v[148:151], v[188:191], v[124:127]
	v_mfma_f32_16x16x32_bf16 v[120:123], v[160:163], v[184:187], v[120:123]
	v_mfma_f32_16x16x32_bf16 v[120:123], v[164:167], v[188:191], v[120:123]
	v_mfma_f32_16x16x32_bf16 v[116:119], v[144:147], v[192:195], v[116:119]
	v_mfma_f32_16x16x32_bf16 v[116:119], v[148:151], v[196:199], v[116:119]
	v_mfma_f32_16x16x32_bf16 v[112:115], v[160:163], v[192:195], v[112:115]
	v_mfma_f32_16x16x32_bf16 v[112:115], v[164:167], v[196:199], v[112:115]
	v_mfma_f32_16x16x32_bf16 v[108:111], v[144:147], v[200:203], v[108:111]
	v_mfma_f32_16x16x32_bf16 v[108:111], v[148:151], v[204:207], v[108:111]
	v_mfma_f32_16x16x32_bf16 v[104:107], v[160:163], v[200:203], v[104:107]
	v_mfma_f32_16x16x32_bf16 v[104:107], v[164:167], v[204:207], v[104:107]
	v_mfma_f32_16x16x32_bf16 v[100:103], v[144:147], v[208:211], v[100:103]
	v_mfma_f32_16x16x32_bf16 v[100:103], v[148:151], v[212:215], v[100:103]
	v_mfma_f32_16x16x32_bf16 v[96:99], v[160:163], v[208:211], v[96:99]
	v_mfma_f32_16x16x32_bf16 v[96:99], v[164:167], v[212:215], v[96:99]
	s_setprio 0
	s_setprio 1
	v_mfma_f32_16x16x32_bf16 v[92:95], v[168:171], v[184:187], v[92:95]
	v_mfma_f32_16x16x32_bf16 v[92:95], v[172:175], v[188:191], v[92:95]
	v_mfma_f32_16x16x32_bf16 v[88:91], v[176:179], v[184:187], v[88:91]
	v_mfma_f32_16x16x32_bf16 v[88:91], v[180:183], v[188:191], v[88:91]
	v_mfma_f32_16x16x32_bf16 v[84:87], v[168:171], v[192:195], v[84:87]
	v_mfma_f32_16x16x32_bf16 v[84:87], v[172:175], v[196:199], v[84:87]
	v_mfma_f32_16x16x32_bf16 v[80:83], v[176:179], v[192:195], v[80:83]
	v_mfma_f32_16x16x32_bf16 v[80:83], v[180:183], v[196:199], v[80:83]
	v_mfma_f32_16x16x32_bf16 v[76:79], v[168:171], v[200:203], v[76:79]
	v_mfma_f32_16x16x32_bf16 v[76:79], v[172:175], v[204:207], v[76:79]
	v_mfma_f32_16x16x32_bf16 v[72:75], v[176:179], v[200:203], v[72:75]
	v_mfma_f32_16x16x32_bf16 v[72:75], v[180:183], v[204:207], v[72:75]
	v_mfma_f32_16x16x32_bf16 v[68:71], v[168:171], v[208:211], v[68:71]
	v_mfma_f32_16x16x32_bf16 v[68:71], v[172:175], v[212:215], v[68:71]
	v_mfma_f32_16x16x32_bf16 v[64:67], v[176:179], v[208:211], v[64:67]
	v_mfma_f32_16x16x32_bf16 v[64:67], v[180:183], v[212:215], v[64:67]
	s_setprio 0
	s_barrier
; #define PG8_STAGE(bufoff, gbase, voff) do { _Pragma("unroll") for (int _i = 0; _i < 2; ++_i) \
;         __builtin_amdgcn_global_load_lds((const unsigned*)((const char*)(gbase) + (voff)[_i]), (PG8_LAS unsigned*)(lds + (bufoff) + ldsw + _i * 8192), 16, 0, 0); } while (0)
; #define PG8_LDA(dst, b, h) do { _Pragma("unroll") for (int m = 0; m < 4; ++m) _Pragma("unroll") for (int k = 0; k < 2; ++k) dst[m][k] = *(const PG8_LAS bf16x8*)(lds + PG8_SA(b, h) + aoff + m * 2048 + k * 1024); } while (0)
; #define PG8_MMA(ai, bj, At, Bt) do { __builtin_amdgcn_s_setprio(1); _Pragma("unroll") for (int m = 0; m < 4; ++m) _Pragma("unroll") for (int n = 0; n < 2; ++n) _Pragma("unroll") for (int k = 0; k < 2; ++k) \
;         acc[ai][bj][m][n] = __builtin_amdgcn_mfma_f32_16x16x32_bf16(Bt[n][k], At[m][k], acc[ai][bj][m][n], 0, 0, 0); __builtin_amdgcn_s_setprio(0); } while (0)
; #define PG8_WAIT_V(n) asm volatile("s_waitcnt vmcnt(" #n ")" ::: "memory")
; #define PG8_WAIT_L(n) asm volatile("s_waitcnt lgkmcnt(" #n ")" ::: "memory")
; #define PG8_BAR __builtin_amdgcn_s_barrier()
; #define PG8_SCHED __builtin_amdgcn_sched_barrier(0)
; template <class Epi, class Sched, bool ALIGN_EPI = false, bool SP2 = false, bool APERM = false  >
; __device__ __forceinline__ void gemm_phase(PG8_LAS unsigned char* lds, const Gemm g, const Sched& S, const Epi& E, const int wid  ) {
;     ...
;             PG8_LDA(At, 1, 1); PG8_STAGE(PG8_SB(1, 0), b3, voffB); PG8_STAGE(PG8_SB(1, 1), b3 + hstep, voffB); PG8_STAGE(PG8_SA(1, 0), a3, voffA);
;             PG8_WAIT_V(8); PG8_WAIT_L(0); PG8_BAR; PG8_MMA(1, 0, At, B0); PG8_MMA(1, 1, At, B1); PG8_BAR; PG8_SCHED;
	s_add_i32 s64, s68, s91
	v_lshl_add_u64 v[216:217], v[216:217], 0, s[60:61]
	s_mov_b32 m0, s64
	ds_read_b128 v[184:187], v158 offset:49152
	ds_read_b128 v[188:191], v158 offset:50176
	ds_read_b128 v[192:195], v158 offset:51200
	ds_read_b128 v[196:199], v158 offset:52224
	ds_read_b128 v[200:203], v158 offset:53248
	ds_read_b128 v[204:207], v158 offset:54272
	ds_read_b128 v[208:211], v158 offset:55296
	ds_read_b128 v[212:215], v158 offset:56320
	global_load_lds_dwordx4 v[216:217], off
	s_add_i32 m0, s64, 0x2000
	s_add_u32 s64, s72, 0x80080
	v_lshl_add_u64 v[216:217], v[218:219], 0, s[60:61]
	s_addc_u32 s65, s73, 0
	s_add_i32 s68, s69, s91
	global_load_lds_dwordx4 v[216:217], off
	v_lshl_add_u64 v[216:217], s[64:65], 0, v[128:129]
	s_mov_b32 m0, s68
	s_nop 0
	global_load_lds_dwordx4 v[216:217], off
	v_lshl_add_u64 v[216:217], s[64:65], 0, v[130:131]
	s_add_i32 m0, s68, 0x2000
	s_nop 0
	global_load_lds_dwordx4 v[216:217], off
	v_lshl_add_u64 v[216:217], v[220:221], 0, s[60:61]
	s_mov_b32 m0, s94
	s_nop 0
	global_load_lds_dwordx4 v[216:217], off
	v_lshl_add_u64 v[216:217], v[222:223], 0, s[60:61]
	s_mov_b32 m0, s95
	s_nop 0
	global_load_lds_dwordx4 v[216:217], off
	s_waitcnt vmcnt(8)
	s_waitcnt lgkmcnt(0)
	s_barrier
	s_setprio 1
	s_waitcnt lgkmcnt(0)
	v_mfma_f32_16x16x32_bf16 v[60:63], v[144:147], v[184:187], v[60:63]
	v_mfma_f32_16x16x32_bf16 v[60:63], v[148:151], v[188:191], v[60:63]
	v_mfma_f32_16x16x32_bf16 v[56:59], v[160:163], v[184:187], v[56:59]
	v_mfma_f32_16x16x32_bf16 v[56:59], v[164:167], v[188:191], v[56:59]
	v_mfma_f32_16x16x32_bf16 v[52:55], v[144:147], v[192:195], v[52:55]
	v_mfma_f32_16x16x32_bf16 v[52:55], v[148:151], v[196:199], v[52:55]
	v_mfma_f32_16x16x32_bf16 v[48:51], v[160:163], v[192:195], v[48:51]
	v_mfma_f32_16x16x32_bf16 v[48:51], v[164:167], v[196:199], v[48:51]
	v_mfma_f32_16x16x32_bf16 v[44:47], v[144:147], v[200:203], v[44:47]
	v_mfma_f32_16x16x32_bf16 v[44:47], v[148:151], v[204:207], v[44:47]
	v_mfma_f32_16x16x32_bf16 v[40:43], v[160:163], v[200:203], v[40:43]
	v_mfma_f32_16x16x32_bf16 v[40:43], v[164:167], v[204:207], v[40:43]
	v_mfma_f32_16x16x32_bf16 v[36:39], v[144:147], v[208:211], v[36:39]
	v_mfma_f32_16x16x32_bf16 v[36:39], v[148:151], v[212:215], v[36:39]
	v_mfma_f32_16x16x32_bf16 v[32:35], v[160:163], v[208:211], v[32:35]
	v_mfma_f32_16x16x32_bf16 v[32:35], v[164:167], v[212:215], v[32:35]
	s_setprio 0
	s_setprio 1
	v_mfma_f32_16x16x32_bf16 v[28:31], v[168:171], v[184:187], v[28:31]
	v_mfma_f32_16x16x32_bf16 v[28:31], v[172:175], v[188:191], v[28:31]
	v_mfma_f32_16x16x32_bf16 v[24:27], v[176:179], v[184:187], v[24:27]
	v_mfma_f32_16x16x32_bf16 v[24:27], v[180:183], v[188:191], v[24:27]
	v_mfma_f32_16x16x32_bf16 v[20:23], v[168:171], v[192:195], v[20:23]
	v_mfma_f32_16x16x32_bf16 v[20:23], v[172:175], v[196:199], v[20:23]
	v_mfma_f32_16x16x32_bf16 v[16:19], v[176:179], v[192:195], v[16:19]
	v_mfma_f32_16x16x32_bf16 v[16:19], v[180:183], v[196:199], v[16:19]
	v_mfma_f32_16x16x32_bf16 v[12:15], v[168:171], v[200:203], v[12:15]
	v_mfma_f32_16x16x32_bf16 v[12:15], v[172:175], v[204:207], v[12:15]
	v_mfma_f32_16x16x32_bf16 v[8:11], v[176:179], v[200:203], v[8:11]
	v_mfma_f32_16x16x32_bf16 v[8:11], v[180:183], v[204:207], v[8:11]
	v_mfma_f32_16x16x32_bf16 v[4:7], v[168:171], v[208:211], v[4:7]
	v_mfma_f32_16x16x32_bf16 v[4:7], v[172:175], v[212:215], v[4:7]
	v_mfma_f32_16x16x32_bf16 v[0:3], v[176:179], v[208:211], v[0:3]
	v_mfma_f32_16x16x32_bf16 v[0:3], v[180:183], v[212:215], v[0:3]
	s_setprio 0
	s_barrier
	s_cmp_gt_u32 s55, 29
	s_cbranch_scc1 .LBB0_312
	s_mov_b32 s55, s58
	s_branch .LBB0_293

; #define PG8_STAGE(bufoff, gbase, voff) do { _Pragma("unroll") for (int _i = 0; _i < 2; ++_i) \
;         __builtin_amdgcn_global_load_lds((const unsigned*)((const char*)(gbase) + (voff)[_i]), (PG8_LAS unsigned*)(lds + (bufoff) + ldsw + _i * 8192), 16, 0, 0); } while (0)
; #define PG8_LDA(dst, b, h) do { _Pragma("unroll") for (int m = 0; m < 4; ++m) _Pragma("unroll") for (int k = 0; k < 2; ++k) dst[m][k] = *(const PG8_LAS bf16x8*)(lds + PG8_SA(b, h) + aoff + m * 2048 + k * 1024); } while (0)
; #define PG8_LDB(dst, b, h) do { _Pragma("unroll") for (int n = 0; n < 2; ++n) _Pragma("unroll") for (int k = 0; k < 2; ++k) dst[n][k] = *(const PG8_LAS bf16x8*)(lds + PG8_SB(b, h) + boff + n * 2048 + k * 1024); } while (0)
; #define PG8_MMA(ai, bj, At, Bt) do { __builtin_amdgcn_s_setprio(1); _Pragma("unroll") for (int m = 0; m < 4; ++m) _Pragma("unroll") for (int n = 0; n < 2; ++n) _Pragma("unroll") for (int k = 0; k < 2; ++k) \
;         acc[ai][bj][m][n] = __builtin_amdgcn_mfma_f32_16x16x32_bf16(Bt[n][k], At[m][k], acc[ai][bj][m][n], 0, 0, 0); __builtin_amdgcn_s_setprio(0); } while (0)
; #define PG8_WAIT_V(n) asm volatile("s_waitcnt vmcnt(" #n ")" ::: "memory")
; #define PG8_WAIT_L(n) asm volatile("s_waitcnt lgkmcnt(" #n ")" ::: "memory")
; template <class Epi, class Sched, bool ALIGN_EPI = false, bool SP2 = false, bool APERM = false  >
; __device__ __forceinline__ void gemm_phase(PG8_LAS unsigned char* lds, const Gemm g, const Sched& S, const Epi& E, const int wid  ) {
;     ...
;             const bool last = (t == nt - 2);
;             const char* a1 = cA + (size_t)(t + 1) * kstep;
;             const char* a2 = last ? nA : cA + (size_t)(t + 2) * kstep; const char* b2 = last ? nB : cB + (size_t)(t + 2) * kstep;
;             const char* a3 = a2 + kstep; const char* b3 = b2 + kstep;
;             if (last && has_next) S.a_ready(nxt);
;             if constexpr (SP2) {
;             PG8_LDB(B0, 0, 0); PG8_LDB(B1, 0, 1); PG8_SCHED; PG8_LDA(At, 0, 0); PG8_STAGE(PG8_SA(1, 1), a1 + hstep, voffA);
;             PG8_WAIT_V(8); PG8_WAIT_L(0); PG8_BAR; PG8_MMA(0, 0, At, B0); PG8_MMA(0, 1, At, B1); PG8_BAR; PG8_SCHED;
;             PG8_LDA(At, 0, 1); PG8_STAGE(PG8_SB(0, 0), b2, voffB); PG8_STAGE(PG8_SB(0, 1), b2 + hstep, voffB); PG8_STAGE(PG8_SA(0, 0), a2, voffA);
;             PG8_WAIT_V(8); PG8_WAIT_L(0); PG8_BAR; PG8_MMA(1, 0, At, B0); PG8_MMA(1, 1, At, B1); PG8_BAR; PG8_SCHED;
.LBB0_390:
	s_lshl_b32 s6, s47, 7
	s_add_u32 s7, s60, s6
	s_addc_u32 s16, s61, 0
	s_add_u32 s14, s7, 0x100
	s_addc_u32 s15, s16, 0
	v_add_u32_e32 v140, s90, v230
	v_add_u32_e32 v156, s74, v230
	s_and_b64 s[0:1], s[12:13], exec
	ds_read_b128 v[128:131], v140
	ds_read_b128 v[132:135], v140 offset:1024
	ds_read_b128 v[136:139], v140 offset:2048
	ds_read_b128 v[140:143], v140 offset:3072
	ds_read_b128 v[144:147], v156
	ds_read_b128 v[148:151], v156 offset:1024
	ds_read_b128 v[152:155], v156 offset:2048
	ds_read_b128 v[156:159], v156 offset:3072
	s_cselect_b32 s15, s31, s15
	s_cselect_b32 s14, s33, s14
	s_add_u32 s0, s56, s6
	s_addc_u32 s1, s57, 0
	s_add_u32 s6, s0, 0x100
	s_addc_u32 s17, s1, 0
	s_and_b64 s[0:1], s[12:13], exec
	s_cselect_b32 s0, s46, s6
	s_cselect_b32 s1, s35, s17
	s_add_u32 s6, s7, 0x80080
	s_addc_u32 s7, s16, 0
	v_lshl_add_u64 v[206:207], s[6:7], 0, v[188:189]
	s_add_i32 m0, s5, 0xc000
	ds_read_b128 v[160:163], v243
	ds_read_b128 v[164:167], v243 offset:1024
	ds_read_b128 v[168:171], v243 offset:2048
	ds_read_b128 v[172:175], v243 offset:3072
	ds_read_b128 v[176:179], v243 offset:4096
	ds_read_b128 v[180:183], v243 offset:5120
	ds_read_b128 v[198:201], v243 offset:6144
	ds_read_b128 v[202:205], v243 offset:7168
	global_load_lds_dwordx4 v[206:207], off
	v_lshl_add_u64 v[206:207], s[6:7], 0, v[190:191]
	s_add_i32 m0, s5, 0xe000
	s_nop 0
	global_load_lds_dwordx4 v[206:207], off
	s_waitcnt vmcnt(8)
	s_waitcnt lgkmcnt(0)
	s_barrier
	s_setprio 1
	s_waitcnt lgkmcnt(0)
	v_mfma_f32_16x16x32_bf16 v[124:127], v[128:131], v[160:163], v[124:127]
	v_mfma_f32_16x16x32_bf16 v[124:127], v[132:135], v[164:167], v[124:127]
	v_mfma_f32_16x16x32_bf16 v[120:123], v[136:139], v[160:163], v[120:123]
	v_mfma_f32_16x16x32_bf16 v[120:123], v[140:143], v[164:167], v[120:123]
	v_mfma_f32_16x16x32_bf16 v[116:119], v[128:131], v[168:171], v[116:119]
	v_mfma_f32_16x16x32_bf16 v[116:119], v[132:135], v[172:175], v[116:119]
	v_mfma_f32_16x16x32_bf16 v[112:115], v[136:139], v[168:171], v[112:115]
	v_mfma_f32_16x16x32_bf16 v[112:115], v[140:143], v[172:175], v[112:115]
	v_mfma_f32_16x16x32_bf16 v[108:111], v[128:131], v[176:179], v[108:111]
	v_mfma_f32_16x16x32_bf16 v[108:111], v[132:135], v[180:183], v[108:111]
	v_mfma_f32_16x16x32_bf16 v[104:107], v[136:139], v[176:179], v[104:107]
	v_mfma_f32_16x16x32_bf16 v[104:107], v[140:143], v[180:183], v[104:107]
	v_mfma_f32_16x16x32_bf16 v[100:103], v[128:131], v[198:201], v[100:103]
	v_mfma_f32_16x16x32_bf16 v[100:103], v[132:135], v[202:205], v[100:103]
	v_mfma_f32_16x16x32_bf16 v[96:99], v[136:139], v[198:201], v[96:99]
	v_mfma_f32_16x16x32_bf16 v[96:99], v[140:143], v[202:205], v[96:99]
	s_setprio 0
	s_setprio 1
	v_mfma_f32_16x16x32_bf16 v[92:95], v[144:147], v[160:163], v[92:95]
	v_mfma_f32_16x16x32_bf16 v[92:95], v[148:151], v[164:167], v[92:95]
	v_mfma_f32_16x16x32_bf16 v[88:91], v[152:155], v[160:163], v[88:91]
	v_mfma_f32_16x16x32_bf16 v[88:91], v[156:159], v[164:167], v[88:91]
	v_mfma_f32_16x16x32_bf16 v[84:87], v[144:147], v[168:171], v[84:87]
	v_mfma_f32_16x16x32_bf16 v[84:87], v[148:151], v[172:175], v[84:87]
	v_mfma_f32_16x16x32_bf16 v[80:83], v[152:155], v[168:171], v[80:83]
	v_mfma_f32_16x16x32_bf16 v[80:83], v[156:159], v[172:175], v[80:83]
	v_mfma_f32_16x16x32_bf16 v[76:79], v[144:147], v[176:179], v[76:79]
	v_mfma_f32_16x16x32_bf16 v[76:79], v[148:151], v[180:183], v[76:79]
	v_mfma_f32_16x16x32_bf16 v[72:75], v[152:155], v[176:179], v[72:75]
	v_mfma_f32_16x16x32_bf16 v[72:75], v[156:159], v[180:183], v[72:75]
	v_mfma_f32_16x16x32_bf16 v[68:71], v[144:147], v[198:201], v[68:71]
	v_mfma_f32_16x16x32_bf16 v[68:71], v[148:151], v[202:205], v[68:71]
	v_mfma_f32_16x16x32_bf16 v[64:67], v[152:155], v[198:201], v[64:67]
	v_mfma_f32_16x16x32_bf16 v[64:67], v[156:159], v[202:205], v[64:67]
	s_setprio 0
	s_barrier
	s_add_i32 s6, s90, s63
	v_lshl_add_u64 v[206:207], s[0:1], 0, v[184:185]
	s_mov_b32 m0, s6
	ds_read_b128 v[160:163], v243 offset:16384
	ds_read_b128 v[164:167], v243 offset:17408
	ds_read_b128 v[168:171], v243 offset:18432
	ds_read_b128 v[172:175], v243 offset:19456
	ds_read_b128 v[176:179], v243 offset:20480
	ds_read_b128 v[180:183], v243 offset:21504
	ds_read_b128 v[198:201], v243 offset:22528
	ds_read_b128 v[202:205], v243 offset:23552
	global_load_lds_dwordx4 v[206:207], off
	s_add_i32 m0, s6, 0x2000
	s_add_u32 s6, s0, 0x80000
	v_lshl_add_u64 v[208:209], s[0:1], 0, v[186:187]
	s_addc_u32 s7, s1, 0
	s_add_i32 s12, s74, s63
	global_load_lds_dwordx4 v[208:209], off
	v_lshl_add_u64 v[210:211], s[6:7], 0, v[184:185]
	s_mov_b32 m0, s12
	v_lshl_add_u64 v[212:213], s[14:15], 0, v[190:191]
	global_load_lds_dwordx4 v[210:211], off
	v_lshl_add_u64 v[210:211], s[6:7], 0, v[186:187]
	s_add_i32 m0, s12, 0x2000
	s_nop 0
	global_load_lds_dwordx4 v[210:211], off
	v_lshl_add_u64 v[210:211], s[14:15], 0, v[188:189]
	s_mov_b32 m0, s5
	s_nop 0
	global_load_lds_dwordx4 v[210:211], off
	s_mov_b32 m0, s87
	s_nop 0
	global_load_lds_dwordx4 v[212:213], off
	s_waitcnt vmcnt(8)
	s_waitcnt lgkmcnt(0)
	s_barrier
; #define PG8_STAGE(bufoff, gbase, voff) do { _Pragma("unroll") for (int _i = 0; _i < 2; ++_i) \
;         __builtin_amdgcn_global_load_lds((const unsigned*)((const char*)(gbase) + (voff)[_i]), (PG8_LAS unsigned*)(lds + (bufoff) + ldsw + _i * 8192), 16, 0, 0); } while (0)
; #define PG8_LDA(dst, b, h) do { _Pragma("unroll") for (int m = 0; m < 4; ++m) _Pragma("unroll") for (int k = 0; k < 2; ++k) dst[m][k] = *(const PG8_LAS bf16x8*)(lds + PG8_SA(b, h) + aoff + m * 2048 + k * 1024); } while (0)
; #define PG8_LDB(dst, b, h) do { _Pragma("unroll") for (int n = 0; n < 2; ++n) _Pragma("unroll") for (int k = 0; k < 2; ++k) dst[n][k] = *(const PG8_LAS bf16x8*)(lds + PG8_SB(b, h) + boff + n * 2048 + k * 1024); } while (0)
; #define PG8_MMA(ai, bj, At, Bt) do { __builtin_amdgcn_s_setprio(1); _Pragma("unroll") for (int m = 0; m < 4; ++m) _Pragma("unroll") for (int n = 0; n < 2; ++n) _Pragma("unroll") for (int k = 0; k < 2; ++k) \
;         acc[ai][bj][m][n] = __builtin_amdgcn_mfma_f32_16x16x32_bf16(Bt[n][k], At[m][k], acc[ai][bj][m][n], 0, 0, 0); __builtin_amdgcn_s_setprio(0); } while (0)
; #define PG8_WAIT_V(n) asm volatile("s_waitcnt vmcnt(" #n ")" ::: "memory")
; #define PG8_WAIT_L(n) asm volatile("s_waitcnt lgkmcnt(" #n ")" ::: "memory")
; #define PG8_BAR __builtin_amdgcn_s_barrier()
; #define PG8_SCHED __builtin_amdgcn_sched_barrier(0)
; template <class Epi, class Sched, bool ALIGN_EPI = false, bool SP2 = false, bool APERM = false  >
; __device__ __forceinline__ void gemm_phase(PG8_LAS unsigned char* lds, const Gemm g, const Sched& S, const Epi& E, const int wid  ) {
;     ...
;             PG8_WAIT_V(8); PG8_WAIT_L(0); PG8_BAR; PG8_MMA(1, 0, At, B0); PG8_MMA(1, 1, At, B1); PG8_BAR; PG8_SCHED;
;             PG8_LDB(B0, 1, 0); PG8_LDB(B1, 1, 1); PG8_SCHED; PG8_LDA(At, 1, 0); PG8_STAGE(PG8_SA(0, 1), a2 + hstep, voffA);
;             PG8_WAIT_V(8); PG8_WAIT_L(0); PG8_BAR; PG8_MMA(0, 0, At, B0); PG8_MMA(0, 1, At, B1); PG8_BAR; PG8_SCHED;
	s_setprio 1
	s_waitcnt lgkmcnt(0)
	v_mfma_f32_16x16x32_bf16 v[60:63], v[128:131], v[160:163], v[60:63]
	v_mfma_f32_16x16x32_bf16 v[60:63], v[132:135], v[164:167], v[60:63]
	v_mfma_f32_16x16x32_bf16 v[56:59], v[136:139], v[160:163], v[56:59]
	v_mfma_f32_16x16x32_bf16 v[56:59], v[140:143], v[164:167], v[56:59]
	v_mfma_f32_16x16x32_bf16 v[52:55], v[128:131], v[168:171], v[52:55]
	v_mfma_f32_16x16x32_bf16 v[52:55], v[132:135], v[172:175], v[52:55]
	v_mfma_f32_16x16x32_bf16 v[48:51], v[136:139], v[168:171], v[48:51]
	v_mfma_f32_16x16x32_bf16 v[48:51], v[140:143], v[172:175], v[48:51]
	v_mfma_f32_16x16x32_bf16 v[44:47], v[128:131], v[176:179], v[44:47]
	v_mfma_f32_16x16x32_bf16 v[44:47], v[132:135], v[180:183], v[44:47]
	v_mfma_f32_16x16x32_bf16 v[40:43], v[136:139], v[176:179], v[40:43]
	v_mfma_f32_16x16x32_bf16 v[40:43], v[140:143], v[180:183], v[40:43]
	v_mfma_f32_16x16x32_bf16 v[36:39], v[128:131], v[198:201], v[36:39]
	v_mfma_f32_16x16x32_bf16 v[36:39], v[132:135], v[202:205], v[36:39]
	v_mfma_f32_16x16x32_bf16 v[32:35], v[136:139], v[198:201], v[32:35]
	v_mfma_f32_16x16x32_bf16 v[32:35], v[140:143], v[202:205], v[32:35]
	s_setprio 0
	s_setprio 1
	v_mfma_f32_16x16x32_bf16 v[28:31], v[144:147], v[160:163], v[28:31]
	v_mfma_f32_16x16x32_bf16 v[28:31], v[148:151], v[164:167], v[28:31]
	v_mfma_f32_16x16x32_bf16 v[24:27], v[152:155], v[160:163], v[24:27]
	v_mfma_f32_16x16x32_bf16 v[24:27], v[156:159], v[164:167], v[24:27]
	v_mfma_f32_16x16x32_bf16 v[20:23], v[144:147], v[168:171], v[20:23]
	v_mfma_f32_16x16x32_bf16 v[20:23], v[148:151], v[172:175], v[20:23]
	v_mfma_f32_16x16x32_bf16 v[16:19], v[152:155], v[168:171], v[16:19]
	v_mfma_f32_16x16x32_bf16 v[16:19], v[156:159], v[172:175], v[16:19]
	v_mfma_f32_16x16x32_bf16 v[12:15], v[144:147], v[176:179], v[12:15]
	v_mfma_f32_16x16x32_bf16 v[12:15], v[148:151], v[180:183], v[12:15]
	v_mfma_f32_16x16x32_bf16 v[8:11], v[152:155], v[176:179], v[8:11]
	v_mfma_f32_16x16x32_bf16 v[8:11], v[156:159], v[180:183], v[8:11]
	v_mfma_f32_16x16x32_bf16 v[4:7], v[144:147], v[198:201], v[4:7]
	v_mfma_f32_16x16x32_bf16 v[4:7], v[148:151], v[202:205], v[4:7]
	v_mfma_f32_16x16x32_bf16 v[0:3], v[152:155], v[198:201], v[0:3]
	v_mfma_f32_16x16x32_bf16 v[0:3], v[156:159], v[202:205], v[0:3]
	s_setprio 0
	s_barrier
	s_add_i32 s12, 0, 0x18000
	s_add_i32 s13, 0, 0x1c000
	v_add_u32_e32 v140, s12, v230
	v_add_u32_e32 v156, s13, v230
	ds_read_b128 v[128:131], v140
	ds_read_b128 v[132:135], v140 offset:1024
	ds_read_b128 v[136:139], v140 offset:2048
	ds_read_b128 v[140:143], v140 offset:3072
	ds_read_b128 v[144:147], v156
	ds_read_b128 v[148:151], v156 offset:1024
	ds_read_b128 v[152:155], v156 offset:2048
	ds_read_b128 v[156:159], v156 offset:3072
	s_add_u32 s6, s14, 0x80000
	s_addc_u32 s7, s15, 0
	s_mov_b32 m0, s10
	v_lshl_add_u64 v[214:215], s[6:7], 0, v[188:189]
	ds_read_b128 v[160:163], v243 offset:32768
	ds_read_b128 v[164:167], v243 offset:33792
	ds_read_b128 v[168:171], v243 offset:34816
	ds_read_b128 v[172:175], v243 offset:35840
	ds_read_b128 v[176:179], v243 offset:36864
	ds_read_b128 v[180:183], v243 offset:37888
	ds_read_b128 v[198:201], v243 offset:38912
	ds_read_b128 v[202:205], v243 offset:39936
	global_load_lds_dwordx4 v[214:215], off
	v_lshl_add_u64 v[214:215], s[6:7], 0, v[190:191]
	s_mov_b32 m0, s11
	s_nop 0
	global_load_lds_dwordx4 v[214:215], off
	s_waitcnt vmcnt(8)
	s_waitcnt lgkmcnt(0)
	s_barrier
	s_setprio 1
	s_waitcnt lgkmcnt(0)
	v_mfma_f32_16x16x32_bf16 v[124:127], v[128:131], v[160:163], v[124:127]
	v_mfma_f32_16x16x32_bf16 v[124:127], v[132:135], v[164:167], v[124:127]
	v_mfma_f32_16x16x32_bf16 v[120:123], v[136:139], v[160:163], v[120:123]
	v_mfma_f32_16x16x32_bf16 v[120:123], v[140:143], v[164:167], v[120:123]
	v_mfma_f32_16x16x32_bf16 v[116:119], v[128:131], v[168:171], v[116:119]
	v_mfma_f32_16x16x32_bf16 v[116:119], v[132:135], v[172:175], v[116:119]
	v_mfma_f32_16x16x32_bf16 v[112:115], v[136:139], v[168:171], v[112:115]
	v_mfma_f32_16x16x32_bf16 v[112:115], v[140:143], v[172:175], v[112:115]
	v_mfma_f32_16x16x32_bf16 v[108:111], v[128:131], v[176:179], v[108:111]
	v_mfma_f32_16x16x32_bf16 v[108:111], v[132:135], v[180:183], v[108:111]
	v_mfma_f32_16x16x32_bf16 v[104:107], v[136:139], v[176:179], v[104:107]
	v_mfma_f32_16x16x32_bf16 v[104:107], v[140:143], v[180:183], v[104:107]
	v_mfma_f32_16x16x32_bf16 v[100:103], v[128:131], v[198:201], v[100:103]
	v_mfma_f32_16x16x32_bf16 v[100:103], v[132:135], v[202:205], v[100:103]
	v_mfma_f32_16x16x32_bf16 v[96:99], v[136:139], v[198:201], v[96:99]
	v_mfma_f32_16x16x32_bf16 v[96:99], v[140:143], v[202:205], v[96:99]
	s_setprio 0
	s_setprio 1
	v_mfma_f32_16x16x32_bf16 v[92:95], v[144:147], v[160:163], v[92:95]
	v_mfma_f32_16x16x32_bf16 v[92:95], v[148:151], v[164:167], v[92:95]
	v_mfma_f32_16x16x32_bf16 v[88:91], v[152:155], v[160:163], v[88:91]
	v_mfma_f32_16x16x32_bf16 v[88:91], v[156:159], v[164:167], v[88:91]
	v_mfma_f32_16x16x32_bf16 v[84:87], v[144:147], v[168:171], v[84:87]
	v_mfma_f32_16x16x32_bf16 v[84:87], v[148:151], v[172:175], v[84:87]
	v_mfma_f32_16x16x32_bf16 v[80:83], v[152:155], v[168:171], v[80:83]
	v_mfma_f32_16x16x32_bf16 v[80:83], v[156:159], v[172:175], v[80:83]
	v_mfma_f32_16x16x32_bf16 v[76:79], v[144:147], v[176:179], v[76:79]
	v_mfma_f32_16x16x32_bf16 v[76:79], v[148:151], v[180:183], v[76:79]
	v_mfma_f32_16x16x32_bf16 v[72:75], v[152:155], v[176:179], v[72:75]
	v_mfma_f32_16x16x32_bf16 v[72:75], v[156:159], v[180:183], v[72:75]
	v_mfma_f32_16x16x32_bf16 v[68:71], v[144:147], v[198:201], v[68:71]
	v_mfma_f32_16x16x32_bf16 v[68:71], v[148:151], v[202:205], v[68:71]
	v_mfma_f32_16x16x32_bf16 v[64:67], v[152:155], v[198:201], v[64:67]
	v_mfma_f32_16x16x32_bf16 v[64:67], v[156:159], v[202:205], v[64:67]
	s_setprio 0
	s_barrier
; #define PG8_STAGE(bufoff, gbase, voff) do { _Pragma("unroll") for (int _i = 0; _i < 2; ++_i) \
;         __builtin_amdgcn_global_load_lds((const unsigned*)((const char*)(gbase) + (voff)[_i]), (PG8_LAS unsigned*)(lds + (bufoff) + ldsw + _i * 8192), 16, 0, 0); } while (0)
; #define PG8_LDA(dst, b, h) do { _Pragma("unroll") for (int m = 0; m < 4; ++m) _Pragma("unroll") for (int k = 0; k < 2; ++k) dst[m][k] = *(const PG8_LAS bf16x8*)(lds + PG8_SA(b, h) + aoff + m * 2048 + k * 1024); } while (0)
; #define PG8_MMA(ai, bj, At, Bt) do { __builtin_amdgcn_s_setprio(1); _Pragma("unroll") for (int m = 0; m < 4; ++m) _Pragma("unroll") for (int n = 0; n < 2; ++n) _Pragma("unroll") for (int k = 0; k < 2; ++k) \
;         acc[ai][bj][m][n] = __builtin_amdgcn_mfma_f32_16x16x32_bf16(Bt[n][k], At[m][k], acc[ai][bj][m][n], 0, 0, 0); __builtin_amdgcn_s_setprio(0); } while (0)
; #define PG8_WAIT_V(n) asm volatile("s_waitcnt vmcnt(" #n ")" ::: "memory")
; #define PG8_WAIT_L(n) asm volatile("s_waitcnt lgkmcnt(" #n ")" ::: "memory")
; #define PG8_BAR __builtin_amdgcn_s_barrier()
; #define PG8_SCHED __builtin_amdgcn_sched_barrier(0)
; template <class Epi, class Sched, bool ALIGN_EPI = false, bool SP2 = false, bool APERM = false  >
; __device__ __forceinline__ void gemm_phase(PG8_LAS unsigned char* lds, const Gemm g, const Sched& S, const Epi& E, const int wid  ) {
;     ...
;             PG8_LDA(At, 1, 1); PG8_STAGE(PG8_SB(1, 0), b3, voffB); PG8_STAGE(PG8_SB(1, 1), b3 + hstep, voffB); PG8_STAGE(PG8_SA(1, 0), a3, voffA);
;             PG8_WAIT_V(8); PG8_WAIT_L(0); PG8_BAR; PG8_MMA(1, 0, At, B0); PG8_MMA(1, 1, At, B1); PG8_BAR; PG8_SCHED;
	s_add_i32 s6, s12, s63
	v_lshl_add_u64 v[206:207], v[206:207], 0, s[72:73]
	s_mov_b32 m0, s6
	ds_read_b128 v[160:163], v243 offset:49152
	ds_read_b128 v[164:167], v243 offset:50176
	ds_read_b128 v[168:171], v243 offset:51200
	ds_read_b128 v[172:175], v243 offset:52224
	ds_read_b128 v[176:179], v243 offset:53248
	ds_read_b128 v[180:183], v243 offset:54272
	ds_read_b128 v[198:201], v243 offset:55296
	ds_read_b128 v[202:205], v243 offset:56320
	global_load_lds_dwordx4 v[206:207], off
	s_add_i32 m0, s6, 0x2000
	s_add_u32 s0, s0, 0x80080
	v_lshl_add_u64 v[206:207], v[208:209], 0, s[72:73]
	s_addc_u32 s1, s1, 0
	s_add_i32 s6, s13, s63
	global_load_lds_dwordx4 v[206:207], off
	v_lshl_add_u64 v[206:207], s[0:1], 0, v[184:185]
	s_mov_b32 m0, s6
	s_nop 0
	global_load_lds_dwordx4 v[206:207], off
	v_lshl_add_u64 v[206:207], s[0:1], 0, v[186:187]
	s_add_i32 m0, s6, 0x2000
	s_nop 0
	global_load_lds_dwordx4 v[206:207], off
	v_lshl_add_u64 v[206:207], v[210:211], 0, s[72:73]
	s_mov_b32 m0, s88
	s_nop 0
	global_load_lds_dwordx4 v[206:207], off
	v_lshl_add_u64 v[206:207], v[212:213], 0, s[72:73]
	s_mov_b32 m0, s89
	s_nop 0
	global_load_lds_dwordx4 v[206:207], off
	s_waitcnt vmcnt(8)
	s_waitcnt lgkmcnt(0)
	s_barrier
	s_setprio 1
	s_waitcnt lgkmcnt(0)
	v_mfma_f32_16x16x32_bf16 v[60:63], v[128:131], v[160:163], v[60:63]
	v_mfma_f32_16x16x32_bf16 v[60:63], v[132:135], v[164:167], v[60:63]
	v_mfma_f32_16x16x32_bf16 v[56:59], v[136:139], v[160:163], v[56:59]
	v_mfma_f32_16x16x32_bf16 v[56:59], v[140:143], v[164:167], v[56:59]
	v_mfma_f32_16x16x32_bf16 v[52:55], v[128:131], v[168:171], v[52:55]
	v_mfma_f32_16x16x32_bf16 v[52:55], v[132:135], v[172:175], v[52:55]
	v_mfma_f32_16x16x32_bf16 v[48:51], v[136:139], v[168:171], v[48:51]
	v_mfma_f32_16x16x32_bf16 v[48:51], v[140:143], v[172:175], v[48:51]
	v_mfma_f32_16x16x32_bf16 v[44:47], v[128:131], v[176:179], v[44:47]
	v_mfma_f32_16x16x32_bf16 v[44:47], v[132:135], v[180:183], v[44:47]
	v_mfma_f32_16x16x32_bf16 v[40:43], v[136:139], v[176:179], v[40:43]
	v_mfma_f32_16x16x32_bf16 v[40:43], v[140:143], v[180:183], v[40:43]
	v_mfma_f32_16x16x32_bf16 v[36:39], v[128:131], v[198:201], v[36:39]
	v_mfma_f32_16x16x32_bf16 v[36:39], v[132:135], v[202:205], v[36:39]
	v_mfma_f32_16x16x32_bf16 v[32:35], v[136:139], v[198:201], v[32:35]
	v_mfma_f32_16x16x32_bf16 v[32:35], v[140:143], v[202:205], v[32:35]
	s_setprio 0
	s_setprio 1
	v_mfma_f32_16x16x32_bf16 v[28:31], v[144:147], v[160:163], v[28:31]
	v_mfma_f32_16x16x32_bf16 v[28:31], v[148:151], v[164:167], v[28:31]
	v_mfma_f32_16x16x32_bf16 v[24:27], v[152:155], v[160:163], v[24:27]
	v_mfma_f32_16x16x32_bf16 v[24:27], v[156:159], v[164:167], v[24:27]
	v_mfma_f32_16x16x32_bf16 v[20:23], v[144:147], v[168:171], v[20:23]
	v_mfma_f32_16x16x32_bf16 v[20:23], v[148:151], v[172:175], v[20:23]
	v_mfma_f32_16x16x32_bf16 v[16:19], v[152:155], v[168:171], v[16:19]
	v_mfma_f32_16x16x32_bf16 v[16:19], v[156:159], v[172:175], v[16:19]
	v_mfma_f32_16x16x32_bf16 v[12:15], v[144:147], v[176:179], v[12:15]
	v_mfma_f32_16x16x32_bf16 v[12:15], v[148:151], v[180:183], v[12:15]
	v_mfma_f32_16x16x32_bf16 v[8:11], v[152:155], v[176:179], v[8:11]
	v_mfma_f32_16x16x32_bf16 v[8:11], v[156:159], v[180:183], v[8:11]
	v_mfma_f32_16x16x32_bf16 v[4:7], v[144:147], v[198:201], v[4:7]
	v_mfma_f32_16x16x32_bf16 v[4:7], v[148:151], v[202:205], v[4:7]
	v_mfma_f32_16x16x32_bf16 v[0:3], v[152:155], v[198:201], v[0:3]
	v_mfma_f32_16x16x32_bf16 v[0:3], v[156:159], v[202:205], v[0:3]
	s_setprio 0
	s_barrier
	s_add_i32 s0, s47, 2
	s_cmp_gt_u32 s47, 29
	s_cbranch_scc1 .LBB0_392
	s_mov_b32 s47, s0
	s_branch .LBB0_368

; #define PG8_STAGE(bufoff, gbase, voff) do { _Pragma("unroll") for (int _i = 0; _i < 2; ++_i) \
;         __builtin_amdgcn_global_load_lds((const unsigned*)((const char*)(gbase) + (voff)[_i]), (PG8_LAS unsigned*)(lds + (bufoff) + ldsw + _i * 8192), 16, 0, 0); } while (0)
; #define PG8_LDA(dst, b, h) do { _Pragma("unroll") for (int m = 0; m < 4; ++m) _Pragma("unroll") for (int k = 0; k < 2; ++k) dst[m][k] = *(const PG8_LAS bf16x8*)(lds + PG8_SA(b, h) + aoff + m * 2048 + k * 1024); } while (0)
; #define PG8_LDB(dst, b, h) do { _Pragma("unroll") for (int n = 0; n < 2; ++n) _Pragma("unroll") for (int k = 0; k < 2; ++k) dst[n][k] = *(const PG8_LAS bf16x8*)(lds + PG8_SB(b, h) + boff + n * 2048 + k * 1024); } while (0)
; #define PG8_MMA(ai, bj, At, Bt) do { __builtin_amdgcn_s_setprio(1); _Pragma("unroll") for (int m = 0; m < 4; ++m) _Pragma("unroll") for (int n = 0; n < 2; ++n) _Pragma("unroll") for (int k = 0; k < 2; ++k) \
;         acc[ai][bj][m][n] = __builtin_amdgcn_mfma_f32_16x16x32_bf16(Bt[n][k], At[m][k], acc[ai][bj][m][n], 0, 0, 0); __builtin_amdgcn_s_setprio(0); } while (0)
; #define PG8_WAIT_V(n) asm volatile("s_waitcnt vmcnt(" #n ")" ::: "memory")
; #define PG8_WAIT_L(n) asm volatile("s_waitcnt lgkmcnt(" #n ")" ::: "memory")
; template <class Epi, class Sched, bool ALIGN_EPI = false, bool SP2 = false, bool APERM = false  >
; __device__ __forceinline__ void gemm_phase(PG8_LAS unsigned char* lds, const Gemm g, const Sched& S, const Epi& E, const int wid  ) {
;     ...
;             const bool last = (t == nt - 2);
;             const char* a1 = cA + (size_t)(t + 1) * kstep;
;             const char* a2 = last ? nA : cA + (size_t)(t + 2) * kstep; const char* b2 = last ? nB : cB + (size_t)(t + 2) * kstep;
;             const char* a3 = a2 + kstep; const char* b3 = b2 + kstep;
;             if (last && has_next) S.a_ready(nxt);
;             if constexpr (SP2) {
;             PG8_LDB(B0, 0, 0); PG8_LDB(B1, 0, 1); PG8_SCHED; PG8_LDA(At, 0, 0); PG8_STAGE(PG8_SA(1, 1), a1 + hstep, voffA);
;             PG8_WAIT_V(8); PG8_WAIT_L(0); PG8_BAR; PG8_MMA(0, 0, At, B0); PG8_MMA(0, 1, At, B1); PG8_BAR; PG8_SCHED;
;             PG8_LDA(At, 0, 1); PG8_STAGE(PG8_SB(0, 0), b2, voffB); PG8_STAGE(PG8_SB(0, 1), b2 + hstep, voffB); PG8_STAGE(PG8_SA(0, 0), a2, voffA);
;             PG8_WAIT_V(8); PG8_WAIT_L(0); PG8_BAR; PG8_MMA(1, 0, At, B0); PG8_MMA(1, 1, At, B1); PG8_BAR; PG8_SCHED;
.LBB0_543:
	s_lshl_b32 s11, s10, 7
	s_add_u32 s46, s0, s11
	s_addc_u32 s47, s1, 0
	v_add_u32_e32 v146, s33, v150
	s_add_u32 s96, s46, 0x100
	s_waitcnt lgkmcnt(0)
	ds_read_b128 v[142:145], v146
	ds_read_b128 v[154:157], v146 offset:1024
	ds_read_b128 v[158:161], v146 offset:2048
	ds_read_b128 v[162:165], v146 offset:3072
	v_add_u32_e32 v146, s64, v150
	s_addc_u32 s97, s47, 0
	ds_read_b128 v[166:169], v146
	ds_read_b128 v[170:173], v146 offset:1024
	ds_read_b128 v[174:177], v146 offset:2048
	ds_read_b128 v[178:181], v146 offset:3072
	s_and_b64 s[8:9], s[94:95], exec
	s_cselect_b32 s97, s89, s97
	s_cselect_b32 s96, s88, s96
	s_add_u32 s8, s12, s11
	s_addc_u32 s9, s13, 0
	s_add_u32 s11, s8, 0x100
	s_addc_u32 vcc_lo, s9, 0
	s_and_b64 s[8:9], s[94:95], exec
	s_cselect_b32 s95, s91, vcc_lo
	s_cselect_b32 s94, s90, s11
	s_add_u32 s8, s46, 0x160080
	s_addc_u32 s9, s47, 0
	v_lshl_add_u64 v[146:147], s[8:9], 0, v[132:133]
	s_add_i32 m0, s76, 0xc000
	ds_read_b128 v[182:185], v153
	ds_read_b128 v[186:189], v153 offset:1024
	ds_read_b128 v[190:193], v153 offset:2048
	ds_read_b128 v[194:197], v153 offset:3072
	ds_read_b128 v[198:201], v153 offset:4096
	ds_read_b128 v[202:205], v153 offset:5120
	ds_read_b128 v[206:209], v153 offset:6144
	ds_read_b128 v[210:213], v153 offset:7168
	global_load_lds_dwordx4 v[146:147], off
	v_lshl_add_u64 v[146:147], s[8:9], 0, v[134:135]
	s_add_i32 m0, s76, 0xe000
	s_nop 0
	global_load_lds_dwordx4 v[146:147], off
	s_waitcnt vmcnt(8)
	s_waitcnt lgkmcnt(0)
	s_barrier
	s_setprio 1
	s_waitcnt lgkmcnt(0)
	v_mfma_f32_16x16x32_bf16 v[124:127], v[142:145], v[182:185], v[124:127]
	v_mfma_f32_16x16x32_bf16 v[124:127], v[154:157], v[186:189], v[124:127]
	v_mfma_f32_16x16x32_bf16 v[120:123], v[158:161], v[182:185], v[120:123]
	v_mfma_f32_16x16x32_bf16 v[120:123], v[162:165], v[186:189], v[120:123]
	v_mfma_f32_16x16x32_bf16 v[116:119], v[142:145], v[190:193], v[116:119]
	v_mfma_f32_16x16x32_bf16 v[116:119], v[154:157], v[194:197], v[116:119]
	v_mfma_f32_16x16x32_bf16 v[112:115], v[158:161], v[190:193], v[112:115]
	v_mfma_f32_16x16x32_bf16 v[112:115], v[162:165], v[194:197], v[112:115]
	v_mfma_f32_16x16x32_bf16 v[108:111], v[142:145], v[198:201], v[108:111]
	v_mfma_f32_16x16x32_bf16 v[108:111], v[154:157], v[202:205], v[108:111]
	v_mfma_f32_16x16x32_bf16 v[104:107], v[158:161], v[198:201], v[104:107]
	v_mfma_f32_16x16x32_bf16 v[104:107], v[162:165], v[202:205], v[104:107]
	v_mfma_f32_16x16x32_bf16 v[100:103], v[142:145], v[206:209], v[100:103]
	v_mfma_f32_16x16x32_bf16 v[100:103], v[154:157], v[210:213], v[100:103]
	v_mfma_f32_16x16x32_bf16 v[96:99], v[158:161], v[206:209], v[96:99]
	v_mfma_f32_16x16x32_bf16 v[96:99], v[162:165], v[210:213], v[96:99]
	s_setprio 0
	s_setprio 1
	v_mfma_f32_16x16x32_bf16 v[92:95], v[166:169], v[182:185], v[92:95]
	v_mfma_f32_16x16x32_bf16 v[92:95], v[170:173], v[186:189], v[92:95]
	v_mfma_f32_16x16x32_bf16 v[88:91], v[174:177], v[182:185], v[88:91]
	v_mfma_f32_16x16x32_bf16 v[88:91], v[178:181], v[186:189], v[88:91]
	v_mfma_f32_16x16x32_bf16 v[84:87], v[166:169], v[190:193], v[84:87]
	v_mfma_f32_16x16x32_bf16 v[84:87], v[170:173], v[194:197], v[84:87]
	v_mfma_f32_16x16x32_bf16 v[80:83], v[174:177], v[190:193], v[80:83]
	v_mfma_f32_16x16x32_bf16 v[80:83], v[178:181], v[194:197], v[80:83]
	v_mfma_f32_16x16x32_bf16 v[76:79], v[166:169], v[198:201], v[76:79]
	v_mfma_f32_16x16x32_bf16 v[76:79], v[170:173], v[202:205], v[76:79]
	v_mfma_f32_16x16x32_bf16 v[72:75], v[174:177], v[198:201], v[72:75]
	v_mfma_f32_16x16x32_bf16 v[72:75], v[178:181], v[202:205], v[72:75]
	v_mfma_f32_16x16x32_bf16 v[68:71], v[166:169], v[206:209], v[68:71]
	v_mfma_f32_16x16x32_bf16 v[68:71], v[170:173], v[210:213], v[68:71]
	v_mfma_f32_16x16x32_bf16 v[64:67], v[174:177], v[206:209], v[64:67]
	v_mfma_f32_16x16x32_bf16 v[64:67], v[178:181], v[210:213], v[64:67]
	s_setprio 0
	s_barrier
	s_add_i32 s8, s33, s16
	v_lshl_add_u64 v[146:147], s[94:95], 0, v[128:129]
	s_mov_b32 m0, s8
	ds_read_b128 v[182:185], v153 offset:16384
	ds_read_b128 v[186:189], v153 offset:17408
	ds_read_b128 v[190:193], v153 offset:18432
	ds_read_b128 v[194:197], v153 offset:19456
	ds_read_b128 v[198:201], v153 offset:20480
	ds_read_b128 v[202:205], v153 offset:21504
	ds_read_b128 v[206:209], v153 offset:22528
	ds_read_b128 v[210:213], v153 offset:23552
	global_load_lds_dwordx4 v[146:147], off
	s_add_i32 m0, s8, 0x2000
	s_add_u32 s8, s94, 0x160000
	v_lshl_add_u64 v[214:215], s[94:95], 0, v[130:131]
	s_addc_u32 s9, s95, 0
	s_add_i32 s11, s64, s16
	global_load_lds_dwordx4 v[214:215], off
	v_lshl_add_u64 v[216:217], s[8:9], 0, v[128:129]
	s_mov_b32 m0, s11
	v_lshl_add_u64 v[218:219], s[96:97], 0, v[134:135]
	global_load_lds_dwordx4 v[216:217], off
	v_lshl_add_u64 v[216:217], s[8:9], 0, v[130:131]
	s_add_i32 m0, s11, 0x2000
	s_nop 0
	global_load_lds_dwordx4 v[216:217], off
	v_lshl_add_u64 v[216:217], s[96:97], 0, v[132:133]
	s_mov_b32 m0, s76
	s_nop 0
	global_load_lds_dwordx4 v[216:217], off
	s_mov_b32 m0, s77
	s_nop 0
	global_load_lds_dwordx4 v[218:219], off
	s_waitcnt vmcnt(8)
	s_waitcnt lgkmcnt(0)
	s_barrier
; #define PG8_STAGE(bufoff, gbase, voff) do { _Pragma("unroll") for (int _i = 0; _i < 2; ++_i) \
;         __builtin_amdgcn_global_load_lds((const unsigned*)((const char*)(gbase) + (voff)[_i]), (PG8_LAS unsigned*)(lds + (bufoff) + ldsw + _i * 8192), 16, 0, 0); } while (0)
; #define PG8_LDA(dst, b, h) do { _Pragma("unroll") for (int m = 0; m < 4; ++m) _Pragma("unroll") for (int k = 0; k < 2; ++k) dst[m][k] = *(const PG8_LAS bf16x8*)(lds + PG8_SA(b, h) + aoff + m * 2048 + k * 1024); } while (0)
; #define PG8_LDB(dst, b, h) do { _Pragma("unroll") for (int n = 0; n < 2; ++n) _Pragma("unroll") for (int k = 0; k < 2; ++k) dst[n][k] = *(const PG8_LAS bf16x8*)(lds + PG8_SB(b, h) + boff + n * 2048 + k * 1024); } while (0)
; #define PG8_MMA(ai, bj, At, Bt) do { __builtin_amdgcn_s_setprio(1); _Pragma("unroll") for (int m = 0; m < 4; ++m) _Pragma("unroll") for (int n = 0; n < 2; ++n) _Pragma("unroll") for (int k = 0; k < 2; ++k) \
;         acc[ai][bj][m][n] = __builtin_amdgcn_mfma_f32_16x16x32_bf16(Bt[n][k], At[m][k], acc[ai][bj][m][n], 0, 0, 0); __builtin_amdgcn_s_setprio(0); } while (0)
; #define PG8_WAIT_V(n) asm volatile("s_waitcnt vmcnt(" #n ")" ::: "memory")
; #define PG8_WAIT_L(n) asm volatile("s_waitcnt lgkmcnt(" #n ")" ::: "memory")
; #define PG8_BAR __builtin_amdgcn_s_barrier()
; #define PG8_SCHED __builtin_amdgcn_sched_barrier(0)
; template <class Epi, class Sched, bool ALIGN_EPI = false, bool SP2 = false, bool APERM = false  >
; __device__ __forceinline__ void gemm_phase(PG8_LAS unsigned char* lds, const Gemm g, const Sched& S, const Epi& E, const int wid  ) {
;     ...
;             PG8_WAIT_V(8); PG8_WAIT_L(0); PG8_BAR; PG8_MMA(1, 0, At, B0); PG8_MMA(1, 1, At, B1); PG8_BAR; PG8_SCHED;
;             PG8_LDB(B0, 1, 0); PG8_LDB(B1, 1, 1); PG8_SCHED; PG8_LDA(At, 1, 0); PG8_STAGE(PG8_SA(0, 1), a2 + hstep, voffA);
;             PG8_WAIT_V(8); PG8_WAIT_L(0); PG8_BAR; PG8_MMA(0, 0, At, B0); PG8_MMA(0, 1, At, B1); PG8_BAR; PG8_SCHED;
	s_setprio 1
	s_waitcnt lgkmcnt(0)
	v_mfma_f32_16x16x32_bf16 v[60:63], v[142:145], v[182:185], v[60:63]
	v_mfma_f32_16x16x32_bf16 v[60:63], v[154:157], v[186:189], v[60:63]
	v_mfma_f32_16x16x32_bf16 v[56:59], v[158:161], v[182:185], v[56:59]
	v_mfma_f32_16x16x32_bf16 v[56:59], v[162:165], v[186:189], v[56:59]
	v_mfma_f32_16x16x32_bf16 v[52:55], v[142:145], v[190:193], v[52:55]
	v_mfma_f32_16x16x32_bf16 v[52:55], v[154:157], v[194:197], v[52:55]
	v_mfma_f32_16x16x32_bf16 v[48:51], v[158:161], v[190:193], v[48:51]
	v_mfma_f32_16x16x32_bf16 v[48:51], v[162:165], v[194:197], v[48:51]
	v_mfma_f32_16x16x32_bf16 v[44:47], v[142:145], v[198:201], v[44:47]
	v_mfma_f32_16x16x32_bf16 v[44:47], v[154:157], v[202:205], v[44:47]
	v_mfma_f32_16x16x32_bf16 v[40:43], v[158:161], v[198:201], v[40:43]
	v_mfma_f32_16x16x32_bf16 v[40:43], v[162:165], v[202:205], v[40:43]
	v_mfma_f32_16x16x32_bf16 v[36:39], v[142:145], v[206:209], v[36:39]
	v_mfma_f32_16x16x32_bf16 v[36:39], v[154:157], v[210:213], v[36:39]
	v_mfma_f32_16x16x32_bf16 v[32:35], v[158:161], v[206:209], v[32:35]
	v_mfma_f32_16x16x32_bf16 v[32:35], v[162:165], v[210:213], v[32:35]
	s_setprio 0
	s_setprio 1
	v_mfma_f32_16x16x32_bf16 v[28:31], v[166:169], v[182:185], v[28:31]
	v_mfma_f32_16x16x32_bf16 v[28:31], v[170:173], v[186:189], v[28:31]
	v_mfma_f32_16x16x32_bf16 v[24:27], v[174:177], v[182:185], v[24:27]
	v_mfma_f32_16x16x32_bf16 v[24:27], v[178:181], v[186:189], v[24:27]
	v_mfma_f32_16x16x32_bf16 v[20:23], v[166:169], v[190:193], v[20:23]
	v_mfma_f32_16x16x32_bf16 v[20:23], v[170:173], v[194:197], v[20:23]
	v_mfma_f32_16x16x32_bf16 v[16:19], v[174:177], v[190:193], v[16:19]
	v_mfma_f32_16x16x32_bf16 v[16:19], v[178:181], v[194:197], v[16:19]
	v_mfma_f32_16x16x32_bf16 v[12:15], v[166:169], v[198:201], v[12:15]
	v_mfma_f32_16x16x32_bf16 v[12:15], v[170:173], v[202:205], v[12:15]
	v_mfma_f32_16x16x32_bf16 v[8:11], v[174:177], v[198:201], v[8:11]
	v_mfma_f32_16x16x32_bf16 v[8:11], v[178:181], v[202:205], v[8:11]
	v_mfma_f32_16x16x32_bf16 v[4:7], v[166:169], v[206:209], v[4:7]
	v_mfma_f32_16x16x32_bf16 v[4:7], v[170:173], v[210:213], v[4:7]
	v_mfma_f32_16x16x32_bf16 v[0:3], v[174:177], v[206:209], v[0:3]
	v_mfma_f32_16x16x32_bf16 v[0:3], v[178:181], v[210:213], v[0:3]
	s_setprio 0
	s_barrier
	s_add_i32 s11, 0, 0x18000
	s_add_i32 s46, 0, 0x1c000
	v_add_u32_e32 v162, s11, v150
	v_add_u32_e32 v178, s46, v150
	ds_read_b128 v[142:145], v162
	ds_read_b128 v[154:157], v162 offset:1024
	ds_read_b128 v[158:161], v162 offset:2048
	ds_read_b128 v[162:165], v162 offset:3072
	ds_read_b128 v[166:169], v178
	ds_read_b128 v[170:173], v178 offset:1024
	ds_read_b128 v[174:177], v178 offset:2048
	ds_read_b128 v[178:181], v178 offset:3072
	s_add_u32 s8, s96, 0x160000
	s_addc_u32 s9, s97, 0
	s_mov_b32 m0, s74
	v_lshl_add_u64 v[220:221], s[8:9], 0, v[132:133]
	ds_read_b128 v[182:185], v153 offset:32768
	ds_read_b128 v[186:189], v153 offset:33792
	ds_read_b128 v[190:193], v153 offset:34816
	ds_read_b128 v[194:197], v153 offset:35840
	ds_read_b128 v[198:201], v153 offset:36864
	ds_read_b128 v[202:205], v153 offset:37888
	ds_read_b128 v[206:209], v153 offset:38912
	ds_read_b128 v[210:213], v153 offset:39936
	global_load_lds_dwordx4 v[220:221], off
	v_lshl_add_u64 v[220:221], s[8:9], 0, v[134:135]
	s_mov_b32 m0, s78
	s_nop 0
	global_load_lds_dwordx4 v[220:221], off
	s_waitcnt vmcnt(8)
	s_waitcnt lgkmcnt(0)
	s_barrier
	s_setprio 1
	s_waitcnt lgkmcnt(0)
	v_mfma_f32_16x16x32_bf16 v[124:127], v[142:145], v[182:185], v[124:127]
	v_mfma_f32_16x16x32_bf16 v[124:127], v[154:157], v[186:189], v[124:127]
	v_mfma_f32_16x16x32_bf16 v[120:123], v[158:161], v[182:185], v[120:123]
	v_mfma_f32_16x16x32_bf16 v[120:123], v[162:165], v[186:189], v[120:123]
	v_mfma_f32_16x16x32_bf16 v[116:119], v[142:145], v[190:193], v[116:119]
	v_mfma_f32_16x16x32_bf16 v[116:119], v[154:157], v[194:197], v[116:119]
	v_mfma_f32_16x16x32_bf16 v[112:115], v[158:161], v[190:193], v[112:115]
	v_mfma_f32_16x16x32_bf16 v[112:115], v[162:165], v[194:197], v[112:115]
	v_mfma_f32_16x16x32_bf16 v[108:111], v[142:145], v[198:201], v[108:111]
	v_mfma_f32_16x16x32_bf16 v[108:111], v[154:157], v[202:205], v[108:111]
	v_mfma_f32_16x16x32_bf16 v[104:107], v[158:161], v[198:201], v[104:107]
	v_mfma_f32_16x16x32_bf16 v[104:107], v[162:165], v[202:205], v[104:107]
	v_mfma_f32_16x16x32_bf16 v[100:103], v[142:145], v[206:209], v[100:103]
	v_mfma_f32_16x16x32_bf16 v[100:103], v[154:157], v[210:213], v[100:103]
	v_mfma_f32_16x16x32_bf16 v[96:99], v[158:161], v[206:209], v[96:99]
	v_mfma_f32_16x16x32_bf16 v[96:99], v[162:165], v[210:213], v[96:99]
	s_setprio 0
	s_setprio 1
	v_mfma_f32_16x16x32_bf16 v[92:95], v[166:169], v[182:185], v[92:95]
	v_mfma_f32_16x16x32_bf16 v[92:95], v[170:173], v[186:189], v[92:95]
	v_mfma_f32_16x16x32_bf16 v[88:91], v[174:177], v[182:185], v[88:91]
	v_mfma_f32_16x16x32_bf16 v[88:91], v[178:181], v[186:189], v[88:91]
	v_mfma_f32_16x16x32_bf16 v[84:87], v[166:169], v[190:193], v[84:87]
	v_mfma_f32_16x16x32_bf16 v[84:87], v[170:173], v[194:197], v[84:87]
	v_mfma_f32_16x16x32_bf16 v[80:83], v[174:177], v[190:193], v[80:83]
	v_mfma_f32_16x16x32_bf16 v[80:83], v[178:181], v[194:197], v[80:83]
	v_mfma_f32_16x16x32_bf16 v[76:79], v[166:169], v[198:201], v[76:79]
	v_mfma_f32_16x16x32_bf16 v[76:79], v[170:173], v[202:205], v[76:79]
	v_mfma_f32_16x16x32_bf16 v[72:75], v[174:177], v[198:201], v[72:75]
	v_mfma_f32_16x16x32_bf16 v[72:75], v[178:181], v[202:205], v[72:75]
	v_mfma_f32_16x16x32_bf16 v[68:71], v[166:169], v[206:209], v[68:71]
	v_mfma_f32_16x16x32_bf16 v[68:71], v[170:173], v[210:213], v[68:71]
	v_mfma_f32_16x16x32_bf16 v[64:67], v[174:177], v[206:209], v[64:67]
	v_mfma_f32_16x16x32_bf16 v[64:67], v[178:181], v[210:213], v[64:67]
	s_setprio 0
	s_barrier
; #define PG8_STAGE(bufoff, gbase, voff) do { _Pragma("unroll") for (int _i = 0; _i < 2; ++_i) \
;         __builtin_amdgcn_global_load_lds((const unsigned*)((const char*)(gbase) + (voff)[_i]), (PG8_LAS unsigned*)(lds + (bufoff) + ldsw + _i * 8192), 16, 0, 0); } while (0)
; #define PG8_LDA(dst, b, h) do { _Pragma("unroll") for (int m = 0; m < 4; ++m) _Pragma("unroll") for (int k = 0; k < 2; ++k) dst[m][k] = *(const PG8_LAS bf16x8*)(lds + PG8_SA(b, h) + aoff + m * 2048 + k * 1024); } while (0)
; #define PG8_MMA(ai, bj, At, Bt) do { __builtin_amdgcn_s_setprio(1); _Pragma("unroll") for (int m = 0; m < 4; ++m) _Pragma("unroll") for (int n = 0; n < 2; ++n) _Pragma("unroll") for (int k = 0; k < 2; ++k) \
;         acc[ai][bj][m][n] = __builtin_amdgcn_mfma_f32_16x16x32_bf16(Bt[n][k], At[m][k], acc[ai][bj][m][n], 0, 0, 0); __builtin_amdgcn_s_setprio(0); } while (0)
; #define PG8_WAIT_V(n) asm volatile("s_waitcnt vmcnt(" #n ")" ::: "memory")
; #define PG8_WAIT_L(n) asm volatile("s_waitcnt lgkmcnt(" #n ")" ::: "memory")
; #define PG8_BAR __builtin_amdgcn_s_barrier()
; #define PG8_SCHED __builtin_amdgcn_sched_barrier(0)
; template <class Epi, class Sched, bool ALIGN_EPI = false, bool SP2 = false, bool APERM = false  >
; __device__ __forceinline__ void gemm_phase(PG8_LAS unsigned char* lds, const Gemm g, const Sched& S, const Epi& E, const int wid  ) {
;     ...
;             PG8_LDA(At, 1, 1); PG8_STAGE(PG8_SB(1, 0), b3, voffB); PG8_STAGE(PG8_SB(1, 1), b3 + hstep, voffB); PG8_STAGE(PG8_SA(1, 0), a3, voffA);
;             PG8_WAIT_V(8); PG8_WAIT_L(0); PG8_BAR; PG8_MMA(1, 0, At, B0); PG8_MMA(1, 1, At, B1); PG8_BAR; PG8_SCHED;
	s_add_i32 s8, s11, s16
	v_lshl_add_u64 v[146:147], v[146:147], 0, s[24:25]
	s_mov_b32 m0, s8
	ds_read_b128 v[182:185], v153 offset:49152
	ds_read_b128 v[186:189], v153 offset:50176
	ds_read_b128 v[190:193], v153 offset:51200
	ds_read_b128 v[194:197], v153 offset:52224
	ds_read_b128 v[198:201], v153 offset:53248
	ds_read_b128 v[202:205], v153 offset:54272
	ds_read_b128 v[206:209], v153 offset:55296
	ds_read_b128 v[210:213], v153 offset:56320
	global_load_lds_dwordx4 v[146:147], off
	s_add_i32 m0, s8, 0x2000
	s_add_u32 s8, s94, 0x160080
	v_lshl_add_u64 v[146:147], v[214:215], 0, s[24:25]
	s_addc_u32 s9, s95, 0
	s_add_i32 s11, s46, s16
	global_load_lds_dwordx4 v[146:147], off
	v_lshl_add_u64 v[146:147], s[8:9], 0, v[128:129]
	s_mov_b32 m0, s11
	s_nop 0
	global_load_lds_dwordx4 v[146:147], off
	v_lshl_add_u64 v[146:147], s[8:9], 0, v[130:131]
	s_add_i32 m0, s11, 0x2000
	s_nop 0
	global_load_lds_dwordx4 v[146:147], off
	v_lshl_add_u64 v[146:147], v[216:217], 0, s[24:25]
	s_mov_b32 m0, s79
	s_nop 0
	global_load_lds_dwordx4 v[146:147], off
	v_lshl_add_u64 v[146:147], v[218:219], 0, s[24:25]
	s_mov_b32 m0, s75
	s_nop 0
	global_load_lds_dwordx4 v[146:147], off
	s_waitcnt vmcnt(8)
	s_waitcnt lgkmcnt(0)
	s_barrier
	s_setprio 1
	s_waitcnt lgkmcnt(0)
	v_mfma_f32_16x16x32_bf16 v[60:63], v[142:145], v[182:185], v[60:63]
	v_mfma_f32_16x16x32_bf16 v[60:63], v[154:157], v[186:189], v[60:63]
	v_mfma_f32_16x16x32_bf16 v[56:59], v[158:161], v[182:185], v[56:59]
	v_mfma_f32_16x16x32_bf16 v[56:59], v[162:165], v[186:189], v[56:59]
	v_mfma_f32_16x16x32_bf16 v[52:55], v[142:145], v[190:193], v[52:55]
	v_mfma_f32_16x16x32_bf16 v[52:55], v[154:157], v[194:197], v[52:55]
	v_mfma_f32_16x16x32_bf16 v[48:51], v[158:161], v[190:193], v[48:51]
	v_mfma_f32_16x16x32_bf16 v[48:51], v[162:165], v[194:197], v[48:51]
	v_mfma_f32_16x16x32_bf16 v[44:47], v[142:145], v[198:201], v[44:47]
	v_mfma_f32_16x16x32_bf16 v[44:47], v[154:157], v[202:205], v[44:47]
	v_mfma_f32_16x16x32_bf16 v[40:43], v[158:161], v[198:201], v[40:43]
	v_mfma_f32_16x16x32_bf16 v[40:43], v[162:165], v[202:205], v[40:43]
	v_mfma_f32_16x16x32_bf16 v[36:39], v[142:145], v[206:209], v[36:39]
	v_mfma_f32_16x16x32_bf16 v[36:39], v[154:157], v[210:213], v[36:39]
	v_mfma_f32_16x16x32_bf16 v[32:35], v[158:161], v[206:209], v[32:35]
	v_mfma_f32_16x16x32_bf16 v[32:35], v[162:165], v[210:213], v[32:35]
	s_setprio 0
	s_setprio 1
	v_mfma_f32_16x16x32_bf16 v[28:31], v[166:169], v[182:185], v[28:31]
	v_mfma_f32_16x16x32_bf16 v[28:31], v[170:173], v[186:189], v[28:31]
	v_mfma_f32_16x16x32_bf16 v[24:27], v[174:177], v[182:185], v[24:27]
	v_mfma_f32_16x16x32_bf16 v[24:27], v[178:181], v[186:189], v[24:27]
	v_mfma_f32_16x16x32_bf16 v[20:23], v[166:169], v[190:193], v[20:23]
	v_mfma_f32_16x16x32_bf16 v[20:23], v[170:173], v[194:197], v[20:23]
	v_mfma_f32_16x16x32_bf16 v[16:19], v[174:177], v[190:193], v[16:19]
	v_mfma_f32_16x16x32_bf16 v[16:19], v[178:181], v[194:197], v[16:19]
	v_mfma_f32_16x16x32_bf16 v[12:15], v[166:169], v[198:201], v[12:15]
	v_mfma_f32_16x16x32_bf16 v[12:15], v[170:173], v[202:205], v[12:15]
	v_mfma_f32_16x16x32_bf16 v[8:11], v[174:177], v[198:201], v[8:11]
	v_mfma_f32_16x16x32_bf16 v[8:11], v[178:181], v[202:205], v[8:11]
	v_mfma_f32_16x16x32_bf16 v[4:7], v[166:169], v[206:209], v[4:7]
	v_mfma_f32_16x16x32_bf16 v[4:7], v[170:173], v[210:213], v[4:7]
	v_mfma_f32_16x16x32_bf16 v[0:3], v[174:177], v[206:209], v[0:3]
	v_mfma_f32_16x16x32_bf16 v[0:3], v[178:181], v[210:213], v[0:3]
	s_setprio 0
	s_barrier
	s_add_i32 s8, s10, 2
	s_cmp_gt_u32 s10, 41
	s_cbranch_scc1 .LBB0_545
	s_mov_b32 s10, s8
	s_branch .LBB0_526

; #define PG8_STAGE(bufoff, gbase, voff) do { _Pragma("unroll") for (int _i = 0; _i < 2; ++_i) \
;         __builtin_amdgcn_global_load_lds((const unsigned*)((const char*)(gbase) + (voff)[_i]), (PG8_LAS unsigned*)(lds + (bufoff) + ldsw + _i * 8192), 16, 0, 0); } while (0)
; #define PG8_LDA(dst, b, h) do { _Pragma("unroll") for (int m = 0; m < 4; ++m) _Pragma("unroll") for (int k = 0; k < 2; ++k) dst[m][k] = *(const PG8_LAS bf16x8*)(lds + PG8_SA(b, h) + aoff + m * 2048 + k * 1024); } while (0)
; #define PG8_LDB(dst, b, h) do { _Pragma("unroll") for (int n = 0; n < 2; ++n) _Pragma("unroll") for (int k = 0; k < 2; ++k) dst[n][k] = *(const PG8_LAS bf16x8*)(lds + PG8_SB(b, h) + boff + n * 2048 + k * 1024); } while (0)
; #define PG8_MMA(ai, bj, At, Bt) do { __builtin_amdgcn_s_setprio(1); _Pragma("unroll") for (int m = 0; m < 4; ++m) _Pragma("unroll") for (int n = 0; n < 2; ++n) _Pragma("unroll") for (int k = 0; k < 2; ++k) \
;         acc[ai][bj][m][n] = __builtin_amdgcn_mfma_f32_16x16x32_bf16(Bt[n][k], At[m][k], acc[ai][bj][m][n], 0, 0, 0); __builtin_amdgcn_s_setprio(0); } while (0)
; #define PG8_WAIT_V(n) asm volatile("s_waitcnt vmcnt(" #n ")" ::: "memory")
; #define PG8_WAIT_L(n) asm volatile("s_waitcnt lgkmcnt(" #n ")" ::: "memory")
; template <class Epi, class Sched, bool ALIGN_EPI = false, bool SP2 = false, bool APERM = false  >
; __device__ __forceinline__ void gemm_phase(PG8_LAS unsigned char* lds, const Gemm g, const Sched& S, const Epi& E, const int wid  ) {
;     ...
;             const bool last = (t == nt - 2);
;             const char* a1 = cA + (size_t)(t + 1) * kstep;
;             const char* a2 = last ? nA : cA + (size_t)(t + 2) * kstep; const char* b2 = last ? nB : cB + (size_t)(t + 2) * kstep;
;             const char* a3 = a2 + kstep; const char* b3 = b2 + kstep;
;             if (last && has_next) S.a_ready(nxt);
;             if constexpr (SP2) {
;             PG8_LDB(B0, 0, 0); PG8_LDB(B1, 0, 1); PG8_SCHED; PG8_LDA(At, 0, 0); PG8_STAGE(PG8_SA(1, 1), a1 + hstep, voffA);
;             PG8_WAIT_V(8); PG8_WAIT_L(0); PG8_BAR; PG8_MMA(0, 0, At, B0); PG8_MMA(0, 1, At, B1); PG8_BAR; PG8_SCHED;
;             PG8_LDA(At, 0, 1); PG8_STAGE(PG8_SB(0, 0), b2, voffB); PG8_STAGE(PG8_SB(0, 1), b2 + hstep, voffB); PG8_STAGE(PG8_SA(0, 0), a2, voffA);
;             PG8_WAIT_V(8); PG8_WAIT_L(0); PG8_BAR; PG8_MMA(1, 0, At, B0); PG8_MMA(1, 1, At, B1); PG8_BAR; PG8_SCHED;
.LBB0_605:
	s_or_b32 s56, s65, 1
	v_add_u32_e32 v159, s88, v153
	s_lshl_b64 s[10:11], s[56:57], 7
	s_add_i32 s56, s65, 2
	s_waitcnt lgkmcnt(0)
	ds_read_b128 v[144:147], v159
	ds_read_b128 v[148:151], v159 offset:1024
	ds_read_b128 v[160:163], v159 offset:2048
	ds_read_b128 v[164:167], v159 offset:3072
	v_add_u32_e32 v159, s89, v153
	s_lshl_b64 s[46:47], s[56:57], 7
	ds_read_b128 v[168:171], v159
	ds_read_b128 v[172:175], v159 offset:1024
	ds_read_b128 v[176:179], v159 offset:2048
	ds_read_b128 v[180:183], v159 offset:3072
	s_add_u32 s68, s0, s46
	s_addc_u32 s69, s1, s47
	s_and_b64 s[52:53], s[30:31], exec
	s_cselect_b32 vcc_hi, s25, s69
	s_cselect_b32 vcc_lo, s24, s68
	s_add_u32 s46, s12, s46
	s_addc_u32 s47, s13, s47
	s_and_b64 s[30:31], s[30:31], exec
	s_cselect_b32 s31, s29, s47
	s_cselect_b32 s30, s28, s46
	s_add_u32 s10, s33, s10
	s_addc_u32 s11, s64, s11
	v_lshl_add_u64 v[216:217], s[10:11], 0, v[132:133]
	s_add_i32 m0, s70, 0xc000
	ds_read_b128 v[184:187], v158
	ds_read_b128 v[188:191], v158 offset:1024
	ds_read_b128 v[192:195], v158 offset:2048
	ds_read_b128 v[196:199], v158 offset:3072
	ds_read_b128 v[200:203], v158 offset:4096
	ds_read_b128 v[204:207], v158 offset:5120
	ds_read_b128 v[208:211], v158 offset:6144
	ds_read_b128 v[212:215], v158 offset:7168
	global_load_lds_dwordx4 v[216:217], off
	v_lshl_add_u64 v[216:217], s[10:11], 0, v[136:137]
	s_add_i32 m0, s70, 0xe000
	s_nop 0
	global_load_lds_dwordx4 v[216:217], off
	s_waitcnt vmcnt(8)
	s_waitcnt lgkmcnt(0)
	s_barrier
	s_setprio 1
	s_waitcnt lgkmcnt(0)
	v_mfma_f32_16x16x32_bf16 v[124:127], v[144:147], v[184:187], v[124:127]
	v_mfma_f32_16x16x32_bf16 v[124:127], v[148:151], v[188:191], v[124:127]
	v_mfma_f32_16x16x32_bf16 v[120:123], v[160:163], v[184:187], v[120:123]
	v_mfma_f32_16x16x32_bf16 v[120:123], v[164:167], v[188:191], v[120:123]
	v_mfma_f32_16x16x32_bf16 v[116:119], v[144:147], v[192:195], v[116:119]
	v_mfma_f32_16x16x32_bf16 v[116:119], v[148:151], v[196:199], v[116:119]
	v_mfma_f32_16x16x32_bf16 v[112:115], v[160:163], v[192:195], v[112:115]
	v_mfma_f32_16x16x32_bf16 v[112:115], v[164:167], v[196:199], v[112:115]
	v_mfma_f32_16x16x32_bf16 v[108:111], v[144:147], v[200:203], v[108:111]
	v_mfma_f32_16x16x32_bf16 v[108:111], v[148:151], v[204:207], v[108:111]
	v_mfma_f32_16x16x32_bf16 v[104:107], v[160:163], v[200:203], v[104:107]
	v_mfma_f32_16x16x32_bf16 v[104:107], v[164:167], v[204:207], v[104:107]
	v_mfma_f32_16x16x32_bf16 v[100:103], v[144:147], v[208:211], v[100:103]
	v_mfma_f32_16x16x32_bf16 v[100:103], v[148:151], v[212:215], v[100:103]
	v_mfma_f32_16x16x32_bf16 v[96:99], v[160:163], v[208:211], v[96:99]
	v_mfma_f32_16x16x32_bf16 v[96:99], v[164:167], v[212:215], v[96:99]
	s_setprio 0
	s_setprio 1
	v_mfma_f32_16x16x32_bf16 v[92:95], v[168:171], v[184:187], v[92:95]
	v_mfma_f32_16x16x32_bf16 v[92:95], v[172:175], v[188:191], v[92:95]
	v_mfma_f32_16x16x32_bf16 v[88:91], v[176:179], v[184:187], v[88:91]
	v_mfma_f32_16x16x32_bf16 v[88:91], v[180:183], v[188:191], v[88:91]
	v_mfma_f32_16x16x32_bf16 v[84:87], v[168:171], v[192:195], v[84:87]
	v_mfma_f32_16x16x32_bf16 v[84:87], v[172:175], v[196:199], v[84:87]
	v_mfma_f32_16x16x32_bf16 v[80:83], v[176:179], v[192:195], v[80:83]
	v_mfma_f32_16x16x32_bf16 v[80:83], v[180:183], v[196:199], v[80:83]
	v_mfma_f32_16x16x32_bf16 v[76:79], v[168:171], v[200:203], v[76:79]
	v_mfma_f32_16x16x32_bf16 v[76:79], v[172:175], v[204:207], v[76:79]
	v_mfma_f32_16x16x32_bf16 v[72:75], v[176:179], v[200:203], v[72:75]
	v_mfma_f32_16x16x32_bf16 v[72:75], v[180:183], v[204:207], v[72:75]
	v_mfma_f32_16x16x32_bf16 v[68:71], v[168:171], v[208:211], v[68:71]
	v_mfma_f32_16x16x32_bf16 v[68:71], v[172:175], v[212:215], v[68:71]
	v_mfma_f32_16x16x32_bf16 v[64:67], v[176:179], v[208:211], v[64:67]
	v_mfma_f32_16x16x32_bf16 v[64:67], v[180:183], v[212:215], v[64:67]
	s_setprio 0
	s_barrier
	s_add_i32 s10, s88, s16
	v_lshl_add_u64 v[216:217], s[30:31], 0, v[128:129]
	s_mov_b32 m0, s10
	ds_read_b128 v[184:187], v158 offset:16384
	ds_read_b128 v[188:191], v158 offset:17408
	ds_read_b128 v[192:195], v158 offset:18432
	ds_read_b128 v[196:199], v158 offset:19456
	ds_read_b128 v[200:203], v158 offset:20480
	ds_read_b128 v[204:207], v158 offset:21504
	ds_read_b128 v[208:211], v158 offset:22528
	ds_read_b128 v[212:215], v158 offset:23552
	global_load_lds_dwordx4 v[216:217], off
	s_add_i32 m0, s10, 0x2000
	s_add_u32 s10, s30, 0x160000
	v_lshl_add_u64 v[218:219], s[30:31], 0, v[130:131]
	s_addc_u32 s11, s31, 0
	s_add_i32 s46, s89, s16
	global_load_lds_dwordx4 v[218:219], off
	v_lshl_add_u64 v[220:221], s[10:11], 0, v[128:129]
	s_mov_b32 m0, s46
	v_lshl_add_u64 v[222:223], vcc, 0, v[136:137]
	global_load_lds_dwordx4 v[220:221], off
	v_lshl_add_u64 v[220:221], s[10:11], 0, v[130:131]
	s_add_i32 m0, s46, 0x2000
	s_nop 0
	global_load_lds_dwordx4 v[220:221], off
	v_lshl_add_u64 v[220:221], vcc, 0, v[132:133]
	s_mov_b32 m0, s70
	s_nop 0
	global_load_lds_dwordx4 v[220:221], off
	s_mov_b32 m0, s71
	s_nop 0
	global_load_lds_dwordx4 v[222:223], off
	s_waitcnt vmcnt(8)
	s_waitcnt lgkmcnt(0)
	s_barrier
; #define PG8_STAGE(bufoff, gbase, voff) do { _Pragma("unroll") for (int _i = 0; _i < 2; ++_i) \
;         __builtin_amdgcn_global_load_lds((const unsigned*)((const char*)(gbase) + (voff)[_i]), (PG8_LAS unsigned*)(lds + (bufoff) + ldsw + _i * 8192), 16, 0, 0); } while (0)
; #define PG8_LDA(dst, b, h) do { _Pragma("unroll") for (int m = 0; m < 4; ++m) _Pragma("unroll") for (int k = 0; k < 2; ++k) dst[m][k] = *(const PG8_LAS bf16x8*)(lds + PG8_SA(b, h) + aoff + m * 2048 + k * 1024); } while (0)
; #define PG8_LDB(dst, b, h) do { _Pragma("unroll") for (int n = 0; n < 2; ++n) _Pragma("unroll") for (int k = 0; k < 2; ++k) dst[n][k] = *(const PG8_LAS bf16x8*)(lds + PG8_SB(b, h) + boff + n * 2048 + k * 1024); } while (0)
; #define PG8_MMA(ai, bj, At, Bt) do { __builtin_amdgcn_s_setprio(1); _Pragma("unroll") for (int m = 0; m < 4; ++m) _Pragma("unroll") for (int n = 0; n < 2; ++n) _Pragma("unroll") for (int k = 0; k < 2; ++k) \
;         acc[ai][bj][m][n] = __builtin_amdgcn_mfma_f32_16x16x32_bf16(Bt[n][k], At[m][k], acc[ai][bj][m][n], 0, 0, 0); __builtin_amdgcn_s_setprio(0); } while (0)
; #define PG8_WAIT_V(n) asm volatile("s_waitcnt vmcnt(" #n ")" ::: "memory")
; #define PG8_WAIT_L(n) asm volatile("s_waitcnt lgkmcnt(" #n ")" ::: "memory")
; #define PG8_BAR __builtin_amdgcn_s_barrier()
; #define PG8_SCHED __builtin_amdgcn_sched_barrier(0)
; template <class Epi, class Sched, bool ALIGN_EPI = false, bool SP2 = false, bool APERM = false  >
; __device__ __forceinline__ void gemm_phase(PG8_LAS unsigned char* lds, const Gemm g, const Sched& S, const Epi& E, const int wid  ) {
;     ...
;             PG8_WAIT_V(8); PG8_WAIT_L(0); PG8_BAR; PG8_MMA(1, 0, At, B0); PG8_MMA(1, 1, At, B1); PG8_BAR; PG8_SCHED;
;             PG8_LDB(B0, 1, 0); PG8_LDB(B1, 1, 1); PG8_SCHED; PG8_LDA(At, 1, 0); PG8_STAGE(PG8_SA(0, 1), a2 + hstep, voffA);
;             PG8_WAIT_V(8); PG8_WAIT_L(0); PG8_BAR; PG8_MMA(0, 0, At, B0); PG8_MMA(0, 1, At, B1); PG8_BAR; PG8_SCHED;
	s_setprio 1
	s_waitcnt lgkmcnt(0)
	v_mfma_f32_16x16x32_bf16 v[60:63], v[144:147], v[184:187], v[60:63]
	v_mfma_f32_16x16x32_bf16 v[60:63], v[148:151], v[188:191], v[60:63]
	v_mfma_f32_16x16x32_bf16 v[56:59], v[160:163], v[184:187], v[56:59]
	v_mfma_f32_16x16x32_bf16 v[56:59], v[164:167], v[188:191], v[56:59]
	v_mfma_f32_16x16x32_bf16 v[52:55], v[144:147], v[192:195], v[52:55]
	v_mfma_f32_16x16x32_bf16 v[52:55], v[148:151], v[196:199], v[52:55]
	v_mfma_f32_16x16x32_bf16 v[48:51], v[160:163], v[192:195], v[48:51]
	v_mfma_f32_16x16x32_bf16 v[48:51], v[164:167], v[196:199], v[48:51]
	v_mfma_f32_16x16x32_bf16 v[44:47], v[144:147], v[200:203], v[44:47]
	v_mfma_f32_16x16x32_bf16 v[44:47], v[148:151], v[204:207], v[44:47]
	v_mfma_f32_16x16x32_bf16 v[40:43], v[160:163], v[200:203], v[40:43]
	v_mfma_f32_16x16x32_bf16 v[40:43], v[164:167], v[204:207], v[40:43]
	v_mfma_f32_16x16x32_bf16 v[36:39], v[144:147], v[208:211], v[36:39]
	v_mfma_f32_16x16x32_bf16 v[36:39], v[148:151], v[212:215], v[36:39]
	v_mfma_f32_16x16x32_bf16 v[32:35], v[160:163], v[208:211], v[32:35]
	v_mfma_f32_16x16x32_bf16 v[32:35], v[164:167], v[212:215], v[32:35]
	s_setprio 0
	s_setprio 1
	v_mfma_f32_16x16x32_bf16 v[28:31], v[168:171], v[184:187], v[28:31]
	v_mfma_f32_16x16x32_bf16 v[28:31], v[172:175], v[188:191], v[28:31]
	v_mfma_f32_16x16x32_bf16 v[24:27], v[176:179], v[184:187], v[24:27]
	v_mfma_f32_16x16x32_bf16 v[24:27], v[180:183], v[188:191], v[24:27]
	v_mfma_f32_16x16x32_bf16 v[20:23], v[168:171], v[192:195], v[20:23]
	v_mfma_f32_16x16x32_bf16 v[20:23], v[172:175], v[196:199], v[20:23]
	v_mfma_f32_16x16x32_bf16 v[16:19], v[176:179], v[192:195], v[16:19]
	v_mfma_f32_16x16x32_bf16 v[16:19], v[180:183], v[196:199], v[16:19]
	v_mfma_f32_16x16x32_bf16 v[12:15], v[168:171], v[200:203], v[12:15]
	v_mfma_f32_16x16x32_bf16 v[12:15], v[172:175], v[204:207], v[12:15]
	v_mfma_f32_16x16x32_bf16 v[8:11], v[176:179], v[200:203], v[8:11]
	v_mfma_f32_16x16x32_bf16 v[8:11], v[180:183], v[204:207], v[8:11]
	v_mfma_f32_16x16x32_bf16 v[4:7], v[168:171], v[208:211], v[4:7]
	v_mfma_f32_16x16x32_bf16 v[4:7], v[172:175], v[212:215], v[4:7]
	v_mfma_f32_16x16x32_bf16 v[0:3], v[176:179], v[208:211], v[0:3]
	v_mfma_f32_16x16x32_bf16 v[0:3], v[180:183], v[212:215], v[0:3]
	s_setprio 0
	s_barrier
	s_add_i32 s46, 0, 0x18000
	v_add_u32_e32 v159, s46, v153
	s_add_i32 s47, 0, 0x1c000
	ds_read_b128 v[144:147], v159
	ds_read_b128 v[148:151], v159 offset:1024
	ds_read_b128 v[160:163], v159 offset:2048
	ds_read_b128 v[164:167], v159 offset:3072
	v_add_u32_e32 v159, s47, v153
	ds_read_b128 v[168:171], v159
	ds_read_b128 v[172:175], v159 offset:1024
	ds_read_b128 v[176:179], v159 offset:2048
	ds_read_b128 v[180:183], v159 offset:3072
	s_add_u32 s10, vcc_lo, 0x160000
	s_addc_u32 s11, vcc_hi, 0
	s_mov_b32 m0, s72
	v_lshl_add_u64 v[224:225], s[10:11], 0, v[132:133]
	ds_read_b128 v[184:187], v158 offset:32768
	ds_read_b128 v[188:191], v158 offset:33792
	ds_read_b128 v[192:195], v158 offset:34816
	ds_read_b128 v[196:199], v158 offset:35840
	ds_read_b128 v[200:203], v158 offset:36864
	ds_read_b128 v[204:207], v158 offset:37888
	ds_read_b128 v[208:211], v158 offset:38912
	ds_read_b128 v[212:215], v158 offset:39936
	global_load_lds_dwordx4 v[224:225], off
	v_lshl_add_u64 v[224:225], s[10:11], 0, v[136:137]
	s_mov_b32 m0, s73
	s_nop 0
	global_load_lds_dwordx4 v[224:225], off
	s_waitcnt vmcnt(8)
	s_waitcnt lgkmcnt(0)
	s_barrier
	s_setprio 1
	s_waitcnt lgkmcnt(0)
	v_mfma_f32_16x16x32_bf16 v[124:127], v[144:147], v[184:187], v[124:127]
	v_mfma_f32_16x16x32_bf16 v[124:127], v[148:151], v[188:191], v[124:127]
	v_mfma_f32_16x16x32_bf16 v[120:123], v[160:163], v[184:187], v[120:123]
	v_mfma_f32_16x16x32_bf16 v[120:123], v[164:167], v[188:191], v[120:123]
	v_mfma_f32_16x16x32_bf16 v[116:119], v[144:147], v[192:195], v[116:119]
	v_mfma_f32_16x16x32_bf16 v[116:119], v[148:151], v[196:199], v[116:119]
	v_mfma_f32_16x16x32_bf16 v[112:115], v[160:163], v[192:195], v[112:115]
	v_mfma_f32_16x16x32_bf16 v[112:115], v[164:167], v[196:199], v[112:115]
	v_mfma_f32_16x16x32_bf16 v[108:111], v[144:147], v[200:203], v[108:111]
	v_mfma_f32_16x16x32_bf16 v[108:111], v[148:151], v[204:207], v[108:111]
	v_mfma_f32_16x16x32_bf16 v[104:107], v[160:163], v[200:203], v[104:107]
	v_mfma_f32_16x16x32_bf16 v[104:107], v[164:167], v[204:207], v[104:107]
	v_mfma_f32_16x16x32_bf16 v[100:103], v[144:147], v[208:211], v[100:103]
	v_mfma_f32_16x16x32_bf16 v[100:103], v[148:151], v[212:215], v[100:103]
	v_mfma_f32_16x16x32_bf16 v[96:99], v[160:163], v[208:211], v[96:99]
	v_mfma_f32_16x16x32_bf16 v[96:99], v[164:167], v[212:215], v[96:99]
	s_setprio 0
	s_setprio 1
	v_mfma_f32_16x16x32_bf16 v[92:95], v[168:171], v[184:187], v[92:95]
	v_mfma_f32_16x16x32_bf16 v[92:95], v[172:175], v[188:191], v[92:95]
	v_mfma_f32_16x16x32_bf16 v[88:91], v[176:179], v[184:187], v[88:91]
	v_mfma_f32_16x16x32_bf16 v[88:91], v[180:183], v[188:191], v[88:91]
	v_mfma_f32_16x16x32_bf16 v[84:87], v[168:171], v[192:195], v[84:87]
	v_mfma_f32_16x16x32_bf16 v[84:87], v[172:175], v[196:199], v[84:87]
	v_mfma_f32_16x16x32_bf16 v[80:83], v[176:179], v[192:195], v[80:83]
	v_mfma_f32_16x16x32_bf16 v[80:83], v[180:183], v[196:199], v[80:83]
	v_mfma_f32_16x16x32_bf16 v[76:79], v[168:171], v[200:203], v[76:79]
	v_mfma_f32_16x16x32_bf16 v[76:79], v[172:175], v[204:207], v[76:79]
	v_mfma_f32_16x16x32_bf16 v[72:75], v[176:179], v[200:203], v[72:75]
	v_mfma_f32_16x16x32_bf16 v[72:75], v[180:183], v[204:207], v[72:75]
	v_mfma_f32_16x16x32_bf16 v[68:71], v[168:171], v[208:211], v[68:71]
	v_mfma_f32_16x16x32_bf16 v[68:71], v[172:175], v[212:215], v[68:71]
	v_mfma_f32_16x16x32_bf16 v[64:67], v[176:179], v[208:211], v[64:67]
	v_mfma_f32_16x16x32_bf16 v[64:67], v[180:183], v[212:215], v[64:67]
	s_setprio 0
	s_barrier
; #define PG8_STAGE(bufoff, gbase, voff) do { _Pragma("unroll") for (int _i = 0; _i < 2; ++_i) \
;         __builtin_amdgcn_global_load_lds((const unsigned*)((const char*)(gbase) + (voff)[_i]), (PG8_LAS unsigned*)(lds + (bufoff) + ldsw + _i * 8192), 16, 0, 0); } while (0)
; #define PG8_LDA(dst, b, h) do { _Pragma("unroll") for (int m = 0; m < 4; ++m) _Pragma("unroll") for (int k = 0; k < 2; ++k) dst[m][k] = *(const PG8_LAS bf16x8*)(lds + PG8_SA(b, h) + aoff + m * 2048 + k * 1024); } while (0)
; #define PG8_MMA(ai, bj, At, Bt) do { __builtin_amdgcn_s_setprio(1); _Pragma("unroll") for (int m = 0; m < 4; ++m) _Pragma("unroll") for (int n = 0; n < 2; ++n) _Pragma("unroll") for (int k = 0; k < 2; ++k) \
;         acc[ai][bj][m][n] = __builtin_amdgcn_mfma_f32_16x16x32_bf16(Bt[n][k], At[m][k], acc[ai][bj][m][n], 0, 0, 0); __builtin_amdgcn_s_setprio(0); } while (0)
; #define PG8_WAIT_V(n) asm volatile("s_waitcnt vmcnt(" #n ")" ::: "memory")
; #define PG8_WAIT_L(n) asm volatile("s_waitcnt lgkmcnt(" #n ")" ::: "memory")
; #define PG8_BAR __builtin_amdgcn_s_barrier()
; #define PG8_SCHED __builtin_amdgcn_sched_barrier(0)
; template <class Epi, class Sched, bool ALIGN_EPI = false, bool SP2 = false, bool APERM = false  >
; __device__ __forceinline__ void gemm_phase(PG8_LAS unsigned char* lds, const Gemm g, const Sched& S, const Epi& E, const int wid  ) {
;     ...
;             PG8_LDA(At, 1, 1); PG8_STAGE(PG8_SB(1, 0), b3, voffB); PG8_STAGE(PG8_SB(1, 1), b3 + hstep, voffB); PG8_STAGE(PG8_SA(1, 0), a3, voffA);
;             PG8_WAIT_V(8); PG8_WAIT_L(0); PG8_BAR; PG8_MMA(1, 0, At, B0); PG8_MMA(1, 1, At, B1); PG8_BAR; PG8_SCHED;
	s_add_i32 s10, s46, s16
	v_lshl_add_u64 v[216:217], v[216:217], 0, s[58:59]
	s_mov_b32 m0, s10
	ds_read_b128 v[184:187], v158 offset:49152
	ds_read_b128 v[188:191], v158 offset:50176
	ds_read_b128 v[192:195], v158 offset:51200
	ds_read_b128 v[196:199], v158 offset:52224
	ds_read_b128 v[200:203], v158 offset:53248
	ds_read_b128 v[204:207], v158 offset:54272
	ds_read_b128 v[208:211], v158 offset:55296
	ds_read_b128 v[212:215], v158 offset:56320
	global_load_lds_dwordx4 v[216:217], off
	s_add_i32 m0, s10, 0x2000
	s_add_u32 s10, s30, 0x160080
	v_lshl_add_u64 v[216:217], v[218:219], 0, s[58:59]
	s_addc_u32 s11, s31, 0
	s_add_i32 s30, s47, s16
	global_load_lds_dwordx4 v[216:217], off
	v_lshl_add_u64 v[216:217], s[10:11], 0, v[128:129]
	s_mov_b32 m0, s30
	s_nop 0
	global_load_lds_dwordx4 v[216:217], off
	v_lshl_add_u64 v[216:217], s[10:11], 0, v[130:131]
	s_add_i32 m0, s30, 0x2000
	s_nop 0
	global_load_lds_dwordx4 v[216:217], off
	v_lshl_add_u64 v[216:217], v[220:221], 0, s[58:59]
	s_mov_b32 m0, s86
	s_nop 0
	global_load_lds_dwordx4 v[216:217], off
	v_lshl_add_u64 v[216:217], v[222:223], 0, s[58:59]
	s_mov_b32 m0, s87
	s_nop 0
	global_load_lds_dwordx4 v[216:217], off
	s_waitcnt vmcnt(8)
	s_waitcnt lgkmcnt(0)
	s_barrier
	s_setprio 1
	s_waitcnt lgkmcnt(0)
	v_mfma_f32_16x16x32_bf16 v[60:63], v[144:147], v[184:187], v[60:63]
	v_mfma_f32_16x16x32_bf16 v[60:63], v[148:151], v[188:191], v[60:63]
	v_mfma_f32_16x16x32_bf16 v[56:59], v[160:163], v[184:187], v[56:59]
	v_mfma_f32_16x16x32_bf16 v[56:59], v[164:167], v[188:191], v[56:59]
	v_mfma_f32_16x16x32_bf16 v[52:55], v[144:147], v[192:195], v[52:55]
	v_mfma_f32_16x16x32_bf16 v[52:55], v[148:151], v[196:199], v[52:55]
	v_mfma_f32_16x16x32_bf16 v[48:51], v[160:163], v[192:195], v[48:51]
	v_mfma_f32_16x16x32_bf16 v[48:51], v[164:167], v[196:199], v[48:51]
	v_mfma_f32_16x16x32_bf16 v[44:47], v[144:147], v[200:203], v[44:47]
	v_mfma_f32_16x16x32_bf16 v[44:47], v[148:151], v[204:207], v[44:47]
	v_mfma_f32_16x16x32_bf16 v[40:43], v[160:163], v[200:203], v[40:43]
	v_mfma_f32_16x16x32_bf16 v[40:43], v[164:167], v[204:207], v[40:43]
	v_mfma_f32_16x16x32_bf16 v[36:39], v[144:147], v[208:211], v[36:39]
	v_mfma_f32_16x16x32_bf16 v[36:39], v[148:151], v[212:215], v[36:39]
	v_mfma_f32_16x16x32_bf16 v[32:35], v[160:163], v[208:211], v[32:35]
	v_mfma_f32_16x16x32_bf16 v[32:35], v[164:167], v[212:215], v[32:35]
	s_setprio 0
	s_setprio 1
	v_mfma_f32_16x16x32_bf16 v[28:31], v[168:171], v[184:187], v[28:31]
	v_mfma_f32_16x16x32_bf16 v[28:31], v[172:175], v[188:191], v[28:31]
	v_mfma_f32_16x16x32_bf16 v[24:27], v[176:179], v[184:187], v[24:27]
	v_mfma_f32_16x16x32_bf16 v[24:27], v[180:183], v[188:191], v[24:27]
	v_mfma_f32_16x16x32_bf16 v[20:23], v[168:171], v[192:195], v[20:23]
	v_mfma_f32_16x16x32_bf16 v[20:23], v[172:175], v[196:199], v[20:23]
	v_mfma_f32_16x16x32_bf16 v[16:19], v[176:179], v[192:195], v[16:19]
	v_mfma_f32_16x16x32_bf16 v[16:19], v[180:183], v[196:199], v[16:19]
	v_mfma_f32_16x16x32_bf16 v[12:15], v[168:171], v[200:203], v[12:15]
	v_mfma_f32_16x16x32_bf16 v[12:15], v[172:175], v[204:207], v[12:15]
	v_mfma_f32_16x16x32_bf16 v[8:11], v[176:179], v[200:203], v[8:11]
	v_mfma_f32_16x16x32_bf16 v[8:11], v[180:183], v[204:207], v[8:11]
	v_mfma_f32_16x16x32_bf16 v[4:7], v[168:171], v[208:211], v[4:7]
	v_mfma_f32_16x16x32_bf16 v[4:7], v[172:175], v[212:215], v[4:7]
	v_mfma_f32_16x16x32_bf16 v[0:3], v[176:179], v[208:211], v[0:3]
	v_mfma_f32_16x16x32_bf16 v[0:3], v[180:183], v[212:215], v[0:3]
	s_setprio 0
	s_barrier
	s_cmp_gt_u32 s65, 41
	s_cbranch_scc1 .LBB0_607
	s_mov_b32 s65, s56
	s_branch .LBB0_588

; #define PG8_STAGE(bufoff, gbase, voff) do { _Pragma("unroll") for (int _i = 0; _i < 2; ++_i) \
;         __builtin_amdgcn_global_load_lds((const unsigned*)((const char*)(gbase) + (voff)[_i]), (PG8_LAS unsigned*)(lds + (bufoff) + ldsw + _i * 8192), 16, 0, 0); } while (0)
; #define PG8_LDA(dst, b, h) do { _Pragma("unroll") for (int m = 0; m < 4; ++m) _Pragma("unroll") for (int k = 0; k < 2; ++k) dst[m][k] = *(const PG8_LAS bf16x8*)(lds + PG8_SA(b, h) + aoff + m * 2048 + k * 1024); } while (0)
; #define PG8_LDB(dst, b, h) do { _Pragma("unroll") for (int n = 0; n < 2; ++n) _Pragma("unroll") for (int k = 0; k < 2; ++k) dst[n][k] = *(const PG8_LAS bf16x8*)(lds + PG8_SB(b, h) + boff + n * 2048 + k * 1024); } while (0)
; #define PG8_MMA(ai, bj, At, Bt) do { __builtin_amdgcn_s_setprio(1); _Pragma("unroll") for (int m = 0; m < 4; ++m) _Pragma("unroll") for (int n = 0; n < 2; ++n) _Pragma("unroll") for (int k = 0; k < 2; ++k) \
;         acc[ai][bj][m][n] = __builtin_amdgcn_mfma_f32_16x16x32_bf16(Bt[n][k], At[m][k], acc[ai][bj][m][n], 0, 0, 0); __builtin_amdgcn_s_setprio(0); } while (0)
; #define PG8_WAIT_V(n) asm volatile("s_waitcnt vmcnt(" #n ")" ::: "memory")
; #define PG8_WAIT_L(n) asm volatile("s_waitcnt lgkmcnt(" #n ")" ::: "memory")
; template <class Epi, class Sched, bool ALIGN_EPI = false, bool SP2 = false, bool APERM = false  >
; __device__ __forceinline__ void gemm_phase(PG8_LAS unsigned char* lds, const Gemm g, const Sched& S, const Epi& E, const int wid  ) {
;     ...
;             const bool last = (t == nt - 2);
;             const char* a1 = cA + (size_t)(t + 1) * kstep;
;             const char* a2 = last ? nA : cA + (size_t)(t + 2) * kstep; const char* b2 = last ? nB : cB + (size_t)(t + 2) * kstep;
;             const char* a3 = a2 + kstep; const char* b3 = b2 + kstep;
;             if (last && has_next) S.a_ready(nxt);
;             if constexpr (SP2) {
;             PG8_LDB(B0, 0, 0); PG8_LDB(B1, 0, 1); PG8_SCHED; PG8_LDA(At, 0, 0); PG8_STAGE(PG8_SA(1, 1), a1 + hstep, voffA);
;             PG8_WAIT_V(8); PG8_WAIT_L(0); PG8_BAR; PG8_MMA(0, 0, At, B0); PG8_MMA(0, 1, At, B1); PG8_BAR; PG8_SCHED;
;             PG8_LDA(At, 0, 1); PG8_STAGE(PG8_SB(0, 0), b2, voffB); PG8_STAGE(PG8_SB(0, 1), b2 + hstep, voffB); PG8_STAGE(PG8_SA(0, 0), a2, voffA);
;             PG8_WAIT_V(8); PG8_WAIT_L(0); PG8_BAR; PG8_MMA(1, 0, At, B0); PG8_MMA(1, 1, At, B1); PG8_BAR; PG8_SCHED;
.LBB0_669:
	v_add_u32_e32 v1, s70, v145
	ds_read_b128 v[152:155], v1
	ds_read_b128 v[156:159], v1 offset:1024
	ds_read_b128 v[160:163], v1 offset:2048
	ds_read_b128 v[164:167], v1 offset:3072
	v_add_u32_e32 v1, s71, v145
	ds_read_b128 v[168:171], v1
	ds_read_b128 v[172:175], v1 offset:1024
	ds_read_b128 v[176:179], v1 offset:2048
	ds_read_b128 v[180:183], v1 offset:3072
	s_add_i32 s80, s54, 2
	s_add_u32 s81, s34, 0x80
	s_addc_u32 s55, s35, 0
	s_cmp_eq_u32 s69, s54
	s_cselect_b32 s54, s28, s81
	s_cselect_b32 s55, s29, s55
	s_cselect_b32 s83, s31, s79
	s_cselect_b32 s82, s30, s78
	s_mov_b32 m0, s72
	v_lshl_add_u64 v[2:3], s[34:35], 0, v[140:141]
	ds_read_b128 v[184:187], v147
	ds_read_b128 v[188:191], v147 offset:1024
	ds_read_b128 v[192:195], v147 offset:2048
	ds_read_b128 v[196:199], v147 offset:3072
	ds_read_b128 v[200:203], v147 offset:4096
	ds_read_b128 v[204:207], v147 offset:5120
	ds_read_b128 v[208:211], v147 offset:6144
	ds_read_b128 v[212:215], v147 offset:7168
	global_load_lds_dwordx4 v[2:3], off
	v_lshl_add_u64 v[2:3], s[34:35], 0, v[142:143]
	s_mov_b32 m0, s73
	s_nop 0
	global_load_lds_dwordx4 v[2:3], off
	s_waitcnt vmcnt(8)
	s_waitcnt lgkmcnt(0)
	s_barrier
	s_setprio 1
	s_waitcnt lgkmcnt(0)
	v_mfma_f32_16x16x32_bf16 v[128:131], v[152:155], v[184:187], v[128:131]
	v_mfma_f32_16x16x32_bf16 v[128:131], v[156:159], v[188:191], v[128:131]
	v_mfma_f32_16x16x32_bf16 v[124:127], v[160:163], v[184:187], v[124:127]
	v_mfma_f32_16x16x32_bf16 v[124:127], v[164:167], v[188:191], v[124:127]
	v_mfma_f32_16x16x32_bf16 v[120:123], v[152:155], v[192:195], v[120:123]
	v_mfma_f32_16x16x32_bf16 v[120:123], v[156:159], v[196:199], v[120:123]
	v_mfma_f32_16x16x32_bf16 v[116:119], v[160:163], v[192:195], v[116:119]
	v_mfma_f32_16x16x32_bf16 v[116:119], v[164:167], v[196:199], v[116:119]
	v_mfma_f32_16x16x32_bf16 v[112:115], v[152:155], v[200:203], v[112:115]
	v_mfma_f32_16x16x32_bf16 v[112:115], v[156:159], v[204:207], v[112:115]
	v_mfma_f32_16x16x32_bf16 v[108:111], v[160:163], v[200:203], v[108:111]
	v_mfma_f32_16x16x32_bf16 v[108:111], v[164:167], v[204:207], v[108:111]
	v_mfma_f32_16x16x32_bf16 v[104:107], v[152:155], v[208:211], v[104:107]
	v_mfma_f32_16x16x32_bf16 v[104:107], v[156:159], v[212:215], v[104:107]
	v_mfma_f32_16x16x32_bf16 v[100:103], v[160:163], v[208:211], v[100:103]
	v_mfma_f32_16x16x32_bf16 v[100:103], v[164:167], v[212:215], v[100:103]
	s_setprio 0
	s_setprio 1
	v_mfma_f32_16x16x32_bf16 v[96:99], v[168:171], v[184:187], v[96:99]
	v_mfma_f32_16x16x32_bf16 v[96:99], v[172:175], v[188:191], v[96:99]
	v_mfma_f32_16x16x32_bf16 v[92:95], v[176:179], v[184:187], v[92:95]
	v_mfma_f32_16x16x32_bf16 v[92:95], v[180:183], v[188:191], v[92:95]
	v_mfma_f32_16x16x32_bf16 v[88:91], v[168:171], v[192:195], v[88:91]
	v_mfma_f32_16x16x32_bf16 v[88:91], v[172:175], v[196:199], v[88:91]
	v_mfma_f32_16x16x32_bf16 v[84:87], v[176:179], v[192:195], v[84:87]
	v_mfma_f32_16x16x32_bf16 v[84:87], v[180:183], v[196:199], v[84:87]
	v_mfma_f32_16x16x32_bf16 v[80:83], v[168:171], v[200:203], v[80:83]
	v_mfma_f32_16x16x32_bf16 v[80:83], v[172:175], v[204:207], v[80:83]
	v_mfma_f32_16x16x32_bf16 v[76:79], v[176:179], v[200:203], v[76:79]
	v_mfma_f32_16x16x32_bf16 v[76:79], v[180:183], v[204:207], v[76:79]
	v_mfma_f32_16x16x32_bf16 v[72:75], v[168:171], v[208:211], v[72:75]
	v_mfma_f32_16x16x32_bf16 v[72:75], v[172:175], v[212:215], v[72:75]
	v_mfma_f32_16x16x32_bf16 v[68:71], v[176:179], v[208:211], v[68:71]
	v_mfma_f32_16x16x32_bf16 v[68:71], v[180:183], v[212:215], v[68:71]
	s_setprio 0
	s_barrier
	s_add_i32 s81, s70, s46
	v_lshl_add_u64 v[148:149], s[82:83], 0, v[136:137]
	s_mov_b32 m0, s81
	ds_read_b128 v[184:187], v147 offset:16384
	ds_read_b128 v[188:191], v147 offset:17408
	ds_read_b128 v[192:195], v147 offset:18432
	ds_read_b128 v[196:199], v147 offset:19456
	ds_read_b128 v[200:203], v147 offset:20480
	ds_read_b128 v[204:207], v147 offset:21504
	ds_read_b128 v[208:211], v147 offset:22528
	ds_read_b128 v[212:215], v147 offset:23552
	global_load_lds_dwordx4 v[148:149], off
	s_add_i32 m0, s81, 0x2000
	v_lshl_add_u64 v[216:217], s[82:83], 0, v[132:133]
	s_add_u32 s82, s82, s4
	s_addc_u32 s83, s83, s5
	s_add_i32 s81, s71, s46
	global_load_lds_dwordx4 v[216:217], off
	v_lshl_add_u64 v[218:219], s[82:83], 0, v[136:137]
	s_mov_b32 m0, s81
	v_lshl_add_u64 v[220:221], s[82:83], 0, v[132:133]
	global_load_lds_dwordx4 v[218:219], off
	s_add_i32 m0, s81, 0x2000
	v_lshl_add_u64 v[222:223], s[54:55], 0, v[138:139]
	global_load_lds_dwordx4 v[220:221], off
	s_mov_b32 m0, s59
	v_lshl_add_u64 v[224:225], s[54:55], 0, v[134:135]
	global_load_lds_dwordx4 v[222:223], off
	s_mov_b32 m0, s63
	s_nop 0
	global_load_lds_dwordx4 v[224:225], off
	s_waitcnt vmcnt(8)
	s_waitcnt lgkmcnt(0)
	s_barrier
; #define PG8_STAGE(bufoff, gbase, voff) do { _Pragma("unroll") for (int _i = 0; _i < 2; ++_i) \
;         __builtin_amdgcn_global_load_lds((const unsigned*)((const char*)(gbase) + (voff)[_i]), (PG8_LAS unsigned*)(lds + (bufoff) + ldsw + _i * 8192), 16, 0, 0); } while (0)
; #define PG8_LDA(dst, b, h) do { _Pragma("unroll") for (int m = 0; m < 4; ++m) _Pragma("unroll") for (int k = 0; k < 2; ++k) dst[m][k] = *(const PG8_LAS bf16x8*)(lds + PG8_SA(b, h) + aoff + m * 2048 + k * 1024); } while (0)
; #define PG8_LDB(dst, b, h) do { _Pragma("unroll") for (int n = 0; n < 2; ++n) _Pragma("unroll") for (int k = 0; k < 2; ++k) dst[n][k] = *(const PG8_LAS bf16x8*)(lds + PG8_SB(b, h) + boff + n * 2048 + k * 1024); } while (0)
; #define PG8_MMA(ai, bj, At, Bt) do { __builtin_amdgcn_s_setprio(1); _Pragma("unroll") for (int m = 0; m < 4; ++m) _Pragma("unroll") for (int n = 0; n < 2; ++n) _Pragma("unroll") for (int k = 0; k < 2; ++k) \
;         acc[ai][bj][m][n] = __builtin_amdgcn_mfma_f32_16x16x32_bf16(Bt[n][k], At[m][k], acc[ai][bj][m][n], 0, 0, 0); __builtin_amdgcn_s_setprio(0); } while (0)
; #define PG8_WAIT_V(n) asm volatile("s_waitcnt vmcnt(" #n ")" ::: "memory")
; #define PG8_WAIT_L(n) asm volatile("s_waitcnt lgkmcnt(" #n ")" ::: "memory")
; #define PG8_BAR __builtin_amdgcn_s_barrier()
; #define PG8_SCHED __builtin_amdgcn_sched_barrier(0)
; template <class Epi, class Sched, bool ALIGN_EPI = false, bool SP2 = false, bool APERM = false  >
; __device__ __forceinline__ void gemm_phase(PG8_LAS unsigned char* lds, const Gemm g, const Sched& S, const Epi& E, const int wid  ) {
;     ...
;             PG8_WAIT_V(8); PG8_WAIT_L(0); PG8_BAR; PG8_MMA(1, 0, At, B0); PG8_MMA(1, 1, At, B1); PG8_BAR; PG8_SCHED;
;             PG8_LDB(B0, 1, 0); PG8_LDB(B1, 1, 1); PG8_SCHED; PG8_LDA(At, 1, 0); PG8_STAGE(PG8_SA(0, 1), a2 + hstep, voffA);
;             PG8_WAIT_V(8); PG8_WAIT_L(0); PG8_BAR; PG8_MMA(0, 0, At, B0); PG8_MMA(0, 1, At, B1); PG8_BAR; PG8_SCHED;
	s_setprio 1
	s_waitcnt lgkmcnt(0)
	v_mfma_f32_16x16x32_bf16 v[64:67], v[152:155], v[184:187], v[64:67]
	v_mfma_f32_16x16x32_bf16 v[64:67], v[156:159], v[188:191], v[64:67]
	v_mfma_f32_16x16x32_bf16 v[60:63], v[160:163], v[184:187], v[60:63]
	v_mfma_f32_16x16x32_bf16 v[60:63], v[164:167], v[188:191], v[60:63]
	v_mfma_f32_16x16x32_bf16 v[56:59], v[152:155], v[192:195], v[56:59]
	v_mfma_f32_16x16x32_bf16 v[56:59], v[156:159], v[196:199], v[56:59]
	v_mfma_f32_16x16x32_bf16 v[52:55], v[160:163], v[192:195], v[52:55]
	v_mfma_f32_16x16x32_bf16 v[52:55], v[164:167], v[196:199], v[52:55]
	v_mfma_f32_16x16x32_bf16 v[48:51], v[152:155], v[200:203], v[48:51]
	v_mfma_f32_16x16x32_bf16 v[48:51], v[156:159], v[204:207], v[48:51]
	v_mfma_f32_16x16x32_bf16 v[44:47], v[160:163], v[200:203], v[44:47]
	v_mfma_f32_16x16x32_bf16 v[44:47], v[164:167], v[204:207], v[44:47]
	v_mfma_f32_16x16x32_bf16 v[40:43], v[152:155], v[208:211], v[40:43]
	v_mfma_f32_16x16x32_bf16 v[40:43], v[156:159], v[212:215], v[40:43]
	v_mfma_f32_16x16x32_bf16 v[36:39], v[160:163], v[208:211], v[36:39]
	v_mfma_f32_16x16x32_bf16 v[36:39], v[164:167], v[212:215], v[36:39]
	s_setprio 0
	s_setprio 1
	v_mfma_f32_16x16x32_bf16 v[32:35], v[168:171], v[184:187], v[32:35]
	v_mfma_f32_16x16x32_bf16 v[32:35], v[172:175], v[188:191], v[32:35]
	v_mfma_f32_16x16x32_bf16 v[28:31], v[176:179], v[184:187], v[28:31]
	v_mfma_f32_16x16x32_bf16 v[28:31], v[180:183], v[188:191], v[28:31]
	v_mfma_f32_16x16x32_bf16 v[24:27], v[168:171], v[192:195], v[24:27]
	v_mfma_f32_16x16x32_bf16 v[24:27], v[172:175], v[196:199], v[24:27]
	v_mfma_f32_16x16x32_bf16 v[20:23], v[176:179], v[192:195], v[20:23]
	v_mfma_f32_16x16x32_bf16 v[20:23], v[180:183], v[196:199], v[20:23]
	v_mfma_f32_16x16x32_bf16 v[16:19], v[168:171], v[200:203], v[16:19]
	v_mfma_f32_16x16x32_bf16 v[16:19], v[172:175], v[204:207], v[16:19]
	v_mfma_f32_16x16x32_bf16 v[12:15], v[176:179], v[200:203], v[12:15]
	v_mfma_f32_16x16x32_bf16 v[12:15], v[180:183], v[204:207], v[12:15]
	v_mfma_f32_16x16x32_bf16 v[8:11], v[168:171], v[208:211], v[8:11]
	v_mfma_f32_16x16x32_bf16 v[8:11], v[172:175], v[212:215], v[8:11]
	v_mfma_f32_16x16x32_bf16 v[2:5], v[176:179], v[208:211], v[4:7]
	v_mfma_f32_16x16x32_bf16 v[2:5], v[180:183], v[212:215], v[2:5]
	s_setprio 0
	s_barrier
	s_add_i32 s81, 0, 0x18000
	v_add_u32_e32 v1, s81, v145
	s_add_i32 s82, 0, 0x1c000
	ds_read_b128 v[152:155], v1
	ds_read_b128 v[156:159], v1 offset:1024
	ds_read_b128 v[160:163], v1 offset:2048
	ds_read_b128 v[164:167], v1 offset:3072
	v_add_u32_e32 v1, s82, v145
	ds_read_b128 v[168:171], v1
	ds_read_b128 v[172:175], v1 offset:1024
	ds_read_b128 v[176:179], v1 offset:2048
	ds_read_b128 v[180:183], v1 offset:3072
	s_add_u32 s54, s54, s4
	s_addc_u32 s55, s55, s5
	s_mov_b32 m0, s64
	v_lshl_add_u64 v[6:7], s[54:55], 0, v[138:139]
	ds_read_b128 v[184:187], v147 offset:32768
	ds_read_b128 v[188:191], v147 offset:33792
	ds_read_b128 v[192:195], v147 offset:34816
	ds_read_b128 v[196:199], v147 offset:35840
	ds_read_b128 v[200:203], v147 offset:36864
	ds_read_b128 v[204:207], v147 offset:37888
	ds_read_b128 v[208:211], v147 offset:38912
	ds_read_b128 v[212:215], v147 offset:39936
	global_load_lds_dwordx4 v[6:7], off
	v_lshl_add_u64 v[6:7], s[54:55], 0, v[134:135]
	s_mov_b32 m0, s65
	s_nop 0
	global_load_lds_dwordx4 v[6:7], off
	s_waitcnt vmcnt(8)
	s_waitcnt lgkmcnt(0)
	s_barrier
	s_setprio 1
	s_waitcnt lgkmcnt(0)
	v_mfma_f32_16x16x32_bf16 v[128:131], v[152:155], v[184:187], v[128:131]
	v_mfma_f32_16x16x32_bf16 v[128:131], v[156:159], v[188:191], v[128:131]
	v_mfma_f32_16x16x32_bf16 v[124:127], v[160:163], v[184:187], v[124:127]
	v_mfma_f32_16x16x32_bf16 v[124:127], v[164:167], v[188:191], v[124:127]
	v_mfma_f32_16x16x32_bf16 v[120:123], v[152:155], v[192:195], v[120:123]
	v_mfma_f32_16x16x32_bf16 v[120:123], v[156:159], v[196:199], v[120:123]
	v_mfma_f32_16x16x32_bf16 v[116:119], v[160:163], v[192:195], v[116:119]
	v_mfma_f32_16x16x32_bf16 v[116:119], v[164:167], v[196:199], v[116:119]
	v_mfma_f32_16x16x32_bf16 v[112:115], v[152:155], v[200:203], v[112:115]
	v_mfma_f32_16x16x32_bf16 v[112:115], v[156:159], v[204:207], v[112:115]
	v_mfma_f32_16x16x32_bf16 v[108:111], v[160:163], v[200:203], v[108:111]
	v_mfma_f32_16x16x32_bf16 v[108:111], v[164:167], v[204:207], v[108:111]
	v_mfma_f32_16x16x32_bf16 v[104:107], v[152:155], v[208:211], v[104:107]
	v_mfma_f32_16x16x32_bf16 v[104:107], v[156:159], v[212:215], v[104:107]
	v_mfma_f32_16x16x32_bf16 v[100:103], v[160:163], v[208:211], v[100:103]
	v_mfma_f32_16x16x32_bf16 v[100:103], v[164:167], v[212:215], v[100:103]
	s_setprio 0
	s_setprio 1
	v_mfma_f32_16x16x32_bf16 v[96:99], v[168:171], v[184:187], v[96:99]
	v_mfma_f32_16x16x32_bf16 v[96:99], v[172:175], v[188:191], v[96:99]
	v_mfma_f32_16x16x32_bf16 v[92:95], v[176:179], v[184:187], v[92:95]
	v_mfma_f32_16x16x32_bf16 v[92:95], v[180:183], v[188:191], v[92:95]
	v_mfma_f32_16x16x32_bf16 v[88:91], v[168:171], v[192:195], v[88:91]
	v_mfma_f32_16x16x32_bf16 v[88:91], v[172:175], v[196:199], v[88:91]
	v_mfma_f32_16x16x32_bf16 v[84:87], v[176:179], v[192:195], v[84:87]
	v_mfma_f32_16x16x32_bf16 v[84:87], v[180:183], v[196:199], v[84:87]
	v_mfma_f32_16x16x32_bf16 v[80:83], v[168:171], v[200:203], v[80:83]
	v_mfma_f32_16x16x32_bf16 v[80:83], v[172:175], v[204:207], v[80:83]
	v_mfma_f32_16x16x32_bf16 v[76:79], v[176:179], v[200:203], v[76:79]
	v_mfma_f32_16x16x32_bf16 v[76:79], v[180:183], v[204:207], v[76:79]
	v_mfma_f32_16x16x32_bf16 v[72:75], v[168:171], v[208:211], v[72:75]
	v_mfma_f32_16x16x32_bf16 v[72:75], v[172:175], v[212:215], v[72:75]
	v_mfma_f32_16x16x32_bf16 v[68:71], v[176:179], v[208:211], v[68:71]
	v_mfma_f32_16x16x32_bf16 v[68:71], v[180:183], v[212:215], v[68:71]
	s_setprio 0
	s_barrier
; #define PG8_STAGE(bufoff, gbase, voff) do { _Pragma("unroll") for (int _i = 0; _i < 2; ++_i) \
;         __builtin_amdgcn_global_load_lds((const unsigned*)((const char*)(gbase) + (voff)[_i]), (PG8_LAS unsigned*)(lds + (bufoff) + ldsw + _i * 8192), 16, 0, 0); } while (0)
; #define PG8_LDA(dst, b, h) do { _Pragma("unroll") for (int m = 0; m < 4; ++m) _Pragma("unroll") for (int k = 0; k < 2; ++k) dst[m][k] = *(const PG8_LAS bf16x8*)(lds + PG8_SA(b, h) + aoff + m * 2048 + k * 1024); } while (0)
; #define PG8_MMA(ai, bj, At, Bt) do { __builtin_amdgcn_s_setprio(1); _Pragma("unroll") for (int m = 0; m < 4; ++m) _Pragma("unroll") for (int n = 0; n < 2; ++n) _Pragma("unroll") for (int k = 0; k < 2; ++k) \
;         acc[ai][bj][m][n] = __builtin_amdgcn_mfma_f32_16x16x32_bf16(Bt[n][k], At[m][k], acc[ai][bj][m][n], 0, 0, 0); __builtin_amdgcn_s_setprio(0); } while (0)
; #define PG8_WAIT_V(n) asm volatile("s_waitcnt vmcnt(" #n ")" ::: "memory")
; #define PG8_WAIT_L(n) asm volatile("s_waitcnt lgkmcnt(" #n ")" ::: "memory")
; #define PG8_BAR __builtin_amdgcn_s_barrier()
; #define PG8_SCHED __builtin_amdgcn_sched_barrier(0)
; template <class Epi, class Sched, bool ALIGN_EPI = false, bool SP2 = false, bool APERM = false  >
; __device__ __forceinline__ void gemm_phase(PG8_LAS unsigned char* lds, const Gemm g, const Sched& S, const Epi& E, const int wid  ) {
;     ...
;         for (int t = 0; t < nt; t += 2) {
;             const bool last = (t == nt - 2);
;             const char* a1 = cA + (size_t)(t + 1) * kstep;
;             const char* a2 = last ? nA : cA + (size_t)(t + 2) * kstep; const char* b2 = last ? nB : cB + (size_t)(t + 2) * kstep;
;     ...
;             PG8_LDA(At, 1, 1); PG8_STAGE(PG8_SB(1, 0), b3, voffB); PG8_STAGE(PG8_SB(1, 1), b3 + hstep, voffB); PG8_STAGE(PG8_SA(1, 0), a3, voffA);
;             PG8_WAIT_V(8); PG8_WAIT_L(0); PG8_BAR; PG8_MMA(1, 0, At, B0); PG8_MMA(1, 1, At, B1); PG8_BAR; PG8_SCHED;
	s_add_i32 s54, s81, s46
	v_lshl_add_u64 v[6:7], v[148:149], 0, s[16:17]
	s_mov_b32 m0, s54
	ds_read_b128 v[184:187], v147 offset:49152
	ds_read_b128 v[188:191], v147 offset:50176
	ds_read_b128 v[192:195], v147 offset:51200
	ds_read_b128 v[196:199], v147 offset:52224
	ds_read_b128 v[200:203], v147 offset:53248
	ds_read_b128 v[204:207], v147 offset:54272
	ds_read_b128 v[208:211], v147 offset:55296
	ds_read_b128 v[212:215], v147 offset:56320
	global_load_lds_dwordx4 v[6:7], off
	v_lshl_add_u64 v[6:7], v[216:217], 0, s[16:17]
	s_add_i32 m0, s54, 0x2000
	s_add_i32 s54, s82, s46
	global_load_lds_dwordx4 v[6:7], off
	v_lshl_add_u64 v[6:7], v[218:219], 0, s[16:17]
	s_mov_b32 m0, s54
	s_nop 0
	global_load_lds_dwordx4 v[6:7], off
	v_lshl_add_u64 v[6:7], v[220:221], 0, s[16:17]
	s_add_i32 m0, s54, 0x2000
	s_nop 0
	global_load_lds_dwordx4 v[6:7], off
	v_lshl_add_u64 v[6:7], v[222:223], 0, s[16:17]
	s_mov_b32 m0, s67
	s_nop 0
	global_load_lds_dwordx4 v[6:7], off
	v_lshl_add_u64 v[6:7], v[224:225], 0, s[16:17]
	s_mov_b32 m0, s68
	s_nop 0
	global_load_lds_dwordx4 v[6:7], off
	s_waitcnt vmcnt(8)
	s_waitcnt lgkmcnt(0)
	s_barrier
	s_setprio 1
	s_waitcnt lgkmcnt(0)
	v_mfma_f32_16x16x32_bf16 v[64:67], v[152:155], v[184:187], v[64:67]
	v_mfma_f32_16x16x32_bf16 v[64:67], v[156:159], v[188:191], v[64:67]
	v_mfma_f32_16x16x32_bf16 v[60:63], v[160:163], v[184:187], v[60:63]
	v_mfma_f32_16x16x32_bf16 v[60:63], v[164:167], v[188:191], v[60:63]
	v_mfma_f32_16x16x32_bf16 v[56:59], v[152:155], v[192:195], v[56:59]
	v_mfma_f32_16x16x32_bf16 v[56:59], v[156:159], v[196:199], v[56:59]
	v_mfma_f32_16x16x32_bf16 v[52:55], v[160:163], v[192:195], v[52:55]
	v_mfma_f32_16x16x32_bf16 v[52:55], v[164:167], v[196:199], v[52:55]
	v_mfma_f32_16x16x32_bf16 v[48:51], v[152:155], v[200:203], v[48:51]
	v_mfma_f32_16x16x32_bf16 v[48:51], v[156:159], v[204:207], v[48:51]
	v_mfma_f32_16x16x32_bf16 v[44:47], v[160:163], v[200:203], v[44:47]
	v_mfma_f32_16x16x32_bf16 v[44:47], v[164:167], v[204:207], v[44:47]
	v_mfma_f32_16x16x32_bf16 v[40:43], v[152:155], v[208:211], v[40:43]
	v_mfma_f32_16x16x32_bf16 v[40:43], v[156:159], v[212:215], v[40:43]
	v_mfma_f32_16x16x32_bf16 v[36:39], v[160:163], v[208:211], v[36:39]
	v_mfma_f32_16x16x32_bf16 v[36:39], v[164:167], v[212:215], v[36:39]
	s_setprio 0
	s_setprio 1
	v_mfma_f32_16x16x32_bf16 v[32:35], v[168:171], v[184:187], v[32:35]
	v_mfma_f32_16x16x32_bf16 v[28:31], v[176:179], v[184:187], v[28:31]
	v_mfma_f32_16x16x32_bf16 v[24:27], v[168:171], v[192:195], v[24:27]
	v_mfma_f32_16x16x32_bf16 v[20:23], v[176:179], v[192:195], v[20:23]
	v_mfma_f32_16x16x32_bf16 v[16:19], v[168:171], v[200:203], v[16:19]
	v_mfma_f32_16x16x32_bf16 v[12:15], v[176:179], v[200:203], v[12:15]
	v_mfma_f32_16x16x32_bf16 v[6:9], v[168:171], v[208:211], v[8:11]
	v_mfma_f32_16x16x32_bf16 v[2:5], v[176:179], v[208:211], v[2:5]
	v_mfma_f32_16x16x32_bf16 v[32:35], v[172:175], v[188:191], v[32:35]
	v_mfma_f32_16x16x32_bf16 v[28:31], v[180:183], v[188:191], v[28:31]
	v_mfma_f32_16x16x32_bf16 v[24:27], v[172:175], v[196:199], v[24:27]
	v_mfma_f32_16x16x32_bf16 v[20:23], v[180:183], v[196:199], v[20:23]
	v_mfma_f32_16x16x32_bf16 v[16:19], v[172:175], v[204:207], v[16:19]
	v_mfma_f32_16x16x32_bf16 v[12:15], v[180:183], v[204:207], v[12:15]
	v_mfma_f32_16x16x32_bf16 v[8:11], v[172:175], v[212:215], v[6:9]
	v_mfma_f32_16x16x32_bf16 v[4:7], v[180:183], v[212:215], v[2:5]
	s_setprio 0
	s_barrier
	s_add_u32 s34, s34, 0x100
	s_addc_u32 s35, s35, 0
	s_add_u32 s78, s78, 0x100
	s_addc_u32 s79, s79, 0
	s_cmp_ge_i32 s80, s66
	s_mov_b32 s54, s80
	s_cbranch_scc0 .LBB0_669
	v_readlane_b32 s80, v250, 61
	v_readlane_b32 s82, v249, 5
	v_readlane_b32 s81, v250, 62
	s_and_b64 vcc, exec, s[24:25]
	s_cbranch_vccnz .LBB0_662
	s_branch .LBB0_663

; #define PG8_STAGE(bufoff, gbase, voff) do { _Pragma("unroll") for (int _i = 0; _i < 2; ++_i) \
;         __builtin_amdgcn_global_load_lds((const unsigned*)((const char*)(gbase) + (voff)[_i]), (PG8_LAS unsigned*)(lds + (bufoff) + ldsw + _i * 8192), 16, 0, 0); } while (0)
; #define PG8_LDA(dst, b, h) do { _Pragma("unroll") for (int m = 0; m < 4; ++m) _Pragma("unroll") for (int k = 0; k < 2; ++k) dst[m][k] = *(const PG8_LAS bf16x8*)(lds + PG8_SA(b, h) + aoff + m * 2048 + k * 1024); } while (0)
; #define PG8_LDB(dst, b, h) do { _Pragma("unroll") for (int n = 0; n < 2; ++n) _Pragma("unroll") for (int k = 0; k < 2; ++k) dst[n][k] = *(const PG8_LAS bf16x8*)(lds + PG8_SB(b, h) + boff + n * 2048 + k * 1024); } while (0)
; #define PG8_MMA(ai, bj, At, Bt) do { __builtin_amdgcn_s_setprio(1); _Pragma("unroll") for (int m = 0; m < 4; ++m) _Pragma("unroll") for (int n = 0; n < 2; ++n) _Pragma("unroll") for (int k = 0; k < 2; ++k) \
;         acc[ai][bj][m][n] = __builtin_amdgcn_mfma_f32_16x16x32_bf16(Bt[n][k], At[m][k], acc[ai][bj][m][n], 0, 0, 0); __builtin_amdgcn_s_setprio(0); } while (0)
; #define PG8_WAIT_V(n) asm volatile("s_waitcnt vmcnt(" #n ")" ::: "memory")
; #define PG8_WAIT_L(n) asm volatile("s_waitcnt lgkmcnt(" #n ")" ::: "memory")
; template <class Epi, class Sched, bool ALIGN_EPI = false, bool SP2 = false, bool APERM = false  >
; __device__ __forceinline__ void gemm_phase(PG8_LAS unsigned char* lds, const Gemm g, const Sched& S, const Epi& E, const int wid  ) {
;     ...
;             const bool last = (t == nt - 2);
;             const char* a1 = cA + (size_t)(t + 1) * kstep;
;             const char* a2 = last ? nA : cA + (size_t)(t + 2) * kstep; const char* b2 = last ? nB : cB + (size_t)(t + 2) * kstep;
;             const char* a3 = a2 + kstep; const char* b3 = b2 + kstep;
;             if (last && has_next) S.a_ready(nxt);
;             if constexpr (SP2) {
;             PG8_LDB(B0, 0, 0); PG8_LDB(B1, 0, 1); PG8_SCHED; PG8_LDA(At, 0, 0); PG8_STAGE(PG8_SA(1, 1), a1 + hstep, voffA);
;             PG8_WAIT_V(8); PG8_WAIT_L(0); PG8_BAR; PG8_MMA(0, 0, At, B0); PG8_MMA(0, 1, At, B1); PG8_BAR; PG8_SCHED;
;             PG8_LDA(At, 0, 1); PG8_STAGE(PG8_SB(0, 0), b2, voffB); PG8_STAGE(PG8_SB(0, 1), b2 + hstep, voffB); PG8_STAGE(PG8_SA(0, 0), a2, voffA);
;             PG8_WAIT_V(8); PG8_WAIT_L(0); PG8_BAR; PG8_MMA(1, 0, At, B0); PG8_MMA(1, 1, At, B1); PG8_BAR; PG8_SCHED;
.LBB0_715:
	s_lshl_b32 s24, s71, 7
	s_add_u32 s25, s0, s24
	s_addc_u32 s26, s1, 0
	s_add_u32 s27, s25, 0x100
	v_add_u32_e32 v146, s94, v175
	s_addc_u32 s73, s26, 0
	s_waitcnt lgkmcnt(0)
	ds_read_b128 v[128:131], v146
	ds_read_b128 v[132:135], v146 offset:1024
	ds_read_b128 v[136:139], v146 offset:2048
	ds_read_b128 v[154:157], v146 offset:3072
	v_add_u32_e32 v146, s95, v175
	s_and_b64 s[18:19], s[16:17], exec
	ds_read_b128 v[158:161], v146
	ds_read_b128 v[162:165], v146 offset:1024
	ds_read_b128 v[166:169], v146 offset:2048
	ds_read_b128 v[170:173], v146 offset:3072
	s_cselect_b32 s19, s33, s73
	s_cselect_b32 s18, s52, s27
	s_add_u32 s24, s14, s24
	s_addc_u32 s27, s15, 0
	s_add_u32 s24, s24, 0x100
	s_addc_u32 s27, s27, 0
	s_and_b64 s[16:17], s[16:17], exec
	s_cselect_b32 s16, s65, s24
	s_cselect_b32 s17, s64, s27
	s_add_u32 s24, s25, 0x80080
	s_addc_u32 s25, s26, 0
	v_lshl_add_u64 v[214:215], s[24:25], 0, v[144:145]
	s_add_i32 m0, s11, 0xc000
	ds_read_b128 v[182:185], v180
	ds_read_b128 v[186:189], v180 offset:1024
	ds_read_b128 v[190:193], v180 offset:2048
	ds_read_b128 v[194:197], v180 offset:3072
	ds_read_b128 v[198:201], v180 offset:4096
	ds_read_b128 v[202:205], v180 offset:5120
	ds_read_b128 v[206:209], v180 offset:6144
	ds_read_b128 v[210:213], v180 offset:7168
	global_load_lds_dwordx4 v[214:215], off
	v_lshl_add_u64 v[214:215], s[24:25], 0, v[148:149]
	s_add_i32 m0, s11, 0xe000
	s_nop 0
	global_load_lds_dwordx4 v[214:215], off
	s_waitcnt vmcnt(8)
	s_waitcnt lgkmcnt(0)
	s_barrier
	s_setprio 1
	s_waitcnt lgkmcnt(0)
	v_mfma_f32_16x16x32_bf16 v[124:127], v[128:131], v[182:185], v[124:127]
	v_mfma_f32_16x16x32_bf16 v[124:127], v[132:135], v[186:189], v[124:127]
	v_mfma_f32_16x16x32_bf16 v[120:123], v[136:139], v[182:185], v[120:123]
	v_mfma_f32_16x16x32_bf16 v[120:123], v[154:157], v[186:189], v[120:123]
	v_mfma_f32_16x16x32_bf16 v[116:119], v[128:131], v[190:193], v[116:119]
	v_mfma_f32_16x16x32_bf16 v[116:119], v[132:135], v[194:197], v[116:119]
	v_mfma_f32_16x16x32_bf16 v[112:115], v[136:139], v[190:193], v[112:115]
	v_mfma_f32_16x16x32_bf16 v[112:115], v[154:157], v[194:197], v[112:115]
	v_mfma_f32_16x16x32_bf16 v[108:111], v[128:131], v[198:201], v[108:111]
	v_mfma_f32_16x16x32_bf16 v[108:111], v[132:135], v[202:205], v[108:111]
	v_mfma_f32_16x16x32_bf16 v[104:107], v[136:139], v[198:201], v[104:107]
	v_mfma_f32_16x16x32_bf16 v[104:107], v[154:157], v[202:205], v[104:107]
	v_mfma_f32_16x16x32_bf16 v[100:103], v[128:131], v[206:209], v[100:103]
	v_mfma_f32_16x16x32_bf16 v[100:103], v[132:135], v[210:213], v[100:103]
	v_mfma_f32_16x16x32_bf16 v[96:99], v[136:139], v[206:209], v[96:99]
	v_mfma_f32_16x16x32_bf16 v[96:99], v[154:157], v[210:213], v[96:99]
	s_setprio 0
	s_setprio 1
	v_mfma_f32_16x16x32_bf16 v[92:95], v[158:161], v[182:185], v[92:95]
	v_mfma_f32_16x16x32_bf16 v[92:95], v[162:165], v[186:189], v[92:95]
	v_mfma_f32_16x16x32_bf16 v[88:91], v[166:169], v[182:185], v[88:91]
	v_mfma_f32_16x16x32_bf16 v[88:91], v[170:173], v[186:189], v[88:91]
	v_mfma_f32_16x16x32_bf16 v[84:87], v[158:161], v[190:193], v[84:87]
	v_mfma_f32_16x16x32_bf16 v[84:87], v[162:165], v[194:197], v[84:87]
	v_mfma_f32_16x16x32_bf16 v[80:83], v[166:169], v[190:193], v[80:83]
	v_mfma_f32_16x16x32_bf16 v[80:83], v[170:173], v[194:197], v[80:83]
	v_mfma_f32_16x16x32_bf16 v[76:79], v[158:161], v[198:201], v[76:79]
	v_mfma_f32_16x16x32_bf16 v[76:79], v[162:165], v[202:205], v[76:79]
	v_mfma_f32_16x16x32_bf16 v[72:75], v[166:169], v[198:201], v[72:75]
	v_mfma_f32_16x16x32_bf16 v[72:75], v[170:173], v[202:205], v[72:75]
	v_mfma_f32_16x16x32_bf16 v[68:71], v[158:161], v[206:209], v[68:71]
	v_mfma_f32_16x16x32_bf16 v[68:71], v[162:165], v[210:213], v[68:71]
	v_mfma_f32_16x16x32_bf16 v[64:67], v[166:169], v[206:209], v[64:67]
	v_mfma_f32_16x16x32_bf16 v[64:67], v[170:173], v[210:213], v[64:67]
	s_setprio 0
	s_barrier
	s_add_i32 s24, s94, s46
	v_lshl_add_u64 v[214:215], s[16:17], 0, v[140:141]
	s_mov_b32 m0, s24
	ds_read_b128 v[182:185], v180 offset:16384
	ds_read_b128 v[186:189], v180 offset:17408
	ds_read_b128 v[190:193], v180 offset:18432
	ds_read_b128 v[194:197], v180 offset:19456
	ds_read_b128 v[198:201], v180 offset:20480
	ds_read_b128 v[202:205], v180 offset:21504
	ds_read_b128 v[206:209], v180 offset:22528
	ds_read_b128 v[210:213], v180 offset:23552
	global_load_lds_dwordx4 v[214:215], off
	s_add_i32 m0, s24, 0x2000
	s_add_u32 s24, s16, 0x80000
	v_lshl_add_u64 v[216:217], s[16:17], 0, v[142:143]
	s_addc_u32 s25, s17, 0
	s_add_i32 s26, s95, s46
	global_load_lds_dwordx4 v[216:217], off
	v_lshl_add_u64 v[218:219], s[24:25], 0, v[140:141]
	s_mov_b32 m0, s26
	v_lshl_add_u64 v[220:221], s[18:19], 0, v[148:149]
	global_load_lds_dwordx4 v[218:219], off
	v_lshl_add_u64 v[218:219], s[24:25], 0, v[142:143]
	s_add_i32 m0, s26, 0x2000
	s_nop 0
	global_load_lds_dwordx4 v[218:219], off
	v_lshl_add_u64 v[218:219], s[18:19], 0, v[144:145]
	s_mov_b32 m0, s11
	s_nop 0
	global_load_lds_dwordx4 v[218:219], off
	s_mov_b32 m0, s13
	s_nop 0
	global_load_lds_dwordx4 v[220:221], off
	s_waitcnt vmcnt(8)
	s_waitcnt lgkmcnt(0)
	s_barrier
; #define PG8_STAGE(bufoff, gbase, voff) do { _Pragma("unroll") for (int _i = 0; _i < 2; ++_i) \
;         __builtin_amdgcn_global_load_lds((const unsigned*)((const char*)(gbase) + (voff)[_i]), (PG8_LAS unsigned*)(lds + (bufoff) + ldsw + _i * 8192), 16, 0, 0); } while (0)
; #define PG8_LDA(dst, b, h) do { _Pragma("unroll") for (int m = 0; m < 4; ++m) _Pragma("unroll") for (int k = 0; k < 2; ++k) dst[m][k] = *(const PG8_LAS bf16x8*)(lds + PG8_SA(b, h) + aoff + m * 2048 + k * 1024); } while (0)
; #define PG8_LDB(dst, b, h) do { _Pragma("unroll") for (int n = 0; n < 2; ++n) _Pragma("unroll") for (int k = 0; k < 2; ++k) dst[n][k] = *(const PG8_LAS bf16x8*)(lds + PG8_SB(b, h) + boff + n * 2048 + k * 1024); } while (0)
; #define PG8_MMA(ai, bj, At, Bt) do { __builtin_amdgcn_s_setprio(1); _Pragma("unroll") for (int m = 0; m < 4; ++m) _Pragma("unroll") for (int n = 0; n < 2; ++n) _Pragma("unroll") for (int k = 0; k < 2; ++k) \
;         acc[ai][bj][m][n] = __builtin_amdgcn_mfma_f32_16x16x32_bf16(Bt[n][k], At[m][k], acc[ai][bj][m][n], 0, 0, 0); __builtin_amdgcn_s_setprio(0); } while (0)
; #define PG8_WAIT_V(n) asm volatile("s_waitcnt vmcnt(" #n ")" ::: "memory")
; #define PG8_WAIT_L(n) asm volatile("s_waitcnt lgkmcnt(" #n ")" ::: "memory")
; #define PG8_BAR __builtin_amdgcn_s_barrier()
; #define PG8_SCHED __builtin_amdgcn_sched_barrier(0)
; template <class Epi, class Sched, bool ALIGN_EPI = false, bool SP2 = false, bool APERM = false  >
; __device__ __forceinline__ void gemm_phase(PG8_LAS unsigned char* lds, const Gemm g, const Sched& S, const Epi& E, const int wid  ) {
;     ...
;             PG8_WAIT_V(8); PG8_WAIT_L(0); PG8_BAR; PG8_MMA(1, 0, At, B0); PG8_MMA(1, 1, At, B1); PG8_BAR; PG8_SCHED;
;             PG8_LDB(B0, 1, 0); PG8_LDB(B1, 1, 1); PG8_SCHED; PG8_LDA(At, 1, 0); PG8_STAGE(PG8_SA(0, 1), a2 + hstep, voffA);
;             PG8_WAIT_V(8); PG8_WAIT_L(0); PG8_BAR; PG8_MMA(0, 0, At, B0); PG8_MMA(0, 1, At, B1); PG8_BAR; PG8_SCHED;
	s_setprio 1
	s_waitcnt lgkmcnt(0)
	v_mfma_f32_16x16x32_bf16 v[60:63], v[128:131], v[182:185], v[60:63]
	v_mfma_f32_16x16x32_bf16 v[60:63], v[132:135], v[186:189], v[60:63]
	v_mfma_f32_16x16x32_bf16 v[56:59], v[136:139], v[182:185], v[56:59]
	v_mfma_f32_16x16x32_bf16 v[56:59], v[154:157], v[186:189], v[56:59]
	v_mfma_f32_16x16x32_bf16 v[52:55], v[128:131], v[190:193], v[52:55]
	v_mfma_f32_16x16x32_bf16 v[52:55], v[132:135], v[194:197], v[52:55]
	v_mfma_f32_16x16x32_bf16 v[48:51], v[136:139], v[190:193], v[48:51]
	v_mfma_f32_16x16x32_bf16 v[48:51], v[154:157], v[194:197], v[48:51]
	v_mfma_f32_16x16x32_bf16 v[44:47], v[128:131], v[198:201], v[44:47]
	v_mfma_f32_16x16x32_bf16 v[44:47], v[132:135], v[202:205], v[44:47]
	v_mfma_f32_16x16x32_bf16 v[40:43], v[136:139], v[198:201], v[40:43]
	v_mfma_f32_16x16x32_bf16 v[40:43], v[154:157], v[202:205], v[40:43]
	v_mfma_f32_16x16x32_bf16 v[36:39], v[128:131], v[206:209], v[36:39]
	v_mfma_f32_16x16x32_bf16 v[36:39], v[132:135], v[210:213], v[36:39]
	v_mfma_f32_16x16x32_bf16 v[32:35], v[136:139], v[206:209], v[32:35]
	v_mfma_f32_16x16x32_bf16 v[32:35], v[154:157], v[210:213], v[32:35]
	s_setprio 0
	s_setprio 1
	v_mfma_f32_16x16x32_bf16 v[28:31], v[158:161], v[182:185], v[28:31]
	v_mfma_f32_16x16x32_bf16 v[28:31], v[162:165], v[186:189], v[28:31]
	v_mfma_f32_16x16x32_bf16 v[24:27], v[166:169], v[182:185], v[24:27]
	v_mfma_f32_16x16x32_bf16 v[24:27], v[170:173], v[186:189], v[24:27]
	v_mfma_f32_16x16x32_bf16 v[20:23], v[158:161], v[190:193], v[20:23]
	v_mfma_f32_16x16x32_bf16 v[20:23], v[162:165], v[194:197], v[20:23]
	v_mfma_f32_16x16x32_bf16 v[16:19], v[166:169], v[190:193], v[16:19]
	v_mfma_f32_16x16x32_bf16 v[16:19], v[170:173], v[194:197], v[16:19]
	v_mfma_f32_16x16x32_bf16 v[12:15], v[158:161], v[198:201], v[12:15]
	v_mfma_f32_16x16x32_bf16 v[12:15], v[162:165], v[202:205], v[12:15]
	v_mfma_f32_16x16x32_bf16 v[8:11], v[166:169], v[198:201], v[8:11]
	v_mfma_f32_16x16x32_bf16 v[8:11], v[170:173], v[202:205], v[8:11]
	v_mfma_f32_16x16x32_bf16 v[4:7], v[158:161], v[206:209], v[4:7]
	v_mfma_f32_16x16x32_bf16 v[4:7], v[162:165], v[210:213], v[4:7]
	v_mfma_f32_16x16x32_bf16 v[0:3], v[166:169], v[206:209], v[0:3]
	v_mfma_f32_16x16x32_bf16 v[0:3], v[170:173], v[210:213], v[0:3]
	s_setprio 0
	s_barrier
	s_add_i32 s24, 0, 0x18000
	v_add_u32_e32 v146, s24, v175
	s_add_i32 s25, 0, 0x1c000
	ds_read_b128 v[128:131], v146
	ds_read_b128 v[132:135], v146 offset:1024
	ds_read_b128 v[136:139], v146 offset:2048
	ds_read_b128 v[154:157], v146 offset:3072
	v_add_u32_e32 v146, s25, v175
	ds_read_b128 v[158:161], v146
	ds_read_b128 v[162:165], v146 offset:1024
	ds_read_b128 v[166:169], v146 offset:2048
	ds_read_b128 v[170:173], v146 offset:3072
	s_add_u32 s18, s18, 0x80000
	s_addc_u32 s19, s19, 0
	s_mov_b32 m0, s30
	v_lshl_add_u64 v[222:223], s[18:19], 0, v[144:145]
	ds_read_b128 v[182:185], v180 offset:32768
	ds_read_b128 v[186:189], v180 offset:33792
	ds_read_b128 v[190:193], v180 offset:34816
	ds_read_b128 v[194:197], v180 offset:35840
	ds_read_b128 v[198:201], v180 offset:36864
	ds_read_b128 v[202:205], v180 offset:37888
	ds_read_b128 v[206:209], v180 offset:38912
	ds_read_b128 v[210:213], v180 offset:39936
	global_load_lds_dwordx4 v[222:223], off
	v_lshl_add_u64 v[222:223], s[18:19], 0, v[148:149]
	s_mov_b32 m0, s31
	s_nop 0
	global_load_lds_dwordx4 v[222:223], off
	s_waitcnt vmcnt(8)
	s_waitcnt lgkmcnt(0)
	s_barrier
	s_setprio 1
	s_waitcnt lgkmcnt(0)
	v_mfma_f32_16x16x32_bf16 v[124:127], v[128:131], v[182:185], v[124:127]
	v_mfma_f32_16x16x32_bf16 v[124:127], v[132:135], v[186:189], v[124:127]
	v_mfma_f32_16x16x32_bf16 v[120:123], v[136:139], v[182:185], v[120:123]
	v_mfma_f32_16x16x32_bf16 v[120:123], v[154:157], v[186:189], v[120:123]
	v_mfma_f32_16x16x32_bf16 v[116:119], v[128:131], v[190:193], v[116:119]
	v_mfma_f32_16x16x32_bf16 v[116:119], v[132:135], v[194:197], v[116:119]
	v_mfma_f32_16x16x32_bf16 v[112:115], v[136:139], v[190:193], v[112:115]
	v_mfma_f32_16x16x32_bf16 v[112:115], v[154:157], v[194:197], v[112:115]
	v_mfma_f32_16x16x32_bf16 v[108:111], v[128:131], v[198:201], v[108:111]
	v_mfma_f32_16x16x32_bf16 v[108:111], v[132:135], v[202:205], v[108:111]
	v_mfma_f32_16x16x32_bf16 v[104:107], v[136:139], v[198:201], v[104:107]
	v_mfma_f32_16x16x32_bf16 v[104:107], v[154:157], v[202:205], v[104:107]
	v_mfma_f32_16x16x32_bf16 v[100:103], v[128:131], v[206:209], v[100:103]
	v_mfma_f32_16x16x32_bf16 v[100:103], v[132:135], v[210:213], v[100:103]
	v_mfma_f32_16x16x32_bf16 v[96:99], v[136:139], v[206:209], v[96:99]
	v_mfma_f32_16x16x32_bf16 v[96:99], v[154:157], v[210:213], v[96:99]
	s_setprio 0
	s_setprio 1
	v_mfma_f32_16x16x32_bf16 v[92:95], v[158:161], v[182:185], v[92:95]
	v_mfma_f32_16x16x32_bf16 v[92:95], v[162:165], v[186:189], v[92:95]
	v_mfma_f32_16x16x32_bf16 v[88:91], v[166:169], v[182:185], v[88:91]
	v_mfma_f32_16x16x32_bf16 v[88:91], v[170:173], v[186:189], v[88:91]
	v_mfma_f32_16x16x32_bf16 v[84:87], v[158:161], v[190:193], v[84:87]
	v_mfma_f32_16x16x32_bf16 v[84:87], v[162:165], v[194:197], v[84:87]
	v_mfma_f32_16x16x32_bf16 v[80:83], v[166:169], v[190:193], v[80:83]
	v_mfma_f32_16x16x32_bf16 v[80:83], v[170:173], v[194:197], v[80:83]
	v_mfma_f32_16x16x32_bf16 v[76:79], v[158:161], v[198:201], v[76:79]
	v_mfma_f32_16x16x32_bf16 v[76:79], v[162:165], v[202:205], v[76:79]
	v_mfma_f32_16x16x32_bf16 v[72:75], v[166:169], v[198:201], v[72:75]
	v_mfma_f32_16x16x32_bf16 v[72:75], v[170:173], v[202:205], v[72:75]
	v_mfma_f32_16x16x32_bf16 v[68:71], v[158:161], v[206:209], v[68:71]
	v_mfma_f32_16x16x32_bf16 v[68:71], v[162:165], v[210:213], v[68:71]
	v_mfma_f32_16x16x32_bf16 v[64:67], v[166:169], v[206:209], v[64:67]
	v_mfma_f32_16x16x32_bf16 v[64:67], v[170:173], v[210:213], v[64:67]
	s_setprio 0
	s_barrier
; #define PG8_STAGE(bufoff, gbase, voff) do { _Pragma("unroll") for (int _i = 0; _i < 2; ++_i) \
;         __builtin_amdgcn_global_load_lds((const unsigned*)((const char*)(gbase) + (voff)[_i]), (PG8_LAS unsigned*)(lds + (bufoff) + ldsw + _i * 8192), 16, 0, 0); } while (0)
; #define PG8_LDA(dst, b, h) do { _Pragma("unroll") for (int m = 0; m < 4; ++m) _Pragma("unroll") for (int k = 0; k < 2; ++k) dst[m][k] = *(const PG8_LAS bf16x8*)(lds + PG8_SA(b, h) + aoff + m * 2048 + k * 1024); } while (0)
; #define PG8_MMA(ai, bj, At, Bt) do { __builtin_amdgcn_s_setprio(1); _Pragma("unroll") for (int m = 0; m < 4; ++m) _Pragma("unroll") for (int n = 0; n < 2; ++n) _Pragma("unroll") for (int k = 0; k < 2; ++k) \
;         acc[ai][bj][m][n] = __builtin_amdgcn_mfma_f32_16x16x32_bf16(Bt[n][k], At[m][k], acc[ai][bj][m][n], 0, 0, 0); __builtin_amdgcn_s_setprio(0); } while (0)
; #define PG8_WAIT_V(n) asm volatile("s_waitcnt vmcnt(" #n ")" ::: "memory")
; #define PG8_WAIT_L(n) asm volatile("s_waitcnt lgkmcnt(" #n ")" ::: "memory")
; #define PG8_BAR __builtin_amdgcn_s_barrier()
; #define PG8_SCHED __builtin_amdgcn_sched_barrier(0)
; template <class Epi, class Sched, bool ALIGN_EPI = false, bool SP2 = false, bool APERM = false  >
; __device__ __forceinline__ void gemm_phase(PG8_LAS unsigned char* lds, const Gemm g, const Sched& S, const Epi& E, const int wid  ) {
;     ...
;             PG8_LDA(At, 1, 1); PG8_STAGE(PG8_SB(1, 0), b3, voffB); PG8_STAGE(PG8_SB(1, 1), b3 + hstep, voffB); PG8_STAGE(PG8_SA(1, 0), a3, voffA);
;             PG8_WAIT_V(8); PG8_WAIT_L(0); PG8_BAR; PG8_MMA(1, 0, At, B0); PG8_MMA(1, 1, At, B1); PG8_BAR; PG8_SCHED;
	s_add_i32 s18, s24, s46
	v_lshl_add_u64 v[214:215], v[214:215], 0, s[62:63]
	s_mov_b32 m0, s18
	ds_read_b128 v[182:185], v180 offset:49152
	ds_read_b128 v[186:189], v180 offset:50176
	ds_read_b128 v[190:193], v180 offset:51200
	ds_read_b128 v[194:197], v180 offset:52224
	ds_read_b128 v[198:201], v180 offset:53248
	ds_read_b128 v[202:205], v180 offset:54272
	ds_read_b128 v[206:209], v180 offset:55296
	ds_read_b128 v[210:213], v180 offset:56320
	global_load_lds_dwordx4 v[214:215], off
	s_add_i32 m0, s18, 0x2000
	s_add_u32 s16, s16, 0x80080
	v_lshl_add_u64 v[214:215], v[216:217], 0, s[62:63]
	s_addc_u32 s17, s17, 0
	s_add_i32 s18, s25, s46
	global_load_lds_dwordx4 v[214:215], off
	v_lshl_add_u64 v[214:215], s[16:17], 0, v[140:141]
	s_mov_b32 m0, s18
	s_nop 0
	global_load_lds_dwordx4 v[214:215], off
	v_lshl_add_u64 v[214:215], s[16:17], 0, v[142:143]
	s_add_i32 m0, s18, 0x2000
	s_nop 0
	global_load_lds_dwordx4 v[214:215], off
	v_lshl_add_u64 v[214:215], v[218:219], 0, s[62:63]
	s_mov_b32 m0, s53
	s_nop 0
	global_load_lds_dwordx4 v[214:215], off
	v_lshl_add_u64 v[214:215], v[220:221], 0, s[62:63]
	s_mov_b32 m0, s85
	s_nop 0
	global_load_lds_dwordx4 v[214:215], off
	s_waitcnt vmcnt(8)
	s_waitcnt lgkmcnt(0)
	s_barrier
	s_setprio 1
	s_waitcnt lgkmcnt(0)
	v_mfma_f32_16x16x32_bf16 v[60:63], v[128:131], v[182:185], v[60:63]
	v_mfma_f32_16x16x32_bf16 v[60:63], v[132:135], v[186:189], v[60:63]
	v_mfma_f32_16x16x32_bf16 v[56:59], v[136:139], v[182:185], v[56:59]
	v_mfma_f32_16x16x32_bf16 v[56:59], v[154:157], v[186:189], v[56:59]
	v_mfma_f32_16x16x32_bf16 v[52:55], v[128:131], v[190:193], v[52:55]
	v_mfma_f32_16x16x32_bf16 v[52:55], v[132:135], v[194:197], v[52:55]
	v_mfma_f32_16x16x32_bf16 v[48:51], v[136:139], v[190:193], v[48:51]
	v_mfma_f32_16x16x32_bf16 v[48:51], v[154:157], v[194:197], v[48:51]
	v_mfma_f32_16x16x32_bf16 v[44:47], v[128:131], v[198:201], v[44:47]
	v_mfma_f32_16x16x32_bf16 v[44:47], v[132:135], v[202:205], v[44:47]
	v_mfma_f32_16x16x32_bf16 v[40:43], v[136:139], v[198:201], v[40:43]
	v_mfma_f32_16x16x32_bf16 v[40:43], v[154:157], v[202:205], v[40:43]
	v_mfma_f32_16x16x32_bf16 v[36:39], v[128:131], v[206:209], v[36:39]
	v_mfma_f32_16x16x32_bf16 v[36:39], v[132:135], v[210:213], v[36:39]
	v_mfma_f32_16x16x32_bf16 v[32:35], v[136:139], v[206:209], v[32:35]
	v_mfma_f32_16x16x32_bf16 v[32:35], v[154:157], v[210:213], v[32:35]
	s_setprio 0
	s_setprio 1
	v_mfma_f32_16x16x32_bf16 v[28:31], v[158:161], v[182:185], v[28:31]
	v_mfma_f32_16x16x32_bf16 v[28:31], v[162:165], v[186:189], v[28:31]
	v_mfma_f32_16x16x32_bf16 v[24:27], v[166:169], v[182:185], v[24:27]
	v_mfma_f32_16x16x32_bf16 v[24:27], v[170:173], v[186:189], v[24:27]
	v_mfma_f32_16x16x32_bf16 v[20:23], v[158:161], v[190:193], v[20:23]
	v_mfma_f32_16x16x32_bf16 v[20:23], v[162:165], v[194:197], v[20:23]
	v_mfma_f32_16x16x32_bf16 v[16:19], v[166:169], v[190:193], v[16:19]
	v_mfma_f32_16x16x32_bf16 v[16:19], v[170:173], v[194:197], v[16:19]
	v_mfma_f32_16x16x32_bf16 v[12:15], v[158:161], v[198:201], v[12:15]
	v_mfma_f32_16x16x32_bf16 v[12:15], v[162:165], v[202:205], v[12:15]
	v_mfma_f32_16x16x32_bf16 v[8:11], v[166:169], v[198:201], v[8:11]
	v_mfma_f32_16x16x32_bf16 v[8:11], v[170:173], v[202:205], v[8:11]
	v_mfma_f32_16x16x32_bf16 v[4:7], v[158:161], v[206:209], v[4:7]
	v_mfma_f32_16x16x32_bf16 v[4:7], v[162:165], v[210:213], v[4:7]
	v_mfma_f32_16x16x32_bf16 v[0:3], v[166:169], v[206:209], v[0:3]
	v_mfma_f32_16x16x32_bf16 v[0:3], v[170:173], v[210:213], v[0:3]
	s_setprio 0
	s_barrier
	s_add_i32 s16, s71, 2
	s_cmp_gt_u32 s71, 29
	s_cbranch_scc1 .LBB0_717
	s_mov_b32 s71, s16
	s_branch .LBB0_698

; #define PG8_STAGE(bufoff, gbase, voff) do { _Pragma("unroll") for (int _i = 0; _i < 2; ++_i) \
;         __builtin_amdgcn_global_load_lds((const unsigned*)((const char*)(gbase) + (voff)[_i]), (PG8_LAS unsigned*)(lds + (bufoff) + ldsw + _i * 8192), 16, 0, 0); } while (0)
; #define PG8_LDA(dst, b, h) do { _Pragma("unroll") for (int m = 0; m < 4; ++m) _Pragma("unroll") for (int k = 0; k < 2; ++k) dst[m][k] = *(const PG8_LAS bf16x8*)(lds + PG8_SA(b, h) + aoff + m * 2048 + k * 1024); } while (0)
; #define PG8_LDB(dst, b, h) do { _Pragma("unroll") for (int n = 0; n < 2; ++n) _Pragma("unroll") for (int k = 0; k < 2; ++k) dst[n][k] = *(const PG8_LAS bf16x8*)(lds + PG8_SB(b, h) + boff + n * 2048 + k * 1024); } while (0)
; #define PG8_MMA(ai, bj, At, Bt) do { __builtin_amdgcn_s_setprio(1); _Pragma("unroll") for (int m = 0; m < 4; ++m) _Pragma("unroll") for (int n = 0; n < 2; ++n) _Pragma("unroll") for (int k = 0; k < 2; ++k) \
;         acc[ai][bj][m][n] = __builtin_amdgcn_mfma_f32_16x16x32_bf16(Bt[n][k], At[m][k], acc[ai][bj][m][n], 0, 0, 0); __builtin_amdgcn_s_setprio(0); } while (0)
; #define PG8_WAIT_V(n) asm volatile("s_waitcnt vmcnt(" #n ")" ::: "memory")
; #define PG8_WAIT_L(n) asm volatile("s_waitcnt lgkmcnt(" #n ")" ::: "memory")
; template <class Epi, class Sched, bool ALIGN_EPI = false, bool SP2 = false, bool APERM = false  >
; __device__ __forceinline__ void gemm_phase(PG8_LAS unsigned char* lds, const Gemm g, const Sched& S, const Epi& E, const int wid  ) {
;     ...
;             const bool last = (t == nt - 2);
;             const char* a1 = cA + (size_t)(t + 1) * kstep;
;             const char* a2 = last ? nA : cA + (size_t)(t + 2) * kstep; const char* b2 = last ? nB : cB + (size_t)(t + 2) * kstep;
;             const char* a3 = a2 + kstep; const char* b3 = b2 + kstep;
;             if (last && has_next) S.a_ready(nxt);
;             if constexpr (SP2) {
;             PG8_LDB(B0, 0, 0); PG8_LDB(B1, 0, 1); PG8_SCHED; PG8_LDA(At, 0, 0); PG8_STAGE(PG8_SA(1, 1), a1 + hstep, voffA);
;             PG8_WAIT_V(8); PG8_WAIT_L(0); PG8_BAR; PG8_MMA(0, 0, At, B0); PG8_MMA(0, 1, At, B1); PG8_BAR; PG8_SCHED;
;             PG8_LDA(At, 0, 1); PG8_STAGE(PG8_SB(0, 0), b2, voffB); PG8_STAGE(PG8_SB(0, 1), b2 + hstep, voffB); PG8_STAGE(PG8_SA(0, 0), a2, voffA);
;             PG8_WAIT_V(8); PG8_WAIT_L(0); PG8_BAR; PG8_MMA(1, 0, At, B0); PG8_MMA(1, 1, At, B1); PG8_BAR; PG8_SCHED;
.LBB0_793:
	s_lshl_b32 s19, s74, 7
	s_add_u32 s24, s60, s19
	s_addc_u32 s25, s61, 0
	s_add_u32 s16, s24, 0x100
	v_add_u32_e32 v138, s55, v160
	s_addc_u32 s17, s25, 0
	s_waitcnt lgkmcnt(0)
	ds_read_b128 v[128:131], v138
	ds_read_b128 v[146:149], v138 offset:1024
	ds_read_b128 v[150:153], v138 offset:2048
	ds_read_b128 v[154:157], v138 offset:3072
	v_add_u32_e32 v138, s84, v160
	s_and_b64 s[0:1], s[6:7], exec
	ds_read_b128 v[168:171], v138
	ds_read_b128 v[172:175], v138 offset:1024
	ds_read_b128 v[176:179], v138 offset:2048
	ds_read_b128 v[180:183], v138 offset:3072
	s_cselect_b32 s17, s33, s17
	s_cselect_b32 s16, s52, s16
	s_add_u32 s0, s56, s19
	s_addc_u32 s1, s57, 0
	s_add_u32 s19, s0, 0x100
	s_addc_u32 s75, s1, 0
	s_and_b64 s[0:1], s[6:7], exec
	s_cselect_b32 s0, s65, s19
	s_cselect_b32 s1, s64, s75
	s_add_u32 s6, s24, 0x80080
	s_addc_u32 s7, s25, 0
	v_lshl_add_u64 v[216:217], s[6:7], 0, v[136:137]
	s_add_i32 m0, s15, 0xc000
	ds_read_b128 v[184:187], v165
	ds_read_b128 v[188:191], v165 offset:1024
	ds_read_b128 v[192:195], v165 offset:2048
	ds_read_b128 v[196:199], v165 offset:3072
	ds_read_b128 v[200:203], v165 offset:4096
	ds_read_b128 v[204:207], v165 offset:5120
	ds_read_b128 v[208:211], v165 offset:6144
	ds_read_b128 v[212:215], v165 offset:7168
	global_load_lds_dwordx4 v[216:217], off
	v_lshl_add_u64 v[216:217], s[6:7], 0, v[140:141]
	s_add_i32 m0, s15, 0xe000
	s_nop 0
	global_load_lds_dwordx4 v[216:217], off
	s_waitcnt vmcnt(8)
	s_waitcnt lgkmcnt(0)
	s_barrier
	s_setprio 1
	s_waitcnt lgkmcnt(0)
	v_mfma_f32_16x16x32_bf16 v[124:127], v[128:131], v[184:187], v[124:127]
	v_mfma_f32_16x16x32_bf16 v[124:127], v[146:149], v[188:191], v[124:127]
	v_mfma_f32_16x16x32_bf16 v[120:123], v[150:153], v[184:187], v[120:123]
	v_mfma_f32_16x16x32_bf16 v[120:123], v[154:157], v[188:191], v[120:123]
	v_mfma_f32_16x16x32_bf16 v[116:119], v[128:131], v[192:195], v[116:119]
	v_mfma_f32_16x16x32_bf16 v[116:119], v[146:149], v[196:199], v[116:119]
	v_mfma_f32_16x16x32_bf16 v[112:115], v[150:153], v[192:195], v[112:115]
	v_mfma_f32_16x16x32_bf16 v[112:115], v[154:157], v[196:199], v[112:115]
	v_mfma_f32_16x16x32_bf16 v[108:111], v[128:131], v[200:203], v[108:111]
	v_mfma_f32_16x16x32_bf16 v[108:111], v[146:149], v[204:207], v[108:111]
	v_mfma_f32_16x16x32_bf16 v[104:107], v[150:153], v[200:203], v[104:107]
	v_mfma_f32_16x16x32_bf16 v[104:107], v[154:157], v[204:207], v[104:107]
	v_mfma_f32_16x16x32_bf16 v[100:103], v[128:131], v[208:211], v[100:103]
	v_mfma_f32_16x16x32_bf16 v[100:103], v[146:149], v[212:215], v[100:103]
	v_mfma_f32_16x16x32_bf16 v[96:99], v[150:153], v[208:211], v[96:99]
	v_mfma_f32_16x16x32_bf16 v[96:99], v[154:157], v[212:215], v[96:99]
	s_setprio 0
	s_setprio 1
	v_mfma_f32_16x16x32_bf16 v[92:95], v[168:171], v[184:187], v[92:95]
	v_mfma_f32_16x16x32_bf16 v[92:95], v[172:175], v[188:191], v[92:95]
	v_mfma_f32_16x16x32_bf16 v[88:91], v[176:179], v[184:187], v[88:91]
	v_mfma_f32_16x16x32_bf16 v[88:91], v[180:183], v[188:191], v[88:91]
	v_mfma_f32_16x16x32_bf16 v[84:87], v[168:171], v[192:195], v[84:87]
	v_mfma_f32_16x16x32_bf16 v[84:87], v[172:175], v[196:199], v[84:87]
	v_mfma_f32_16x16x32_bf16 v[80:83], v[176:179], v[192:195], v[80:83]
	v_mfma_f32_16x16x32_bf16 v[80:83], v[180:183], v[196:199], v[80:83]
	v_mfma_f32_16x16x32_bf16 v[76:79], v[168:171], v[200:203], v[76:79]
	v_mfma_f32_16x16x32_bf16 v[76:79], v[172:175], v[204:207], v[76:79]
	v_mfma_f32_16x16x32_bf16 v[72:75], v[176:179], v[200:203], v[72:75]
	v_mfma_f32_16x16x32_bf16 v[72:75], v[180:183], v[204:207], v[72:75]
	v_mfma_f32_16x16x32_bf16 v[68:71], v[168:171], v[208:211], v[68:71]
	v_mfma_f32_16x16x32_bf16 v[68:71], v[172:175], v[212:215], v[68:71]
	v_mfma_f32_16x16x32_bf16 v[64:67], v[176:179], v[208:211], v[64:67]
	v_mfma_f32_16x16x32_bf16 v[64:67], v[180:183], v[212:215], v[64:67]
	s_setprio 0
	s_barrier
	s_add_i32 s6, s55, s29
	v_lshl_add_u64 v[216:217], s[0:1], 0, v[132:133]
	s_mov_b32 m0, s6
	ds_read_b128 v[184:187], v165 offset:16384
	ds_read_b128 v[188:191], v165 offset:17408
	ds_read_b128 v[192:195], v165 offset:18432
	ds_read_b128 v[196:199], v165 offset:19456
	ds_read_b128 v[200:203], v165 offset:20480
	ds_read_b128 v[204:207], v165 offset:21504
	ds_read_b128 v[208:211], v165 offset:22528
	ds_read_b128 v[212:215], v165 offset:23552
	global_load_lds_dwordx4 v[216:217], off
	s_add_i32 m0, s6, 0x2000
	s_add_u32 s6, s0, 0x80000
	v_lshl_add_u64 v[218:219], s[0:1], 0, v[134:135]
	s_addc_u32 s7, s1, 0
	s_add_i32 s19, s84, s29
	global_load_lds_dwordx4 v[218:219], off
	v_lshl_add_u64 v[220:221], s[6:7], 0, v[132:133]
	s_mov_b32 m0, s19
	v_lshl_add_u64 v[222:223], s[16:17], 0, v[140:141]
	global_load_lds_dwordx4 v[220:221], off
	v_lshl_add_u64 v[220:221], s[6:7], 0, v[134:135]
	s_add_i32 m0, s19, 0x2000
	s_nop 0
	global_load_lds_dwordx4 v[220:221], off
	v_lshl_add_u64 v[220:221], s[16:17], 0, v[136:137]
	s_mov_b32 m0, s15
	s_nop 0
	global_load_lds_dwordx4 v[220:221], off
	s_mov_b32 m0, s30
	s_nop 0
	global_load_lds_dwordx4 v[222:223], off
	s_waitcnt vmcnt(8)
	s_waitcnt lgkmcnt(0)
	s_barrier
; #define PG8_STAGE(bufoff, gbase, voff) do { _Pragma("unroll") for (int _i = 0; _i < 2; ++_i) \
;         __builtin_amdgcn_global_load_lds((const unsigned*)((const char*)(gbase) + (voff)[_i]), (PG8_LAS unsigned*)(lds + (bufoff) + ldsw + _i * 8192), 16, 0, 0); } while (0)
; #define PG8_LDA(dst, b, h) do { _Pragma("unroll") for (int m = 0; m < 4; ++m) _Pragma("unroll") for (int k = 0; k < 2; ++k) dst[m][k] = *(const PG8_LAS bf16x8*)(lds + PG8_SA(b, h) + aoff + m * 2048 + k * 1024); } while (0)
; #define PG8_LDB(dst, b, h) do { _Pragma("unroll") for (int n = 0; n < 2; ++n) _Pragma("unroll") for (int k = 0; k < 2; ++k) dst[n][k] = *(const PG8_LAS bf16x8*)(lds + PG8_SB(b, h) + boff + n * 2048 + k * 1024); } while (0)
; #define PG8_MMA(ai, bj, At, Bt) do { __builtin_amdgcn_s_setprio(1); _Pragma("unroll") for (int m = 0; m < 4; ++m) _Pragma("unroll") for (int n = 0; n < 2; ++n) _Pragma("unroll") for (int k = 0; k < 2; ++k) \
;         acc[ai][bj][m][n] = __builtin_amdgcn_mfma_f32_16x16x32_bf16(Bt[n][k], At[m][k], acc[ai][bj][m][n], 0, 0, 0); __builtin_amdgcn_s_setprio(0); } while (0)
; #define PG8_WAIT_V(n) asm volatile("s_waitcnt vmcnt(" #n ")" ::: "memory")
; #define PG8_WAIT_L(n) asm volatile("s_waitcnt lgkmcnt(" #n ")" ::: "memory")
; #define PG8_BAR __builtin_amdgcn_s_barrier()
; #define PG8_SCHED __builtin_amdgcn_sched_barrier(0)
; template <class Epi, class Sched, bool ALIGN_EPI = false, bool SP2 = false, bool APERM = false  >
; __device__ __forceinline__ void gemm_phase(PG8_LAS unsigned char* lds, const Gemm g, const Sched& S, const Epi& E, const int wid  ) {
;     ...
;             PG8_WAIT_V(8); PG8_WAIT_L(0); PG8_BAR; PG8_MMA(1, 0, At, B0); PG8_MMA(1, 1, At, B1); PG8_BAR; PG8_SCHED;
;             PG8_LDB(B0, 1, 0); PG8_LDB(B1, 1, 1); PG8_SCHED; PG8_LDA(At, 1, 0); PG8_STAGE(PG8_SA(0, 1), a2 + hstep, voffA);
;             PG8_WAIT_V(8); PG8_WAIT_L(0); PG8_BAR; PG8_MMA(0, 0, At, B0); PG8_MMA(0, 1, At, B1); PG8_BAR; PG8_SCHED;
	s_setprio 1
	s_waitcnt lgkmcnt(0)
	v_mfma_f32_16x16x32_bf16 v[60:63], v[128:131], v[184:187], v[60:63]
	v_mfma_f32_16x16x32_bf16 v[60:63], v[146:149], v[188:191], v[60:63]
	v_mfma_f32_16x16x32_bf16 v[56:59], v[150:153], v[184:187], v[56:59]
	v_mfma_f32_16x16x32_bf16 v[56:59], v[154:157], v[188:191], v[56:59]
	v_mfma_f32_16x16x32_bf16 v[52:55], v[128:131], v[192:195], v[52:55]
	v_mfma_f32_16x16x32_bf16 v[52:55], v[146:149], v[196:199], v[52:55]
	v_mfma_f32_16x16x32_bf16 v[48:51], v[150:153], v[192:195], v[48:51]
	v_mfma_f32_16x16x32_bf16 v[48:51], v[154:157], v[196:199], v[48:51]
	v_mfma_f32_16x16x32_bf16 v[44:47], v[128:131], v[200:203], v[44:47]
	v_mfma_f32_16x16x32_bf16 v[44:47], v[146:149], v[204:207], v[44:47]
	v_mfma_f32_16x16x32_bf16 v[40:43], v[150:153], v[200:203], v[40:43]
	v_mfma_f32_16x16x32_bf16 v[40:43], v[154:157], v[204:207], v[40:43]
	v_mfma_f32_16x16x32_bf16 v[36:39], v[128:131], v[208:211], v[36:39]
	v_mfma_f32_16x16x32_bf16 v[36:39], v[146:149], v[212:215], v[36:39]
	v_mfma_f32_16x16x32_bf16 v[32:35], v[150:153], v[208:211], v[32:35]
	v_mfma_f32_16x16x32_bf16 v[32:35], v[154:157], v[212:215], v[32:35]
	s_setprio 0
	s_setprio 1
	v_mfma_f32_16x16x32_bf16 v[28:31], v[168:171], v[184:187], v[28:31]
	v_mfma_f32_16x16x32_bf16 v[28:31], v[172:175], v[188:191], v[28:31]
	v_mfma_f32_16x16x32_bf16 v[24:27], v[176:179], v[184:187], v[24:27]
	v_mfma_f32_16x16x32_bf16 v[24:27], v[180:183], v[188:191], v[24:27]
	v_mfma_f32_16x16x32_bf16 v[20:23], v[168:171], v[192:195], v[20:23]
	v_mfma_f32_16x16x32_bf16 v[20:23], v[172:175], v[196:199], v[20:23]
	v_mfma_f32_16x16x32_bf16 v[16:19], v[176:179], v[192:195], v[16:19]
	v_mfma_f32_16x16x32_bf16 v[16:19], v[180:183], v[196:199], v[16:19]
	v_mfma_f32_16x16x32_bf16 v[12:15], v[168:171], v[200:203], v[12:15]
	v_mfma_f32_16x16x32_bf16 v[12:15], v[172:175], v[204:207], v[12:15]
	v_mfma_f32_16x16x32_bf16 v[8:11], v[176:179], v[200:203], v[8:11]
	v_mfma_f32_16x16x32_bf16 v[8:11], v[180:183], v[204:207], v[8:11]
	v_mfma_f32_16x16x32_bf16 v[4:7], v[168:171], v[208:211], v[4:7]
	v_mfma_f32_16x16x32_bf16 v[4:7], v[172:175], v[212:215], v[4:7]
	v_mfma_f32_16x16x32_bf16 v[0:3], v[176:179], v[208:211], v[0:3]
	v_mfma_f32_16x16x32_bf16 v[0:3], v[180:183], v[212:215], v[0:3]
	s_setprio 0
	s_barrier
	s_add_i32 s19, 0, 0x18000
	v_add_u32_e32 v138, s19, v160
	s_add_i32 s24, 0, 0x1c000
	ds_read_b128 v[128:131], v138
	ds_read_b128 v[146:149], v138 offset:1024
	ds_read_b128 v[150:153], v138 offset:2048
	ds_read_b128 v[154:157], v138 offset:3072
	v_add_u32_e32 v138, s24, v160
	ds_read_b128 v[168:171], v138
	ds_read_b128 v[172:175], v138 offset:1024
	ds_read_b128 v[176:179], v138 offset:2048
	ds_read_b128 v[180:183], v138 offset:3072
	s_add_u32 s6, s16, 0x80000
	s_addc_u32 s7, s17, 0
	s_mov_b32 m0, s31
	v_lshl_add_u64 v[224:225], s[6:7], 0, v[136:137]
	ds_read_b128 v[184:187], v165 offset:32768
	ds_read_b128 v[188:191], v165 offset:33792
	ds_read_b128 v[192:195], v165 offset:34816
	ds_read_b128 v[196:199], v165 offset:35840
	ds_read_b128 v[200:203], v165 offset:36864
	ds_read_b128 v[204:207], v165 offset:37888
	ds_read_b128 v[208:211], v165 offset:38912
	ds_read_b128 v[212:215], v165 offset:39936
	global_load_lds_dwordx4 v[224:225], off
	v_lshl_add_u64 v[224:225], s[6:7], 0, v[140:141]
	s_mov_b32 m0, s34
	s_nop 0
	global_load_lds_dwordx4 v[224:225], off
	s_waitcnt vmcnt(8)
	s_waitcnt lgkmcnt(0)
	s_barrier
	s_setprio 1
	s_waitcnt lgkmcnt(0)
	v_mfma_f32_16x16x32_bf16 v[124:127], v[128:131], v[184:187], v[124:127]
	v_mfma_f32_16x16x32_bf16 v[124:127], v[146:149], v[188:191], v[124:127]
	v_mfma_f32_16x16x32_bf16 v[120:123], v[150:153], v[184:187], v[120:123]
	v_mfma_f32_16x16x32_bf16 v[120:123], v[154:157], v[188:191], v[120:123]
	v_mfma_f32_16x16x32_bf16 v[116:119], v[128:131], v[192:195], v[116:119]
	v_mfma_f32_16x16x32_bf16 v[116:119], v[146:149], v[196:199], v[116:119]
	v_mfma_f32_16x16x32_bf16 v[112:115], v[150:153], v[192:195], v[112:115]
	v_mfma_f32_16x16x32_bf16 v[112:115], v[154:157], v[196:199], v[112:115]
	v_mfma_f32_16x16x32_bf16 v[108:111], v[128:131], v[200:203], v[108:111]
	v_mfma_f32_16x16x32_bf16 v[108:111], v[146:149], v[204:207], v[108:111]
	v_mfma_f32_16x16x32_bf16 v[104:107], v[150:153], v[200:203], v[104:107]
	v_mfma_f32_16x16x32_bf16 v[104:107], v[154:157], v[204:207], v[104:107]
	v_mfma_f32_16x16x32_bf16 v[100:103], v[128:131], v[208:211], v[100:103]
	v_mfma_f32_16x16x32_bf16 v[100:103], v[146:149], v[212:215], v[100:103]
	v_mfma_f32_16x16x32_bf16 v[96:99], v[150:153], v[208:211], v[96:99]
	v_mfma_f32_16x16x32_bf16 v[96:99], v[154:157], v[212:215], v[96:99]
	s_setprio 0
	s_setprio 1
	v_mfma_f32_16x16x32_bf16 v[92:95], v[168:171], v[184:187], v[92:95]
	v_mfma_f32_16x16x32_bf16 v[92:95], v[172:175], v[188:191], v[92:95]
	v_mfma_f32_16x16x32_bf16 v[88:91], v[176:179], v[184:187], v[88:91]
	v_mfma_f32_16x16x32_bf16 v[88:91], v[180:183], v[188:191], v[88:91]
	v_mfma_f32_16x16x32_bf16 v[84:87], v[168:171], v[192:195], v[84:87]
	v_mfma_f32_16x16x32_bf16 v[84:87], v[172:175], v[196:199], v[84:87]
	v_mfma_f32_16x16x32_bf16 v[80:83], v[176:179], v[192:195], v[80:83]
	v_mfma_f32_16x16x32_bf16 v[80:83], v[180:183], v[196:199], v[80:83]
	v_mfma_f32_16x16x32_bf16 v[76:79], v[168:171], v[200:203], v[76:79]
	v_mfma_f32_16x16x32_bf16 v[76:79], v[172:175], v[204:207], v[76:79]
	v_mfma_f32_16x16x32_bf16 v[72:75], v[176:179], v[200:203], v[72:75]
	v_mfma_f32_16x16x32_bf16 v[72:75], v[180:183], v[204:207], v[72:75]
	v_mfma_f32_16x16x32_bf16 v[68:71], v[168:171], v[208:211], v[68:71]
	v_mfma_f32_16x16x32_bf16 v[68:71], v[172:175], v[212:215], v[68:71]
	v_mfma_f32_16x16x32_bf16 v[64:67], v[176:179], v[208:211], v[64:67]
	v_mfma_f32_16x16x32_bf16 v[64:67], v[180:183], v[212:215], v[64:67]
	s_setprio 0
	s_barrier
; #define PG8_STAGE(bufoff, gbase, voff) do { _Pragma("unroll") for (int _i = 0; _i < 2; ++_i) \
;         __builtin_amdgcn_global_load_lds((const unsigned*)((const char*)(gbase) + (voff)[_i]), (PG8_LAS unsigned*)(lds + (bufoff) + ldsw + _i * 8192), 16, 0, 0); } while (0)
; #define PG8_LDA(dst, b, h) do { _Pragma("unroll") for (int m = 0; m < 4; ++m) _Pragma("unroll") for (int k = 0; k < 2; ++k) dst[m][k] = *(const PG8_LAS bf16x8*)(lds + PG8_SA(b, h) + aoff + m * 2048 + k * 1024); } while (0)
; #define PG8_MMA(ai, bj, At, Bt) do { __builtin_amdgcn_s_setprio(1); _Pragma("unroll") for (int m = 0; m < 4; ++m) _Pragma("unroll") for (int n = 0; n < 2; ++n) _Pragma("unroll") for (int k = 0; k < 2; ++k) \
;         acc[ai][bj][m][n] = __builtin_amdgcn_mfma_f32_16x16x32_bf16(Bt[n][k], At[m][k], acc[ai][bj][m][n], 0, 0, 0); __builtin_amdgcn_s_setprio(0); } while (0)
; #define PG8_WAIT_V(n) asm volatile("s_waitcnt vmcnt(" #n ")" ::: "memory")
; #define PG8_WAIT_L(n) asm volatile("s_waitcnt lgkmcnt(" #n ")" ::: "memory")
; #define PG8_BAR __builtin_amdgcn_s_barrier()
; #define PG8_SCHED __builtin_amdgcn_sched_barrier(0)
; template <class Epi, class Sched, bool ALIGN_EPI = false, bool SP2 = false, bool APERM = false  >
; __device__ __forceinline__ void gemm_phase(PG8_LAS unsigned char* lds, const Gemm g, const Sched& S, const Epi& E, const int wid  ) {
;     ...
;             PG8_LDA(At, 1, 1); PG8_STAGE(PG8_SB(1, 0), b3, voffB); PG8_STAGE(PG8_SB(1, 1), b3 + hstep, voffB); PG8_STAGE(PG8_SA(1, 0), a3, voffA);
;             PG8_WAIT_V(8); PG8_WAIT_L(0); PG8_BAR; PG8_MMA(1, 0, At, B0); PG8_MMA(1, 1, At, B1); PG8_BAR; PG8_SCHED;
	s_add_i32 s6, s19, s29
	v_lshl_add_u64 v[216:217], v[216:217], 0, s[70:71]
	s_mov_b32 m0, s6
	ds_read_b128 v[184:187], v165 offset:49152
	ds_read_b128 v[188:191], v165 offset:50176
	ds_read_b128 v[192:195], v165 offset:51200
	ds_read_b128 v[196:199], v165 offset:52224
	ds_read_b128 v[200:203], v165 offset:53248
	ds_read_b128 v[204:207], v165 offset:54272
	ds_read_b128 v[208:211], v165 offset:55296
	ds_read_b128 v[212:215], v165 offset:56320
	global_load_lds_dwordx4 v[216:217], off
	s_add_i32 m0, s6, 0x2000
	s_add_u32 s0, s0, 0x80080
	v_lshl_add_u64 v[216:217], v[218:219], 0, s[70:71]
	s_addc_u32 s1, s1, 0
	s_add_i32 s6, s24, s29
	global_load_lds_dwordx4 v[216:217], off
	v_lshl_add_u64 v[216:217], s[0:1], 0, v[132:133]
	s_mov_b32 m0, s6
	s_nop 0
	global_load_lds_dwordx4 v[216:217], off
	v_lshl_add_u64 v[216:217], s[0:1], 0, v[134:135]
	s_add_i32 m0, s6, 0x2000
	s_nop 0
	global_load_lds_dwordx4 v[216:217], off
	v_lshl_add_u64 v[216:217], v[220:221], 0, s[70:71]
	s_mov_b32 m0, s35
	s_nop 0
	global_load_lds_dwordx4 v[216:217], off
	v_lshl_add_u64 v[216:217], v[222:223], 0, s[70:71]
	s_mov_b32 m0, s47
	s_nop 0
	global_load_lds_dwordx4 v[216:217], off
	s_waitcnt vmcnt(8)
	s_waitcnt lgkmcnt(0)
	s_barrier
	s_setprio 1
	s_waitcnt lgkmcnt(0)
	v_mfma_f32_16x16x32_bf16 v[60:63], v[128:131], v[184:187], v[60:63]
	v_mfma_f32_16x16x32_bf16 v[60:63], v[146:149], v[188:191], v[60:63]
	v_mfma_f32_16x16x32_bf16 v[56:59], v[150:153], v[184:187], v[56:59]
	v_mfma_f32_16x16x32_bf16 v[56:59], v[154:157], v[188:191], v[56:59]
	v_mfma_f32_16x16x32_bf16 v[52:55], v[128:131], v[192:195], v[52:55]
	v_mfma_f32_16x16x32_bf16 v[52:55], v[146:149], v[196:199], v[52:55]
	v_mfma_f32_16x16x32_bf16 v[48:51], v[150:153], v[192:195], v[48:51]
	v_mfma_f32_16x16x32_bf16 v[48:51], v[154:157], v[196:199], v[48:51]
	v_mfma_f32_16x16x32_bf16 v[44:47], v[128:131], v[200:203], v[44:47]
	v_mfma_f32_16x16x32_bf16 v[44:47], v[146:149], v[204:207], v[44:47]
	v_mfma_f32_16x16x32_bf16 v[40:43], v[150:153], v[200:203], v[40:43]
	v_mfma_f32_16x16x32_bf16 v[40:43], v[154:157], v[204:207], v[40:43]
	v_mfma_f32_16x16x32_bf16 v[36:39], v[128:131], v[208:211], v[36:39]
	v_mfma_f32_16x16x32_bf16 v[36:39], v[146:149], v[212:215], v[36:39]
	v_mfma_f32_16x16x32_bf16 v[32:35], v[150:153], v[208:211], v[32:35]
	v_mfma_f32_16x16x32_bf16 v[32:35], v[154:157], v[212:215], v[32:35]
	s_setprio 0
	s_setprio 1
	v_mfma_f32_16x16x32_bf16 v[28:31], v[168:171], v[184:187], v[28:31]
	v_mfma_f32_16x16x32_bf16 v[28:31], v[172:175], v[188:191], v[28:31]
	v_mfma_f32_16x16x32_bf16 v[24:27], v[176:179], v[184:187], v[24:27]
	v_mfma_f32_16x16x32_bf16 v[24:27], v[180:183], v[188:191], v[24:27]
	v_mfma_f32_16x16x32_bf16 v[20:23], v[168:171], v[192:195], v[20:23]
	v_mfma_f32_16x16x32_bf16 v[20:23], v[172:175], v[196:199], v[20:23]
	v_mfma_f32_16x16x32_bf16 v[16:19], v[176:179], v[192:195], v[16:19]
	v_mfma_f32_16x16x32_bf16 v[16:19], v[180:183], v[196:199], v[16:19]
	v_mfma_f32_16x16x32_bf16 v[12:15], v[168:171], v[200:203], v[12:15]
	v_mfma_f32_16x16x32_bf16 v[12:15], v[172:175], v[204:207], v[12:15]
	v_mfma_f32_16x16x32_bf16 v[8:11], v[176:179], v[200:203], v[8:11]
	v_mfma_f32_16x16x32_bf16 v[8:11], v[180:183], v[204:207], v[8:11]
	v_mfma_f32_16x16x32_bf16 v[4:7], v[168:171], v[208:211], v[4:7]
	v_mfma_f32_16x16x32_bf16 v[4:7], v[172:175], v[212:215], v[4:7]
	v_mfma_f32_16x16x32_bf16 v[0:3], v[176:179], v[208:211], v[0:3]
	v_mfma_f32_16x16x32_bf16 v[0:3], v[180:183], v[212:215], v[0:3]
	s_setprio 0
	s_barrier
	s_add_i32 s0, s74, 2
	s_cmp_gt_u32 s74, 29
	s_cbranch_scc1 .LBB0_795
	s_mov_b32 s74, s0
	s_branch .LBB0_771

; #define PG8_STAGE(bufoff, gbase, voff) do { _Pragma("unroll") for (int _i = 0; _i < 2; ++_i) \
;         __builtin_amdgcn_global_load_lds((const unsigned*)((const char*)(gbase) + (voff)[_i]), (PG8_LAS unsigned*)(lds + (bufoff) + ldsw + _i * 8192), 16, 0, 0); } while (0)
; #define PG8_LDA(dst, b, h) do { _Pragma("unroll") for (int m = 0; m < 4; ++m) _Pragma("unroll") for (int k = 0; k < 2; ++k) dst[m][k] = *(const PG8_LAS bf16x8*)(lds + PG8_SA(b, h) + aoff + m * 2048 + k * 1024); } while (0)
; #define PG8_LDB(dst, b, h) do { _Pragma("unroll") for (int n = 0; n < 2; ++n) _Pragma("unroll") for (int k = 0; k < 2; ++k) dst[n][k] = *(const PG8_LAS bf16x8*)(lds + PG8_SB(b, h) + boff + n * 2048 + k * 1024); } while (0)
; #define PG8_MMA(ai, bj, At, Bt) do { __builtin_amdgcn_s_setprio(1); _Pragma("unroll") for (int m = 0; m < 4; ++m) _Pragma("unroll") for (int n = 0; n < 2; ++n) _Pragma("unroll") for (int k = 0; k < 2; ++k) \
;         acc[ai][bj][m][n] = __builtin_amdgcn_mfma_f32_16x16x32_bf16(Bt[n][k], At[m][k], acc[ai][bj][m][n], 0, 0, 0); __builtin_amdgcn_s_setprio(0); } while (0)
; #define PG8_WAIT_V(n) asm volatile("s_waitcnt vmcnt(" #n ")" ::: "memory")
; #define PG8_WAIT_L(n) asm volatile("s_waitcnt lgkmcnt(" #n ")" ::: "memory")
; template <class Epi, class Sched, bool ALIGN_EPI = false, bool SP2 = false, bool APERM = false  >
; __device__ __forceinline__ void gemm_phase(PG8_LAS unsigned char* lds, const Gemm g, const Sched& S, const Epi& E, const int wid  ) {
;     ...
;             const bool last = (t == nt - 2);
;             const char* a1 = cA + (size_t)(t + 1) * kstep;
;             const char* a2 = last ? nA : cA + (size_t)(t + 2) * kstep; const char* b2 = last ? nB : cB + (size_t)(t + 2) * kstep;
;             const char* a3 = a2 + kstep; const char* b3 = b2 + kstep;
;             if (last && has_next) S.a_ready(nxt);
;             if constexpr (SP2) {
;             PG8_LDB(B0, 0, 0); PG8_LDB(B1, 0, 1); PG8_SCHED; PG8_LDA(At, 0, 0); PG8_STAGE(PG8_SA(1, 1), a1 + hstep, voffA);
;             PG8_WAIT_V(8); PG8_WAIT_L(0); PG8_BAR; PG8_MMA(0, 0, At, B0); PG8_MMA(0, 1, At, B1); PG8_BAR; PG8_SCHED;
;             PG8_LDA(At, 0, 1); PG8_STAGE(PG8_SB(0, 0), b2, voffB); PG8_STAGE(PG8_SB(0, 1), b2 + hstep, voffB); PG8_STAGE(PG8_SA(0, 0), a2, voffA);
;             PG8_WAIT_V(8); PG8_WAIT_L(0); PG8_BAR; PG8_MMA(1, 0, At, B0); PG8_MMA(1, 1, At, B1); PG8_BAR; PG8_SCHED;
.LBB0_1019:
	v_add_u32_e32 v157, s92, v151
	ds_read_b128 v[146:149], v157
	ds_read_b128 v[158:161], v157 offset:1024
	ds_read_b128 v[162:165], v157 offset:2048
	ds_read_b128 v[166:169], v157 offset:3072
	v_add_u32_e32 v157, s93, v151
	s_add_u32 s65, s34, s78
	ds_read_b128 v[170:173], v157
	ds_read_b128 v[174:177], v157 offset:1024
	ds_read_b128 v[178:181], v157 offset:2048
	ds_read_b128 v[182:185], v157 offset:3072
	s_addc_u32 s73, s35, s79
	s_add_u32 s65, s65, 0x100
	s_addc_u32 s73, s73, 0
	s_add_u32 s80, s96, s78
	s_addc_u32 s81, s97, s79
	s_cmpk_eq_i32 s78, 0xf00
	s_cselect_b32 s83, s29, s73
	s_cselect_b32 s82, s33, s65
	s_cselect_b32 s81, s46, s81
	s_cselect_b32 s80, s47, s80
	v_lshl_add_u64 v[218:219], v[142:143], 0, s[78:79]
	s_add_i32 m0, s7, 0xc000
	ds_read_b128 v[186:189], v156
	ds_read_b128 v[190:193], v156 offset:1024
	ds_read_b128 v[194:197], v156 offset:2048
	ds_read_b128 v[198:201], v156 offset:3072
	ds_read_b128 v[202:205], v156 offset:4096
	ds_read_b128 v[206:209], v156 offset:5120
	ds_read_b128 v[210:213], v156 offset:6144
	ds_read_b128 v[214:217], v156 offset:7168
	global_load_lds_dwordx4 v[218:219], off
	v_lshl_add_u64 v[218:219], v[144:145], 0, s[78:79]
	s_add_i32 m0, s7, 0xe000
	s_nop 0
	global_load_lds_dwordx4 v[218:219], off
	s_waitcnt vmcnt(8)
	s_waitcnt lgkmcnt(0)
	s_barrier
	s_setprio 1
	s_waitcnt lgkmcnt(0)
	v_mfma_f32_16x16x32_bf16 v[124:127], v[146:149], v[186:189], v[124:127]
	v_mfma_f32_16x16x32_bf16 v[124:127], v[158:161], v[190:193], v[124:127]
	v_mfma_f32_16x16x32_bf16 v[120:123], v[162:165], v[186:189], v[120:123]
	v_mfma_f32_16x16x32_bf16 v[120:123], v[166:169], v[190:193], v[120:123]
	v_mfma_f32_16x16x32_bf16 v[116:119], v[146:149], v[194:197], v[116:119]
	v_mfma_f32_16x16x32_bf16 v[116:119], v[158:161], v[198:201], v[116:119]
	v_mfma_f32_16x16x32_bf16 v[112:115], v[162:165], v[194:197], v[112:115]
	v_mfma_f32_16x16x32_bf16 v[112:115], v[166:169], v[198:201], v[112:115]
	v_mfma_f32_16x16x32_bf16 v[108:111], v[146:149], v[202:205], v[108:111]
	v_mfma_f32_16x16x32_bf16 v[108:111], v[158:161], v[206:209], v[108:111]
	v_mfma_f32_16x16x32_bf16 v[104:107], v[162:165], v[202:205], v[104:107]
	v_mfma_f32_16x16x32_bf16 v[104:107], v[166:169], v[206:209], v[104:107]
	v_mfma_f32_16x16x32_bf16 v[100:103], v[146:149], v[210:213], v[100:103]
	v_mfma_f32_16x16x32_bf16 v[100:103], v[158:161], v[214:217], v[100:103]
	v_mfma_f32_16x16x32_bf16 v[96:99], v[162:165], v[210:213], v[96:99]
	v_mfma_f32_16x16x32_bf16 v[96:99], v[166:169], v[214:217], v[96:99]
	s_setprio 0
	s_setprio 1
	v_mfma_f32_16x16x32_bf16 v[92:95], v[170:173], v[186:189], v[92:95]
	v_mfma_f32_16x16x32_bf16 v[92:95], v[174:177], v[190:193], v[92:95]
	v_mfma_f32_16x16x32_bf16 v[88:91], v[178:181], v[186:189], v[88:91]
	v_mfma_f32_16x16x32_bf16 v[88:91], v[182:185], v[190:193], v[88:91]
	v_mfma_f32_16x16x32_bf16 v[84:87], v[170:173], v[194:197], v[84:87]
	v_mfma_f32_16x16x32_bf16 v[84:87], v[174:177], v[198:201], v[84:87]
	v_mfma_f32_16x16x32_bf16 v[80:83], v[178:181], v[194:197], v[80:83]
	v_mfma_f32_16x16x32_bf16 v[80:83], v[182:185], v[198:201], v[80:83]
	v_mfma_f32_16x16x32_bf16 v[76:79], v[170:173], v[202:205], v[76:79]
	v_mfma_f32_16x16x32_bf16 v[76:79], v[174:177], v[206:209], v[76:79]
	v_mfma_f32_16x16x32_bf16 v[72:75], v[178:181], v[202:205], v[72:75]
	v_mfma_f32_16x16x32_bf16 v[72:75], v[182:185], v[206:209], v[72:75]
	v_mfma_f32_16x16x32_bf16 v[68:71], v[170:173], v[210:213], v[68:71]
	v_mfma_f32_16x16x32_bf16 v[68:71], v[174:177], v[214:217], v[68:71]
	v_mfma_f32_16x16x32_bf16 v[64:67], v[178:181], v[210:213], v[64:67]
	v_mfma_f32_16x16x32_bf16 v[64:67], v[182:185], v[214:217], v[64:67]
	s_setprio 0
	s_barrier
	s_add_i32 s65, s92, s85
	v_lshl_add_u64 v[218:219], s[80:81], 0, v[130:131]
	s_mov_b32 m0, s65
	ds_read_b128 v[186:189], v156 offset:16384
	ds_read_b128 v[190:193], v156 offset:17408
	ds_read_b128 v[194:197], v156 offset:18432
	ds_read_b128 v[198:201], v156 offset:19456
	ds_read_b128 v[202:205], v156 offset:20480
	ds_read_b128 v[206:209], v156 offset:21504
	ds_read_b128 v[210:213], v156 offset:22528
	ds_read_b128 v[214:217], v156 offset:23552
	global_load_lds_dwordx4 v[218:219], off
	s_add_i32 m0, s65, 0x2000
	s_add_u32 vcc_lo, s80, 0x80000
	v_lshl_add_u64 v[220:221], s[80:81], 0, v[134:135]
	s_addc_u32 vcc_hi, s81, 0
	s_add_i32 s65, s93, s85
	global_load_lds_dwordx4 v[220:221], off
	v_lshl_add_u64 v[222:223], vcc, 0, v[130:131]
	s_mov_b32 m0, s65
	v_lshl_add_u64 v[224:225], s[82:83], 0, v[132:133]
	global_load_lds_dwordx4 v[222:223], off
	v_lshl_add_u64 v[222:223], vcc, 0, v[134:135]
	s_add_i32 m0, s65, 0x2000
	s_nop 0
	global_load_lds_dwordx4 v[222:223], off
	v_lshl_add_u64 v[222:223], s[82:83], 0, v[128:129]
	s_mov_b32 m0, s7
	s_nop 0
	global_load_lds_dwordx4 v[222:223], off
	s_mov_b32 m0, s9
	s_nop 0
	global_load_lds_dwordx4 v[224:225], off
	s_waitcnt vmcnt(8)
	s_waitcnt lgkmcnt(0)
	s_barrier
; #define PG8_STAGE(bufoff, gbase, voff) do { _Pragma("unroll") for (int _i = 0; _i < 2; ++_i) \
;         __builtin_amdgcn_global_load_lds((const unsigned*)((const char*)(gbase) + (voff)[_i]), (PG8_LAS unsigned*)(lds + (bufoff) + ldsw + _i * 8192), 16, 0, 0); } while (0)
; #define PG8_LDA(dst, b, h) do { _Pragma("unroll") for (int m = 0; m < 4; ++m) _Pragma("unroll") for (int k = 0; k < 2; ++k) dst[m][k] = *(const PG8_LAS bf16x8*)(lds + PG8_SA(b, h) + aoff + m * 2048 + k * 1024); } while (0)
; #define PG8_LDB(dst, b, h) do { _Pragma("unroll") for (int n = 0; n < 2; ++n) _Pragma("unroll") for (int k = 0; k < 2; ++k) dst[n][k] = *(const PG8_LAS bf16x8*)(lds + PG8_SB(b, h) + boff + n * 2048 + k * 1024); } while (0)
; #define PG8_MMA(ai, bj, At, Bt) do { __builtin_amdgcn_s_setprio(1); _Pragma("unroll") for (int m = 0; m < 4; ++m) _Pragma("unroll") for (int n = 0; n < 2; ++n) _Pragma("unroll") for (int k = 0; k < 2; ++k) \
;         acc[ai][bj][m][n] = __builtin_amdgcn_mfma_f32_16x16x32_bf16(Bt[n][k], At[m][k], acc[ai][bj][m][n], 0, 0, 0); __builtin_amdgcn_s_setprio(0); } while (0)
; #define PG8_WAIT_V(n) asm volatile("s_waitcnt vmcnt(" #n ")" ::: "memory")
; #define PG8_WAIT_L(n) asm volatile("s_waitcnt lgkmcnt(" #n ")" ::: "memory")
; #define PG8_BAR __builtin_amdgcn_s_barrier()
; #define PG8_SCHED __builtin_amdgcn_sched_barrier(0)
; template <class Epi, class Sched, bool ALIGN_EPI = false, bool SP2 = false, bool APERM = false  >
; __device__ __forceinline__ void gemm_phase(PG8_LAS unsigned char* lds, const Gemm g, const Sched& S, const Epi& E, const int wid  ) {
;     ...
;             PG8_WAIT_V(8); PG8_WAIT_L(0); PG8_BAR; PG8_MMA(1, 0, At, B0); PG8_MMA(1, 1, At, B1); PG8_BAR; PG8_SCHED;
;             PG8_LDB(B0, 1, 0); PG8_LDB(B1, 1, 1); PG8_SCHED; PG8_LDA(At, 1, 0); PG8_STAGE(PG8_SA(0, 1), a2 + hstep, voffA);
;             PG8_WAIT_V(8); PG8_WAIT_L(0); PG8_BAR; PG8_MMA(0, 0, At, B0); PG8_MMA(0, 1, At, B1); PG8_BAR; PG8_SCHED;
	s_setprio 1
	s_waitcnt lgkmcnt(0)
	v_mfma_f32_16x16x32_bf16 v[60:63], v[146:149], v[186:189], v[60:63]
	v_mfma_f32_16x16x32_bf16 v[60:63], v[158:161], v[190:193], v[60:63]
	v_mfma_f32_16x16x32_bf16 v[56:59], v[162:165], v[186:189], v[56:59]
	v_mfma_f32_16x16x32_bf16 v[56:59], v[166:169], v[190:193], v[56:59]
	v_mfma_f32_16x16x32_bf16 v[52:55], v[146:149], v[194:197], v[52:55]
	v_mfma_f32_16x16x32_bf16 v[52:55], v[158:161], v[198:201], v[52:55]
	v_mfma_f32_16x16x32_bf16 v[48:51], v[162:165], v[194:197], v[48:51]
	v_mfma_f32_16x16x32_bf16 v[48:51], v[166:169], v[198:201], v[48:51]
	v_mfma_f32_16x16x32_bf16 v[44:47], v[146:149], v[202:205], v[44:47]
	v_mfma_f32_16x16x32_bf16 v[44:47], v[158:161], v[206:209], v[44:47]
	v_mfma_f32_16x16x32_bf16 v[40:43], v[162:165], v[202:205], v[40:43]
	v_mfma_f32_16x16x32_bf16 v[40:43], v[166:169], v[206:209], v[40:43]
	v_mfma_f32_16x16x32_bf16 v[36:39], v[146:149], v[210:213], v[36:39]
	v_mfma_f32_16x16x32_bf16 v[36:39], v[158:161], v[214:217], v[36:39]
	v_mfma_f32_16x16x32_bf16 v[32:35], v[162:165], v[210:213], v[32:35]
	v_mfma_f32_16x16x32_bf16 v[32:35], v[166:169], v[214:217], v[32:35]
	s_setprio 0
	s_setprio 1
	v_mfma_f32_16x16x32_bf16 v[28:31], v[170:173], v[186:189], v[28:31]
	v_mfma_f32_16x16x32_bf16 v[28:31], v[174:177], v[190:193], v[28:31]
	v_mfma_f32_16x16x32_bf16 v[24:27], v[178:181], v[186:189], v[24:27]
	v_mfma_f32_16x16x32_bf16 v[24:27], v[182:185], v[190:193], v[24:27]
	v_mfma_f32_16x16x32_bf16 v[20:23], v[170:173], v[194:197], v[20:23]
	v_mfma_f32_16x16x32_bf16 v[20:23], v[174:177], v[198:201], v[20:23]
	v_mfma_f32_16x16x32_bf16 v[16:19], v[178:181], v[194:197], v[16:19]
	v_mfma_f32_16x16x32_bf16 v[16:19], v[182:185], v[198:201], v[16:19]
	v_mfma_f32_16x16x32_bf16 v[12:15], v[170:173], v[202:205], v[12:15]
	v_mfma_f32_16x16x32_bf16 v[12:15], v[174:177], v[206:209], v[12:15]
	v_mfma_f32_16x16x32_bf16 v[8:11], v[178:181], v[202:205], v[8:11]
	v_mfma_f32_16x16x32_bf16 v[8:11], v[182:185], v[206:209], v[8:11]
	v_mfma_f32_16x16x32_bf16 v[4:7], v[170:173], v[210:213], v[4:7]
	v_mfma_f32_16x16x32_bf16 v[4:7], v[174:177], v[214:217], v[4:7]
	v_mfma_f32_16x16x32_bf16 v[0:3], v[178:181], v[210:213], v[0:3]
	v_mfma_f32_16x16x32_bf16 v[0:3], v[182:185], v[214:217], v[0:3]
	s_setprio 0
	s_barrier
	s_add_i32 s65, 0, 0x18000
	v_add_u32_e32 v157, s65, v151
	s_add_i32 s73, 0, 0x1c000
	ds_read_b128 v[146:149], v157
	ds_read_b128 v[158:161], v157 offset:1024
	ds_read_b128 v[162:165], v157 offset:2048
	ds_read_b128 v[166:169], v157 offset:3072
	v_add_u32_e32 v157, s73, v151
	ds_read_b128 v[170:173], v157
	ds_read_b128 v[174:177], v157 offset:1024
	ds_read_b128 v[178:181], v157 offset:2048
	ds_read_b128 v[182:185], v157 offset:3072
	s_add_u32 s82, s82, 0x80000
	s_addc_u32 s83, s83, 0
	s_mov_b32 m0, s86
	v_lshl_add_u64 v[226:227], s[82:83], 0, v[128:129]
	ds_read_b128 v[186:189], v156 offset:32768
	ds_read_b128 v[190:193], v156 offset:33792
	ds_read_b128 v[194:197], v156 offset:34816
	ds_read_b128 v[198:201], v156 offset:35840
	ds_read_b128 v[202:205], v156 offset:36864
	ds_read_b128 v[206:209], v156 offset:37888
	ds_read_b128 v[210:213], v156 offset:38912
	ds_read_b128 v[214:217], v156 offset:39936
	global_load_lds_dwordx4 v[226:227], off
	v_lshl_add_u64 v[226:227], s[82:83], 0, v[132:133]
	s_mov_b32 m0, s87
	s_nop 0
	global_load_lds_dwordx4 v[226:227], off
	s_waitcnt vmcnt(8)
	s_waitcnt lgkmcnt(0)
	s_barrier
	s_setprio 1
	s_waitcnt lgkmcnt(0)
	v_mfma_f32_16x16x32_bf16 v[124:127], v[146:149], v[186:189], v[124:127]
	v_mfma_f32_16x16x32_bf16 v[124:127], v[158:161], v[190:193], v[124:127]
	v_mfma_f32_16x16x32_bf16 v[120:123], v[162:165], v[186:189], v[120:123]
	v_mfma_f32_16x16x32_bf16 v[120:123], v[166:169], v[190:193], v[120:123]
	v_mfma_f32_16x16x32_bf16 v[116:119], v[146:149], v[194:197], v[116:119]
	v_mfma_f32_16x16x32_bf16 v[116:119], v[158:161], v[198:201], v[116:119]
	v_mfma_f32_16x16x32_bf16 v[112:115], v[162:165], v[194:197], v[112:115]
	v_mfma_f32_16x16x32_bf16 v[112:115], v[166:169], v[198:201], v[112:115]
	v_mfma_f32_16x16x32_bf16 v[108:111], v[146:149], v[202:205], v[108:111]
	v_mfma_f32_16x16x32_bf16 v[108:111], v[158:161], v[206:209], v[108:111]
	v_mfma_f32_16x16x32_bf16 v[104:107], v[162:165], v[202:205], v[104:107]
	v_mfma_f32_16x16x32_bf16 v[104:107], v[166:169], v[206:209], v[104:107]
	v_mfma_f32_16x16x32_bf16 v[100:103], v[146:149], v[210:213], v[100:103]
	v_mfma_f32_16x16x32_bf16 v[100:103], v[158:161], v[214:217], v[100:103]
	v_mfma_f32_16x16x32_bf16 v[96:99], v[162:165], v[210:213], v[96:99]
	v_mfma_f32_16x16x32_bf16 v[96:99], v[166:169], v[214:217], v[96:99]
	s_setprio 0
	s_setprio 1
	v_mfma_f32_16x16x32_bf16 v[92:95], v[170:173], v[186:189], v[92:95]
	v_mfma_f32_16x16x32_bf16 v[92:95], v[174:177], v[190:193], v[92:95]
	v_mfma_f32_16x16x32_bf16 v[88:91], v[178:181], v[186:189], v[88:91]
	v_mfma_f32_16x16x32_bf16 v[88:91], v[182:185], v[190:193], v[88:91]
	v_mfma_f32_16x16x32_bf16 v[84:87], v[170:173], v[194:197], v[84:87]
	v_mfma_f32_16x16x32_bf16 v[84:87], v[174:177], v[198:201], v[84:87]
	v_mfma_f32_16x16x32_bf16 v[80:83], v[178:181], v[194:197], v[80:83]
	v_mfma_f32_16x16x32_bf16 v[80:83], v[182:185], v[198:201], v[80:83]
	v_mfma_f32_16x16x32_bf16 v[76:79], v[170:173], v[202:205], v[76:79]
	v_mfma_f32_16x16x32_bf16 v[76:79], v[174:177], v[206:209], v[76:79]
	v_mfma_f32_16x16x32_bf16 v[72:75], v[178:181], v[202:205], v[72:75]
	v_mfma_f32_16x16x32_bf16 v[72:75], v[182:185], v[206:209], v[72:75]
	v_mfma_f32_16x16x32_bf16 v[68:71], v[170:173], v[210:213], v[68:71]
	v_mfma_f32_16x16x32_bf16 v[68:71], v[174:177], v[214:217], v[68:71]
	v_mfma_f32_16x16x32_bf16 v[64:67], v[178:181], v[210:213], v[64:67]
	v_mfma_f32_16x16x32_bf16 v[64:67], v[182:185], v[214:217], v[64:67]
	s_setprio 0
	s_barrier
; #define PG8_STAGE(bufoff, gbase, voff) do { _Pragma("unroll") for (int _i = 0; _i < 2; ++_i) \
;         __builtin_amdgcn_global_load_lds((const unsigned*)((const char*)(gbase) + (voff)[_i]), (PG8_LAS unsigned*)(lds + (bufoff) + ldsw + _i * 8192), 16, 0, 0); } while (0)
; #define PG8_LDA(dst, b, h) do { _Pragma("unroll") for (int m = 0; m < 4; ++m) _Pragma("unroll") for (int k = 0; k < 2; ++k) dst[m][k] = *(const PG8_LAS bf16x8*)(lds + PG8_SA(b, h) + aoff + m * 2048 + k * 1024); } while (0)
; #define PG8_MMA(ai, bj, At, Bt) do { __builtin_amdgcn_s_setprio(1); _Pragma("unroll") for (int m = 0; m < 4; ++m) _Pragma("unroll") for (int n = 0; n < 2; ++n) _Pragma("unroll") for (int k = 0; k < 2; ++k) \
;         acc[ai][bj][m][n] = __builtin_amdgcn_mfma_f32_16x16x32_bf16(Bt[n][k], At[m][k], acc[ai][bj][m][n], 0, 0, 0); __builtin_amdgcn_s_setprio(0); } while (0)
; #define PG8_WAIT_V(n) asm volatile("s_waitcnt vmcnt(" #n ")" ::: "memory")
; #define PG8_WAIT_L(n) asm volatile("s_waitcnt lgkmcnt(" #n ")" ::: "memory")
; #define PG8_BAR __builtin_amdgcn_s_barrier()
; #define PG8_SCHED __builtin_amdgcn_sched_barrier(0)
; template <class Epi, class Sched, bool ALIGN_EPI = false, bool SP2 = false, bool APERM = false  >
; __device__ __forceinline__ void gemm_phase(PG8_LAS unsigned char* lds, const Gemm g, const Sched& S, const Epi& E, const int wid  ) {
;     ...
;             PG8_LDA(At, 1, 1); PG8_STAGE(PG8_SB(1, 0), b3, voffB); PG8_STAGE(PG8_SB(1, 1), b3 + hstep, voffB); PG8_STAGE(PG8_SA(1, 0), a3, voffA);
;             PG8_WAIT_V(8); PG8_WAIT_L(0); PG8_BAR; PG8_MMA(1, 0, At, B0); PG8_MMA(1, 1, At, B1); PG8_BAR; PG8_SCHED;
;     ...
;         if constexpr (ALIGN_EPI) { if (wr == 0) PG8_BAR; }
	s_add_i32 s65, s65, s85
	v_lshl_add_u64 v[218:219], v[218:219], 0, s[14:15]
	s_mov_b32 m0, s65
	ds_read_b128 v[186:189], v156 offset:49152
	ds_read_b128 v[190:193], v156 offset:50176
	ds_read_b128 v[194:197], v156 offset:51200
	ds_read_b128 v[198:201], v156 offset:52224
	ds_read_b128 v[202:205], v156 offset:53248
	ds_read_b128 v[206:209], v156 offset:54272
	ds_read_b128 v[210:213], v156 offset:55296
	ds_read_b128 v[214:217], v156 offset:56320
	global_load_lds_dwordx4 v[218:219], off
	s_add_i32 m0, s65, 0x2000
	s_add_u32 s80, s80, 0x80080
	v_lshl_add_u64 v[218:219], v[220:221], 0, s[14:15]
	s_addc_u32 s81, s81, 0
	s_add_i32 s65, s73, s85
	global_load_lds_dwordx4 v[218:219], off
	v_lshl_add_u64 v[218:219], s[80:81], 0, v[130:131]
	s_mov_b32 m0, s65
	s_nop 0
	global_load_lds_dwordx4 v[218:219], off
	v_lshl_add_u64 v[218:219], s[80:81], 0, v[134:135]
	s_add_i32 m0, s65, 0x2000
	s_nop 0
	global_load_lds_dwordx4 v[218:219], off
	v_lshl_add_u64 v[218:219], v[222:223], 0, s[14:15]
	s_mov_b32 m0, s90
	s_nop 0
	global_load_lds_dwordx4 v[218:219], off
	v_lshl_add_u64 v[218:219], v[224:225], 0, s[14:15]
	s_mov_b32 m0, s91
	s_nop 0
	global_load_lds_dwordx4 v[218:219], off
	s_waitcnt vmcnt(8)
	s_waitcnt lgkmcnt(0)
	s_barrier
	s_setprio 1
	s_waitcnt lgkmcnt(0)
	v_mfma_f32_16x16x32_bf16 v[60:63], v[146:149], v[186:189], v[60:63]
	v_mfma_f32_16x16x32_bf16 v[60:63], v[158:161], v[190:193], v[60:63]
	v_mfma_f32_16x16x32_bf16 v[56:59], v[162:165], v[186:189], v[56:59]
	v_mfma_f32_16x16x32_bf16 v[56:59], v[166:169], v[190:193], v[56:59]
	v_mfma_f32_16x16x32_bf16 v[52:55], v[146:149], v[194:197], v[52:55]
	v_mfma_f32_16x16x32_bf16 v[52:55], v[158:161], v[198:201], v[52:55]
	v_mfma_f32_16x16x32_bf16 v[48:51], v[162:165], v[194:197], v[48:51]
	v_mfma_f32_16x16x32_bf16 v[48:51], v[166:169], v[198:201], v[48:51]
	v_mfma_f32_16x16x32_bf16 v[44:47], v[146:149], v[202:205], v[44:47]
	v_mfma_f32_16x16x32_bf16 v[44:47], v[158:161], v[206:209], v[44:47]
	v_mfma_f32_16x16x32_bf16 v[40:43], v[162:165], v[202:205], v[40:43]
	v_mfma_f32_16x16x32_bf16 v[40:43], v[166:169], v[206:209], v[40:43]
	v_mfma_f32_16x16x32_bf16 v[36:39], v[146:149], v[210:213], v[36:39]
	v_mfma_f32_16x16x32_bf16 v[36:39], v[158:161], v[214:217], v[36:39]
	v_mfma_f32_16x16x32_bf16 v[32:35], v[162:165], v[210:213], v[32:35]
	v_mfma_f32_16x16x32_bf16 v[32:35], v[166:169], v[214:217], v[32:35]
	s_setprio 0
	s_setprio 1
	v_mfma_f32_16x16x32_bf16 v[28:31], v[170:173], v[186:189], v[28:31]
	v_mfma_f32_16x16x32_bf16 v[28:31], v[174:177], v[190:193], v[28:31]
	v_mfma_f32_16x16x32_bf16 v[24:27], v[178:181], v[186:189], v[24:27]
	v_mfma_f32_16x16x32_bf16 v[24:27], v[182:185], v[190:193], v[24:27]
	v_mfma_f32_16x16x32_bf16 v[20:23], v[170:173], v[194:197], v[20:23]
	v_mfma_f32_16x16x32_bf16 v[20:23], v[174:177], v[198:201], v[20:23]
	v_mfma_f32_16x16x32_bf16 v[16:19], v[178:181], v[194:197], v[16:19]
	v_mfma_f32_16x16x32_bf16 v[16:19], v[182:185], v[198:201], v[16:19]
	v_mfma_f32_16x16x32_bf16 v[12:15], v[170:173], v[202:205], v[12:15]
	v_mfma_f32_16x16x32_bf16 v[12:15], v[174:177], v[206:209], v[12:15]
	v_mfma_f32_16x16x32_bf16 v[8:11], v[178:181], v[202:205], v[8:11]
	v_mfma_f32_16x16x32_bf16 v[8:11], v[182:185], v[206:209], v[8:11]
	v_mfma_f32_16x16x32_bf16 v[4:7], v[170:173], v[210:213], v[4:7]
	v_mfma_f32_16x16x32_bf16 v[4:7], v[174:177], v[214:217], v[4:7]
	v_mfma_f32_16x16x32_bf16 v[0:3], v[178:181], v[210:213], v[0:3]
	v_mfma_f32_16x16x32_bf16 v[0:3], v[182:185], v[214:217], v[0:3]
	s_setprio 0
	s_barrier
	s_add_i32 s64, s64, 2
	s_add_u32 s78, s78, 0x100
	s_addc_u32 s79, s79, 0
	s_cmp_gt_u32 s64, 29
	s_cbranch_scc0 .LBB0_1019
	s_and_b64 vcc, exec, s[16:17]
	s_cbranch_vccz .LBB0_1022
	s_barrier

; #define PG8_STAGE(bufoff, gbase, voff) do { _Pragma("unroll") for (int _i = 0; _i < 2; ++_i) \
;         __builtin_amdgcn_global_load_lds((const unsigned*)((const char*)(gbase) + (voff)[_i]), (PG8_LAS unsigned*)(lds + (bufoff) + ldsw + _i * 8192), 16, 0, 0); } while (0)
; #define PG8_LDA(dst, b, h) do { _Pragma("unroll") for (int m = 0; m < 4; ++m) _Pragma("unroll") for (int k = 0; k < 2; ++k) dst[m][k] = *(const PG8_LAS bf16x8*)(lds + PG8_SA(b, h) + aoff + m * 2048 + k * 1024); } while (0)
; #define PG8_LDB(dst, b, h) do { _Pragma("unroll") for (int n = 0; n < 2; ++n) _Pragma("unroll") for (int k = 0; k < 2; ++k) dst[n][k] = *(const PG8_LAS bf16x8*)(lds + PG8_SB(b, h) + boff + n * 2048 + k * 1024); } while (0)
; #define PG8_MMA(ai, bj, At, Bt) do { __builtin_amdgcn_s_setprio(1); _Pragma("unroll") for (int m = 0; m < 4; ++m) _Pragma("unroll") for (int n = 0; n < 2; ++n) _Pragma("unroll") for (int k = 0; k < 2; ++k) \
;         acc[ai][bj][m][n] = __builtin_amdgcn_mfma_f32_16x16x32_bf16(Bt[n][k], At[m][k], acc[ai][bj][m][n], 0, 0, 0); __builtin_amdgcn_s_setprio(0); } while (0)
; #define PG8_WAIT_V(n) asm volatile("s_waitcnt vmcnt(" #n ")" ::: "memory")
; #define PG8_WAIT_L(n) asm volatile("s_waitcnt lgkmcnt(" #n ")" ::: "memory")
; template <class Epi, class Sched, bool ALIGN_EPI = false, bool SP2 = false, bool APERM = false  >
; __device__ __forceinline__ void gemm_phase(PG8_LAS unsigned char* lds, const Gemm g, const Sched& S, const Epi& E, const int wid  ) {
;     ...
;             const bool last = (t == nt - 2);
;             const char* a1 = cA + (size_t)(t + 1) * kstep;
;             const char* a2 = last ? nA : cA + (size_t)(t + 2) * kstep; const char* b2 = last ? nB : cB + (size_t)(t + 2) * kstep;
;             const char* a3 = a2 + kstep; const char* b3 = b2 + kstep;
;             if (last && has_next) S.a_ready(nxt);
;             if constexpr (SP2) {
;             PG8_LDB(B0, 0, 0); PG8_LDB(B1, 0, 1); PG8_SCHED; PG8_LDA(At, 0, 0); PG8_STAGE(PG8_SA(1, 1), a1 + hstep, voffA);
;             PG8_WAIT_V(8); PG8_WAIT_L(0); PG8_BAR; PG8_MMA(0, 0, At, B0); PG8_MMA(0, 1, At, B1); PG8_BAR; PG8_SCHED;
;             PG8_LDA(At, 0, 1); PG8_STAGE(PG8_SB(0, 0), b2, voffB); PG8_STAGE(PG8_SB(0, 1), b2 + hstep, voffB); PG8_STAGE(PG8_SA(0, 0), a2, voffA);
;             PG8_WAIT_V(8); PG8_WAIT_L(0); PG8_BAR; PG8_MMA(1, 0, At, B0); PG8_MMA(1, 1, At, B1); PG8_BAR; PG8_SCHED;
.LBB0_1099:
	s_lshl_b32 s30, s69, 7
	s_add_u32 s31, s44, s30
	s_addc_u32 s46, s45, 0
	s_add_u32 s14, s31, 0x100
	s_addc_u32 s15, s46, 0
	v_add_u32_e32 v140, s49, v235
	v_add_u32_e32 v156, s62, v235
	s_and_b64 s[10:11], s[12:13], exec
	ds_read_b128 v[128:131], v140
	ds_read_b128 v[132:135], v140 offset:1024
	ds_read_b128 v[136:139], v140 offset:2048
	ds_read_b128 v[140:143], v140 offset:3072
	ds_read_b128 v[144:147], v156
	ds_read_b128 v[148:151], v156 offset:1024
	ds_read_b128 v[152:155], v156 offset:2048
	ds_read_b128 v[156:159], v156 offset:3072
	s_cselect_b32 s15, s8, s15
	s_cselect_b32 s14, s9, s14
	s_add_u32 s10, s36, s30
	s_addc_u32 s11, s37, 0
	s_add_u32 s30, s10, 0x100
	s_addc_u32 s47, s11, 0
	s_and_b64 s[10:11], s[12:13], exec
	s_cselect_b32 s10, s68, s30
	s_cselect_b32 s11, s33, s47
	s_add_u32 s12, s31, 0x80080
	s_addc_u32 s13, s46, 0
	v_lshl_add_u64 v[206:207], s[12:13], 0, v[188:189]
	s_add_i32 m0, s35, 0xc000
	ds_read_b128 v[160:163], v247
	ds_read_b128 v[164:167], v247 offset:1024
	ds_read_b128 v[168:171], v247 offset:2048
	ds_read_b128 v[172:175], v247 offset:3072
	ds_read_b128 v[176:179], v247 offset:4096
	ds_read_b128 v[180:183], v247 offset:5120
	ds_read_b128 v[198:201], v247 offset:6144
	ds_read_b128 v[202:205], v247 offset:7168
	global_load_lds_dwordx4 v[206:207], off
	v_lshl_add_u64 v[206:207], s[12:13], 0, v[190:191]
	s_add_i32 m0, s35, 0xe000
	s_nop 0
	global_load_lds_dwordx4 v[206:207], off
	s_waitcnt vmcnt(8)
	s_waitcnt lgkmcnt(0)
	s_barrier
	s_setprio 1
	s_waitcnt lgkmcnt(0)
	v_mfma_f32_16x16x32_bf16 v[124:127], v[128:131], v[160:163], v[124:127]
	v_mfma_f32_16x16x32_bf16 v[124:127], v[132:135], v[164:167], v[124:127]
	v_mfma_f32_16x16x32_bf16 v[120:123], v[136:139], v[160:163], v[120:123]
	v_mfma_f32_16x16x32_bf16 v[120:123], v[140:143], v[164:167], v[120:123]
	v_mfma_f32_16x16x32_bf16 v[116:119], v[128:131], v[168:171], v[116:119]
	v_mfma_f32_16x16x32_bf16 v[116:119], v[132:135], v[172:175], v[116:119]
	v_mfma_f32_16x16x32_bf16 v[112:115], v[136:139], v[168:171], v[112:115]
	v_mfma_f32_16x16x32_bf16 v[112:115], v[140:143], v[172:175], v[112:115]
	v_mfma_f32_16x16x32_bf16 v[108:111], v[128:131], v[176:179], v[108:111]
	v_mfma_f32_16x16x32_bf16 v[108:111], v[132:135], v[180:183], v[108:111]
	v_mfma_f32_16x16x32_bf16 v[104:107], v[136:139], v[176:179], v[104:107]
	v_mfma_f32_16x16x32_bf16 v[104:107], v[140:143], v[180:183], v[104:107]
	v_mfma_f32_16x16x32_bf16 v[100:103], v[128:131], v[198:201], v[100:103]
	v_mfma_f32_16x16x32_bf16 v[100:103], v[132:135], v[202:205], v[100:103]
	v_mfma_f32_16x16x32_bf16 v[96:99], v[136:139], v[198:201], v[96:99]
	v_mfma_f32_16x16x32_bf16 v[96:99], v[140:143], v[202:205], v[96:99]
	s_setprio 0
	s_setprio 1
	v_mfma_f32_16x16x32_bf16 v[92:95], v[144:147], v[160:163], v[92:95]
	v_mfma_f32_16x16x32_bf16 v[92:95], v[148:151], v[164:167], v[92:95]
	v_mfma_f32_16x16x32_bf16 v[88:91], v[152:155], v[160:163], v[88:91]
	v_mfma_f32_16x16x32_bf16 v[88:91], v[156:159], v[164:167], v[88:91]
	v_mfma_f32_16x16x32_bf16 v[84:87], v[144:147], v[168:171], v[84:87]
	v_mfma_f32_16x16x32_bf16 v[84:87], v[148:151], v[172:175], v[84:87]
	v_mfma_f32_16x16x32_bf16 v[80:83], v[152:155], v[168:171], v[80:83]
	v_mfma_f32_16x16x32_bf16 v[80:83], v[156:159], v[172:175], v[80:83]
	v_mfma_f32_16x16x32_bf16 v[76:79], v[144:147], v[176:179], v[76:79]
	v_mfma_f32_16x16x32_bf16 v[76:79], v[148:151], v[180:183], v[76:79]
	v_mfma_f32_16x16x32_bf16 v[72:75], v[152:155], v[176:179], v[72:75]
	v_mfma_f32_16x16x32_bf16 v[72:75], v[156:159], v[180:183], v[72:75]
	v_mfma_f32_16x16x32_bf16 v[68:71], v[144:147], v[198:201], v[68:71]
	v_mfma_f32_16x16x32_bf16 v[68:71], v[148:151], v[202:205], v[68:71]
	v_mfma_f32_16x16x32_bf16 v[64:67], v[152:155], v[198:201], v[64:67]
	v_mfma_f32_16x16x32_bf16 v[64:67], v[156:159], v[202:205], v[64:67]
	s_setprio 0
	s_barrier
	s_add_i32 s12, s49, s96
	v_lshl_add_u64 v[206:207], s[10:11], 0, v[184:185]
	s_mov_b32 m0, s12
	ds_read_b128 v[160:163], v247 offset:16384
	ds_read_b128 v[164:167], v247 offset:17408
	ds_read_b128 v[168:171], v247 offset:18432
	ds_read_b128 v[172:175], v247 offset:19456
	ds_read_b128 v[176:179], v247 offset:20480
	ds_read_b128 v[180:183], v247 offset:21504
	ds_read_b128 v[198:201], v247 offset:22528
	ds_read_b128 v[202:205], v247 offset:23552
	global_load_lds_dwordx4 v[206:207], off
	s_add_i32 m0, s12, 0x2000
	s_add_u32 s12, s10, 0x80000
	v_lshl_add_u64 v[208:209], s[10:11], 0, v[186:187]
	s_addc_u32 s13, s11, 0
	s_add_i32 s30, s62, s96
	global_load_lds_dwordx4 v[208:209], off
	v_lshl_add_u64 v[210:211], s[12:13], 0, v[184:185]
	s_mov_b32 m0, s30
	v_lshl_add_u64 v[212:213], s[14:15], 0, v[190:191]
	global_load_lds_dwordx4 v[210:211], off
	v_lshl_add_u64 v[210:211], s[12:13], 0, v[186:187]
	s_add_i32 m0, s30, 0x2000
	s_nop 0
	global_load_lds_dwordx4 v[210:211], off
	v_lshl_add_u64 v[210:211], s[14:15], 0, v[188:189]
	s_mov_b32 m0, s35
	s_nop 0
	global_load_lds_dwordx4 v[210:211], off
	s_mov_b32 m0, s2
	s_nop 0
	global_load_lds_dwordx4 v[212:213], off
	s_waitcnt vmcnt(8)
	s_waitcnt lgkmcnt(0)
	s_barrier
; #define PG8_STAGE(bufoff, gbase, voff) do { _Pragma("unroll") for (int _i = 0; _i < 2; ++_i) \
;         __builtin_amdgcn_global_load_lds((const unsigned*)((const char*)(gbase) + (voff)[_i]), (PG8_LAS unsigned*)(lds + (bufoff) + ldsw + _i * 8192), 16, 0, 0); } while (0)
; #define PG8_LDA(dst, b, h) do { _Pragma("unroll") for (int m = 0; m < 4; ++m) _Pragma("unroll") for (int k = 0; k < 2; ++k) dst[m][k] = *(const PG8_LAS bf16x8*)(lds + PG8_SA(b, h) + aoff + m * 2048 + k * 1024); } while (0)
; #define PG8_LDB(dst, b, h) do { _Pragma("unroll") for (int n = 0; n < 2; ++n) _Pragma("unroll") for (int k = 0; k < 2; ++k) dst[n][k] = *(const PG8_LAS bf16x8*)(lds + PG8_SB(b, h) + boff + n * 2048 + k * 1024); } while (0)
; #define PG8_MMA(ai, bj, At, Bt) do { __builtin_amdgcn_s_setprio(1); _Pragma("unroll") for (int m = 0; m < 4; ++m) _Pragma("unroll") for (int n = 0; n < 2; ++n) _Pragma("unroll") for (int k = 0; k < 2; ++k) \
;         acc[ai][bj][m][n] = __builtin_amdgcn_mfma_f32_16x16x32_bf16(Bt[n][k], At[m][k], acc[ai][bj][m][n], 0, 0, 0); __builtin_amdgcn_s_setprio(0); } while (0)
; #define PG8_WAIT_V(n) asm volatile("s_waitcnt vmcnt(" #n ")" ::: "memory")
; #define PG8_WAIT_L(n) asm volatile("s_waitcnt lgkmcnt(" #n ")" ::: "memory")
; #define PG8_BAR __builtin_amdgcn_s_barrier()
; #define PG8_SCHED __builtin_amdgcn_sched_barrier(0)
; template <class Epi, class Sched, bool ALIGN_EPI = false, bool SP2 = false, bool APERM = false  >
; __device__ __forceinline__ void gemm_phase(PG8_LAS unsigned char* lds, const Gemm g, const Sched& S, const Epi& E, const int wid  ) {
;     ...
;             PG8_WAIT_V(8); PG8_WAIT_L(0); PG8_BAR; PG8_MMA(1, 0, At, B0); PG8_MMA(1, 1, At, B1); PG8_BAR; PG8_SCHED;
;             PG8_LDB(B0, 1, 0); PG8_LDB(B1, 1, 1); PG8_SCHED; PG8_LDA(At, 1, 0); PG8_STAGE(PG8_SA(0, 1), a2 + hstep, voffA);
;             PG8_WAIT_V(8); PG8_WAIT_L(0); PG8_BAR; PG8_MMA(0, 0, At, B0); PG8_MMA(0, 1, At, B1); PG8_BAR; PG8_SCHED;
	s_setprio 1
	s_waitcnt lgkmcnt(0)
	v_mfma_f32_16x16x32_bf16 v[60:63], v[128:131], v[160:163], v[60:63]
	v_mfma_f32_16x16x32_bf16 v[60:63], v[132:135], v[164:167], v[60:63]
	v_mfma_f32_16x16x32_bf16 v[56:59], v[136:139], v[160:163], v[56:59]
	v_mfma_f32_16x16x32_bf16 v[56:59], v[140:143], v[164:167], v[56:59]
	v_mfma_f32_16x16x32_bf16 v[52:55], v[128:131], v[168:171], v[52:55]
	v_mfma_f32_16x16x32_bf16 v[52:55], v[132:135], v[172:175], v[52:55]
	v_mfma_f32_16x16x32_bf16 v[48:51], v[136:139], v[168:171], v[48:51]
	v_mfma_f32_16x16x32_bf16 v[48:51], v[140:143], v[172:175], v[48:51]
	v_mfma_f32_16x16x32_bf16 v[44:47], v[128:131], v[176:179], v[44:47]
	v_mfma_f32_16x16x32_bf16 v[44:47], v[132:135], v[180:183], v[44:47]
	v_mfma_f32_16x16x32_bf16 v[40:43], v[136:139], v[176:179], v[40:43]
	v_mfma_f32_16x16x32_bf16 v[40:43], v[140:143], v[180:183], v[40:43]
	v_mfma_f32_16x16x32_bf16 v[36:39], v[128:131], v[198:201], v[36:39]
	v_mfma_f32_16x16x32_bf16 v[36:39], v[132:135], v[202:205], v[36:39]
	v_mfma_f32_16x16x32_bf16 v[32:35], v[136:139], v[198:201], v[32:35]
	v_mfma_f32_16x16x32_bf16 v[32:35], v[140:143], v[202:205], v[32:35]
	s_setprio 0
	s_setprio 1
	v_mfma_f32_16x16x32_bf16 v[28:31], v[144:147], v[160:163], v[28:31]
	v_mfma_f32_16x16x32_bf16 v[28:31], v[148:151], v[164:167], v[28:31]
	v_mfma_f32_16x16x32_bf16 v[24:27], v[152:155], v[160:163], v[24:27]
	v_mfma_f32_16x16x32_bf16 v[24:27], v[156:159], v[164:167], v[24:27]
	v_mfma_f32_16x16x32_bf16 v[20:23], v[144:147], v[168:171], v[20:23]
	v_mfma_f32_16x16x32_bf16 v[20:23], v[148:151], v[172:175], v[20:23]
	v_mfma_f32_16x16x32_bf16 v[16:19], v[152:155], v[168:171], v[16:19]
	v_mfma_f32_16x16x32_bf16 v[16:19], v[156:159], v[172:175], v[16:19]
	v_mfma_f32_16x16x32_bf16 v[12:15], v[144:147], v[176:179], v[12:15]
	v_mfma_f32_16x16x32_bf16 v[12:15], v[148:151], v[180:183], v[12:15]
	v_mfma_f32_16x16x32_bf16 v[8:11], v[152:155], v[176:179], v[8:11]
	v_mfma_f32_16x16x32_bf16 v[8:11], v[156:159], v[180:183], v[8:11]
	v_mfma_f32_16x16x32_bf16 v[4:7], v[144:147], v[198:201], v[4:7]
	v_mfma_f32_16x16x32_bf16 v[4:7], v[148:151], v[202:205], v[4:7]
	v_mfma_f32_16x16x32_bf16 v[0:3], v[152:155], v[198:201], v[0:3]
	v_mfma_f32_16x16x32_bf16 v[0:3], v[156:159], v[202:205], v[0:3]
	s_setprio 0
	s_barrier
	s_add_i32 s30, 0, 0x18000
	s_add_i32 s31, 0, 0x1c000
	v_add_u32_e32 v140, s30, v235
	v_add_u32_e32 v156, s31, v235
	ds_read_b128 v[128:131], v140
	ds_read_b128 v[132:135], v140 offset:1024
	ds_read_b128 v[136:139], v140 offset:2048
	ds_read_b128 v[140:143], v140 offset:3072
	ds_read_b128 v[144:147], v156
	ds_read_b128 v[148:151], v156 offset:1024
	ds_read_b128 v[152:155], v156 offset:2048
	ds_read_b128 v[156:159], v156 offset:3072
	s_add_u32 s12, s14, 0x80000
	s_addc_u32 s13, s15, 0
	s_mov_b32 m0, s3
	v_lshl_add_u64 v[214:215], s[12:13], 0, v[188:189]
	ds_read_b128 v[160:163], v247 offset:32768
	ds_read_b128 v[164:167], v247 offset:33792
	ds_read_b128 v[168:171], v247 offset:34816
	ds_read_b128 v[172:175], v247 offset:35840
	ds_read_b128 v[176:179], v247 offset:36864
	ds_read_b128 v[180:183], v247 offset:37888
	ds_read_b128 v[198:201], v247 offset:38912
	ds_read_b128 v[202:205], v247 offset:39936
	global_load_lds_dwordx4 v[214:215], off
	v_lshl_add_u64 v[214:215], s[12:13], 0, v[190:191]
	s_mov_b32 m0, s52
	s_nop 0
	global_load_lds_dwordx4 v[214:215], off
	s_waitcnt vmcnt(8)
	s_waitcnt lgkmcnt(0)
	s_barrier
	s_setprio 1
	s_waitcnt lgkmcnt(0)
	v_mfma_f32_16x16x32_bf16 v[124:127], v[128:131], v[160:163], v[124:127]
	v_mfma_f32_16x16x32_bf16 v[124:127], v[132:135], v[164:167], v[124:127]
	v_mfma_f32_16x16x32_bf16 v[120:123], v[136:139], v[160:163], v[120:123]
	v_mfma_f32_16x16x32_bf16 v[120:123], v[140:143], v[164:167], v[120:123]
	v_mfma_f32_16x16x32_bf16 v[116:119], v[128:131], v[168:171], v[116:119]
	v_mfma_f32_16x16x32_bf16 v[116:119], v[132:135], v[172:175], v[116:119]
	v_mfma_f32_16x16x32_bf16 v[112:115], v[136:139], v[168:171], v[112:115]
	v_mfma_f32_16x16x32_bf16 v[112:115], v[140:143], v[172:175], v[112:115]
	v_mfma_f32_16x16x32_bf16 v[108:111], v[128:131], v[176:179], v[108:111]
	v_mfma_f32_16x16x32_bf16 v[108:111], v[132:135], v[180:183], v[108:111]
	v_mfma_f32_16x16x32_bf16 v[104:107], v[136:139], v[176:179], v[104:107]
	v_mfma_f32_16x16x32_bf16 v[104:107], v[140:143], v[180:183], v[104:107]
	v_mfma_f32_16x16x32_bf16 v[100:103], v[128:131], v[198:201], v[100:103]
	v_mfma_f32_16x16x32_bf16 v[100:103], v[132:135], v[202:205], v[100:103]
	v_mfma_f32_16x16x32_bf16 v[96:99], v[136:139], v[198:201], v[96:99]
	v_mfma_f32_16x16x32_bf16 v[96:99], v[140:143], v[202:205], v[96:99]
	s_setprio 0
	s_setprio 1
	v_mfma_f32_16x16x32_bf16 v[92:95], v[144:147], v[160:163], v[92:95]
	v_mfma_f32_16x16x32_bf16 v[92:95], v[148:151], v[164:167], v[92:95]
	v_mfma_f32_16x16x32_bf16 v[88:91], v[152:155], v[160:163], v[88:91]
	v_mfma_f32_16x16x32_bf16 v[88:91], v[156:159], v[164:167], v[88:91]
	v_mfma_f32_16x16x32_bf16 v[84:87], v[144:147], v[168:171], v[84:87]
	v_mfma_f32_16x16x32_bf16 v[84:87], v[148:151], v[172:175], v[84:87]
	v_mfma_f32_16x16x32_bf16 v[80:83], v[152:155], v[168:171], v[80:83]
	v_mfma_f32_16x16x32_bf16 v[80:83], v[156:159], v[172:175], v[80:83]
	v_mfma_f32_16x16x32_bf16 v[76:79], v[144:147], v[176:179], v[76:79]
	v_mfma_f32_16x16x32_bf16 v[76:79], v[148:151], v[180:183], v[76:79]
	v_mfma_f32_16x16x32_bf16 v[72:75], v[152:155], v[176:179], v[72:75]
	v_mfma_f32_16x16x32_bf16 v[72:75], v[156:159], v[180:183], v[72:75]
	v_mfma_f32_16x16x32_bf16 v[68:71], v[144:147], v[198:201], v[68:71]
	v_mfma_f32_16x16x32_bf16 v[68:71], v[148:151], v[202:205], v[68:71]
	v_mfma_f32_16x16x32_bf16 v[64:67], v[152:155], v[198:201], v[64:67]
	v_mfma_f32_16x16x32_bf16 v[64:67], v[156:159], v[202:205], v[64:67]
	s_setprio 0
	s_barrier
; #define PG8_STAGE(bufoff, gbase, voff) do { _Pragma("unroll") for (int _i = 0; _i < 2; ++_i) \
;         __builtin_amdgcn_global_load_lds((const unsigned*)((const char*)(gbase) + (voff)[_i]), (PG8_LAS unsigned*)(lds + (bufoff) + ldsw + _i * 8192), 16, 0, 0); } while (0)
; #define PG8_LDA(dst, b, h) do { _Pragma("unroll") for (int m = 0; m < 4; ++m) _Pragma("unroll") for (int k = 0; k < 2; ++k) dst[m][k] = *(const PG8_LAS bf16x8*)(lds + PG8_SA(b, h) + aoff + m * 2048 + k * 1024); } while (0)
; #define PG8_MMA(ai, bj, At, Bt) do { __builtin_amdgcn_s_setprio(1); _Pragma("unroll") for (int m = 0; m < 4; ++m) _Pragma("unroll") for (int n = 0; n < 2; ++n) _Pragma("unroll") for (int k = 0; k < 2; ++k) \
;         acc[ai][bj][m][n] = __builtin_amdgcn_mfma_f32_16x16x32_bf16(Bt[n][k], At[m][k], acc[ai][bj][m][n], 0, 0, 0); __builtin_amdgcn_s_setprio(0); } while (0)
; #define PG8_WAIT_V(n) asm volatile("s_waitcnt vmcnt(" #n ")" ::: "memory")
; #define PG8_WAIT_L(n) asm volatile("s_waitcnt lgkmcnt(" #n ")" ::: "memory")
; #define PG8_BAR __builtin_amdgcn_s_barrier()
; #define PG8_SCHED __builtin_amdgcn_sched_barrier(0)
; template <class Epi, class Sched, bool ALIGN_EPI = false, bool SP2 = false, bool APERM = false  >
; __device__ __forceinline__ void gemm_phase(PG8_LAS unsigned char* lds, const Gemm g, const Sched& S, const Epi& E, const int wid  ) {
;     ...
;             PG8_LDA(At, 1, 1); PG8_STAGE(PG8_SB(1, 0), b3, voffB); PG8_STAGE(PG8_SB(1, 1), b3 + hstep, voffB); PG8_STAGE(PG8_SA(1, 0), a3, voffA);
;             PG8_WAIT_V(8); PG8_WAIT_L(0); PG8_BAR; PG8_MMA(1, 0, At, B0); PG8_MMA(1, 1, At, B1); PG8_BAR; PG8_SCHED;
	s_add_i32 s12, s30, s96
	v_lshl_add_u64 v[206:207], v[206:207], 0, s[64:65]
	s_mov_b32 m0, s12
	ds_read_b128 v[160:163], v247 offset:49152
	ds_read_b128 v[164:167], v247 offset:50176
	ds_read_b128 v[168:171], v247 offset:51200
	ds_read_b128 v[172:175], v247 offset:52224
	ds_read_b128 v[176:179], v247 offset:53248
	ds_read_b128 v[180:183], v247 offset:54272
	ds_read_b128 v[198:201], v247 offset:55296
	ds_read_b128 v[202:205], v247 offset:56320
	global_load_lds_dwordx4 v[206:207], off
	s_add_i32 m0, s12, 0x2000
	s_add_u32 s10, s10, 0x80080
	v_lshl_add_u64 v[206:207], v[208:209], 0, s[64:65]
	s_addc_u32 s11, s11, 0
	s_add_i32 s12, s31, s96
	global_load_lds_dwordx4 v[206:207], off
	v_lshl_add_u64 v[206:207], s[10:11], 0, v[184:185]
	s_mov_b32 m0, s12
	s_nop 0
	global_load_lds_dwordx4 v[206:207], off
	v_lshl_add_u64 v[206:207], s[10:11], 0, v[186:187]
	s_add_i32 m0, s12, 0x2000
	s_nop 0
	global_load_lds_dwordx4 v[206:207], off
	v_lshl_add_u64 v[206:207], v[210:211], 0, s[64:65]
	s_mov_b32 m0, s58
	s_nop 0
	global_load_lds_dwordx4 v[206:207], off
	v_lshl_add_u64 v[206:207], v[212:213], 0, s[64:65]
	s_mov_b32 m0, s59
	s_nop 0
	global_load_lds_dwordx4 v[206:207], off
	s_waitcnt vmcnt(8)
	s_waitcnt lgkmcnt(0)
	s_barrier
	s_setprio 1
	s_waitcnt lgkmcnt(0)
	v_mfma_f32_16x16x32_bf16 v[60:63], v[128:131], v[160:163], v[60:63]
	v_mfma_f32_16x16x32_bf16 v[60:63], v[132:135], v[164:167], v[60:63]
	v_mfma_f32_16x16x32_bf16 v[56:59], v[136:139], v[160:163], v[56:59]
	v_mfma_f32_16x16x32_bf16 v[56:59], v[140:143], v[164:167], v[56:59]
	v_mfma_f32_16x16x32_bf16 v[52:55], v[128:131], v[168:171], v[52:55]
	v_mfma_f32_16x16x32_bf16 v[52:55], v[132:135], v[172:175], v[52:55]
	v_mfma_f32_16x16x32_bf16 v[48:51], v[136:139], v[168:171], v[48:51]
	v_mfma_f32_16x16x32_bf16 v[48:51], v[140:143], v[172:175], v[48:51]
	v_mfma_f32_16x16x32_bf16 v[44:47], v[128:131], v[176:179], v[44:47]
	v_mfma_f32_16x16x32_bf16 v[44:47], v[132:135], v[180:183], v[44:47]
	v_mfma_f32_16x16x32_bf16 v[40:43], v[136:139], v[176:179], v[40:43]
	v_mfma_f32_16x16x32_bf16 v[40:43], v[140:143], v[180:183], v[40:43]
	v_mfma_f32_16x16x32_bf16 v[36:39], v[128:131], v[198:201], v[36:39]
	v_mfma_f32_16x16x32_bf16 v[36:39], v[132:135], v[202:205], v[36:39]
	v_mfma_f32_16x16x32_bf16 v[32:35], v[136:139], v[198:201], v[32:35]
	v_mfma_f32_16x16x32_bf16 v[32:35], v[140:143], v[202:205], v[32:35]
	s_setprio 0
	s_setprio 1
	v_mfma_f32_16x16x32_bf16 v[28:31], v[144:147], v[160:163], v[28:31]
	v_mfma_f32_16x16x32_bf16 v[28:31], v[148:151], v[164:167], v[28:31]
	v_mfma_f32_16x16x32_bf16 v[24:27], v[152:155], v[160:163], v[24:27]
	v_mfma_f32_16x16x32_bf16 v[24:27], v[156:159], v[164:167], v[24:27]
	v_mfma_f32_16x16x32_bf16 v[20:23], v[144:147], v[168:171], v[20:23]
	v_mfma_f32_16x16x32_bf16 v[20:23], v[148:151], v[172:175], v[20:23]
	v_mfma_f32_16x16x32_bf16 v[16:19], v[152:155], v[168:171], v[16:19]
	v_mfma_f32_16x16x32_bf16 v[16:19], v[156:159], v[172:175], v[16:19]
	v_mfma_f32_16x16x32_bf16 v[12:15], v[144:147], v[176:179], v[12:15]
	v_mfma_f32_16x16x32_bf16 v[12:15], v[148:151], v[180:183], v[12:15]
	v_mfma_f32_16x16x32_bf16 v[8:11], v[152:155], v[176:179], v[8:11]
	v_mfma_f32_16x16x32_bf16 v[8:11], v[156:159], v[180:183], v[8:11]
	v_mfma_f32_16x16x32_bf16 v[4:7], v[144:147], v[198:201], v[4:7]
	v_mfma_f32_16x16x32_bf16 v[4:7], v[148:151], v[202:205], v[4:7]
	v_mfma_f32_16x16x32_bf16 v[0:3], v[152:155], v[198:201], v[0:3]
	v_mfma_f32_16x16x32_bf16 v[0:3], v[156:159], v[202:205], v[0:3]
	s_setprio 0
	s_barrier
	s_add_i32 s10, s69, 2
	s_cmp_gt_u32 s69, 29
	s_cbranch_scc1 .LBB0_1101
	s_mov_b32 s69, s10
	s_branch .LBB0_1077

; #define PG8_STAGE(bufoff, gbase, voff) do { _Pragma("unroll") for (int _i = 0; _i < 2; ++_i) \
;         __builtin_amdgcn_global_load_lds((const unsigned*)((const char*)(gbase) + (voff)[_i]), (PG8_LAS unsigned*)(lds + (bufoff) + ldsw + _i * 8192), 16, 0, 0); } while (0)
; #define PG8_LDA(dst, b, h) do { _Pragma("unroll") for (int m = 0; m < 4; ++m) _Pragma("unroll") for (int k = 0; k < 2; ++k) dst[m][k] = *(const PG8_LAS bf16x8*)(lds + PG8_SA(b, h) + aoff + m * 2048 + k * 1024); } while (0)
; #define PG8_LDB(dst, b, h) do { _Pragma("unroll") for (int n = 0; n < 2; ++n) _Pragma("unroll") for (int k = 0; k < 2; ++k) dst[n][k] = *(const PG8_LAS bf16x8*)(lds + PG8_SB(b, h) + boff + n * 2048 + k * 1024); } while (0)
; #define PG8_MMA(ai, bj, At, Bt) do { __builtin_amdgcn_s_setprio(1); _Pragma("unroll") for (int m = 0; m < 4; ++m) _Pragma("unroll") for (int n = 0; n < 2; ++n) _Pragma("unroll") for (int k = 0; k < 2; ++k) \
;         acc[ai][bj][m][n] = __builtin_amdgcn_mfma_f32_16x16x32_bf16(Bt[n][k], At[m][k], acc[ai][bj][m][n], 0, 0, 0); __builtin_amdgcn_s_setprio(0); } while (0)
; #define PG8_WAIT_V(n) asm volatile("s_waitcnt vmcnt(" #n ")" ::: "memory")
; #define PG8_WAIT_L(n) asm volatile("s_waitcnt lgkmcnt(" #n ")" ::: "memory")
; template <class Epi, class Sched, bool ALIGN_EPI = false, bool SP2 = false, bool APERM = false  >
; __device__ __forceinline__ void gemm_phase(PG8_LAS unsigned char* lds, const Gemm g, const Sched& S, const Epi& E, const int wid  ) {
;     ...
;             const bool last = (t == nt - 2);
;             const char* a1 = cA + (size_t)(t + 1) * kstep;
;             const char* a2 = last ? nA : cA + (size_t)(t + 2) * kstep; const char* b2 = last ? nB : cB + (size_t)(t + 2) * kstep;
;             const char* a3 = a2 + kstep; const char* b3 = b2 + kstep;
;             if (last && has_next) S.a_ready(nxt);
;             if constexpr (SP2) {
;             PG8_LDB(B0, 0, 0); PG8_LDB(B1, 0, 1); PG8_SCHED; PG8_LDA(At, 0, 0); PG8_STAGE(PG8_SA(1, 1), a1 + hstep, voffA);
;             PG8_WAIT_V(8); PG8_WAIT_L(0); PG8_BAR; PG8_MMA(0, 0, At, B0); PG8_MMA(0, 1, At, B1); PG8_BAR; PG8_SCHED;
;             PG8_LDA(At, 0, 1); PG8_STAGE(PG8_SB(0, 0), b2, voffB); PG8_STAGE(PG8_SB(0, 1), b2 + hstep, voffB); PG8_STAGE(PG8_SA(0, 0), a2, voffA);
;             PG8_WAIT_V(8); PG8_WAIT_L(0); PG8_BAR; PG8_MMA(1, 0, At, B0); PG8_MMA(1, 1, At, B1); PG8_BAR; PG8_SCHED;
.LBB0_1252:
	s_lshl_b32 s74, s53, 7
	s_add_u32 s75, s14, s74
	s_addc_u32 s78, s15, 0
	v_add_u32_e32 v146, s33, v150
	s_add_u32 s72, s75, 0x100
	ds_read_b128 v[142:145], v146
	ds_read_b128 v[154:157], v146 offset:1024
	ds_read_b128 v[158:161], v146 offset:2048
	ds_read_b128 v[162:165], v146 offset:3072
	v_add_u32_e32 v146, s96, v150
	s_addc_u32 s73, s78, 0
	ds_read_b128 v[166:169], v146
	ds_read_b128 v[170:173], v146 offset:1024
	ds_read_b128 v[174:177], v146 offset:2048
	ds_read_b128 v[178:181], v146 offset:3072
	s_and_b64 s[46:47], s[70:71], exec
	s_cselect_b32 s73, s65, s73
	s_cselect_b32 s72, s64, s72
	s_add_u32 s46, s10, s74
	s_addc_u32 s47, s11, 0
	s_add_u32 s74, s46, 0x100
	s_addc_u32 vcc_lo, s47, 0
	s_and_b64 s[46:47], s[70:71], exec
	s_cselect_b32 s71, s67, vcc_lo
	s_cselect_b32 s70, s66, s74
	s_add_u32 s46, s75, 0x160080
	s_addc_u32 s47, s78, 0
	v_lshl_add_u64 v[146:147], s[46:47], 0, v[132:133]
	s_add_i32 m0, s87, 0xc000
	ds_read_b128 v[182:185], v153
	ds_read_b128 v[186:189], v153 offset:1024
	ds_read_b128 v[190:193], v153 offset:2048
	ds_read_b128 v[194:197], v153 offset:3072
	ds_read_b128 v[198:201], v153 offset:4096
	ds_read_b128 v[202:205], v153 offset:5120
	ds_read_b128 v[206:209], v153 offset:6144
	ds_read_b128 v[210:213], v153 offset:7168
	global_load_lds_dwordx4 v[146:147], off
	v_lshl_add_u64 v[146:147], s[46:47], 0, v[134:135]
	s_add_i32 m0, s87, 0xe000
	s_nop 0
	global_load_lds_dwordx4 v[146:147], off
	s_waitcnt vmcnt(8)
	s_waitcnt lgkmcnt(0)
	s_barrier
	s_setprio 1
	s_waitcnt lgkmcnt(0)
	v_mfma_f32_16x16x32_bf16 v[124:127], v[142:145], v[182:185], v[124:127]
	v_mfma_f32_16x16x32_bf16 v[124:127], v[154:157], v[186:189], v[124:127]
	v_mfma_f32_16x16x32_bf16 v[120:123], v[158:161], v[182:185], v[120:123]
	v_mfma_f32_16x16x32_bf16 v[120:123], v[162:165], v[186:189], v[120:123]
	v_mfma_f32_16x16x32_bf16 v[116:119], v[142:145], v[190:193], v[116:119]
	v_mfma_f32_16x16x32_bf16 v[116:119], v[154:157], v[194:197], v[116:119]
	v_mfma_f32_16x16x32_bf16 v[112:115], v[158:161], v[190:193], v[112:115]
	v_mfma_f32_16x16x32_bf16 v[112:115], v[162:165], v[194:197], v[112:115]
	v_mfma_f32_16x16x32_bf16 v[108:111], v[142:145], v[198:201], v[108:111]
	v_mfma_f32_16x16x32_bf16 v[108:111], v[154:157], v[202:205], v[108:111]
	v_mfma_f32_16x16x32_bf16 v[104:107], v[158:161], v[198:201], v[104:107]
	v_mfma_f32_16x16x32_bf16 v[104:107], v[162:165], v[202:205], v[104:107]
	v_mfma_f32_16x16x32_bf16 v[100:103], v[142:145], v[206:209], v[100:103]
	v_mfma_f32_16x16x32_bf16 v[100:103], v[154:157], v[210:213], v[100:103]
	v_mfma_f32_16x16x32_bf16 v[96:99], v[158:161], v[206:209], v[96:99]
	v_mfma_f32_16x16x32_bf16 v[96:99], v[162:165], v[210:213], v[96:99]
	s_setprio 0
	s_setprio 1
	v_mfma_f32_16x16x32_bf16 v[92:95], v[166:169], v[182:185], v[92:95]
	v_mfma_f32_16x16x32_bf16 v[92:95], v[170:173], v[186:189], v[92:95]
	v_mfma_f32_16x16x32_bf16 v[88:91], v[174:177], v[182:185], v[88:91]
	v_mfma_f32_16x16x32_bf16 v[88:91], v[178:181], v[186:189], v[88:91]
	v_mfma_f32_16x16x32_bf16 v[84:87], v[166:169], v[190:193], v[84:87]
	v_mfma_f32_16x16x32_bf16 v[84:87], v[170:173], v[194:197], v[84:87]
	v_mfma_f32_16x16x32_bf16 v[80:83], v[174:177], v[190:193], v[80:83]
	v_mfma_f32_16x16x32_bf16 v[80:83], v[178:181], v[194:197], v[80:83]
	v_mfma_f32_16x16x32_bf16 v[76:79], v[166:169], v[198:201], v[76:79]
	v_mfma_f32_16x16x32_bf16 v[76:79], v[170:173], v[202:205], v[76:79]
	v_mfma_f32_16x16x32_bf16 v[72:75], v[174:177], v[198:201], v[72:75]
	v_mfma_f32_16x16x32_bf16 v[72:75], v[178:181], v[202:205], v[72:75]
	v_mfma_f32_16x16x32_bf16 v[68:71], v[166:169], v[206:209], v[68:71]
	v_mfma_f32_16x16x32_bf16 v[68:71], v[170:173], v[210:213], v[68:71]
	v_mfma_f32_16x16x32_bf16 v[64:67], v[174:177], v[206:209], v[64:67]
	v_mfma_f32_16x16x32_bf16 v[64:67], v[178:181], v[210:213], v[64:67]
	s_setprio 0
	s_barrier
	s_add_i32 s46, s33, s79
	v_lshl_add_u64 v[146:147], s[70:71], 0, v[128:129]
	s_mov_b32 m0, s46
	ds_read_b128 v[182:185], v153 offset:16384
	ds_read_b128 v[186:189], v153 offset:17408
	ds_read_b128 v[190:193], v153 offset:18432
	ds_read_b128 v[194:197], v153 offset:19456
	ds_read_b128 v[198:201], v153 offset:20480
	ds_read_b128 v[202:205], v153 offset:21504
	ds_read_b128 v[206:209], v153 offset:22528
	ds_read_b128 v[210:213], v153 offset:23552
	global_load_lds_dwordx4 v[146:147], off
	s_add_i32 m0, s46, 0x2000
	s_add_u32 s46, s70, 0x160000
	v_lshl_add_u64 v[214:215], s[70:71], 0, v[130:131]
	s_addc_u32 s47, s71, 0
	s_add_i32 s74, s96, s79
	global_load_lds_dwordx4 v[214:215], off
	v_lshl_add_u64 v[216:217], s[46:47], 0, v[128:129]
	s_mov_b32 m0, s74
	v_lshl_add_u64 v[218:219], s[72:73], 0, v[134:135]
	global_load_lds_dwordx4 v[216:217], off
	v_lshl_add_u64 v[216:217], s[46:47], 0, v[130:131]
	s_add_i32 m0, s74, 0x2000
	s_nop 0
	global_load_lds_dwordx4 v[216:217], off
	v_lshl_add_u64 v[216:217], s[72:73], 0, v[132:133]
	s_mov_b32 m0, s87
	s_nop 0
	global_load_lds_dwordx4 v[216:217], off
	s_mov_b32 m0, s88
	s_nop 0
	global_load_lds_dwordx4 v[218:219], off
	s_waitcnt vmcnt(8)
	s_waitcnt lgkmcnt(0)
	s_barrier
; #define PG8_STAGE(bufoff, gbase, voff) do { _Pragma("unroll") for (int _i = 0; _i < 2; ++_i) \
;         __builtin_amdgcn_global_load_lds((const unsigned*)((const char*)(gbase) + (voff)[_i]), (PG8_LAS unsigned*)(lds + (bufoff) + ldsw + _i * 8192), 16, 0, 0); } while (0)
; #define PG8_LDA(dst, b, h) do { _Pragma("unroll") for (int m = 0; m < 4; ++m) _Pragma("unroll") for (int k = 0; k < 2; ++k) dst[m][k] = *(const PG8_LAS bf16x8*)(lds + PG8_SA(b, h) + aoff + m * 2048 + k * 1024); } while (0)
; #define PG8_LDB(dst, b, h) do { _Pragma("unroll") for (int n = 0; n < 2; ++n) _Pragma("unroll") for (int k = 0; k < 2; ++k) dst[n][k] = *(const PG8_LAS bf16x8*)(lds + PG8_SB(b, h) + boff + n * 2048 + k * 1024); } while (0)
; #define PG8_MMA(ai, bj, At, Bt) do { __builtin_amdgcn_s_setprio(1); _Pragma("unroll") for (int m = 0; m < 4; ++m) _Pragma("unroll") for (int n = 0; n < 2; ++n) _Pragma("unroll") for (int k = 0; k < 2; ++k) \
;         acc[ai][bj][m][n] = __builtin_amdgcn_mfma_f32_16x16x32_bf16(Bt[n][k], At[m][k], acc[ai][bj][m][n], 0, 0, 0); __builtin_amdgcn_s_setprio(0); } while (0)
; #define PG8_WAIT_V(n) asm volatile("s_waitcnt vmcnt(" #n ")" ::: "memory")
; #define PG8_WAIT_L(n) asm volatile("s_waitcnt lgkmcnt(" #n ")" ::: "memory")
; #define PG8_BAR __builtin_amdgcn_s_barrier()
; #define PG8_SCHED __builtin_amdgcn_sched_barrier(0)
; template <class Epi, class Sched, bool ALIGN_EPI = false, bool SP2 = false, bool APERM = false  >
; __device__ __forceinline__ void gemm_phase(PG8_LAS unsigned char* lds, const Gemm g, const Sched& S, const Epi& E, const int wid  ) {
;     ...
;             PG8_WAIT_V(8); PG8_WAIT_L(0); PG8_BAR; PG8_MMA(1, 0, At, B0); PG8_MMA(1, 1, At, B1); PG8_BAR; PG8_SCHED;
;             PG8_LDB(B0, 1, 0); PG8_LDB(B1, 1, 1); PG8_SCHED; PG8_LDA(At, 1, 0); PG8_STAGE(PG8_SA(0, 1), a2 + hstep, voffA);
;             PG8_WAIT_V(8); PG8_WAIT_L(0); PG8_BAR; PG8_MMA(0, 0, At, B0); PG8_MMA(0, 1, At, B1); PG8_BAR; PG8_SCHED;
	s_setprio 1
	s_waitcnt lgkmcnt(0)
	v_mfma_f32_16x16x32_bf16 v[60:63], v[142:145], v[182:185], v[60:63]
	v_mfma_f32_16x16x32_bf16 v[60:63], v[154:157], v[186:189], v[60:63]
	v_mfma_f32_16x16x32_bf16 v[56:59], v[158:161], v[182:185], v[56:59]
	v_mfma_f32_16x16x32_bf16 v[56:59], v[162:165], v[186:189], v[56:59]
	v_mfma_f32_16x16x32_bf16 v[52:55], v[142:145], v[190:193], v[52:55]
	v_mfma_f32_16x16x32_bf16 v[52:55], v[154:157], v[194:197], v[52:55]
	v_mfma_f32_16x16x32_bf16 v[48:51], v[158:161], v[190:193], v[48:51]
	v_mfma_f32_16x16x32_bf16 v[48:51], v[162:165], v[194:197], v[48:51]
	v_mfma_f32_16x16x32_bf16 v[44:47], v[142:145], v[198:201], v[44:47]
	v_mfma_f32_16x16x32_bf16 v[44:47], v[154:157], v[202:205], v[44:47]
	v_mfma_f32_16x16x32_bf16 v[40:43], v[158:161], v[198:201], v[40:43]
	v_mfma_f32_16x16x32_bf16 v[40:43], v[162:165], v[202:205], v[40:43]
	v_mfma_f32_16x16x32_bf16 v[36:39], v[142:145], v[206:209], v[36:39]
	v_mfma_f32_16x16x32_bf16 v[36:39], v[154:157], v[210:213], v[36:39]
	v_mfma_f32_16x16x32_bf16 v[32:35], v[158:161], v[206:209], v[32:35]
	v_mfma_f32_16x16x32_bf16 v[32:35], v[162:165], v[210:213], v[32:35]
	s_setprio 0
	s_setprio 1
	v_mfma_f32_16x16x32_bf16 v[28:31], v[166:169], v[182:185], v[28:31]
	v_mfma_f32_16x16x32_bf16 v[28:31], v[170:173], v[186:189], v[28:31]
	v_mfma_f32_16x16x32_bf16 v[24:27], v[174:177], v[182:185], v[24:27]
	v_mfma_f32_16x16x32_bf16 v[24:27], v[178:181], v[186:189], v[24:27]
	v_mfma_f32_16x16x32_bf16 v[20:23], v[166:169], v[190:193], v[20:23]
	v_mfma_f32_16x16x32_bf16 v[20:23], v[170:173], v[194:197], v[20:23]
	v_mfma_f32_16x16x32_bf16 v[16:19], v[174:177], v[190:193], v[16:19]
	v_mfma_f32_16x16x32_bf16 v[16:19], v[178:181], v[194:197], v[16:19]
	v_mfma_f32_16x16x32_bf16 v[12:15], v[166:169], v[198:201], v[12:15]
	v_mfma_f32_16x16x32_bf16 v[12:15], v[170:173], v[202:205], v[12:15]
	v_mfma_f32_16x16x32_bf16 v[8:11], v[174:177], v[198:201], v[8:11]
	v_mfma_f32_16x16x32_bf16 v[8:11], v[178:181], v[202:205], v[8:11]
	v_mfma_f32_16x16x32_bf16 v[4:7], v[166:169], v[206:209], v[4:7]
	v_mfma_f32_16x16x32_bf16 v[4:7], v[170:173], v[210:213], v[4:7]
	v_mfma_f32_16x16x32_bf16 v[0:3], v[174:177], v[206:209], v[0:3]
	v_mfma_f32_16x16x32_bf16 v[0:3], v[178:181], v[210:213], v[0:3]
	s_setprio 0
	s_barrier
	s_add_i32 s74, 0, 0x18000
	s_add_i32 s75, 0, 0x1c000
	v_add_u32_e32 v162, s74, v150
	v_add_u32_e32 v178, s75, v150
	ds_read_b128 v[142:145], v162
	ds_read_b128 v[154:157], v162 offset:1024
	ds_read_b128 v[158:161], v162 offset:2048
	ds_read_b128 v[162:165], v162 offset:3072
	ds_read_b128 v[166:169], v178
	ds_read_b128 v[170:173], v178 offset:1024
	ds_read_b128 v[174:177], v178 offset:2048
	ds_read_b128 v[178:181], v178 offset:3072
	s_add_u32 s46, s72, 0x160000
	s_addc_u32 s47, s73, 0
	s_mov_b32 m0, s89
	v_lshl_add_u64 v[220:221], s[46:47], 0, v[132:133]
	ds_read_b128 v[182:185], v153 offset:32768
	ds_read_b128 v[186:189], v153 offset:33792
	ds_read_b128 v[190:193], v153 offset:34816
	ds_read_b128 v[194:197], v153 offset:35840
	ds_read_b128 v[198:201], v153 offset:36864
	ds_read_b128 v[202:205], v153 offset:37888
	ds_read_b128 v[206:209], v153 offset:38912
	ds_read_b128 v[210:213], v153 offset:39936
	global_load_lds_dwordx4 v[220:221], off
	v_lshl_add_u64 v[220:221], s[46:47], 0, v[134:135]
	s_mov_b32 m0, s90
	s_nop 0
	global_load_lds_dwordx4 v[220:221], off
	s_waitcnt vmcnt(8)
	s_waitcnt lgkmcnt(0)
	s_barrier
	s_setprio 1
	s_waitcnt lgkmcnt(0)
	v_mfma_f32_16x16x32_bf16 v[124:127], v[142:145], v[182:185], v[124:127]
	v_mfma_f32_16x16x32_bf16 v[124:127], v[154:157], v[186:189], v[124:127]
	v_mfma_f32_16x16x32_bf16 v[120:123], v[158:161], v[182:185], v[120:123]
	v_mfma_f32_16x16x32_bf16 v[120:123], v[162:165], v[186:189], v[120:123]
	v_mfma_f32_16x16x32_bf16 v[116:119], v[142:145], v[190:193], v[116:119]
	v_mfma_f32_16x16x32_bf16 v[116:119], v[154:157], v[194:197], v[116:119]
	v_mfma_f32_16x16x32_bf16 v[112:115], v[158:161], v[190:193], v[112:115]
	v_mfma_f32_16x16x32_bf16 v[112:115], v[162:165], v[194:197], v[112:115]
	v_mfma_f32_16x16x32_bf16 v[108:111], v[142:145], v[198:201], v[108:111]
	v_mfma_f32_16x16x32_bf16 v[108:111], v[154:157], v[202:205], v[108:111]
	v_mfma_f32_16x16x32_bf16 v[104:107], v[158:161], v[198:201], v[104:107]
	v_mfma_f32_16x16x32_bf16 v[104:107], v[162:165], v[202:205], v[104:107]
	v_mfma_f32_16x16x32_bf16 v[100:103], v[142:145], v[206:209], v[100:103]
	v_mfma_f32_16x16x32_bf16 v[100:103], v[154:157], v[210:213], v[100:103]
	v_mfma_f32_16x16x32_bf16 v[96:99], v[158:161], v[206:209], v[96:99]
	v_mfma_f32_16x16x32_bf16 v[96:99], v[162:165], v[210:213], v[96:99]
	s_setprio 0
	s_setprio 1
	v_mfma_f32_16x16x32_bf16 v[92:95], v[166:169], v[182:185], v[92:95]
	v_mfma_f32_16x16x32_bf16 v[92:95], v[170:173], v[186:189], v[92:95]
	v_mfma_f32_16x16x32_bf16 v[88:91], v[174:177], v[182:185], v[88:91]
	v_mfma_f32_16x16x32_bf16 v[88:91], v[178:181], v[186:189], v[88:91]
	v_mfma_f32_16x16x32_bf16 v[84:87], v[166:169], v[190:193], v[84:87]
	v_mfma_f32_16x16x32_bf16 v[84:87], v[170:173], v[194:197], v[84:87]
	v_mfma_f32_16x16x32_bf16 v[80:83], v[174:177], v[190:193], v[80:83]
	v_mfma_f32_16x16x32_bf16 v[80:83], v[178:181], v[194:197], v[80:83]
	v_mfma_f32_16x16x32_bf16 v[76:79], v[166:169], v[198:201], v[76:79]
	v_mfma_f32_16x16x32_bf16 v[76:79], v[170:173], v[202:205], v[76:79]
	v_mfma_f32_16x16x32_bf16 v[72:75], v[174:177], v[198:201], v[72:75]
	v_mfma_f32_16x16x32_bf16 v[72:75], v[178:181], v[202:205], v[72:75]
	v_mfma_f32_16x16x32_bf16 v[68:71], v[166:169], v[206:209], v[68:71]
	v_mfma_f32_16x16x32_bf16 v[68:71], v[170:173], v[210:213], v[68:71]
	v_mfma_f32_16x16x32_bf16 v[64:67], v[174:177], v[206:209], v[64:67]
	v_mfma_f32_16x16x32_bf16 v[64:67], v[178:181], v[210:213], v[64:67]
	s_setprio 0
	s_barrier
; #define PG8_STAGE(bufoff, gbase, voff) do { _Pragma("unroll") for (int _i = 0; _i < 2; ++_i) \
;         __builtin_amdgcn_global_load_lds((const unsigned*)((const char*)(gbase) + (voff)[_i]), (PG8_LAS unsigned*)(lds + (bufoff) + ldsw + _i * 8192), 16, 0, 0); } while (0)
; #define PG8_LDA(dst, b, h) do { _Pragma("unroll") for (int m = 0; m < 4; ++m) _Pragma("unroll") for (int k = 0; k < 2; ++k) dst[m][k] = *(const PG8_LAS bf16x8*)(lds + PG8_SA(b, h) + aoff + m * 2048 + k * 1024); } while (0)
; #define PG8_MMA(ai, bj, At, Bt) do { __builtin_amdgcn_s_setprio(1); _Pragma("unroll") for (int m = 0; m < 4; ++m) _Pragma("unroll") for (int n = 0; n < 2; ++n) _Pragma("unroll") for (int k = 0; k < 2; ++k) \
;         acc[ai][bj][m][n] = __builtin_amdgcn_mfma_f32_16x16x32_bf16(Bt[n][k], At[m][k], acc[ai][bj][m][n], 0, 0, 0); __builtin_amdgcn_s_setprio(0); } while (0)
; #define PG8_WAIT_V(n) asm volatile("s_waitcnt vmcnt(" #n ")" ::: "memory")
; #define PG8_WAIT_L(n) asm volatile("s_waitcnt lgkmcnt(" #n ")" ::: "memory")
; #define PG8_BAR __builtin_amdgcn_s_barrier()
; #define PG8_SCHED __builtin_amdgcn_sched_barrier(0)
; template <class Epi, class Sched, bool ALIGN_EPI = false, bool SP2 = false, bool APERM = false  >
; __device__ __forceinline__ void gemm_phase(PG8_LAS unsigned char* lds, const Gemm g, const Sched& S, const Epi& E, const int wid  ) {
;     ...
;         for (int t = 0; t < nt; t += 2) {
;             const bool last = (t == nt - 2);
;             const char* a1 = cA + (size_t)(t + 1) * kstep;
;             const char* a2 = last ? nA : cA + (size_t)(t + 2) * kstep; const char* b2 = last ? nB : cB + (size_t)(t + 2) * kstep;
;     ...
;             PG8_LDA(At, 1, 1); PG8_STAGE(PG8_SB(1, 0), b3, voffB); PG8_STAGE(PG8_SB(1, 1), b3 + hstep, voffB); PG8_STAGE(PG8_SA(1, 0), a3, voffA);
;             PG8_WAIT_V(8); PG8_WAIT_L(0); PG8_BAR; PG8_MMA(1, 0, At, B0); PG8_MMA(1, 1, At, B1); PG8_BAR; PG8_SCHED;
	s_add_i32 s46, s74, s79
	v_lshl_add_u64 v[146:147], v[146:147], 0, s[24:25]
	s_mov_b32 m0, s46
	ds_read_b128 v[182:185], v153 offset:49152
	ds_read_b128 v[186:189], v153 offset:50176
	ds_read_b128 v[190:193], v153 offset:51200
	ds_read_b128 v[194:197], v153 offset:52224
	ds_read_b128 v[198:201], v153 offset:53248
	ds_read_b128 v[202:205], v153 offset:54272
	ds_read_b128 v[206:209], v153 offset:55296
	ds_read_b128 v[210:213], v153 offset:56320
	global_load_lds_dwordx4 v[146:147], off
	s_add_i32 m0, s46, 0x2000
	s_add_u32 s46, s70, 0x160080
	v_lshl_add_u64 v[146:147], v[214:215], 0, s[24:25]
	s_addc_u32 s47, s71, 0
	s_add_i32 s70, s75, s79
	global_load_lds_dwordx4 v[146:147], off
	v_lshl_add_u64 v[146:147], s[46:47], 0, v[128:129]
	s_mov_b32 m0, s70
	s_nop 0
	global_load_lds_dwordx4 v[146:147], off
	v_lshl_add_u64 v[146:147], s[46:47], 0, v[130:131]
	s_add_i32 m0, s70, 0x2000
	s_nop 0
	global_load_lds_dwordx4 v[146:147], off
	v_lshl_add_u64 v[146:147], v[216:217], 0, s[24:25]
	s_mov_b32 m0, s93
	s_nop 0
	global_load_lds_dwordx4 v[146:147], off
	v_lshl_add_u64 v[146:147], v[218:219], 0, s[24:25]
	s_mov_b32 m0, s95
	s_nop 0
	global_load_lds_dwordx4 v[146:147], off
	s_waitcnt vmcnt(8)
	s_waitcnt lgkmcnt(0)
	s_barrier
	s_setprio 1
	s_waitcnt lgkmcnt(0)
	v_mfma_f32_16x16x32_bf16 v[60:63], v[142:145], v[182:185], v[60:63]
	v_mfma_f32_16x16x32_bf16 v[60:63], v[154:157], v[186:189], v[60:63]
	v_mfma_f32_16x16x32_bf16 v[56:59], v[158:161], v[182:185], v[56:59]
	v_mfma_f32_16x16x32_bf16 v[56:59], v[162:165], v[186:189], v[56:59]
	v_mfma_f32_16x16x32_bf16 v[52:55], v[142:145], v[190:193], v[52:55]
	v_mfma_f32_16x16x32_bf16 v[52:55], v[154:157], v[194:197], v[52:55]
	v_mfma_f32_16x16x32_bf16 v[48:51], v[158:161], v[190:193], v[48:51]
	v_mfma_f32_16x16x32_bf16 v[48:51], v[162:165], v[194:197], v[48:51]
	v_mfma_f32_16x16x32_bf16 v[44:47], v[142:145], v[198:201], v[44:47]
	v_mfma_f32_16x16x32_bf16 v[44:47], v[154:157], v[202:205], v[44:47]
	v_mfma_f32_16x16x32_bf16 v[40:43], v[158:161], v[198:201], v[40:43]
	v_mfma_f32_16x16x32_bf16 v[40:43], v[162:165], v[202:205], v[40:43]
	v_mfma_f32_16x16x32_bf16 v[36:39], v[142:145], v[206:209], v[36:39]
	v_mfma_f32_16x16x32_bf16 v[36:39], v[154:157], v[210:213], v[36:39]
	v_mfma_f32_16x16x32_bf16 v[32:35], v[158:161], v[206:209], v[32:35]
	v_mfma_f32_16x16x32_bf16 v[32:35], v[162:165], v[210:213], v[32:35]
	s_setprio 0
	s_setprio 1
	v_mfma_f32_16x16x32_bf16 v[28:31], v[166:169], v[182:185], v[28:31]
	v_mfma_f32_16x16x32_bf16 v[28:31], v[170:173], v[186:189], v[28:31]
	v_mfma_f32_16x16x32_bf16 v[24:27], v[174:177], v[182:185], v[24:27]
	v_mfma_f32_16x16x32_bf16 v[24:27], v[178:181], v[186:189], v[24:27]
	v_mfma_f32_16x16x32_bf16 v[20:23], v[166:169], v[190:193], v[20:23]
	v_mfma_f32_16x16x32_bf16 v[20:23], v[170:173], v[194:197], v[20:23]
	v_mfma_f32_16x16x32_bf16 v[16:19], v[174:177], v[190:193], v[16:19]
	v_mfma_f32_16x16x32_bf16 v[16:19], v[178:181], v[194:197], v[16:19]
	v_mfma_f32_16x16x32_bf16 v[12:15], v[166:169], v[198:201], v[12:15]
	v_mfma_f32_16x16x32_bf16 v[12:15], v[170:173], v[202:205], v[12:15]
	v_mfma_f32_16x16x32_bf16 v[8:11], v[174:177], v[198:201], v[8:11]
	v_mfma_f32_16x16x32_bf16 v[8:11], v[178:181], v[202:205], v[8:11]
	v_mfma_f32_16x16x32_bf16 v[4:7], v[166:169], v[206:209], v[4:7]
	v_mfma_f32_16x16x32_bf16 v[4:7], v[170:173], v[210:213], v[4:7]
	v_mfma_f32_16x16x32_bf16 v[0:3], v[174:177], v[206:209], v[0:3]
	v_mfma_f32_16x16x32_bf16 v[0:3], v[178:181], v[210:213], v[0:3]
	s_setprio 0
	s_barrier
	s_add_i32 s46, s53, 2
	s_cmp_gt_u32 s53, 41
	s_cbranch_scc1 .LBB0_1254
	s_mov_b32 s53, s46
	s_branch .LBB0_1235

; #define PG8_STAGE(bufoff, gbase, voff) do { _Pragma("unroll") for (int _i = 0; _i < 2; ++_i) \
;         __builtin_amdgcn_global_load_lds((const unsigned*)((const char*)(gbase) + (voff)[_i]), (PG8_LAS unsigned*)(lds + (bufoff) + ldsw + _i * 8192), 16, 0, 0); } while (0)
; #define PG8_LDA(dst, b, h) do { _Pragma("unroll") for (int m = 0; m < 4; ++m) _Pragma("unroll") for (int k = 0; k < 2; ++k) dst[m][k] = *(const PG8_LAS bf16x8*)(lds + PG8_SA(b, h) + aoff + m * 2048 + k * 1024); } while (0)
; #define PG8_LDB(dst, b, h) do { _Pragma("unroll") for (int n = 0; n < 2; ++n) _Pragma("unroll") for (int k = 0; k < 2; ++k) dst[n][k] = *(const PG8_LAS bf16x8*)(lds + PG8_SB(b, h) + boff + n * 2048 + k * 1024); } while (0)
; #define PG8_MMA(ai, bj, At, Bt) do { __builtin_amdgcn_s_setprio(1); _Pragma("unroll") for (int m = 0; m < 4; ++m) _Pragma("unroll") for (int n = 0; n < 2; ++n) _Pragma("unroll") for (int k = 0; k < 2; ++k) \
;         acc[ai][bj][m][n] = __builtin_amdgcn_mfma_f32_16x16x32_bf16(Bt[n][k], At[m][k], acc[ai][bj][m][n], 0, 0, 0); __builtin_amdgcn_s_setprio(0); } while (0)
; #define PG8_WAIT_V(n) asm volatile("s_waitcnt vmcnt(" #n ")" ::: "memory")
; #define PG8_WAIT_L(n) asm volatile("s_waitcnt lgkmcnt(" #n ")" ::: "memory")
; template <class Epi, class Sched, bool ALIGN_EPI = false, bool SP2 = false, bool APERM = false  >
; __device__ __forceinline__ void gemm_phase(PG8_LAS unsigned char* lds, const Gemm g, const Sched& S, const Epi& E, const int wid  ) {
;     ...
;             const bool last = (t == nt - 2);
;             const char* a1 = cA + (size_t)(t + 1) * kstep;
;             const char* a2 = last ? nA : cA + (size_t)(t + 2) * kstep; const char* b2 = last ? nB : cB + (size_t)(t + 2) * kstep;
;             const char* a3 = a2 + kstep; const char* b3 = b2 + kstep;
;             if (last && has_next) S.a_ready(nxt);
;             if constexpr (SP2) {
;             PG8_LDB(B0, 0, 0); PG8_LDB(B1, 0, 1); PG8_SCHED; PG8_LDA(At, 0, 0); PG8_STAGE(PG8_SA(1, 1), a1 + hstep, voffA);
;             PG8_WAIT_V(8); PG8_WAIT_L(0); PG8_BAR; PG8_MMA(0, 0, At, B0); PG8_MMA(0, 1, At, B1); PG8_BAR; PG8_SCHED;
;             PG8_LDA(At, 0, 1); PG8_STAGE(PG8_SB(0, 0), b2, voffB); PG8_STAGE(PG8_SB(0, 1), b2 + hstep, voffB); PG8_STAGE(PG8_SA(0, 0), a2, voffA);
;             PG8_WAIT_V(8); PG8_WAIT_L(0); PG8_BAR; PG8_MMA(1, 0, At, B0); PG8_MMA(1, 1, At, B1); PG8_BAR; PG8_SCHED;
.LBB0_1314:
	s_or_b32 s36, s78, 1
	v_add_u32_e32 v159, s52, v153
	s_lshl_b64 s[74:75], s[36:37], 7
	s_add_i32 s36, s78, 2
	s_waitcnt lgkmcnt(0)
	ds_read_b128 v[144:147], v159
	ds_read_b128 v[148:151], v159 offset:1024
	ds_read_b128 v[160:163], v159 offset:2048
	ds_read_b128 v[164:167], v159 offset:3072
	v_add_u32_e32 v159, s95, v153
	s_lshl_b64 s[76:77], s[36:37], 7
	ds_read_b128 v[168:171], v159
	ds_read_b128 v[172:175], v159 offset:1024
	ds_read_b128 v[176:179], v159 offset:2048
	ds_read_b128 v[180:183], v159 offset:3072
	s_add_u32 vcc_lo, s14, s76
	s_addc_u32 vcc_hi, s15, s77
	s_and_b64 s[72:73], s[70:71], exec
	s_cselect_b32 s73, s25, vcc_hi
	s_cselect_b32 s72, s24, vcc_lo
	s_add_u32 s76, s10, s76
	s_addc_u32 s77, s11, s77
	s_and_b64 s[70:71], s[70:71], exec
	s_cselect_b32 s71, s29, s77
	s_cselect_b32 s70, s28, s76
	s_add_u32 s74, s33, s74
	s_addc_u32 s75, s53, s75
	v_lshl_add_u64 v[216:217], s[74:75], 0, v[132:133]
	s_add_i32 m0, s85, 0xc000
	ds_read_b128 v[184:187], v158
	ds_read_b128 v[188:191], v158 offset:1024
	ds_read_b128 v[192:195], v158 offset:2048
	ds_read_b128 v[196:199], v158 offset:3072
	ds_read_b128 v[200:203], v158 offset:4096
	ds_read_b128 v[204:207], v158 offset:5120
	ds_read_b128 v[208:211], v158 offset:6144
	ds_read_b128 v[212:215], v158 offset:7168
	global_load_lds_dwordx4 v[216:217], off
	v_lshl_add_u64 v[216:217], s[74:75], 0, v[136:137]
	s_add_i32 m0, s85, 0xe000
	s_nop 0
	global_load_lds_dwordx4 v[216:217], off
	s_waitcnt vmcnt(8)
	s_waitcnt lgkmcnt(0)
	s_barrier
	s_setprio 1
	s_waitcnt lgkmcnt(0)
	v_mfma_f32_16x16x32_bf16 v[124:127], v[144:147], v[184:187], v[124:127]
	v_mfma_f32_16x16x32_bf16 v[124:127], v[148:151], v[188:191], v[124:127]
	v_mfma_f32_16x16x32_bf16 v[120:123], v[160:163], v[184:187], v[120:123]
	v_mfma_f32_16x16x32_bf16 v[120:123], v[164:167], v[188:191], v[120:123]
	v_mfma_f32_16x16x32_bf16 v[116:119], v[144:147], v[192:195], v[116:119]
	v_mfma_f32_16x16x32_bf16 v[116:119], v[148:151], v[196:199], v[116:119]
	v_mfma_f32_16x16x32_bf16 v[112:115], v[160:163], v[192:195], v[112:115]
	v_mfma_f32_16x16x32_bf16 v[112:115], v[164:167], v[196:199], v[112:115]
	v_mfma_f32_16x16x32_bf16 v[108:111], v[144:147], v[200:203], v[108:111]
	v_mfma_f32_16x16x32_bf16 v[108:111], v[148:151], v[204:207], v[108:111]
	v_mfma_f32_16x16x32_bf16 v[104:107], v[160:163], v[200:203], v[104:107]
	v_mfma_f32_16x16x32_bf16 v[104:107], v[164:167], v[204:207], v[104:107]
	v_mfma_f32_16x16x32_bf16 v[100:103], v[144:147], v[208:211], v[100:103]
	v_mfma_f32_16x16x32_bf16 v[100:103], v[148:151], v[212:215], v[100:103]
	v_mfma_f32_16x16x32_bf16 v[96:99], v[160:163], v[208:211], v[96:99]
	v_mfma_f32_16x16x32_bf16 v[96:99], v[164:167], v[212:215], v[96:99]
	s_setprio 0
	s_setprio 1
	v_mfma_f32_16x16x32_bf16 v[92:95], v[168:171], v[184:187], v[92:95]
	v_mfma_f32_16x16x32_bf16 v[92:95], v[172:175], v[188:191], v[92:95]
	v_mfma_f32_16x16x32_bf16 v[88:91], v[176:179], v[184:187], v[88:91]
	v_mfma_f32_16x16x32_bf16 v[88:91], v[180:183], v[188:191], v[88:91]
	v_mfma_f32_16x16x32_bf16 v[84:87], v[168:171], v[192:195], v[84:87]
	v_mfma_f32_16x16x32_bf16 v[84:87], v[172:175], v[196:199], v[84:87]
	v_mfma_f32_16x16x32_bf16 v[80:83], v[176:179], v[192:195], v[80:83]
	v_mfma_f32_16x16x32_bf16 v[80:83], v[180:183], v[196:199], v[80:83]
	v_mfma_f32_16x16x32_bf16 v[76:79], v[168:171], v[200:203], v[76:79]
	v_mfma_f32_16x16x32_bf16 v[76:79], v[172:175], v[204:207], v[76:79]
	v_mfma_f32_16x16x32_bf16 v[72:75], v[176:179], v[200:203], v[72:75]
	v_mfma_f32_16x16x32_bf16 v[72:75], v[180:183], v[204:207], v[72:75]
	v_mfma_f32_16x16x32_bf16 v[68:71], v[168:171], v[208:211], v[68:71]
	v_mfma_f32_16x16x32_bf16 v[68:71], v[172:175], v[212:215], v[68:71]
	v_mfma_f32_16x16x32_bf16 v[64:67], v[176:179], v[208:211], v[64:67]
	v_mfma_f32_16x16x32_bf16 v[64:67], v[180:183], v[212:215], v[64:67]
	s_setprio 0
	s_barrier
	s_add_i32 s74, s52, s79
	v_lshl_add_u64 v[216:217], s[70:71], 0, v[128:129]
	s_mov_b32 m0, s74
	ds_read_b128 v[184:187], v158 offset:16384
	ds_read_b128 v[188:191], v158 offset:17408
	ds_read_b128 v[192:195], v158 offset:18432
	ds_read_b128 v[196:199], v158 offset:19456
	ds_read_b128 v[200:203], v158 offset:20480
	ds_read_b128 v[204:207], v158 offset:21504
	ds_read_b128 v[208:211], v158 offset:22528
	ds_read_b128 v[212:215], v158 offset:23552
	global_load_lds_dwordx4 v[216:217], off
	s_add_i32 m0, s74, 0x2000
	s_add_u32 s74, s70, 0x160000
	v_lshl_add_u64 v[218:219], s[70:71], 0, v[130:131]
	s_addc_u32 s75, s71, 0
	s_add_i32 s76, s95, s79
	global_load_lds_dwordx4 v[218:219], off
	v_lshl_add_u64 v[220:221], s[74:75], 0, v[128:129]
	s_mov_b32 m0, s76
	v_lshl_add_u64 v[222:223], s[72:73], 0, v[136:137]
	global_load_lds_dwordx4 v[220:221], off
	v_lshl_add_u64 v[220:221], s[74:75], 0, v[130:131]
	s_add_i32 m0, s76, 0x2000
	s_nop 0
	global_load_lds_dwordx4 v[220:221], off
	v_lshl_add_u64 v[220:221], s[72:73], 0, v[132:133]
	s_mov_b32 m0, s85
	s_nop 0
	global_load_lds_dwordx4 v[220:221], off
	s_mov_b32 m0, s88
	s_nop 0
	global_load_lds_dwordx4 v[222:223], off
	s_waitcnt vmcnt(8)
	s_waitcnt lgkmcnt(0)
	s_barrier
; #define PG8_STAGE(bufoff, gbase, voff) do { _Pragma("unroll") for (int _i = 0; _i < 2; ++_i) \
;         __builtin_amdgcn_global_load_lds((const unsigned*)((const char*)(gbase) + (voff)[_i]), (PG8_LAS unsigned*)(lds + (bufoff) + ldsw + _i * 8192), 16, 0, 0); } while (0)
; #define PG8_LDA(dst, b, h) do { _Pragma("unroll") for (int m = 0; m < 4; ++m) _Pragma("unroll") for (int k = 0; k < 2; ++k) dst[m][k] = *(const PG8_LAS bf16x8*)(lds + PG8_SA(b, h) + aoff + m * 2048 + k * 1024); } while (0)
; #define PG8_LDB(dst, b, h) do { _Pragma("unroll") for (int n = 0; n < 2; ++n) _Pragma("unroll") for (int k = 0; k < 2; ++k) dst[n][k] = *(const PG8_LAS bf16x8*)(lds + PG8_SB(b, h) + boff + n * 2048 + k * 1024); } while (0)
; #define PG8_MMA(ai, bj, At, Bt) do { __builtin_amdgcn_s_setprio(1); _Pragma("unroll") for (int m = 0; m < 4; ++m) _Pragma("unroll") for (int n = 0; n < 2; ++n) _Pragma("unroll") for (int k = 0; k < 2; ++k) \
;         acc[ai][bj][m][n] = __builtin_amdgcn_mfma_f32_16x16x32_bf16(Bt[n][k], At[m][k], acc[ai][bj][m][n], 0, 0, 0); __builtin_amdgcn_s_setprio(0); } while (0)
; #define PG8_WAIT_V(n) asm volatile("s_waitcnt vmcnt(" #n ")" ::: "memory")
; #define PG8_WAIT_L(n) asm volatile("s_waitcnt lgkmcnt(" #n ")" ::: "memory")
; #define PG8_BAR __builtin_amdgcn_s_barrier()
; #define PG8_SCHED __builtin_amdgcn_sched_barrier(0)
; template <class Epi, class Sched, bool ALIGN_EPI = false, bool SP2 = false, bool APERM = false  >
; __device__ __forceinline__ void gemm_phase(PG8_LAS unsigned char* lds, const Gemm g, const Sched& S, const Epi& E, const int wid  ) {
;     ...
;             PG8_WAIT_V(8); PG8_WAIT_L(0); PG8_BAR; PG8_MMA(1, 0, At, B0); PG8_MMA(1, 1, At, B1); PG8_BAR; PG8_SCHED;
;             PG8_LDB(B0, 1, 0); PG8_LDB(B1, 1, 1); PG8_SCHED; PG8_LDA(At, 1, 0); PG8_STAGE(PG8_SA(0, 1), a2 + hstep, voffA);
;             PG8_WAIT_V(8); PG8_WAIT_L(0); PG8_BAR; PG8_MMA(0, 0, At, B0); PG8_MMA(0, 1, At, B1); PG8_BAR; PG8_SCHED;
	s_setprio 1
	s_waitcnt lgkmcnt(0)
	v_mfma_f32_16x16x32_bf16 v[60:63], v[144:147], v[184:187], v[60:63]
	v_mfma_f32_16x16x32_bf16 v[60:63], v[148:151], v[188:191], v[60:63]
	v_mfma_f32_16x16x32_bf16 v[56:59], v[160:163], v[184:187], v[56:59]
	v_mfma_f32_16x16x32_bf16 v[56:59], v[164:167], v[188:191], v[56:59]
	v_mfma_f32_16x16x32_bf16 v[52:55], v[144:147], v[192:195], v[52:55]
	v_mfma_f32_16x16x32_bf16 v[52:55], v[148:151], v[196:199], v[52:55]
	v_mfma_f32_16x16x32_bf16 v[48:51], v[160:163], v[192:195], v[48:51]
	v_mfma_f32_16x16x32_bf16 v[48:51], v[164:167], v[196:199], v[48:51]
	v_mfma_f32_16x16x32_bf16 v[44:47], v[144:147], v[200:203], v[44:47]
	v_mfma_f32_16x16x32_bf16 v[44:47], v[148:151], v[204:207], v[44:47]
	v_mfma_f32_16x16x32_bf16 v[40:43], v[160:163], v[200:203], v[40:43]
	v_mfma_f32_16x16x32_bf16 v[40:43], v[164:167], v[204:207], v[40:43]
	v_mfma_f32_16x16x32_bf16 v[36:39], v[144:147], v[208:211], v[36:39]
	v_mfma_f32_16x16x32_bf16 v[36:39], v[148:151], v[212:215], v[36:39]
	v_mfma_f32_16x16x32_bf16 v[32:35], v[160:163], v[208:211], v[32:35]
	v_mfma_f32_16x16x32_bf16 v[32:35], v[164:167], v[212:215], v[32:35]
	s_setprio 0
	s_setprio 1
	v_mfma_f32_16x16x32_bf16 v[28:31], v[168:171], v[184:187], v[28:31]
	v_mfma_f32_16x16x32_bf16 v[28:31], v[172:175], v[188:191], v[28:31]
	v_mfma_f32_16x16x32_bf16 v[24:27], v[176:179], v[184:187], v[24:27]
	v_mfma_f32_16x16x32_bf16 v[24:27], v[180:183], v[188:191], v[24:27]
	v_mfma_f32_16x16x32_bf16 v[20:23], v[168:171], v[192:195], v[20:23]
	v_mfma_f32_16x16x32_bf16 v[20:23], v[172:175], v[196:199], v[20:23]
	v_mfma_f32_16x16x32_bf16 v[16:19], v[176:179], v[192:195], v[16:19]
	v_mfma_f32_16x16x32_bf16 v[16:19], v[180:183], v[196:199], v[16:19]
	v_mfma_f32_16x16x32_bf16 v[12:15], v[168:171], v[200:203], v[12:15]
	v_mfma_f32_16x16x32_bf16 v[12:15], v[172:175], v[204:207], v[12:15]
	v_mfma_f32_16x16x32_bf16 v[8:11], v[176:179], v[200:203], v[8:11]
	v_mfma_f32_16x16x32_bf16 v[8:11], v[180:183], v[204:207], v[8:11]
	v_mfma_f32_16x16x32_bf16 v[4:7], v[168:171], v[208:211], v[4:7]
	v_mfma_f32_16x16x32_bf16 v[4:7], v[172:175], v[212:215], v[4:7]
	v_mfma_f32_16x16x32_bf16 v[0:3], v[176:179], v[208:211], v[0:3]
	v_mfma_f32_16x16x32_bf16 v[0:3], v[180:183], v[212:215], v[0:3]
	s_setprio 0
	s_barrier
	s_add_i32 s74, 0, 0x18000
	v_add_u32_e32 v159, s74, v153
	s_add_i32 s75, 0, 0x1c000
	ds_read_b128 v[144:147], v159
	ds_read_b128 v[148:151], v159 offset:1024
	ds_read_b128 v[160:163], v159 offset:2048
	ds_read_b128 v[164:167], v159 offset:3072
	v_add_u32_e32 v159, s75, v153
	ds_read_b128 v[168:171], v159
	ds_read_b128 v[172:175], v159 offset:1024
	ds_read_b128 v[176:179], v159 offset:2048
	ds_read_b128 v[180:183], v159 offset:3072
	s_add_u32 s72, s72, 0x160000
	s_addc_u32 s73, s73, 0
	s_mov_b32 m0, s89
	v_lshl_add_u64 v[224:225], s[72:73], 0, v[132:133]
	ds_read_b128 v[184:187], v158 offset:32768
	ds_read_b128 v[188:191], v158 offset:33792
	ds_read_b128 v[192:195], v158 offset:34816
	ds_read_b128 v[196:199], v158 offset:35840
	ds_read_b128 v[200:203], v158 offset:36864
	ds_read_b128 v[204:207], v158 offset:37888
	ds_read_b128 v[208:211], v158 offset:38912
	ds_read_b128 v[212:215], v158 offset:39936
	global_load_lds_dwordx4 v[224:225], off
	v_lshl_add_u64 v[224:225], s[72:73], 0, v[136:137]
	s_mov_b32 m0, s90
	s_nop 0
	global_load_lds_dwordx4 v[224:225], off
	s_waitcnt vmcnt(8)
	s_waitcnt lgkmcnt(0)
	s_barrier
	s_setprio 1
	s_waitcnt lgkmcnt(0)
	v_mfma_f32_16x16x32_bf16 v[124:127], v[144:147], v[184:187], v[124:127]
	v_mfma_f32_16x16x32_bf16 v[124:127], v[148:151], v[188:191], v[124:127]
	v_mfma_f32_16x16x32_bf16 v[120:123], v[160:163], v[184:187], v[120:123]
	v_mfma_f32_16x16x32_bf16 v[120:123], v[164:167], v[188:191], v[120:123]
	v_mfma_f32_16x16x32_bf16 v[116:119], v[144:147], v[192:195], v[116:119]
	v_mfma_f32_16x16x32_bf16 v[116:119], v[148:151], v[196:199], v[116:119]
	v_mfma_f32_16x16x32_bf16 v[112:115], v[160:163], v[192:195], v[112:115]
	v_mfma_f32_16x16x32_bf16 v[112:115], v[164:167], v[196:199], v[112:115]
	v_mfma_f32_16x16x32_bf16 v[108:111], v[144:147], v[200:203], v[108:111]
	v_mfma_f32_16x16x32_bf16 v[108:111], v[148:151], v[204:207], v[108:111]
	v_mfma_f32_16x16x32_bf16 v[104:107], v[160:163], v[200:203], v[104:107]
	v_mfma_f32_16x16x32_bf16 v[104:107], v[164:167], v[204:207], v[104:107]
	v_mfma_f32_16x16x32_bf16 v[100:103], v[144:147], v[208:211], v[100:103]
	v_mfma_f32_16x16x32_bf16 v[100:103], v[148:151], v[212:215], v[100:103]
	v_mfma_f32_16x16x32_bf16 v[96:99], v[160:163], v[208:211], v[96:99]
	v_mfma_f32_16x16x32_bf16 v[96:99], v[164:167], v[212:215], v[96:99]
	s_setprio 0
	s_setprio 1
	v_mfma_f32_16x16x32_bf16 v[92:95], v[168:171], v[184:187], v[92:95]
	v_mfma_f32_16x16x32_bf16 v[92:95], v[172:175], v[188:191], v[92:95]
	v_mfma_f32_16x16x32_bf16 v[88:91], v[176:179], v[184:187], v[88:91]
	v_mfma_f32_16x16x32_bf16 v[88:91], v[180:183], v[188:191], v[88:91]
	v_mfma_f32_16x16x32_bf16 v[84:87], v[168:171], v[192:195], v[84:87]
	v_mfma_f32_16x16x32_bf16 v[84:87], v[172:175], v[196:199], v[84:87]
	v_mfma_f32_16x16x32_bf16 v[80:83], v[176:179], v[192:195], v[80:83]
	v_mfma_f32_16x16x32_bf16 v[80:83], v[180:183], v[196:199], v[80:83]
	v_mfma_f32_16x16x32_bf16 v[76:79], v[168:171], v[200:203], v[76:79]
	v_mfma_f32_16x16x32_bf16 v[76:79], v[172:175], v[204:207], v[76:79]
	v_mfma_f32_16x16x32_bf16 v[72:75], v[176:179], v[200:203], v[72:75]
	v_mfma_f32_16x16x32_bf16 v[72:75], v[180:183], v[204:207], v[72:75]
	v_mfma_f32_16x16x32_bf16 v[68:71], v[168:171], v[208:211], v[68:71]
	v_mfma_f32_16x16x32_bf16 v[68:71], v[172:175], v[212:215], v[68:71]
	v_mfma_f32_16x16x32_bf16 v[64:67], v[176:179], v[208:211], v[64:67]
	v_mfma_f32_16x16x32_bf16 v[64:67], v[180:183], v[212:215], v[64:67]
	s_setprio 0
	s_barrier
; #define PG8_STAGE(bufoff, gbase, voff) do { _Pragma("unroll") for (int _i = 0; _i < 2; ++_i) \
;         __builtin_amdgcn_global_load_lds((const unsigned*)((const char*)(gbase) + (voff)[_i]), (PG8_LAS unsigned*)(lds + (bufoff) + ldsw + _i * 8192), 16, 0, 0); } while (0)
; #define PG8_LDA(dst, b, h) do { _Pragma("unroll") for (int m = 0; m < 4; ++m) _Pragma("unroll") for (int k = 0; k < 2; ++k) dst[m][k] = *(const PG8_LAS bf16x8*)(lds + PG8_SA(b, h) + aoff + m * 2048 + k * 1024); } while (0)
; #define PG8_MMA(ai, bj, At, Bt) do { __builtin_amdgcn_s_setprio(1); _Pragma("unroll") for (int m = 0; m < 4; ++m) _Pragma("unroll") for (int n = 0; n < 2; ++n) _Pragma("unroll") for (int k = 0; k < 2; ++k) \
;         acc[ai][bj][m][n] = __builtin_amdgcn_mfma_f32_16x16x32_bf16(Bt[n][k], At[m][k], acc[ai][bj][m][n], 0, 0, 0); __builtin_amdgcn_s_setprio(0); } while (0)
; #define PG8_WAIT_V(n) asm volatile("s_waitcnt vmcnt(" #n ")" ::: "memory")
; #define PG8_WAIT_L(n) asm volatile("s_waitcnt lgkmcnt(" #n ")" ::: "memory")
; #define PG8_BAR __builtin_amdgcn_s_barrier()
; #define PG8_SCHED __builtin_amdgcn_sched_barrier(0)
; template <class Epi, class Sched, bool ALIGN_EPI = false, bool SP2 = false, bool APERM = false  >
; __device__ __forceinline__ void gemm_phase(PG8_LAS unsigned char* lds, const Gemm g, const Sched& S, const Epi& E, const int wid  ) {
;     ...
;         for (int t = 0; t < nt; t += 2) {
;             const bool last = (t == nt - 2);
;             const char* a1 = cA + (size_t)(t + 1) * kstep;
;             const char* a2 = last ? nA : cA + (size_t)(t + 2) * kstep; const char* b2 = last ? nB : cB + (size_t)(t + 2) * kstep;
;     ...
;             PG8_LDA(At, 1, 1); PG8_STAGE(PG8_SB(1, 0), b3, voffB); PG8_STAGE(PG8_SB(1, 1), b3 + hstep, voffB); PG8_STAGE(PG8_SA(1, 0), a3, voffA);
;             PG8_WAIT_V(8); PG8_WAIT_L(0); PG8_BAR; PG8_MMA(1, 0, At, B0); PG8_MMA(1, 1, At, B1); PG8_BAR; PG8_SCHED;
	s_add_i32 s72, s74, s79
	v_lshl_add_u64 v[216:217], v[216:217], 0, s[38:39]
	s_mov_b32 m0, s72
	ds_read_b128 v[184:187], v158 offset:49152
	ds_read_b128 v[188:191], v158 offset:50176
	ds_read_b128 v[192:195], v158 offset:51200
	ds_read_b128 v[196:199], v158 offset:52224
	ds_read_b128 v[200:203], v158 offset:53248
	ds_read_b128 v[204:207], v158 offset:54272
	ds_read_b128 v[208:211], v158 offset:55296
	ds_read_b128 v[212:215], v158 offset:56320
	global_load_lds_dwordx4 v[216:217], off
	s_add_i32 m0, s72, 0x2000
	s_add_u32 s70, s70, 0x160080
	v_lshl_add_u64 v[216:217], v[218:219], 0, s[38:39]
	s_addc_u32 s71, s71, 0
	s_add_i32 s72, s75, s79
	global_load_lds_dwordx4 v[216:217], off
	v_lshl_add_u64 v[216:217], s[70:71], 0, v[128:129]
	s_mov_b32 m0, s72
	s_nop 0
	global_load_lds_dwordx4 v[216:217], off
	v_lshl_add_u64 v[216:217], s[70:71], 0, v[130:131]
	s_add_i32 m0, s72, 0x2000
	s_nop 0
	global_load_lds_dwordx4 v[216:217], off
	v_lshl_add_u64 v[216:217], v[220:221], 0, s[38:39]
	s_mov_b32 m0, s93
	s_nop 0
	global_load_lds_dwordx4 v[216:217], off
	v_lshl_add_u64 v[216:217], v[222:223], 0, s[38:39]
	s_mov_b32 m0, s94
	s_nop 0
	global_load_lds_dwordx4 v[216:217], off
	s_waitcnt vmcnt(8)
	s_waitcnt lgkmcnt(0)
	s_barrier
	s_setprio 1
	s_waitcnt lgkmcnt(0)
	v_mfma_f32_16x16x32_bf16 v[60:63], v[144:147], v[184:187], v[60:63]
	v_mfma_f32_16x16x32_bf16 v[60:63], v[148:151], v[188:191], v[60:63]
	v_mfma_f32_16x16x32_bf16 v[56:59], v[160:163], v[184:187], v[56:59]
	v_mfma_f32_16x16x32_bf16 v[56:59], v[164:167], v[188:191], v[56:59]
	v_mfma_f32_16x16x32_bf16 v[52:55], v[144:147], v[192:195], v[52:55]
	v_mfma_f32_16x16x32_bf16 v[52:55], v[148:151], v[196:199], v[52:55]
	v_mfma_f32_16x16x32_bf16 v[48:51], v[160:163], v[192:195], v[48:51]
	v_mfma_f32_16x16x32_bf16 v[48:51], v[164:167], v[196:199], v[48:51]
	v_mfma_f32_16x16x32_bf16 v[44:47], v[144:147], v[200:203], v[44:47]
	v_mfma_f32_16x16x32_bf16 v[44:47], v[148:151], v[204:207], v[44:47]
	v_mfma_f32_16x16x32_bf16 v[40:43], v[160:163], v[200:203], v[40:43]
	v_mfma_f32_16x16x32_bf16 v[40:43], v[164:167], v[204:207], v[40:43]
	v_mfma_f32_16x16x32_bf16 v[36:39], v[144:147], v[208:211], v[36:39]
	v_mfma_f32_16x16x32_bf16 v[36:39], v[148:151], v[212:215], v[36:39]
	v_mfma_f32_16x16x32_bf16 v[32:35], v[160:163], v[208:211], v[32:35]
	v_mfma_f32_16x16x32_bf16 v[32:35], v[164:167], v[212:215], v[32:35]
	s_setprio 0
	s_setprio 1
	v_mfma_f32_16x16x32_bf16 v[28:31], v[168:171], v[184:187], v[28:31]
	v_mfma_f32_16x16x32_bf16 v[28:31], v[172:175], v[188:191], v[28:31]
	v_mfma_f32_16x16x32_bf16 v[24:27], v[176:179], v[184:187], v[24:27]
	v_mfma_f32_16x16x32_bf16 v[24:27], v[180:183], v[188:191], v[24:27]
	v_mfma_f32_16x16x32_bf16 v[20:23], v[168:171], v[192:195], v[20:23]
	v_mfma_f32_16x16x32_bf16 v[20:23], v[172:175], v[196:199], v[20:23]
	v_mfma_f32_16x16x32_bf16 v[16:19], v[176:179], v[192:195], v[16:19]
	v_mfma_f32_16x16x32_bf16 v[16:19], v[180:183], v[196:199], v[16:19]
	v_mfma_f32_16x16x32_bf16 v[12:15], v[168:171], v[200:203], v[12:15]
	v_mfma_f32_16x16x32_bf16 v[12:15], v[172:175], v[204:207], v[12:15]
	v_mfma_f32_16x16x32_bf16 v[8:11], v[176:179], v[200:203], v[8:11]
	v_mfma_f32_16x16x32_bf16 v[8:11], v[180:183], v[204:207], v[8:11]
	v_mfma_f32_16x16x32_bf16 v[4:7], v[168:171], v[208:211], v[4:7]
	v_mfma_f32_16x16x32_bf16 v[4:7], v[172:175], v[212:215], v[4:7]
	v_mfma_f32_16x16x32_bf16 v[0:3], v[176:179], v[208:211], v[0:3]
	v_mfma_f32_16x16x32_bf16 v[0:3], v[180:183], v[212:215], v[0:3]
	s_setprio 0
	s_barrier
	s_cmp_gt_u32 s78, 41
	s_cbranch_scc1 .LBB0_1316
	s_mov_b32 s78, s36
	s_branch .LBB0_1297

; #define PG8_STAGE(bufoff, gbase, voff) do { _Pragma("unroll") for (int _i = 0; _i < 2; ++_i) \
;         __builtin_amdgcn_global_load_lds((const unsigned*)((const char*)(gbase) + (voff)[_i]), (PG8_LAS unsigned*)(lds + (bufoff) + ldsw + _i * 8192), 16, 0, 0); } while (0)
; #define PG8_LDA(dst, b, h) do { _Pragma("unroll") for (int m = 0; m < 4; ++m) _Pragma("unroll") for (int k = 0; k < 2; ++k) dst[m][k] = *(const PG8_LAS bf16x8*)(lds + PG8_SA(b, h) + aoff + m * 2048 + k * 1024); } while (0)
; #define PG8_LDB(dst, b, h) do { _Pragma("unroll") for (int n = 0; n < 2; ++n) _Pragma("unroll") for (int k = 0; k < 2; ++k) dst[n][k] = *(const PG8_LAS bf16x8*)(lds + PG8_SB(b, h) + boff + n * 2048 + k * 1024); } while (0)
; #define PG8_MMA(ai, bj, At, Bt) do { __builtin_amdgcn_s_setprio(1); _Pragma("unroll") for (int m = 0; m < 4; ++m) _Pragma("unroll") for (int n = 0; n < 2; ++n) _Pragma("unroll") for (int k = 0; k < 2; ++k) \
;         acc[ai][bj][m][n] = __builtin_amdgcn_mfma_f32_16x16x32_bf16(Bt[n][k], At[m][k], acc[ai][bj][m][n], 0, 0, 0); __builtin_amdgcn_s_setprio(0); } while (0)
; #define PG8_WAIT_V(n) asm volatile("s_waitcnt vmcnt(" #n ")" ::: "memory")
; #define PG8_WAIT_L(n) asm volatile("s_waitcnt lgkmcnt(" #n ")" ::: "memory")
; template <class Epi, class Sched, bool ALIGN_EPI = false, bool SP2 = false, bool APERM = false  >
; __device__ __forceinline__ void gemm_phase(PG8_LAS unsigned char* lds, const Gemm g, const Sched& S, const Epi& E, const int wid  ) {
;     ...
;             const bool last = (t == nt - 2);
;             const char* a1 = cA + (size_t)(t + 1) * kstep;
;             const char* a2 = last ? nA : cA + (size_t)(t + 2) * kstep; const char* b2 = last ? nB : cB + (size_t)(t + 2) * kstep;
;             const char* a3 = a2 + kstep; const char* b3 = b2 + kstep;
;             if (last && has_next) S.a_ready(nxt);
;             if constexpr (SP2) {
;             PG8_LDB(B0, 0, 0); PG8_LDB(B1, 0, 1); PG8_SCHED; PG8_LDA(At, 0, 0); PG8_STAGE(PG8_SA(1, 1), a1 + hstep, voffA);
;             PG8_WAIT_V(8); PG8_WAIT_L(0); PG8_BAR; PG8_MMA(0, 0, At, B0); PG8_MMA(0, 1, At, B1); PG8_BAR; PG8_SCHED;
;             PG8_LDA(At, 0, 1); PG8_STAGE(PG8_SB(0, 0), b2, voffB); PG8_STAGE(PG8_SB(0, 1), b2 + hstep, voffB); PG8_STAGE(PG8_SA(0, 0), a2, voffA);
;             PG8_WAIT_V(8); PG8_WAIT_L(0); PG8_BAR; PG8_MMA(1, 0, At, B0); PG8_MMA(1, 1, At, B1); PG8_BAR; PG8_SCHED;
.LBB0_1373:
	v_add_u32_e32 v1, s78, v146
	ds_read_b128 v[150:153], v1
	ds_read_b128 v[154:157], v1 offset:1024
	ds_read_b128 v[158:161], v1 offset:2048
	ds_read_b128 v[162:165], v1 offset:3072
	v_add_u32_e32 v1, s79, v146
	ds_read_b128 v[166:169], v1
	ds_read_b128 v[170:173], v1 offset:1024
	ds_read_b128 v[174:177], v1 offset:2048
	ds_read_b128 v[178:181], v1 offset:3072
	s_add_i32 s88, s56, 2
	s_add_u32 s89, s54, 0x80
	s_addc_u32 s57, s55, 0
	s_cmp_eq_u32 s75, s56
	s_cselect_b32 s56, s48, s89
	s_cselect_b32 s57, s49, s57
	s_cselect_b32 s91, s53, s87
	s_cselect_b32 s90, s52, s86
	s_mov_b32 m0, s80
	v_lshl_add_u64 v[2:3], s[54:55], 0, v[140:141]
	ds_read_b128 v[182:185], v148
	ds_read_b128 v[186:189], v148 offset:1024
	ds_read_b128 v[190:193], v148 offset:2048
	ds_read_b128 v[194:197], v148 offset:3072
	ds_read_b128 v[198:201], v148 offset:4096
	ds_read_b128 v[202:205], v148 offset:5120
	ds_read_b128 v[206:209], v148 offset:6144
	ds_read_b128 v[210:213], v148 offset:7168
	global_load_lds_dwordx4 v[2:3], off
	v_lshl_add_u64 v[2:3], s[54:55], 0, v[142:143]
	s_mov_b32 m0, s81
	s_nop 0
	global_load_lds_dwordx4 v[2:3], off
	s_waitcnt vmcnt(8)
	s_waitcnt lgkmcnt(0)
	s_barrier
	s_setprio 1
	s_waitcnt lgkmcnt(0)
	v_mfma_f32_16x16x32_bf16 v[128:131], v[150:153], v[182:185], v[128:131]
	v_mfma_f32_16x16x32_bf16 v[128:131], v[154:157], v[186:189], v[128:131]
	v_mfma_f32_16x16x32_bf16 v[124:127], v[158:161], v[182:185], v[124:127]
	v_mfma_f32_16x16x32_bf16 v[124:127], v[162:165], v[186:189], v[124:127]
	v_mfma_f32_16x16x32_bf16 v[120:123], v[150:153], v[190:193], v[120:123]
	v_mfma_f32_16x16x32_bf16 v[120:123], v[154:157], v[194:197], v[120:123]
	v_mfma_f32_16x16x32_bf16 v[116:119], v[158:161], v[190:193], v[116:119]
	v_mfma_f32_16x16x32_bf16 v[116:119], v[162:165], v[194:197], v[116:119]
	v_mfma_f32_16x16x32_bf16 v[112:115], v[150:153], v[198:201], v[112:115]
	v_mfma_f32_16x16x32_bf16 v[112:115], v[154:157], v[202:205], v[112:115]
	v_mfma_f32_16x16x32_bf16 v[108:111], v[158:161], v[198:201], v[108:111]
	v_mfma_f32_16x16x32_bf16 v[108:111], v[162:165], v[202:205], v[108:111]
	v_mfma_f32_16x16x32_bf16 v[104:107], v[150:153], v[206:209], v[104:107]
	v_mfma_f32_16x16x32_bf16 v[104:107], v[154:157], v[210:213], v[104:107]
	v_mfma_f32_16x16x32_bf16 v[100:103], v[158:161], v[206:209], v[100:103]
	v_mfma_f32_16x16x32_bf16 v[100:103], v[162:165], v[210:213], v[100:103]
	s_setprio 0
	s_setprio 1
	v_mfma_f32_16x16x32_bf16 v[96:99], v[166:169], v[182:185], v[96:99]
	v_mfma_f32_16x16x32_bf16 v[96:99], v[170:173], v[186:189], v[96:99]
	v_mfma_f32_16x16x32_bf16 v[92:95], v[174:177], v[182:185], v[92:95]
	v_mfma_f32_16x16x32_bf16 v[92:95], v[178:181], v[186:189], v[92:95]
	v_mfma_f32_16x16x32_bf16 v[88:91], v[166:169], v[190:193], v[88:91]
	v_mfma_f32_16x16x32_bf16 v[88:91], v[170:173], v[194:197], v[88:91]
	v_mfma_f32_16x16x32_bf16 v[84:87], v[174:177], v[190:193], v[84:87]
	v_mfma_f32_16x16x32_bf16 v[84:87], v[178:181], v[194:197], v[84:87]
	v_mfma_f32_16x16x32_bf16 v[80:83], v[166:169], v[198:201], v[80:83]
	v_mfma_f32_16x16x32_bf16 v[80:83], v[170:173], v[202:205], v[80:83]
	v_mfma_f32_16x16x32_bf16 v[76:79], v[174:177], v[198:201], v[76:79]
	v_mfma_f32_16x16x32_bf16 v[76:79], v[178:181], v[202:205], v[76:79]
	v_mfma_f32_16x16x32_bf16 v[72:75], v[166:169], v[206:209], v[72:75]
	v_mfma_f32_16x16x32_bf16 v[72:75], v[170:173], v[210:213], v[72:75]
	v_mfma_f32_16x16x32_bf16 v[68:71], v[174:177], v[206:209], v[68:71]
	v_mfma_f32_16x16x32_bf16 v[68:71], v[178:181], v[210:213], v[68:71]
	s_setprio 0
	s_barrier
	s_add_i32 s89, s78, s76
	v_lshl_add_u64 v[214:215], s[90:91], 0, v[136:137]
	s_mov_b32 m0, s89
	ds_read_b128 v[182:185], v148 offset:16384
	ds_read_b128 v[186:189], v148 offset:17408
	ds_read_b128 v[190:193], v148 offset:18432
	ds_read_b128 v[194:197], v148 offset:19456
	ds_read_b128 v[198:201], v148 offset:20480
	ds_read_b128 v[202:205], v148 offset:21504
	ds_read_b128 v[206:209], v148 offset:22528
	ds_read_b128 v[210:213], v148 offset:23552
	global_load_lds_dwordx4 v[214:215], off
	s_add_i32 m0, s89, 0x2000
	v_lshl_add_u64 v[216:217], s[90:91], 0, v[132:133]
	s_add_u32 s90, s90, s4
	s_addc_u32 s91, s91, s5
	s_add_i32 s89, s79, s76
	global_load_lds_dwordx4 v[216:217], off
	v_lshl_add_u64 v[218:219], s[90:91], 0, v[136:137]
	s_mov_b32 m0, s89
	v_lshl_add_u64 v[220:221], s[90:91], 0, v[132:133]
	global_load_lds_dwordx4 v[218:219], off
	s_add_i32 m0, s89, 0x2000
	v_lshl_add_u64 v[222:223], s[56:57], 0, v[138:139]
	global_load_lds_dwordx4 v[220:221], off
	s_mov_b32 m0, s66
	v_lshl_add_u64 v[224:225], s[56:57], 0, v[134:135]
	global_load_lds_dwordx4 v[222:223], off
	s_mov_b32 m0, s69
	s_nop 0
	global_load_lds_dwordx4 v[224:225], off
	s_waitcnt vmcnt(8)
	s_waitcnt lgkmcnt(0)
	s_barrier
; #define PG8_STAGE(bufoff, gbase, voff) do { _Pragma("unroll") for (int _i = 0; _i < 2; ++_i) \
;         __builtin_amdgcn_global_load_lds((const unsigned*)((const char*)(gbase) + (voff)[_i]), (PG8_LAS unsigned*)(lds + (bufoff) + ldsw + _i * 8192), 16, 0, 0); } while (0)
; #define PG8_LDA(dst, b, h) do { _Pragma("unroll") for (int m = 0; m < 4; ++m) _Pragma("unroll") for (int k = 0; k < 2; ++k) dst[m][k] = *(const PG8_LAS bf16x8*)(lds + PG8_SA(b, h) + aoff + m * 2048 + k * 1024); } while (0)
; #define PG8_LDB(dst, b, h) do { _Pragma("unroll") for (int n = 0; n < 2; ++n) _Pragma("unroll") for (int k = 0; k < 2; ++k) dst[n][k] = *(const PG8_LAS bf16x8*)(lds + PG8_SB(b, h) + boff + n * 2048 + k * 1024); } while (0)
; #define PG8_MMA(ai, bj, At, Bt) do { __builtin_amdgcn_s_setprio(1); _Pragma("unroll") for (int m = 0; m < 4; ++m) _Pragma("unroll") for (int n = 0; n < 2; ++n) _Pragma("unroll") for (int k = 0; k < 2; ++k) \
;         acc[ai][bj][m][n] = __builtin_amdgcn_mfma_f32_16x16x32_bf16(Bt[n][k], At[m][k], acc[ai][bj][m][n], 0, 0, 0); __builtin_amdgcn_s_setprio(0); } while (0)
; #define PG8_WAIT_V(n) asm volatile("s_waitcnt vmcnt(" #n ")" ::: "memory")
; #define PG8_WAIT_L(n) asm volatile("s_waitcnt lgkmcnt(" #n ")" ::: "memory")
; #define PG8_BAR __builtin_amdgcn_s_barrier()
; #define PG8_SCHED __builtin_amdgcn_sched_barrier(0)
; template <class Epi, class Sched, bool ALIGN_EPI = false, bool SP2 = false, bool APERM = false  >
; __device__ __forceinline__ void gemm_phase(PG8_LAS unsigned char* lds, const Gemm g, const Sched& S, const Epi& E, const int wid  ) {
;     ...
;             PG8_WAIT_V(8); PG8_WAIT_L(0); PG8_BAR; PG8_MMA(1, 0, At, B0); PG8_MMA(1, 1, At, B1); PG8_BAR; PG8_SCHED;
;             PG8_LDB(B0, 1, 0); PG8_LDB(B1, 1, 1); PG8_SCHED; PG8_LDA(At, 1, 0); PG8_STAGE(PG8_SA(0, 1), a2 + hstep, voffA);
;             PG8_WAIT_V(8); PG8_WAIT_L(0); PG8_BAR; PG8_MMA(0, 0, At, B0); PG8_MMA(0, 1, At, B1); PG8_BAR; PG8_SCHED;
	s_setprio 1
	s_waitcnt lgkmcnt(0)
	v_mfma_f32_16x16x32_bf16 v[64:67], v[150:153], v[182:185], v[64:67]
	v_mfma_f32_16x16x32_bf16 v[64:67], v[154:157], v[186:189], v[64:67]
	v_mfma_f32_16x16x32_bf16 v[60:63], v[158:161], v[182:185], v[60:63]
	v_mfma_f32_16x16x32_bf16 v[60:63], v[162:165], v[186:189], v[60:63]
	v_mfma_f32_16x16x32_bf16 v[56:59], v[150:153], v[190:193], v[56:59]
	v_mfma_f32_16x16x32_bf16 v[56:59], v[154:157], v[194:197], v[56:59]
	v_mfma_f32_16x16x32_bf16 v[52:55], v[158:161], v[190:193], v[52:55]
	v_mfma_f32_16x16x32_bf16 v[52:55], v[162:165], v[194:197], v[52:55]
	v_mfma_f32_16x16x32_bf16 v[48:51], v[150:153], v[198:201], v[48:51]
	v_mfma_f32_16x16x32_bf16 v[48:51], v[154:157], v[202:205], v[48:51]
	v_mfma_f32_16x16x32_bf16 v[44:47], v[158:161], v[198:201], v[44:47]
	v_mfma_f32_16x16x32_bf16 v[44:47], v[162:165], v[202:205], v[44:47]
	v_mfma_f32_16x16x32_bf16 v[40:43], v[150:153], v[206:209], v[40:43]
	v_mfma_f32_16x16x32_bf16 v[40:43], v[154:157], v[210:213], v[40:43]
	v_mfma_f32_16x16x32_bf16 v[36:39], v[158:161], v[206:209], v[36:39]
	v_mfma_f32_16x16x32_bf16 v[36:39], v[162:165], v[210:213], v[36:39]
	s_setprio 0
	s_setprio 1
	v_mfma_f32_16x16x32_bf16 v[32:35], v[166:169], v[182:185], v[32:35]
	v_mfma_f32_16x16x32_bf16 v[32:35], v[170:173], v[186:189], v[32:35]
	v_mfma_f32_16x16x32_bf16 v[28:31], v[174:177], v[182:185], v[28:31]
	v_mfma_f32_16x16x32_bf16 v[28:31], v[178:181], v[186:189], v[28:31]
	v_mfma_f32_16x16x32_bf16 v[24:27], v[166:169], v[190:193], v[24:27]
	v_mfma_f32_16x16x32_bf16 v[24:27], v[170:173], v[194:197], v[24:27]
	v_mfma_f32_16x16x32_bf16 v[20:23], v[174:177], v[190:193], v[20:23]
	v_mfma_f32_16x16x32_bf16 v[20:23], v[178:181], v[194:197], v[20:23]
	v_mfma_f32_16x16x32_bf16 v[16:19], v[166:169], v[198:201], v[16:19]
	v_mfma_f32_16x16x32_bf16 v[16:19], v[170:173], v[202:205], v[16:19]
	v_mfma_f32_16x16x32_bf16 v[12:15], v[174:177], v[198:201], v[12:15]
	v_mfma_f32_16x16x32_bf16 v[12:15], v[178:181], v[202:205], v[12:15]
	v_mfma_f32_16x16x32_bf16 v[8:11], v[166:169], v[206:209], v[8:11]
	v_mfma_f32_16x16x32_bf16 v[8:11], v[170:173], v[210:213], v[8:11]
	v_mfma_f32_16x16x32_bf16 v[2:5], v[174:177], v[206:209], v[4:7]
	v_mfma_f32_16x16x32_bf16 v[2:5], v[178:181], v[210:213], v[2:5]
	s_setprio 0
	s_barrier
	s_add_i32 s89, 0, 0x18000
	v_add_u32_e32 v1, s89, v146
	s_add_i32 s90, 0, 0x1c000
	ds_read_b128 v[150:153], v1
	ds_read_b128 v[154:157], v1 offset:1024
	ds_read_b128 v[158:161], v1 offset:2048
	ds_read_b128 v[162:165], v1 offset:3072
	v_add_u32_e32 v1, s90, v146
	ds_read_b128 v[166:169], v1
	ds_read_b128 v[170:173], v1 offset:1024
	ds_read_b128 v[174:177], v1 offset:2048
	ds_read_b128 v[178:181], v1 offset:3072
	s_add_u32 s56, s56, s4
	s_addc_u32 s57, s57, s5
	s_mov_b32 m0, s70
	v_lshl_add_u64 v[6:7], s[56:57], 0, v[138:139]
	ds_read_b128 v[182:185], v148 offset:32768
	ds_read_b128 v[186:189], v148 offset:33792
	ds_read_b128 v[190:193], v148 offset:34816
	ds_read_b128 v[194:197], v148 offset:35840
	ds_read_b128 v[198:201], v148 offset:36864
	ds_read_b128 v[202:205], v148 offset:37888
	ds_read_b128 v[206:209], v148 offset:38912
	ds_read_b128 v[210:213], v148 offset:39936
	global_load_lds_dwordx4 v[6:7], off
	v_lshl_add_u64 v[6:7], s[56:57], 0, v[134:135]
	s_mov_b32 m0, s71
	s_nop 0
	global_load_lds_dwordx4 v[6:7], off
	s_waitcnt vmcnt(8)
	s_waitcnt lgkmcnt(0)
	s_barrier
	s_setprio 1
	s_waitcnt lgkmcnt(0)
	v_mfma_f32_16x16x32_bf16 v[128:131], v[150:153], v[182:185], v[128:131]
	v_mfma_f32_16x16x32_bf16 v[128:131], v[154:157], v[186:189], v[128:131]
	v_mfma_f32_16x16x32_bf16 v[124:127], v[158:161], v[182:185], v[124:127]
	v_mfma_f32_16x16x32_bf16 v[124:127], v[162:165], v[186:189], v[124:127]
	v_mfma_f32_16x16x32_bf16 v[120:123], v[150:153], v[190:193], v[120:123]
	v_mfma_f32_16x16x32_bf16 v[120:123], v[154:157], v[194:197], v[120:123]
	v_mfma_f32_16x16x32_bf16 v[116:119], v[158:161], v[190:193], v[116:119]
	v_mfma_f32_16x16x32_bf16 v[116:119], v[162:165], v[194:197], v[116:119]
	v_mfma_f32_16x16x32_bf16 v[112:115], v[150:153], v[198:201], v[112:115]
	v_mfma_f32_16x16x32_bf16 v[112:115], v[154:157], v[202:205], v[112:115]
	v_mfma_f32_16x16x32_bf16 v[108:111], v[158:161], v[198:201], v[108:111]
	v_mfma_f32_16x16x32_bf16 v[108:111], v[162:165], v[202:205], v[108:111]
	v_mfma_f32_16x16x32_bf16 v[104:107], v[150:153], v[206:209], v[104:107]
	v_mfma_f32_16x16x32_bf16 v[104:107], v[154:157], v[210:213], v[104:107]
	v_mfma_f32_16x16x32_bf16 v[100:103], v[158:161], v[206:209], v[100:103]
	v_mfma_f32_16x16x32_bf16 v[100:103], v[162:165], v[210:213], v[100:103]
	s_setprio 0
	s_setprio 1
	v_mfma_f32_16x16x32_bf16 v[96:99], v[166:169], v[182:185], v[96:99]
	v_mfma_f32_16x16x32_bf16 v[96:99], v[170:173], v[186:189], v[96:99]
	v_mfma_f32_16x16x32_bf16 v[92:95], v[174:177], v[182:185], v[92:95]
	v_mfma_f32_16x16x32_bf16 v[92:95], v[178:181], v[186:189], v[92:95]
	v_mfma_f32_16x16x32_bf16 v[88:91], v[166:169], v[190:193], v[88:91]
	v_mfma_f32_16x16x32_bf16 v[88:91], v[170:173], v[194:197], v[88:91]
	v_mfma_f32_16x16x32_bf16 v[84:87], v[174:177], v[190:193], v[84:87]
	v_mfma_f32_16x16x32_bf16 v[84:87], v[178:181], v[194:197], v[84:87]
	v_mfma_f32_16x16x32_bf16 v[80:83], v[166:169], v[198:201], v[80:83]
	v_mfma_f32_16x16x32_bf16 v[80:83], v[170:173], v[202:205], v[80:83]
	v_mfma_f32_16x16x32_bf16 v[76:79], v[174:177], v[198:201], v[76:79]
	v_mfma_f32_16x16x32_bf16 v[76:79], v[178:181], v[202:205], v[76:79]
	v_mfma_f32_16x16x32_bf16 v[72:75], v[166:169], v[206:209], v[72:75]
	v_mfma_f32_16x16x32_bf16 v[72:75], v[170:173], v[210:213], v[72:75]
	v_mfma_f32_16x16x32_bf16 v[68:71], v[174:177], v[206:209], v[68:71]
	v_mfma_f32_16x16x32_bf16 v[68:71], v[178:181], v[210:213], v[68:71]
	s_setprio 0
	s_barrier
; #define PG8_STAGE(bufoff, gbase, voff) do { _Pragma("unroll") for (int _i = 0; _i < 2; ++_i) \
;         __builtin_amdgcn_global_load_lds((const unsigned*)((const char*)(gbase) + (voff)[_i]), (PG8_LAS unsigned*)(lds + (bufoff) + ldsw + _i * 8192), 16, 0, 0); } while (0)
; #define PG8_LDA(dst, b, h) do { _Pragma("unroll") for (int m = 0; m < 4; ++m) _Pragma("unroll") for (int k = 0; k < 2; ++k) dst[m][k] = *(const PG8_LAS bf16x8*)(lds + PG8_SA(b, h) + aoff + m * 2048 + k * 1024); } while (0)
; #define PG8_MMA(ai, bj, At, Bt) do { __builtin_amdgcn_s_setprio(1); _Pragma("unroll") for (int m = 0; m < 4; ++m) _Pragma("unroll") for (int n = 0; n < 2; ++n) _Pragma("unroll") for (int k = 0; k < 2; ++k) \
;         acc[ai][bj][m][n] = __builtin_amdgcn_mfma_f32_16x16x32_bf16(Bt[n][k], At[m][k], acc[ai][bj][m][n], 0, 0, 0); __builtin_amdgcn_s_setprio(0); } while (0)
; #define PG8_WAIT_V(n) asm volatile("s_waitcnt vmcnt(" #n ")" ::: "memory")
; #define PG8_WAIT_L(n) asm volatile("s_waitcnt lgkmcnt(" #n ")" ::: "memory")
; #define PG8_BAR __builtin_amdgcn_s_barrier()
; #define PG8_SCHED __builtin_amdgcn_sched_barrier(0)
; template <class Epi, class Sched, bool ALIGN_EPI = false, bool SP2 = false, bool APERM = false  >
; __device__ __forceinline__ void gemm_phase(PG8_LAS unsigned char* lds, const Gemm g, const Sched& S, const Epi& E, const int wid  ) {
;     ...
;         for (int t = 0; t < nt; t += 2) {
;             const bool last = (t == nt - 2);
;             const char* a1 = cA + (size_t)(t + 1) * kstep;
;             const char* a2 = last ? nA : cA + (size_t)(t + 2) * kstep; const char* b2 = last ? nB : cB + (size_t)(t + 2) * kstep;
;     ...
;             PG8_LDA(At, 1, 1); PG8_STAGE(PG8_SB(1, 0), b3, voffB); PG8_STAGE(PG8_SB(1, 1), b3 + hstep, voffB); PG8_STAGE(PG8_SA(1, 0), a3, voffA);
;             PG8_WAIT_V(8); PG8_WAIT_L(0); PG8_BAR; PG8_MMA(1, 0, At, B0); PG8_MMA(1, 1, At, B1); PG8_BAR; PG8_SCHED;
	s_add_i32 s56, s89, s76
	v_lshl_add_u64 v[6:7], v[214:215], 0, s[16:17]
	s_mov_b32 m0, s56
	ds_read_b128 v[182:185], v148 offset:49152
	ds_read_b128 v[186:189], v148 offset:50176
	ds_read_b128 v[190:193], v148 offset:51200
	ds_read_b128 v[194:197], v148 offset:52224
	ds_read_b128 v[198:201], v148 offset:53248
	ds_read_b128 v[202:205], v148 offset:54272
	ds_read_b128 v[206:209], v148 offset:55296
	ds_read_b128 v[210:213], v148 offset:56320
	global_load_lds_dwordx4 v[6:7], off
	v_lshl_add_u64 v[6:7], v[216:217], 0, s[16:17]
	s_add_i32 m0, s56, 0x2000
	s_add_i32 s56, s90, s76
	global_load_lds_dwordx4 v[6:7], off
	v_lshl_add_u64 v[6:7], v[218:219], 0, s[16:17]
	s_mov_b32 m0, s56
	s_nop 0
	global_load_lds_dwordx4 v[6:7], off
	v_lshl_add_u64 v[6:7], v[220:221], 0, s[16:17]
	s_add_i32 m0, s56, 0x2000
	s_nop 0
	global_load_lds_dwordx4 v[6:7], off
	v_lshl_add_u64 v[6:7], v[222:223], 0, s[16:17]
	s_mov_b32 m0, s73
	s_nop 0
	global_load_lds_dwordx4 v[6:7], off
	v_lshl_add_u64 v[6:7], v[224:225], 0, s[16:17]
	s_mov_b32 m0, s74
	s_nop 0
	global_load_lds_dwordx4 v[6:7], off
	s_waitcnt vmcnt(8)
	s_waitcnt lgkmcnt(0)
	s_barrier
	s_setprio 1
	s_waitcnt lgkmcnt(0)
	v_mfma_f32_16x16x32_bf16 v[64:67], v[150:153], v[182:185], v[64:67]
	v_mfma_f32_16x16x32_bf16 v[64:67], v[154:157], v[186:189], v[64:67]
	v_mfma_f32_16x16x32_bf16 v[60:63], v[158:161], v[182:185], v[60:63]
	v_mfma_f32_16x16x32_bf16 v[60:63], v[162:165], v[186:189], v[60:63]
	v_mfma_f32_16x16x32_bf16 v[56:59], v[150:153], v[190:193], v[56:59]
	v_mfma_f32_16x16x32_bf16 v[56:59], v[154:157], v[194:197], v[56:59]
	v_mfma_f32_16x16x32_bf16 v[52:55], v[158:161], v[190:193], v[52:55]
	v_mfma_f32_16x16x32_bf16 v[52:55], v[162:165], v[194:197], v[52:55]
	v_mfma_f32_16x16x32_bf16 v[48:51], v[150:153], v[198:201], v[48:51]
	v_mfma_f32_16x16x32_bf16 v[48:51], v[154:157], v[202:205], v[48:51]
	v_mfma_f32_16x16x32_bf16 v[44:47], v[158:161], v[198:201], v[44:47]
	v_mfma_f32_16x16x32_bf16 v[44:47], v[162:165], v[202:205], v[44:47]
	v_mfma_f32_16x16x32_bf16 v[40:43], v[150:153], v[206:209], v[40:43]
	v_mfma_f32_16x16x32_bf16 v[40:43], v[154:157], v[210:213], v[40:43]
	v_mfma_f32_16x16x32_bf16 v[36:39], v[158:161], v[206:209], v[36:39]
	v_mfma_f32_16x16x32_bf16 v[36:39], v[162:165], v[210:213], v[36:39]
	s_setprio 0
	s_setprio 1
	v_mfma_f32_16x16x32_bf16 v[32:35], v[166:169], v[182:185], v[32:35]
	v_mfma_f32_16x16x32_bf16 v[28:31], v[174:177], v[182:185], v[28:31]
	v_mfma_f32_16x16x32_bf16 v[24:27], v[166:169], v[190:193], v[24:27]
	v_mfma_f32_16x16x32_bf16 v[20:23], v[174:177], v[190:193], v[20:23]
	v_mfma_f32_16x16x32_bf16 v[16:19], v[166:169], v[198:201], v[16:19]
	v_mfma_f32_16x16x32_bf16 v[12:15], v[174:177], v[198:201], v[12:15]
	v_mfma_f32_16x16x32_bf16 v[6:9], v[166:169], v[206:209], v[8:11]
	v_mfma_f32_16x16x32_bf16 v[2:5], v[174:177], v[206:209], v[2:5]
	v_mfma_f32_16x16x32_bf16 v[32:35], v[170:173], v[186:189], v[32:35]
	v_mfma_f32_16x16x32_bf16 v[28:31], v[178:181], v[186:189], v[28:31]
	v_mfma_f32_16x16x32_bf16 v[24:27], v[170:173], v[194:197], v[24:27]
	v_mfma_f32_16x16x32_bf16 v[20:23], v[178:181], v[194:197], v[20:23]
	v_mfma_f32_16x16x32_bf16 v[16:19], v[170:173], v[202:205], v[16:19]
	v_mfma_f32_16x16x32_bf16 v[12:15], v[178:181], v[202:205], v[12:15]
	v_mfma_f32_16x16x32_bf16 v[8:11], v[170:173], v[210:213], v[6:9]
	v_mfma_f32_16x16x32_bf16 v[4:7], v[178:181], v[210:213], v[2:5]
	s_setprio 0
	s_barrier
	s_add_u32 s54, s54, 0x100
	s_addc_u32 s55, s55, 0
	s_add_u32 s86, s86, 0x100
	s_addc_u32 s87, s87, 0
	s_cmp_ge_i32 s88, s72
	s_mov_b32 s56, s88
	s_cbranch_scc0 .LBB0_1373

; #define PG8_STAGE(bufoff, gbase, voff) do { _Pragma("unroll") for (int _i = 0; _i < 2; ++_i) \
;         __builtin_amdgcn_global_load_lds((const unsigned*)((const char*)(gbase) + (voff)[_i]), (PG8_LAS unsigned*)(lds + (bufoff) + ldsw + _i * 8192), 16, 0, 0); } while (0)
; #define PG8_LDA(dst, b, h) do { _Pragma("unroll") for (int m = 0; m < 4; ++m) _Pragma("unroll") for (int k = 0; k < 2; ++k) dst[m][k] = *(const PG8_LAS bf16x8*)(lds + PG8_SA(b, h) + aoff + m * 2048 + k * 1024); } while (0)
; #define PG8_LDB(dst, b, h) do { _Pragma("unroll") for (int n = 0; n < 2; ++n) _Pragma("unroll") for (int k = 0; k < 2; ++k) dst[n][k] = *(const PG8_LAS bf16x8*)(lds + PG8_SB(b, h) + boff + n * 2048 + k * 1024); } while (0)
; #define PG8_MMA(ai, bj, At, Bt) do { __builtin_amdgcn_s_setprio(1); _Pragma("unroll") for (int m = 0; m < 4; ++m) _Pragma("unroll") for (int n = 0; n < 2; ++n) _Pragma("unroll") for (int k = 0; k < 2; ++k) \
;         acc[ai][bj][m][n] = __builtin_amdgcn_mfma_f32_16x16x32_bf16(Bt[n][k], At[m][k], acc[ai][bj][m][n], 0, 0, 0); __builtin_amdgcn_s_setprio(0); } while (0)
; #define PG8_WAIT_V(n) asm volatile("s_waitcnt vmcnt(" #n ")" ::: "memory")
; #define PG8_WAIT_L(n) asm volatile("s_waitcnt lgkmcnt(" #n ")" ::: "memory")
; template <class Epi, class Sched, bool ALIGN_EPI = false, bool SP2 = false, bool APERM = false  >
; __device__ __forceinline__ void gemm_phase(PG8_LAS unsigned char* lds, const Gemm g, const Sched& S, const Epi& E, const int wid  ) {
;     ...
;             const bool last = (t == nt - 2);
;             const char* a1 = cA + (size_t)(t + 1) * kstep;
;             const char* a2 = last ? nA : cA + (size_t)(t + 2) * kstep; const char* b2 = last ? nB : cB + (size_t)(t + 2) * kstep;
;             const char* a3 = a2 + kstep; const char* b3 = b2 + kstep;
;             if (last && has_next) S.a_ready(nxt);
;             if constexpr (SP2) {
;             PG8_LDB(B0, 0, 0); PG8_LDB(B1, 0, 1); PG8_SCHED; PG8_LDA(At, 0, 0); PG8_STAGE(PG8_SA(1, 1), a1 + hstep, voffA);
;             PG8_WAIT_V(8); PG8_WAIT_L(0); PG8_BAR; PG8_MMA(0, 0, At, B0); PG8_MMA(0, 1, At, B1); PG8_BAR; PG8_SCHED;
;             PG8_LDA(At, 0, 1); PG8_STAGE(PG8_SB(0, 0), b2, voffB); PG8_STAGE(PG8_SB(0, 1), b2 + hstep, voffB); PG8_STAGE(PG8_SA(0, 0), a2, voffA);
;             PG8_WAIT_V(8); PG8_WAIT_L(0); PG8_BAR; PG8_MMA(1, 0, At, B0); PG8_MMA(1, 1, At, B1); PG8_BAR; PG8_SCHED;
.LBB0_1423:
	s_lshl_b32 s24, s89, 7
	s_add_u32 s25, s30, s24
	s_addc_u32 s26, s31, 0
	s_add_u32 s27, s25, 0x100
	s_addc_u32 s90, s26, 0
	v_add_u32_e32 v140, s85, v173
	v_add_u32_e32 v154, s86, v173
	s_and_b64 s[18:19], s[6:7], exec
	s_waitcnt lgkmcnt(0)
	ds_read_b128 v[128:131], v140
	ds_read_b128 v[132:135], v140 offset:1024
	ds_read_b128 v[136:139], v140 offset:2048
	ds_read_b128 v[140:143], v140 offset:3072
	ds_read_b128 v[144:147], v154
	ds_read_b128 v[162:165], v154 offset:1024
	ds_read_b128 v[166:169], v154 offset:2048
	ds_read_b128 v[180:183], v154 offset:3072
	s_cselect_b32 s19, s33, s90
	s_cselect_b32 s18, s65, s27
	s_add_u32 s24, s14, s24
	s_addc_u32 s27, s15, 0
	s_add_u32 s24, s24, 0x100
	s_addc_u32 s27, s27, 0
	s_and_b64 s[6:7], s[6:7], exec
	s_cselect_b32 s6, s88, s24
	s_cselect_b32 s7, s67, s27
	s_add_u32 s24, s25, 0x80080
	s_addc_u32 s25, s26, 0
	v_lshl_add_u64 v[170:171], s[24:25], 0, v[152:153]
	s_add_i32 m0, s11, 0xc000
	ds_read_b128 v[184:187], v178
	ds_read_b128 v[188:191], v178 offset:1024
	ds_read_b128 v[192:195], v178 offset:2048
	ds_read_b128 v[196:199], v178 offset:3072
	ds_read_b128 v[200:203], v178 offset:4096
	ds_read_b128 v[204:207], v178 offset:5120
	ds_read_b128 v[208:211], v178 offset:6144
	ds_read_b128 v[212:215], v178 offset:7168
	global_load_lds_dwordx4 v[170:171], off
	v_lshl_add_u64 v[170:171], s[24:25], 0, v[156:157]
	s_add_i32 m0, s11, 0xe000
	s_nop 0
	global_load_lds_dwordx4 v[170:171], off
	s_waitcnt vmcnt(8)
	s_waitcnt lgkmcnt(0)
	s_barrier
	s_setprio 1
	s_waitcnt lgkmcnt(0)
	v_mfma_f32_16x16x32_bf16 v[124:127], v[128:131], v[184:187], v[124:127]
	v_mfma_f32_16x16x32_bf16 v[124:127], v[132:135], v[188:191], v[124:127]
	v_mfma_f32_16x16x32_bf16 v[120:123], v[136:139], v[184:187], v[120:123]
	v_mfma_f32_16x16x32_bf16 v[120:123], v[140:143], v[188:191], v[120:123]
	v_mfma_f32_16x16x32_bf16 v[116:119], v[128:131], v[192:195], v[116:119]
	v_mfma_f32_16x16x32_bf16 v[116:119], v[132:135], v[196:199], v[116:119]
	v_mfma_f32_16x16x32_bf16 v[112:115], v[136:139], v[192:195], v[112:115]
	v_mfma_f32_16x16x32_bf16 v[112:115], v[140:143], v[196:199], v[112:115]
	v_mfma_f32_16x16x32_bf16 v[108:111], v[128:131], v[200:203], v[108:111]
	v_mfma_f32_16x16x32_bf16 v[108:111], v[132:135], v[204:207], v[108:111]
	v_mfma_f32_16x16x32_bf16 v[104:107], v[136:139], v[200:203], v[104:107]
	v_mfma_f32_16x16x32_bf16 v[104:107], v[140:143], v[204:207], v[104:107]
	v_mfma_f32_16x16x32_bf16 v[100:103], v[128:131], v[208:211], v[100:103]
	v_mfma_f32_16x16x32_bf16 v[100:103], v[132:135], v[212:215], v[100:103]
	v_mfma_f32_16x16x32_bf16 v[96:99], v[136:139], v[208:211], v[96:99]
	v_mfma_f32_16x16x32_bf16 v[96:99], v[140:143], v[212:215], v[96:99]
	s_setprio 0
	s_setprio 1
	v_mfma_f32_16x16x32_bf16 v[92:95], v[144:147], v[184:187], v[92:95]
	v_mfma_f32_16x16x32_bf16 v[92:95], v[162:165], v[188:191], v[92:95]
	v_mfma_f32_16x16x32_bf16 v[88:91], v[166:169], v[184:187], v[88:91]
	v_mfma_f32_16x16x32_bf16 v[88:91], v[180:183], v[188:191], v[88:91]
	v_mfma_f32_16x16x32_bf16 v[84:87], v[144:147], v[192:195], v[84:87]
	v_mfma_f32_16x16x32_bf16 v[84:87], v[162:165], v[196:199], v[84:87]
	v_mfma_f32_16x16x32_bf16 v[80:83], v[166:169], v[192:195], v[80:83]
	v_mfma_f32_16x16x32_bf16 v[80:83], v[180:183], v[196:199], v[80:83]
	v_mfma_f32_16x16x32_bf16 v[76:79], v[144:147], v[200:203], v[76:79]
	v_mfma_f32_16x16x32_bf16 v[76:79], v[162:165], v[204:207], v[76:79]
	v_mfma_f32_16x16x32_bf16 v[72:75], v[166:169], v[200:203], v[72:75]
	v_mfma_f32_16x16x32_bf16 v[72:75], v[180:183], v[204:207], v[72:75]
	v_mfma_f32_16x16x32_bf16 v[68:71], v[144:147], v[208:211], v[68:71]
	v_mfma_f32_16x16x32_bf16 v[68:71], v[162:165], v[212:215], v[68:71]
	v_mfma_f32_16x16x32_bf16 v[64:67], v[166:169], v[208:211], v[64:67]
	v_mfma_f32_16x16x32_bf16 v[64:67], v[180:183], v[212:215], v[64:67]
	s_setprio 0
	s_barrier
	s_add_i32 s24, s85, s76
	v_lshl_add_u64 v[170:171], s[6:7], 0, v[148:149]
	s_mov_b32 m0, s24
	ds_read_b128 v[184:187], v178 offset:16384
	ds_read_b128 v[188:191], v178 offset:17408
	ds_read_b128 v[192:195], v178 offset:18432
	ds_read_b128 v[196:199], v178 offset:19456
	ds_read_b128 v[200:203], v178 offset:20480
	ds_read_b128 v[204:207], v178 offset:21504
	ds_read_b128 v[208:211], v178 offset:22528
	ds_read_b128 v[212:215], v178 offset:23552
	global_load_lds_dwordx4 v[170:171], off
	s_add_i32 m0, s24, 0x2000
	s_add_u32 s24, s6, 0x80000
	v_lshl_add_u64 v[216:217], s[6:7], 0, v[150:151]
	s_addc_u32 s25, s7, 0
	s_add_i32 s26, s86, s76
	global_load_lds_dwordx4 v[216:217], off
	v_lshl_add_u64 v[218:219], s[24:25], 0, v[148:149]
	s_mov_b32 m0, s26
	v_lshl_add_u64 v[220:221], s[18:19], 0, v[156:157]
	global_load_lds_dwordx4 v[218:219], off
	v_lshl_add_u64 v[218:219], s[24:25], 0, v[150:151]
	s_add_i32 m0, s26, 0x2000
	s_nop 0
	global_load_lds_dwordx4 v[218:219], off
	v_lshl_add_u64 v[218:219], s[18:19], 0, v[152:153]
	s_mov_b32 m0, s11
	s_nop 0
	global_load_lds_dwordx4 v[218:219], off
	s_mov_b32 m0, s13
	s_nop 0
	global_load_lds_dwordx4 v[220:221], off
	s_waitcnt vmcnt(8)
	s_waitcnt lgkmcnt(0)
	s_barrier
; #define PG8_STAGE(bufoff, gbase, voff) do { _Pragma("unroll") for (int _i = 0; _i < 2; ++_i) \
;         __builtin_amdgcn_global_load_lds((const unsigned*)((const char*)(gbase) + (voff)[_i]), (PG8_LAS unsigned*)(lds + (bufoff) + ldsw + _i * 8192), 16, 0, 0); } while (0)
; #define PG8_LDA(dst, b, h) do { _Pragma("unroll") for (int m = 0; m < 4; ++m) _Pragma("unroll") for (int k = 0; k < 2; ++k) dst[m][k] = *(const PG8_LAS bf16x8*)(lds + PG8_SA(b, h) + aoff + m * 2048 + k * 1024); } while (0)
; #define PG8_LDB(dst, b, h) do { _Pragma("unroll") for (int n = 0; n < 2; ++n) _Pragma("unroll") for (int k = 0; k < 2; ++k) dst[n][k] = *(const PG8_LAS bf16x8*)(lds + PG8_SB(b, h) + boff + n * 2048 + k * 1024); } while (0)
; #define PG8_MMA(ai, bj, At, Bt) do { __builtin_amdgcn_s_setprio(1); _Pragma("unroll") for (int m = 0; m < 4; ++m) _Pragma("unroll") for (int n = 0; n < 2; ++n) _Pragma("unroll") for (int k = 0; k < 2; ++k) \
;         acc[ai][bj][m][n] = __builtin_amdgcn_mfma_f32_16x16x32_bf16(Bt[n][k], At[m][k], acc[ai][bj][m][n], 0, 0, 0); __builtin_amdgcn_s_setprio(0); } while (0)
; #define PG8_WAIT_V(n) asm volatile("s_waitcnt vmcnt(" #n ")" ::: "memory")
; #define PG8_WAIT_L(n) asm volatile("s_waitcnt lgkmcnt(" #n ")" ::: "memory")
; #define PG8_BAR __builtin_amdgcn_s_barrier()
; #define PG8_SCHED __builtin_amdgcn_sched_barrier(0)
; template <class Epi, class Sched, bool ALIGN_EPI = false, bool SP2 = false, bool APERM = false  >
; __device__ __forceinline__ void gemm_phase(PG8_LAS unsigned char* lds, const Gemm g, const Sched& S, const Epi& E, const int wid  ) {
;     ...
;             PG8_WAIT_V(8); PG8_WAIT_L(0); PG8_BAR; PG8_MMA(1, 0, At, B0); PG8_MMA(1, 1, At, B1); PG8_BAR; PG8_SCHED;
;             PG8_LDB(B0, 1, 0); PG8_LDB(B1, 1, 1); PG8_SCHED; PG8_LDA(At, 1, 0); PG8_STAGE(PG8_SA(0, 1), a2 + hstep, voffA);
;             PG8_WAIT_V(8); PG8_WAIT_L(0); PG8_BAR; PG8_MMA(0, 0, At, B0); PG8_MMA(0, 1, At, B1); PG8_BAR; PG8_SCHED;
	s_setprio 1
	s_waitcnt lgkmcnt(0)
	v_mfma_f32_16x16x32_bf16 v[60:63], v[128:131], v[184:187], v[60:63]
	v_mfma_f32_16x16x32_bf16 v[60:63], v[132:135], v[188:191], v[60:63]
	v_mfma_f32_16x16x32_bf16 v[56:59], v[136:139], v[184:187], v[56:59]
	v_mfma_f32_16x16x32_bf16 v[56:59], v[140:143], v[188:191], v[56:59]
	v_mfma_f32_16x16x32_bf16 v[52:55], v[128:131], v[192:195], v[52:55]
	v_mfma_f32_16x16x32_bf16 v[52:55], v[132:135], v[196:199], v[52:55]
	v_mfma_f32_16x16x32_bf16 v[48:51], v[136:139], v[192:195], v[48:51]
	v_mfma_f32_16x16x32_bf16 v[48:51], v[140:143], v[196:199], v[48:51]
	v_mfma_f32_16x16x32_bf16 v[44:47], v[128:131], v[200:203], v[44:47]
	v_mfma_f32_16x16x32_bf16 v[44:47], v[132:135], v[204:207], v[44:47]
	v_mfma_f32_16x16x32_bf16 v[40:43], v[136:139], v[200:203], v[40:43]
	v_mfma_f32_16x16x32_bf16 v[40:43], v[140:143], v[204:207], v[40:43]
	v_mfma_f32_16x16x32_bf16 v[36:39], v[128:131], v[208:211], v[36:39]
	v_mfma_f32_16x16x32_bf16 v[36:39], v[132:135], v[212:215], v[36:39]
	v_mfma_f32_16x16x32_bf16 v[32:35], v[136:139], v[208:211], v[32:35]
	v_mfma_f32_16x16x32_bf16 v[32:35], v[140:143], v[212:215], v[32:35]
	s_setprio 0
	s_setprio 1
	v_mfma_f32_16x16x32_bf16 v[28:31], v[144:147], v[184:187], v[28:31]
	v_mfma_f32_16x16x32_bf16 v[28:31], v[162:165], v[188:191], v[28:31]
	v_mfma_f32_16x16x32_bf16 v[24:27], v[166:169], v[184:187], v[24:27]
	v_mfma_f32_16x16x32_bf16 v[24:27], v[180:183], v[188:191], v[24:27]
	v_mfma_f32_16x16x32_bf16 v[20:23], v[144:147], v[192:195], v[20:23]
	v_mfma_f32_16x16x32_bf16 v[20:23], v[162:165], v[196:199], v[20:23]
	v_mfma_f32_16x16x32_bf16 v[16:19], v[166:169], v[192:195], v[16:19]
	v_mfma_f32_16x16x32_bf16 v[16:19], v[180:183], v[196:199], v[16:19]
	v_mfma_f32_16x16x32_bf16 v[12:15], v[144:147], v[200:203], v[12:15]
	v_mfma_f32_16x16x32_bf16 v[12:15], v[162:165], v[204:207], v[12:15]
	v_mfma_f32_16x16x32_bf16 v[8:11], v[166:169], v[200:203], v[8:11]
	v_mfma_f32_16x16x32_bf16 v[8:11], v[180:183], v[204:207], v[8:11]
	v_mfma_f32_16x16x32_bf16 v[4:7], v[144:147], v[208:211], v[4:7]
	v_mfma_f32_16x16x32_bf16 v[4:7], v[162:165], v[212:215], v[4:7]
	v_mfma_f32_16x16x32_bf16 v[0:3], v[166:169], v[208:211], v[0:3]
	v_mfma_f32_16x16x32_bf16 v[0:3], v[180:183], v[212:215], v[0:3]
	s_setprio 0
	s_barrier
	s_add_i32 s24, 0, 0x18000
	s_add_i32 s25, 0, 0x1c000
	v_add_u32_e32 v140, s24, v173
	v_add_u32_e32 v154, s25, v173
	ds_read_b128 v[128:131], v140
	ds_read_b128 v[132:135], v140 offset:1024
	ds_read_b128 v[136:139], v140 offset:2048
	ds_read_b128 v[140:143], v140 offset:3072
	ds_read_b128 v[144:147], v154
	ds_read_b128 v[162:165], v154 offset:1024
	ds_read_b128 v[166:169], v154 offset:2048
	ds_read_b128 v[180:183], v154 offset:3072
	s_add_u32 s18, s18, 0x80000
	s_addc_u32 s19, s19, 0
	s_mov_b32 m0, s78
	v_lshl_add_u64 v[222:223], s[18:19], 0, v[152:153]
	ds_read_b128 v[184:187], v178 offset:32768
	ds_read_b128 v[188:191], v178 offset:33792
	ds_read_b128 v[192:195], v178 offset:34816
	ds_read_b128 v[196:199], v178 offset:35840
	ds_read_b128 v[200:203], v178 offset:36864
	ds_read_b128 v[204:207], v178 offset:37888
	ds_read_b128 v[208:211], v178 offset:38912
	ds_read_b128 v[212:215], v178 offset:39936
	global_load_lds_dwordx4 v[222:223], off
	v_lshl_add_u64 v[222:223], s[18:19], 0, v[156:157]
	s_mov_b32 m0, s79
	s_nop 0
	global_load_lds_dwordx4 v[222:223], off
	s_waitcnt vmcnt(8)
	s_waitcnt lgkmcnt(0)
	s_barrier
	s_setprio 1
	s_waitcnt lgkmcnt(0)
	v_mfma_f32_16x16x32_bf16 v[124:127], v[128:131], v[184:187], v[124:127]
	v_mfma_f32_16x16x32_bf16 v[124:127], v[132:135], v[188:191], v[124:127]
	v_mfma_f32_16x16x32_bf16 v[120:123], v[136:139], v[184:187], v[120:123]
	v_mfma_f32_16x16x32_bf16 v[120:123], v[140:143], v[188:191], v[120:123]
	v_mfma_f32_16x16x32_bf16 v[116:119], v[128:131], v[192:195], v[116:119]
	v_mfma_f32_16x16x32_bf16 v[116:119], v[132:135], v[196:199], v[116:119]
	v_mfma_f32_16x16x32_bf16 v[112:115], v[136:139], v[192:195], v[112:115]
	v_mfma_f32_16x16x32_bf16 v[112:115], v[140:143], v[196:199], v[112:115]
	v_mfma_f32_16x16x32_bf16 v[108:111], v[128:131], v[200:203], v[108:111]
	v_mfma_f32_16x16x32_bf16 v[108:111], v[132:135], v[204:207], v[108:111]
	v_mfma_f32_16x16x32_bf16 v[104:107], v[136:139], v[200:203], v[104:107]
	v_mfma_f32_16x16x32_bf16 v[104:107], v[140:143], v[204:207], v[104:107]
	v_mfma_f32_16x16x32_bf16 v[100:103], v[128:131], v[208:211], v[100:103]
	v_mfma_f32_16x16x32_bf16 v[100:103], v[132:135], v[212:215], v[100:103]
	v_mfma_f32_16x16x32_bf16 v[96:99], v[136:139], v[208:211], v[96:99]
	v_mfma_f32_16x16x32_bf16 v[96:99], v[140:143], v[212:215], v[96:99]
	s_setprio 0
	s_setprio 1
	v_mfma_f32_16x16x32_bf16 v[92:95], v[144:147], v[184:187], v[92:95]
	v_mfma_f32_16x16x32_bf16 v[92:95], v[162:165], v[188:191], v[92:95]
	v_mfma_f32_16x16x32_bf16 v[88:91], v[166:169], v[184:187], v[88:91]
	v_mfma_f32_16x16x32_bf16 v[88:91], v[180:183], v[188:191], v[88:91]
	v_mfma_f32_16x16x32_bf16 v[84:87], v[144:147], v[192:195], v[84:87]
	v_mfma_f32_16x16x32_bf16 v[84:87], v[162:165], v[196:199], v[84:87]
	v_mfma_f32_16x16x32_bf16 v[80:83], v[166:169], v[192:195], v[80:83]
	v_mfma_f32_16x16x32_bf16 v[80:83], v[180:183], v[196:199], v[80:83]
	v_mfma_f32_16x16x32_bf16 v[76:79], v[144:147], v[200:203], v[76:79]
	v_mfma_f32_16x16x32_bf16 v[76:79], v[162:165], v[204:207], v[76:79]
	v_mfma_f32_16x16x32_bf16 v[72:75], v[166:169], v[200:203], v[72:75]
	v_mfma_f32_16x16x32_bf16 v[72:75], v[180:183], v[204:207], v[72:75]
	v_mfma_f32_16x16x32_bf16 v[68:71], v[144:147], v[208:211], v[68:71]
	v_mfma_f32_16x16x32_bf16 v[68:71], v[162:165], v[212:215], v[68:71]
	v_mfma_f32_16x16x32_bf16 v[64:67], v[166:169], v[208:211], v[64:67]
	v_mfma_f32_16x16x32_bf16 v[64:67], v[180:183], v[212:215], v[64:67]
	s_setprio 0
	s_barrier
; #define PG8_STAGE(bufoff, gbase, voff) do { _Pragma("unroll") for (int _i = 0; _i < 2; ++_i) \
;         __builtin_amdgcn_global_load_lds((const unsigned*)((const char*)(gbase) + (voff)[_i]), (PG8_LAS unsigned*)(lds + (bufoff) + ldsw + _i * 8192), 16, 0, 0); } while (0)
; #define PG8_LDA(dst, b, h) do { _Pragma("unroll") for (int m = 0; m < 4; ++m) _Pragma("unroll") for (int k = 0; k < 2; ++k) dst[m][k] = *(const PG8_LAS bf16x8*)(lds + PG8_SA(b, h) + aoff + m * 2048 + k * 1024); } while (0)
; #define PG8_MMA(ai, bj, At, Bt) do { __builtin_amdgcn_s_setprio(1); _Pragma("unroll") for (int m = 0; m < 4; ++m) _Pragma("unroll") for (int n = 0; n < 2; ++n) _Pragma("unroll") for (int k = 0; k < 2; ++k) \
;         acc[ai][bj][m][n] = __builtin_amdgcn_mfma_f32_16x16x32_bf16(Bt[n][k], At[m][k], acc[ai][bj][m][n], 0, 0, 0); __builtin_amdgcn_s_setprio(0); } while (0)
; #define PG8_WAIT_V(n) asm volatile("s_waitcnt vmcnt(" #n ")" ::: "memory")
; #define PG8_WAIT_L(n) asm volatile("s_waitcnt lgkmcnt(" #n ")" ::: "memory")
; #define PG8_BAR __builtin_amdgcn_s_barrier()
; #define PG8_SCHED __builtin_amdgcn_sched_barrier(0)
; template <class Epi, class Sched, bool ALIGN_EPI = false, bool SP2 = false, bool APERM = false  >
; __device__ __forceinline__ void gemm_phase(PG8_LAS unsigned char* lds, const Gemm g, const Sched& S, const Epi& E, const int wid  ) {
;     ...
;         for (int t = 0; t < nt; t += 2) {
;             const bool last = (t == nt - 2);
;             const char* a1 = cA + (size_t)(t + 1) * kstep;
;             const char* a2 = last ? nA : cA + (size_t)(t + 2) * kstep; const char* b2 = last ? nB : cB + (size_t)(t + 2) * kstep;
;     ...
;             PG8_LDA(At, 1, 1); PG8_STAGE(PG8_SB(1, 0), b3, voffB); PG8_STAGE(PG8_SB(1, 1), b3 + hstep, voffB); PG8_STAGE(PG8_SA(1, 0), a3, voffA);
;             PG8_WAIT_V(8); PG8_WAIT_L(0); PG8_BAR; PG8_MMA(1, 0, At, B0); PG8_MMA(1, 1, At, B1); PG8_BAR; PG8_SCHED;
	s_add_i32 s18, s24, s76
	v_lshl_add_u64 v[170:171], v[170:171], 0, s[40:41]
	s_mov_b32 m0, s18
	ds_read_b128 v[184:187], v178 offset:49152
	ds_read_b128 v[188:191], v178 offset:50176
	ds_read_b128 v[192:195], v178 offset:51200
	ds_read_b128 v[196:199], v178 offset:52224
	ds_read_b128 v[200:203], v178 offset:53248
	ds_read_b128 v[204:207], v178 offset:54272
	ds_read_b128 v[208:211], v178 offset:55296
	ds_read_b128 v[212:215], v178 offset:56320
	global_load_lds_dwordx4 v[170:171], off
	s_add_i32 m0, s18, 0x2000
	s_add_u32 s6, s6, 0x80080
	v_lshl_add_u64 v[170:171], v[216:217], 0, s[40:41]
	s_addc_u32 s7, s7, 0
	s_add_i32 s18, s25, s76
	global_load_lds_dwordx4 v[170:171], off
	v_lshl_add_u64 v[170:171], s[6:7], 0, v[148:149]
	s_mov_b32 m0, s18
	s_nop 0
	global_load_lds_dwordx4 v[170:171], off
	v_lshl_add_u64 v[170:171], s[6:7], 0, v[150:151]
	s_add_i32 m0, s18, 0x2000
	s_nop 0
	global_load_lds_dwordx4 v[170:171], off
	v_lshl_add_u64 v[170:171], v[218:219], 0, s[40:41]
	s_mov_b32 m0, s82
	s_nop 0
	global_load_lds_dwordx4 v[170:171], off
	v_lshl_add_u64 v[170:171], v[220:221], 0, s[40:41]
	s_mov_b32 m0, s84
	s_nop 0
	global_load_lds_dwordx4 v[170:171], off
	s_waitcnt vmcnt(8)
	s_waitcnt lgkmcnt(0)
	s_barrier
	s_setprio 1
	s_waitcnt lgkmcnt(0)
	v_mfma_f32_16x16x32_bf16 v[60:63], v[128:131], v[184:187], v[60:63]
	v_mfma_f32_16x16x32_bf16 v[60:63], v[132:135], v[188:191], v[60:63]
	v_mfma_f32_16x16x32_bf16 v[56:59], v[136:139], v[184:187], v[56:59]
	v_mfma_f32_16x16x32_bf16 v[56:59], v[140:143], v[188:191], v[56:59]
	v_mfma_f32_16x16x32_bf16 v[52:55], v[128:131], v[192:195], v[52:55]
	v_mfma_f32_16x16x32_bf16 v[52:55], v[132:135], v[196:199], v[52:55]
	v_mfma_f32_16x16x32_bf16 v[48:51], v[136:139], v[192:195], v[48:51]
	v_mfma_f32_16x16x32_bf16 v[48:51], v[140:143], v[196:199], v[48:51]
	v_mfma_f32_16x16x32_bf16 v[44:47], v[128:131], v[200:203], v[44:47]
	v_mfma_f32_16x16x32_bf16 v[44:47], v[132:135], v[204:207], v[44:47]
	v_mfma_f32_16x16x32_bf16 v[40:43], v[136:139], v[200:203], v[40:43]
	v_mfma_f32_16x16x32_bf16 v[40:43], v[140:143], v[204:207], v[40:43]
	v_mfma_f32_16x16x32_bf16 v[36:39], v[128:131], v[208:211], v[36:39]
	v_mfma_f32_16x16x32_bf16 v[36:39], v[132:135], v[212:215], v[36:39]
	v_mfma_f32_16x16x32_bf16 v[32:35], v[136:139], v[208:211], v[32:35]
	v_mfma_f32_16x16x32_bf16 v[32:35], v[140:143], v[212:215], v[32:35]
	s_setprio 0
	s_setprio 1
	v_mfma_f32_16x16x32_bf16 v[28:31], v[144:147], v[184:187], v[28:31]
	v_mfma_f32_16x16x32_bf16 v[28:31], v[162:165], v[188:191], v[28:31]
	v_mfma_f32_16x16x32_bf16 v[24:27], v[166:169], v[184:187], v[24:27]
	v_mfma_f32_16x16x32_bf16 v[24:27], v[180:183], v[188:191], v[24:27]
	v_mfma_f32_16x16x32_bf16 v[20:23], v[144:147], v[192:195], v[20:23]
	v_mfma_f32_16x16x32_bf16 v[20:23], v[162:165], v[196:199], v[20:23]
	v_mfma_f32_16x16x32_bf16 v[16:19], v[166:169], v[192:195], v[16:19]
	v_mfma_f32_16x16x32_bf16 v[16:19], v[180:183], v[196:199], v[16:19]
	v_mfma_f32_16x16x32_bf16 v[12:15], v[144:147], v[200:203], v[12:15]
	v_mfma_f32_16x16x32_bf16 v[12:15], v[162:165], v[204:207], v[12:15]
	v_mfma_f32_16x16x32_bf16 v[8:11], v[166:169], v[200:203], v[8:11]
	v_mfma_f32_16x16x32_bf16 v[8:11], v[180:183], v[204:207], v[8:11]
	v_mfma_f32_16x16x32_bf16 v[4:7], v[144:147], v[208:211], v[4:7]
	v_mfma_f32_16x16x32_bf16 v[4:7], v[162:165], v[212:215], v[4:7]
	v_mfma_f32_16x16x32_bf16 v[0:3], v[166:169], v[208:211], v[0:3]
	v_mfma_f32_16x16x32_bf16 v[0:3], v[180:183], v[212:215], v[0:3]
	s_setprio 0
	s_barrier
	s_add_i32 s6, s89, 2
	s_cmp_gt_u32 s89, 29
	s_cbranch_scc1 .LBB0_1425
	s_mov_b32 s89, s6
	s_branch .LBB0_1406
